# speedup vs baseline: 1.0036x; 1.0036x over previous
; #define GAS __attribute__((address_space(1)))
; #define STAGE(P, GP, ktrel) do { const GAS char* _g = (GP) + (ktrel) * (BK * 2); \
;     __builtin_amdgcn_global_load_lds((const GAS unsigned*)(_g + so0), (unsigned*)((char*)(P) + tid_ * 16), 16, 0, 0); \
;     __builtin_amdgcn_global_load_lds((const GAS unsigned*)(_g + so1), (unsigned*)((char*)(P) + tid_ * 16 + 8192), 16, 0, 0); } while (0)
; #define WAIT_V(n) asm volatile("s_waitcnt vmcnt(" #n ")" ::: "memory")
; #define WAIT_L(n) asm volatile("s_waitcnt lgkmcnt(" #n ")" ::: "memory")
; #define BAR __builtin_amdgcn_s_barrier()
; #define SCHED __builtin_amdgcn_sched_barrier(0)
; #define LDA(dst, b, h) for (int m = 0; m < 4; ++m) for (int k = 0; k < 2; ++k) \
;     dst[m][k] = *reinterpret_cast<const bf16x8*>((char*)SA(b, h) + lds_byte(wr * 64 + m * 16 + fr, k * 32 + fq * 8))
; #define LDB(dst, b, h) for (int n = 0; n < 2; ++n) for (int k = 0; k < 2; ++k) \
;     dst[n][k] = *reinterpret_cast<const bf16x8*>((char*)SB(b, h) + lds_byte(wc * 32 + n * 16 + fr, k * 32 + fq * 8))
; template <int K, int LD = K>
; __device__ __forceinline__ void gemm_main(const GAS bf16* A, const GAS bf16* Bt, int brow, int bcol, f32x4 (&acc)[2][2][4][2]) {
;     ...
;   bf16x8 At[4][2], B0[2][2], B1[2][2];
;   unsigned so0, so1;
;   { int r_, c_; stage_rc(tid_ * 16, r_, c_); so0 = (unsigned)(r_ * LD + c_) * 2u; stage_rc(tid_ * 16 + 8192, r_, c_); so1 = (unsigned)(r_ * LD + c_) * 2u; }
;   const GAS char* pA0 = (const GAS char*)A + (long)brow * LD * 2; const GAS char* pA1 = pA0 + (long)HALF * LD * 2;
;   const GAS char* pB0 = (const GAS char*)Bt + (long)bcol * LD * 2; const GAS char* pB1 = pB0 + (long)HALF * LD * 2;
;   asm volatile("" : "+s"(pA0), "+s"(pA1), "+s"(pB0), "+s"(pB1));
;   constexpr int nt = K / BK;
;   static_assert(K % 128 == 0 && K >= 256, "K");
;   if (wr == 1) BAR;
;   WAIT_V(0); BAR;
;   BAR;
;   for (int t = 0; t < nt - 2; t += 2) {
;     LDB(B0, 0, 0); SCHED; LDA(At, 0, 0); STAGE(SA(1, 1), pA1, 1);
;     WAIT_L(8); BAR; WAIT_L(0); MMA(0, 0, At, B0); BAR; SCHED;
;     LDB(B1, 0, 1); STAGE(SB(0, 0), pB0, 2);
;     BAR; WAIT_L(0); MMA(0, 1, At, B1); BAR;
;     LDA(At, 0, 1); STAGE(SA(0, 0), pA0, 2);
;     BAR; WAIT_L(0); MMA(1, 0, At, B0); BAR; SCHED;
;     STAGE(SB(0, 1), pB1, 2);
;     WAIT_V(6); BAR; MMA(1, 1, At, B1); BAR;
.LBB0_88:
	s_or_b64 exec, exec, s[24:25]
	v_bfe_i32 v7, v136, 27, 1
	v_lshlrev_b32_e32 v5, 4, v136
	v_lshrrev_b32_e32 v7, 22, v7
	v_add_u32_e32 v7, v5, v7
	v_and_b32_e32 v7, 0xfffffc00, v7
	v_sub_u32_e32 v7, v5, v7
	v_lshrrev_b32_e32 v8, 4, v7
	v_bitop3_b32 v8, v8, v7, 32 bitop3:0x6c
	v_ashrrev_i32_e32 v7, 31, v7
	v_ashrrev_i32_e32 v6, 31, v136
	v_lshrrev_b32_e32 v7, 26, v7
	v_lshrrev_b32_e32 v6, 26, v6
	v_add_u32_e32 v7, v8, v7
	v_add_u32_e32 v6, v136, v6
	v_ashrrev_i32_e32 v7, 6, v7
	v_ashrrev_i32_e32 v6, 6, v6
	v_mul_i32_i24_e32 v10, 64, v7
	v_lshlrev_b32_e32 v9, 3, v6
	v_lshlrev_b32_e32 v6, 5, v6
	v_sub_u32_e32 v8, v8, v10
	v_and_b32_e32 v9, 0x1ffff0, v9
	v_and_b32_e32 v6, 32, v6
	v_ashrrev_i16_sdwa v8, v134, sext(v8) dst_sel:DWORD dst_unused:UNUSED_PAD src0_sel:DWORD src1_sel:BYTE_0
	v_add_u32_sdwa v6, v6, sext(v8) dst_sel:DWORD dst_unused:UNUSED_PAD src0_sel:DWORD src1_sel:WORD_0
	v_add_lshl_u32 v7, v7, v9, 11
	v_lshl_add_u32 v130, v6, 1, v7
	v_add_u32_e32 v6, 0x2000, v5
	v_ashrrev_i32_e32 v7, 31, v6
	v_lshrrev_b32_e32 v7, 22, v7
	v_add_u32_e32 v7, v6, v7
	v_ashrrev_i32_e32 v7, 10, v7
	v_mul_i32_i24_e32 v8, 0x400, v7
	v_sub_u32_e32 v6, v6, v8
	v_lshrrev_b32_e32 v8, 4, v6
	v_bitop3_b32 v6, v8, v6, 32 bitop3:0x6c
	v_ashrrev_i32_e32 v9, 31, v6
	v_lshrrev_b32_e32 v9, 26, v9
	v_add_u32_e32 v9, v6, v9
	v_lshrrev_b32_e32 v10, 6, v9
	v_and_b32_e32 v9, 0xc0, v9
	v_lshlrev_b32_e32 v8, 3, v7
	v_lshlrev_b32_e32 v7, 5, v7
	v_sub_u32_e32 v6, v6, v9
	v_and_b32_e32 v8, 0x1ffff0, v8
	v_and_b32_e32 v7, 32, v7
	v_ashrrev_i16_sdwa v6, v134, sext(v6) dst_sel:DWORD dst_unused:UNUSED_PAD src0_sel:DWORD src1_sel:BYTE_0
	v_add_u32_sdwa v6, v7, sext(v6) dst_sel:DWORD dst_unused:UNUSED_PAD src0_sel:DWORD src1_sel:WORD_0
	v_add_lshl_u32 v7, v10, v8, 11
	v_and_b32_e32 v3, 15, v136
	v_lshl_add_u32 v132, v6, 1, v7
	v_lshlrev_b32_e32 v6, 2, v136
	v_and_b32_e32 v4, 48, v136
	v_lshlrev_b32_e32 v3, 6, v3
	v_and_b32_e32 v6, 32, v6
	v_lshlrev_b32_e32 v11, 6, v136
	v_bitop3_b32 v3, v3, v6, v4 bitop3:0x36
	v_lshlrev_b32_e32 v13, 13, v2
	v_and_or_b32 v2, v11, s38, v4
	v_add_u32_e32 v7, s29, v3
	v_add_u32_e32 v8, s30, v3
	v_add_u32_e32 v9, s31, v3
	v_add_u32_e32 v10, s33, v3
	v_and_b32_e32 v12, 0x3000, v11
	v_add_u32_e32 v3, 0x100, v3
	v_xad_u32 v4, v2, v6, s34
	v_or_b32_e32 v6, 0x800, v13
	v_or_b32_e32 v11, 0x1000, v13
	v_or_b32_e32 v14, 0x1800, v13
	v_mov_b32_e32 v2, 0
	v_add_u32_e32 v145, 0x100, v5
	v_add_u32_e32 v146, s29, v5
	v_add_u32_e32 v147, s30, v5
	v_add_u32_e32 v148, s31, v5
	v_add_u32_e32 v149, s33, v5
	v_mov_b32_e32 v133, v131
	s_mov_b32 s17, -2
	v_add_u32_e32 v144, v7, v12
	v_add_u32_e32 v140, v3, v13
	v_add_u32_e32 v139, v4, v6
	v_add_u32_e32 v138, v4, v11
	v_add_u32_e32 v137, v4, v14
	v_add_u32_e32 v143, v8, v12
	v_add_u32_e32 v142, v9, v12
	v_add_u32_e32 v141, v10, v12
	v_add_u32_e32 v151, 0xc000, v145
	v_add_u32_e32 v150, 0xe000, v145
	v_add_u32_e32 v152, 0x2000, v145
	v_add_u32_e32 v153, 0x4000, v145
	v_add_u32_e32 v154, 0x6000, v145
	v_add_u32_e32 v155, 0x8000, v145
	v_add_u32_e32 v156, 0xa000, v145
	v_add_u32_e32 v157, 0x2000, v146
	v_add_u32_e32 v158, 0x2000, v147
	v_add_u32_e32 v159, 0x2000, v148
	v_add_u32_e32 v160, 0x2000, v149
	s_waitcnt vmcnt(0)
	s_barrier
	s_barrier
	ds_read_b128 v[162:165], v144
	ds_read_b128 v[166:169], v144 offset:1024
	ds_read_b128 v[174:177], v144 offset:2048
	ds_read_b128 v[178:181], v144 offset:3072
	v_lshl_add_u64 v[230:231], s[14:15], 0, v[130:131]
	v_readfirstlane_b32 s24, v151
	v_lshl_add_u64 v[214:215], v[230:231], 0, s[8:9]
	s_mov_b32 m0, s24
	v_lshl_add_u64 v[232:233], s[14:15], 0, v[132:133]
	v_readfirstlane_b32 s24, v150
	ds_read_b128 v[182:185], v140
	ds_read_b128 v[186:189], v140 offset:1024
	ds_read_b128 v[190:193], v139
	ds_read_b128 v[194:197], v139 offset:1024
	ds_read_b128 v[198:201], v138
	ds_read_b128 v[202:205], v138 offset:1024
	ds_read_b128 v[206:209], v137
	ds_read_b128 v[210:213], v137 offset:1024
	global_load_lds_dwordx4 v[214:215], off
	v_lshl_add_u64 v[214:215], v[232:233], 0, s[8:9]
	s_mov_b32 m0, s24
	s_nop 0
	global_load_lds_dwordx4 v[214:215], off
	s_waitcnt lgkmcnt(8)
	s_waitcnt vmcnt(10)
	s_barrier
	s_waitcnt lgkmcnt(0)
	s_waitcnt lgkmcnt(0)
	v_mfma_f32_16x16x32_bf16 v[126:129], v[182:185], v[162:165], 0
	v_mfma_f32_16x16x32_bf16 v[122:125], v[182:185], v[174:177], 0
	v_mfma_f32_16x16x32_bf16 v[118:121], v[190:193], v[162:165], 0
	v_mfma_f32_16x16x32_bf16 v[114:117], v[190:193], v[174:177], 0
	v_mfma_f32_16x16x32_bf16 v[110:113], v[198:201], v[162:165], 0
	v_mfma_f32_16x16x32_bf16 v[106:109], v[198:201], v[174:177], 0
	v_mfma_f32_16x16x32_bf16 v[102:105], v[206:209], v[162:165], 0
	v_mfma_f32_16x16x32_bf16 v[98:101], v[206:209], v[174:177], 0
	v_mfma_f32_16x16x32_bf16 v[126:129], v[186:189], v[166:169], v[126:129]
	v_mfma_f32_16x16x32_bf16 v[122:125], v[186:189], v[178:181], v[122:125]
	v_mfma_f32_16x16x32_bf16 v[118:121], v[194:197], v[166:169], v[118:121]
	v_mfma_f32_16x16x32_bf16 v[114:117], v[194:197], v[178:181], v[114:117]
	v_mfma_f32_16x16x32_bf16 v[110:113], v[202:205], v[166:169], v[110:113]
	v_mfma_f32_16x16x32_bf16 v[106:109], v[202:205], v[178:181], v[106:109]
	v_mfma_f32_16x16x32_bf16 v[102:105], v[210:213], v[166:169], v[102:105]
	v_mfma_f32_16x16x32_bf16 v[98:101], v[210:213], v[178:181], v[98:101]
	s_barrier
	v_lshl_add_u64 v[234:235], s[22:23], 0, v[130:131]
	v_readfirstlane_b32 s24, v146
	v_lshl_add_u64 v[236:237], v[234:235], 0, s[10:11]
	s_mov_b32 m0, s24
	ds_read_b128 v[214:217], v143
	ds_read_b128 v[218:221], v143 offset:1024
	ds_read_b128 v[222:225], v143 offset:2048
	ds_read_b128 v[226:229], v143 offset:3072
	global_load_lds_dwordx4 v[236:237], off
	v_lshl_add_u64 v[236:237], s[22:23], 0, v[132:133]
	v_readfirstlane_b32 s24, v157
	v_lshl_add_u64 v[238:239], v[236:237], 0, s[10:11]
	s_mov_b32 m0, s24
	s_add_u32 s22, s22, 0x100
	global_load_lds_dwordx4 v[238:239], off
	s_waitcnt vmcnt(10)
	s_barrier
; #define STAGE(P, GP, ktrel) do { const GAS char* _g = (GP) + (ktrel) * (BK * 2); \
;     __builtin_amdgcn_global_load_lds((const GAS unsigned*)(_g + so0), (unsigned*)((char*)(P) + tid_ * 16), 16, 0, 0); \
;     __builtin_amdgcn_global_load_lds((const GAS unsigned*)(_g + so1), (unsigned*)((char*)(P) + tid_ * 16 + 8192), 16, 0, 0); } while (0)
; #define WAIT_V(n) asm volatile("s_waitcnt vmcnt(" #n ")" ::: "memory")
; #define WAIT_L(n) asm volatile("s_waitcnt lgkmcnt(" #n ")" ::: "memory")
; #define BAR __builtin_amdgcn_s_barrier()
; #define SCHED __builtin_amdgcn_sched_barrier(0)
; #define LDA(dst, b, h) for (int m = 0; m < 4; ++m) for (int k = 0; k < 2; ++k) \
;     dst[m][k] = *reinterpret_cast<const bf16x8*>((char*)SA(b, h) + lds_byte(wr * 64 + m * 16 + fr, k * 32 + fq * 8))
; #define LDB(dst, b, h) for (int n = 0; n < 2; ++n) for (int k = 0; k < 2; ++k) \
;     dst[n][k] = *reinterpret_cast<const bf16x8*>((char*)SB(b, h) + lds_byte(wc * 32 + n * 16 + fr, k * 32 + fq * 8))
; #define MMA(ai, bj, At_, Bt_) do { __builtin_amdgcn_s_setprio(1); \
;     for (int m = 0; m < 4; ++m) for (int n = 0; n < 2; ++n) for (int k = 0; k < 2; ++k) \
;       acc[ai][bj][m][n] = __builtin_amdgcn_mfma_f32_16x16x32_bf16(At_[m][k], Bt_[n][k], acc[ai][bj][m][n], 0, 0, 0); \
;     __builtin_amdgcn_s_setprio(0); } while (0)
; template <int K, int LD = K>
; __device__ __forceinline__ void gemm_main(const GAS bf16* A, const GAS bf16* Bt, int brow, int bcol, f32x4 (&acc)[2][2][4][2]) {
;     ...
;     LDB(B1, 0, 1); STAGE(SB(0, 0), pB0, 2);
;     BAR; WAIT_L(0); MMA(0, 1, At, B1); BAR;
;     LDA(At, 0, 1); STAGE(SA(0, 0), pA0, 2);
;     BAR; WAIT_L(0); MMA(1, 0, At, B0); BAR; SCHED;
;     STAGE(SB(0, 1), pB1, 2);
;     WAIT_V(6); BAR; MMA(1, 1, At, B1); BAR;
;     LDB(B0, 1, 0); SCHED; LDA(At, 1, 0); STAGE(SA(0, 1), pA1, 2);
;     WAIT_L(8); BAR; WAIT_L(0); MMA(0, 0, At, B0); BAR; SCHED;
	s_waitcnt lgkmcnt(0)
	s_addc_u32 s23, s23, 0
	s_waitcnt lgkmcnt(0)
	v_mfma_f32_16x16x32_bf16 v[94:97], v[182:185], v[214:217], 0
	v_mfma_f32_16x16x32_bf16 v[90:93], v[182:185], v[222:225], 0
	v_mfma_f32_16x16x32_bf16 v[86:89], v[190:193], v[214:217], 0
	v_mfma_f32_16x16x32_bf16 v[82:85], v[190:193], v[222:225], 0
	v_mfma_f32_16x16x32_bf16 v[78:81], v[198:201], v[214:217], 0
	v_mfma_f32_16x16x32_bf16 v[74:77], v[198:201], v[222:225], 0
	v_mfma_f32_16x16x32_bf16 v[70:73], v[206:209], v[214:217], 0
	v_mfma_f32_16x16x32_bf16 v[66:69], v[206:209], v[222:225], 0
	v_mfma_f32_16x16x32_bf16 v[94:97], v[186:189], v[218:221], v[94:97]
	v_mfma_f32_16x16x32_bf16 v[90:93], v[186:189], v[226:229], v[90:93]
	v_mfma_f32_16x16x32_bf16 v[86:89], v[194:197], v[218:221], v[86:89]
	v_mfma_f32_16x16x32_bf16 v[82:85], v[194:197], v[226:229], v[82:85]
	v_mfma_f32_16x16x32_bf16 v[78:81], v[202:205], v[218:221], v[78:81]
	v_mfma_f32_16x16x32_bf16 v[74:77], v[202:205], v[226:229], v[74:77]
	v_mfma_f32_16x16x32_bf16 v[70:73], v[210:213], v[218:221], v[70:73]
	v_mfma_f32_16x16x32_bf16 v[66:69], v[210:213], v[226:229], v[66:69]
	v_lshl_add_u64 v[238:239], s[20:21], 0, v[130:131]
	v_readfirstlane_b32 s24, v145
	v_lshl_add_u64 v[240:241], v[238:239], 0, s[10:11]
	s_mov_b32 m0, s24
	s_barrier
	ds_read_b128 v[182:185], v140 offset:16384
	ds_read_b128 v[186:189], v140 offset:17408
	ds_read_b128 v[190:193], v139 offset:16384
	ds_read_b128 v[194:197], v139 offset:17408
	ds_read_b128 v[198:201], v138 offset:16384
	ds_read_b128 v[202:205], v138 offset:17408
	ds_read_b128 v[206:209], v137 offset:16384
	ds_read_b128 v[210:213], v137 offset:17408
	global_load_lds_dwordx4 v[240:241], off
	v_lshl_add_u64 v[240:241], s[20:21], 0, v[132:133]
	v_readfirstlane_b32 s24, v152
	v_lshl_add_u64 v[242:243], v[240:241], 0, s[10:11]
	s_mov_b32 m0, s24
	s_add_u32 s20, s20, 0x100
	global_load_lds_dwordx4 v[242:243], off
	s_barrier
	s_waitcnt lgkmcnt(0)
	s_addc_u32 s21, s21, 0
	s_waitcnt lgkmcnt(0)
	v_mfma_f32_16x16x32_bf16 v[62:65], v[182:185], v[162:165], 0
	v_mfma_f32_16x16x32_bf16 v[58:61], v[182:185], v[174:177], 0
	v_mfma_f32_16x16x32_bf16 v[54:57], v[190:193], v[162:165], 0
	v_mfma_f32_16x16x32_bf16 v[50:53], v[190:193], v[174:177], 0
	v_mfma_f32_16x16x32_bf16 v[46:49], v[198:201], v[162:165], 0
	v_mfma_f32_16x16x32_bf16 v[42:45], v[198:201], v[174:177], 0
	v_mfma_f32_16x16x32_bf16 v[38:41], v[206:209], v[162:165], 0
	v_mfma_f32_16x16x32_bf16 v[34:37], v[206:209], v[174:177], 0
	v_mfma_f32_16x16x32_bf16 v[62:65], v[186:189], v[166:169], v[62:65]
	v_mfma_f32_16x16x32_bf16 v[58:61], v[186:189], v[178:181], v[58:61]
	v_mfma_f32_16x16x32_bf16 v[54:57], v[194:197], v[166:169], v[54:57]
	v_mfma_f32_16x16x32_bf16 v[50:53], v[194:197], v[178:181], v[50:53]
	v_mfma_f32_16x16x32_bf16 v[46:49], v[202:205], v[166:169], v[46:49]
	v_mfma_f32_16x16x32_bf16 v[42:45], v[202:205], v[178:181], v[42:45]
	v_mfma_f32_16x16x32_bf16 v[38:41], v[210:213], v[166:169], v[38:41]
	v_mfma_f32_16x16x32_bf16 v[34:37], v[210:213], v[178:181], v[34:37]
	s_barrier
	v_lshl_add_u64 v[242:243], s[18:19], 0, v[130:131]
	v_readfirstlane_b32 s24, v147
	v_lshl_add_u64 v[162:163], v[242:243], 0, s[10:11]
	s_mov_b32 m0, s24
	v_lshl_add_u64 v[244:245], s[18:19], 0, v[132:133]
	v_readfirstlane_b32 s24, v158
	global_load_lds_dwordx4 v[162:163], off
	v_lshl_add_u64 v[162:163], v[244:245], 0, s[10:11]
	s_mov_b32 m0, s24
	s_add_u32 s18, s18, 0x100
	global_load_lds_dwordx4 v[162:163], off
	s_waitcnt vmcnt(10)
	s_addc_u32 s19, s19, 0
	s_barrier
	v_mfma_f32_16x16x32_bf16 v[30:33], v[182:185], v[214:217], 0
	v_mfma_f32_16x16x32_bf16 v[26:29], v[182:185], v[222:225], 0
	v_mfma_f32_16x16x32_bf16 v[22:25], v[190:193], v[214:217], 0
	v_mfma_f32_16x16x32_bf16 v[18:21], v[190:193], v[222:225], 0
	v_mfma_f32_16x16x32_bf16 v[14:17], v[198:201], v[214:217], 0
	v_mfma_f32_16x16x32_bf16 v[10:13], v[198:201], v[222:225], 0
	v_mfma_f32_16x16x32_bf16 v[6:9], v[206:209], v[214:217], 0
	v_mfma_f32_16x16x32_bf16 v[2:5], v[206:209], v[222:225], 0
	v_mfma_f32_16x16x32_bf16 v[30:33], v[186:189], v[218:221], v[30:33]
	v_mfma_f32_16x16x32_bf16 v[26:29], v[186:189], v[226:229], v[26:29]
	v_mfma_f32_16x16x32_bf16 v[22:25], v[194:197], v[218:221], v[22:25]
	v_mfma_f32_16x16x32_bf16 v[18:21], v[194:197], v[226:229], v[18:21]
	v_mfma_f32_16x16x32_bf16 v[14:17], v[202:205], v[218:221], v[14:17]
	v_mfma_f32_16x16x32_bf16 v[10:13], v[202:205], v[226:229], v[10:13]
	v_mfma_f32_16x16x32_bf16 v[6:9], v[210:213], v[218:221], v[6:9]
	v_mfma_f32_16x16x32_bf16 v[2:5], v[210:213], v[226:229], v[2:5]
	s_barrier
	ds_read_b128 v[162:165], v142
	ds_read_b128 v[166:169], v142 offset:1024
	ds_read_b128 v[174:177], v142 offset:2048
	ds_read_b128 v[178:181], v142 offset:3072
	v_readfirstlane_b32 s24, v153
	v_lshl_add_u64 v[214:215], v[230:231], 0, s[10:11]
	s_mov_b32 m0, s24
	v_readfirstlane_b32 s24, v154
	ds_read_b128 v[182:185], v140 offset:32768
	ds_read_b128 v[186:189], v140 offset:33792
	ds_read_b128 v[190:193], v139 offset:32768
	ds_read_b128 v[194:197], v139 offset:33792
	ds_read_b128 v[198:201], v138 offset:32768
	ds_read_b128 v[202:205], v138 offset:33792
	ds_read_b128 v[206:209], v137 offset:32768
	ds_read_b128 v[210:213], v137 offset:33792
	global_load_lds_dwordx4 v[214:215], off
	v_lshl_add_u64 v[214:215], v[232:233], 0, s[10:11]
	s_mov_b32 m0, s24
	s_add_u32 s14, s14, 0x100
	global_load_lds_dwordx4 v[214:215], off
	s_waitcnt lgkmcnt(8)
	s_waitcnt vmcnt(10)
	s_barrier
; #define STAGE(P, GP, ktrel) do { const GAS char* _g = (GP) + (ktrel) * (BK * 2); \
;     __builtin_amdgcn_global_load_lds((const GAS unsigned*)(_g + so0), (unsigned*)((char*)(P) + tid_ * 16), 16, 0, 0); \
;     __builtin_amdgcn_global_load_lds((const GAS unsigned*)(_g + so1), (unsigned*)((char*)(P) + tid_ * 16 + 8192), 16, 0, 0); } while (0)
; #define WAIT_V(n) asm volatile("s_waitcnt vmcnt(" #n ")" ::: "memory")
; #define WAIT_L(n) asm volatile("s_waitcnt lgkmcnt(" #n ")" ::: "memory")
; #define BAR __builtin_amdgcn_s_barrier()
; #define SCHED __builtin_amdgcn_sched_barrier(0)
; #define LDA(dst, b, h) for (int m = 0; m < 4; ++m) for (int k = 0; k < 2; ++k) \
;     dst[m][k] = *reinterpret_cast<const bf16x8*>((char*)SA(b, h) + lds_byte(wr * 64 + m * 16 + fr, k * 32 + fq * 8))
; #define LDB(dst, b, h) for (int n = 0; n < 2; ++n) for (int k = 0; k < 2; ++k) \
;     dst[n][k] = *reinterpret_cast<const bf16x8*>((char*)SB(b, h) + lds_byte(wc * 32 + n * 16 + fr, k * 32 + fq * 8))
; #define MMA(ai, bj, At_, Bt_) do { __builtin_amdgcn_s_setprio(1); \
;     for (int m = 0; m < 4; ++m) for (int n = 0; n < 2; ++n) for (int k = 0; k < 2; ++k) \
;       acc[ai][bj][m][n] = __builtin_amdgcn_mfma_f32_16x16x32_bf16(At_[m][k], Bt_[n][k], acc[ai][bj][m][n], 0, 0, 0); \
;     __builtin_amdgcn_s_setprio(0); } while (0)
; template <int K, int LD = K>
; __device__ __forceinline__ void gemm_main(const GAS bf16* A, const GAS bf16* Bt, int brow, int bcol, f32x4 (&acc)[2][2][4][2]) {
;     ...
;     LDB(B0, 1, 0); SCHED; LDA(At, 1, 0); STAGE(SA(0, 1), pA1, 2);
;     WAIT_L(8); BAR; WAIT_L(0); MMA(0, 0, At, B0); BAR; SCHED;
;     LDB(B1, 1, 1); STAGE(SB(1, 0), pB0, 3);
;     BAR; WAIT_L(0); MMA(0, 1, At, B1); BAR;
;     LDA(At, 1, 1); STAGE(SA(1, 0), pA0, 3);
;     BAR; WAIT_L(0); MMA(1, 0, At, B0); BAR; SCHED;
;     STAGE(SB(1, 1), pB1, 3);
;     WAIT_V(6); BAR; MMA(1, 1, At, B1); BAR;
;     pA0 += 4 * BK; pA1 += 4 * BK; pB0 += 4 * BK; pB1 += 4 * BK;
;     asm volatile("" : "+s"(pA0), "+s"(pA1), "+s"(pB0), "+s"(pB1));
	s_waitcnt lgkmcnt(0)
	s_addc_u32 s15, s15, 0
	s_waitcnt lgkmcnt(0)
	v_mfma_f32_16x16x32_bf16 v[126:129], v[182:185], v[162:165], v[126:129]
	v_mfma_f32_16x16x32_bf16 v[122:125], v[182:185], v[174:177], v[122:125]
	v_mfma_f32_16x16x32_bf16 v[118:121], v[190:193], v[162:165], v[118:121]
	v_mfma_f32_16x16x32_bf16 v[114:117], v[190:193], v[174:177], v[114:117]
	v_mfma_f32_16x16x32_bf16 v[110:113], v[198:201], v[162:165], v[110:113]
	v_mfma_f32_16x16x32_bf16 v[106:109], v[198:201], v[174:177], v[106:109]
	v_mfma_f32_16x16x32_bf16 v[102:105], v[206:209], v[162:165], v[102:105]
	v_mfma_f32_16x16x32_bf16 v[98:101], v[206:209], v[174:177], v[98:101]
	v_mfma_f32_16x16x32_bf16 v[126:129], v[186:189], v[166:169], v[126:129]
	v_mfma_f32_16x16x32_bf16 v[122:125], v[186:189], v[178:181], v[122:125]
	v_mfma_f32_16x16x32_bf16 v[118:121], v[194:197], v[166:169], v[118:121]
	v_mfma_f32_16x16x32_bf16 v[114:117], v[194:197], v[178:181], v[114:117]
	v_mfma_f32_16x16x32_bf16 v[110:113], v[202:205], v[166:169], v[110:113]
	v_mfma_f32_16x16x32_bf16 v[106:109], v[202:205], v[178:181], v[106:109]
	v_mfma_f32_16x16x32_bf16 v[102:105], v[210:213], v[166:169], v[102:105]
	v_mfma_f32_16x16x32_bf16 v[98:101], v[210:213], v[178:181], v[98:101]
	s_barrier
	v_readfirstlane_b32 s24, v148
	v_lshl_add_u64 v[230:231], v[234:235], 0, s[12:13]
	s_mov_b32 m0, s24
	v_readfirstlane_b32 s24, v159
	ds_read_b128 v[214:217], v141
	ds_read_b128 v[218:221], v141 offset:1024
	ds_read_b128 v[222:225], v141 offset:2048
	ds_read_b128 v[226:229], v141 offset:3072
	global_load_lds_dwordx4 v[230:231], off
	v_lshl_add_u64 v[230:231], v[236:237], 0, s[12:13]
	s_mov_b32 m0, s24
	s_nop 0
	global_load_lds_dwordx4 v[230:231], off
	s_waitcnt vmcnt(10)
	s_barrier
	s_waitcnt lgkmcnt(0)
	s_waitcnt lgkmcnt(0)
	v_mfma_f32_16x16x32_bf16 v[94:97], v[182:185], v[214:217], v[94:97]
	v_mfma_f32_16x16x32_bf16 v[90:93], v[182:185], v[222:225], v[90:93]
	v_mfma_f32_16x16x32_bf16 v[86:89], v[190:193], v[214:217], v[86:89]
	v_mfma_f32_16x16x32_bf16 v[82:85], v[190:193], v[222:225], v[82:85]
	v_mfma_f32_16x16x32_bf16 v[78:81], v[198:201], v[214:217], v[78:81]
	v_mfma_f32_16x16x32_bf16 v[74:77], v[198:201], v[222:225], v[74:77]
	v_mfma_f32_16x16x32_bf16 v[70:73], v[206:209], v[214:217], v[70:73]
	v_mfma_f32_16x16x32_bf16 v[66:69], v[206:209], v[222:225], v[66:69]
	v_mfma_f32_16x16x32_bf16 v[94:97], v[186:189], v[218:221], v[94:97]
	v_mfma_f32_16x16x32_bf16 v[90:93], v[186:189], v[226:229], v[90:93]
	v_mfma_f32_16x16x32_bf16 v[86:89], v[194:197], v[218:221], v[86:89]
	v_mfma_f32_16x16x32_bf16 v[82:85], v[194:197], v[226:229], v[82:85]
	v_mfma_f32_16x16x32_bf16 v[78:81], v[202:205], v[218:221], v[78:81]
	v_mfma_f32_16x16x32_bf16 v[74:77], v[202:205], v[226:229], v[74:77]
	v_mfma_f32_16x16x32_bf16 v[70:73], v[210:213], v[218:221], v[70:73]
	v_mfma_f32_16x16x32_bf16 v[66:69], v[210:213], v[226:229], v[66:69]
	v_readfirstlane_b32 s24, v155
	v_lshl_add_u64 v[230:231], v[238:239], 0, s[12:13]
	s_mov_b32 m0, s24
	v_readfirstlane_b32 s24, v156
	s_barrier
	ds_read_b128 v[182:185], v140 offset:49152
	ds_read_b128 v[186:189], v140 offset:50176
	ds_read_b128 v[190:193], v139 offset:49152
	ds_read_b128 v[194:197], v139 offset:50176
	ds_read_b128 v[198:201], v138 offset:49152
	ds_read_b128 v[202:205], v138 offset:50176
	ds_read_b128 v[206:209], v137 offset:49152
	ds_read_b128 v[210:213], v137 offset:50176
	global_load_lds_dwordx4 v[230:231], off
	v_lshl_add_u64 v[230:231], v[240:241], 0, s[12:13]
	s_mov_b32 m0, s24
	s_nop 0
	global_load_lds_dwordx4 v[230:231], off
	s_barrier
	s_waitcnt lgkmcnt(0)
	s_waitcnt lgkmcnt(0)
	v_mfma_f32_16x16x32_bf16 v[62:65], v[182:185], v[162:165], v[62:65]
	v_mfma_f32_16x16x32_bf16 v[58:61], v[182:185], v[174:177], v[58:61]
	v_mfma_f32_16x16x32_bf16 v[54:57], v[190:193], v[162:165], v[54:57]
	v_mfma_f32_16x16x32_bf16 v[50:53], v[190:193], v[174:177], v[50:53]
	v_mfma_f32_16x16x32_bf16 v[46:49], v[198:201], v[162:165], v[46:49]
	v_mfma_f32_16x16x32_bf16 v[42:45], v[198:201], v[174:177], v[42:45]
	v_mfma_f32_16x16x32_bf16 v[38:41], v[206:209], v[162:165], v[38:41]
	v_mfma_f32_16x16x32_bf16 v[34:37], v[206:209], v[174:177], v[34:37]
	v_mfma_f32_16x16x32_bf16 v[62:65], v[186:189], v[166:169], v[62:65]
	v_mfma_f32_16x16x32_bf16 v[58:61], v[186:189], v[178:181], v[58:61]
	v_mfma_f32_16x16x32_bf16 v[54:57], v[194:197], v[166:169], v[54:57]
	v_mfma_f32_16x16x32_bf16 v[50:53], v[194:197], v[178:181], v[50:53]
	v_mfma_f32_16x16x32_bf16 v[46:49], v[202:205], v[166:169], v[46:49]
	v_mfma_f32_16x16x32_bf16 v[42:45], v[202:205], v[178:181], v[42:45]
	v_mfma_f32_16x16x32_bf16 v[38:41], v[210:213], v[166:169], v[38:41]
	v_mfma_f32_16x16x32_bf16 v[34:37], v[210:213], v[178:181], v[34:37]
	s_barrier
	v_readfirstlane_b32 s24, v149
	v_lshl_add_u64 v[162:163], v[242:243], 0, s[12:13]
	s_mov_b32 m0, s24
	v_readfirstlane_b32 s24, v160
	global_load_lds_dwordx4 v[162:163], off
	v_lshl_add_u64 v[162:163], v[244:245], 0, s[12:13]
	s_mov_b32 m0, s24
	s_nop 0
	global_load_lds_dwordx4 v[162:163], off
	s_waitcnt vmcnt(10)
	s_barrier
	v_mfma_f32_16x16x32_bf16 v[30:33], v[182:185], v[214:217], v[30:33]
	v_mfma_f32_16x16x32_bf16 v[26:29], v[182:185], v[222:225], v[26:29]
	v_mfma_f32_16x16x32_bf16 v[22:25], v[190:193], v[214:217], v[22:25]
	v_mfma_f32_16x16x32_bf16 v[18:21], v[190:193], v[222:225], v[18:21]
	v_mfma_f32_16x16x32_bf16 v[14:17], v[198:201], v[214:217], v[14:17]
	v_mfma_f32_16x16x32_bf16 v[10:13], v[198:201], v[222:225], v[10:13]
	v_mfma_f32_16x16x32_bf16 v[6:9], v[206:209], v[214:217], v[6:9]
	v_mfma_f32_16x16x32_bf16 v[2:5], v[206:209], v[222:225], v[2:5]
	v_mfma_f32_16x16x32_bf16 v[30:33], v[186:189], v[218:221], v[30:33]
	v_mfma_f32_16x16x32_bf16 v[26:29], v[186:189], v[226:229], v[26:29]
	v_mfma_f32_16x16x32_bf16 v[22:25], v[194:197], v[218:221], v[22:25]
	v_mfma_f32_16x16x32_bf16 v[18:21], v[194:197], v[226:229], v[18:21]
	v_mfma_f32_16x16x32_bf16 v[14:17], v[202:205], v[218:221], v[14:17]
	v_mfma_f32_16x16x32_bf16 v[10:13], v[202:205], v[226:229], v[10:13]
	v_mfma_f32_16x16x32_bf16 v[6:9], v[210:213], v[218:221], v[6:9]
	v_mfma_f32_16x16x32_bf16 v[2:5], v[210:213], v[226:229], v[2:5]
	s_add_i32 s17, s17, 2
	s_cmp_lt_u32 s17, 12
	s_barrier
	s_cbranch_scc1 .LBB0_89
	s_branch .Lpeel8_exit

; #define STAGE(P, GP, ktrel) do { const GAS char* _g = (GP) + (ktrel) * (BK * 2); \
;     __builtin_amdgcn_global_load_lds((const GAS unsigned*)(_g + so0), (unsigned*)((char*)(P) + tid_ * 16), 16, 0, 0); \
;     __builtin_amdgcn_global_load_lds((const GAS unsigned*)(_g + so1), (unsigned*)((char*)(P) + tid_ * 16 + 8192), 16, 0, 0); } while (0)
; #define WAIT_V(n) asm volatile("s_waitcnt vmcnt(" #n ")" ::: "memory")
; #define WAIT_L(n) asm volatile("s_waitcnt lgkmcnt(" #n ")" ::: "memory")
; #define BAR __builtin_amdgcn_s_barrier()
; #define LDA(dst, b, h) for (int m = 0; m < 4; ++m) for (int k = 0; k < 2; ++k) \
;     dst[m][k] = *reinterpret_cast<const bf16x8*>((char*)SA(b, h) + lds_byte(wr * 64 + m * 16 + fr, k * 32 + fq * 8))
; #define LDB(dst, b, h) for (int n = 0; n < 2; ++n) for (int k = 0; k < 2; ++k) \
;     dst[n][k] = *reinterpret_cast<const bf16x8*>((char*)SB(b, h) + lds_byte(wc * 32 + n * 16 + fr, k * 32 + fq * 8))
; #define MMA(ai, bj, At_, Bt_) do { __builtin_amdgcn_s_setprio(1); \
;     for (int m = 0; m < 4; ++m) for (int n = 0; n < 2; ++n) for (int k = 0; k < 2; ++k) \
;       acc[ai][bj][m][n] = __builtin_amdgcn_mfma_f32_16x16x32_bf16(At_[m][k], Bt_[n][k], acc[ai][bj][m][n], 0, 0, 0); \
;     __builtin_amdgcn_s_setprio(0); } while (0)
; template <int K, int LD = K>
; __device__ __forceinline__ void gemm_main(const GAS bf16* A, const GAS bf16* Bt, int brow, int bcol, f32x4 (&acc)[2][2][4][2]) {
;     ...
;   { LDB(B0, 0, 0); LDA(At, 0, 0); STAGE(SA(1, 1), pA1, 1);
;     BAR; WAIT_L(0); MMA(0, 0, At, B0); BAR;
;     LDB(B1, 0, 1); BAR; WAIT_L(0); MMA(0, 1, At, B1); BAR;
;     LDA(At, 0, 1); WAIT_V(4); BAR; WAIT_L(0); MMA(1, 0, At, B0); MMA(1, 1, At, B1); BAR; }
.Lpeel8_exit:
	ds_read_b128 v[146:149], v144
	ds_read_b128 v[152:155], v144 offset:1024
	ds_read_b128 v[156:159], v144 offset:2048
	ds_read_b128 v[160:163], v144 offset:3072
	ds_read_b128 v[164:167], v140
	ds_read_b128 v[174:177], v140 offset:1024
	ds_read_b128 v[178:181], v139
	ds_read_b128 v[182:185], v139 offset:1024
	ds_read_b128 v[186:189], v138
	ds_read_b128 v[190:193], v138 offset:1024
	ds_read_b128 v[194:197], v137
	ds_read_b128 v[198:201], v137 offset:1024
	v_lshl_add_u64 v[144:145], s[14:15], 0, v[130:131]
	v_readfirstlane_b32 s17, v151
	v_lshl_add_u64 v[144:145], v[144:145], 0, s[8:9]
	s_mov_b32 m0, s17
	v_lshl_add_u64 v[132:133], s[14:15], 0, v[132:133]
	v_readfirstlane_b32 s14, v150
	global_load_lds_dwordx4 v[144:145], off
	v_lshl_add_u64 v[132:133], v[132:133], 0, s[8:9]
	s_mov_b32 m0, s14
	s_nop 0
	global_load_lds_dwordx4 v[132:133], off
	s_waitcnt vmcnt(10)
	s_barrier
	s_waitcnt lgkmcnt(0)
	s_waitcnt lgkmcnt(0)
	v_mfma_f32_16x16x32_bf16 v[126:129], v[164:167], v[146:149], v[126:129]
	v_mfma_f32_16x16x32_bf16 v[122:125], v[164:167], v[156:159], v[122:125]
	v_mfma_f32_16x16x32_bf16 v[110:113], v[186:189], v[146:149], v[110:113]
	v_mfma_f32_16x16x32_bf16 v[106:109], v[186:189], v[156:159], v[106:109]
	v_mfma_f32_16x16x32_bf16 v[126:129], v[174:177], v[152:155], v[126:129]
	v_mfma_f32_16x16x32_bf16 v[122:125], v[174:177], v[160:163], v[122:125]
	v_mfma_f32_16x16x32_bf16 v[118:121], v[178:181], v[146:149], v[118:121]
	v_mfma_f32_16x16x32_bf16 v[114:117], v[178:181], v[156:159], v[114:117]
	v_mfma_f32_16x16x32_bf16 v[110:113], v[190:193], v[152:155], v[110:113]
	v_mfma_f32_16x16x32_bf16 v[106:109], v[190:193], v[160:163], v[106:109]
	v_mfma_f32_16x16x32_bf16 v[102:105], v[194:197], v[146:149], v[102:105]
	v_mfma_f32_16x16x32_bf16 v[98:101], v[194:197], v[156:159], v[98:101]
	v_mfma_f32_16x16x32_bf16 v[202:205], v[182:185], v[152:155], v[118:121]
	v_mfma_f32_16x16x32_bf16 v[206:209], v[182:185], v[160:163], v[114:117]
	v_mfma_f32_16x16x32_bf16 v[210:213], v[198:201], v[152:155], v[102:105]
	v_mfma_f32_16x16x32_bf16 v[214:217], v[198:201], v[160:163], v[98:101]
	s_barrier
	s_nop 1
	ds_read_b128 v[98:101], v143
	ds_read_b128 v[102:105], v143 offset:1024
	ds_read_b128 v[114:117], v143 offset:2048
	ds_read_b128 v[118:121], v143 offset:3072
	s_waitcnt vmcnt(8)
	s_barrier
	s_waitcnt lgkmcnt(0)
	s_waitcnt lgkmcnt(0)
	v_mfma_f32_16x16x32_bf16 v[94:97], v[164:167], v[98:101], v[94:97]
	v_mfma_f32_16x16x32_bf16 v[90:93], v[164:167], v[114:117], v[90:93]
	v_mfma_f32_16x16x32_bf16 v[78:81], v[186:189], v[98:101], v[78:81]
	v_mfma_f32_16x16x32_bf16 v[74:77], v[186:189], v[114:117], v[74:77]
	v_mfma_f32_16x16x32_bf16 v[94:97], v[174:177], v[102:105], v[94:97]
	v_mfma_f32_16x16x32_bf16 v[90:93], v[174:177], v[118:121], v[90:93]
	v_mfma_f32_16x16x32_bf16 v[86:89], v[178:181], v[98:101], v[86:89]
	v_mfma_f32_16x16x32_bf16 v[82:85], v[178:181], v[114:117], v[82:85]
	v_mfma_f32_16x16x32_bf16 v[78:81], v[190:193], v[102:105], v[78:81]
	v_mfma_f32_16x16x32_bf16 v[74:77], v[190:193], v[118:121], v[74:77]
	v_mfma_f32_16x16x32_bf16 v[70:73], v[194:197], v[98:101], v[70:73]
	v_mfma_f32_16x16x32_bf16 v[66:69], v[194:197], v[114:117], v[66:69]
	v_mfma_f32_16x16x32_bf16 v[164:167], v[182:185], v[102:105], v[86:89]
	v_mfma_f32_16x16x32_bf16 v[174:177], v[182:185], v[118:121], v[82:85]
	v_mfma_f32_16x16x32_bf16 v[178:181], v[198:201], v[102:105], v[70:73]
	v_mfma_f32_16x16x32_bf16 v[182:185], v[198:201], v[118:121], v[66:69]
	s_barrier
	s_nop 1
	ds_read_b128 v[66:69], v140 offset:16384
	ds_read_b128 v[70:73], v140 offset:17408
	ds_read_b128 v[82:85], v139 offset:16384
	ds_read_b128 v[86:89], v139 offset:17408
	ds_read_b128 v[186:189], v138 offset:16384
	ds_read_b128 v[190:193], v138 offset:17408
	ds_read_b128 v[194:197], v137 offset:16384
	ds_read_b128 v[198:201], v137 offset:17408
	s_waitcnt vmcnt(4)
	s_barrier
	s_waitcnt lgkmcnt(0)
	s_waitcnt lgkmcnt(0)
	v_mfma_f32_16x16x32_bf16 v[62:65], v[66:69], v[146:149], v[62:65]
	v_mfma_f32_16x16x32_bf16 v[58:61], v[66:69], v[156:159], v[58:61]
	v_mfma_f32_16x16x32_bf16 v[46:49], v[186:189], v[146:149], v[46:49]
	v_mfma_f32_16x16x32_bf16 v[38:41], v[194:197], v[146:149], v[38:41]
	v_mfma_f32_16x16x32_bf16 v[62:65], v[70:73], v[152:155], v[62:65]
	v_mfma_f32_16x16x32_bf16 v[58:61], v[70:73], v[160:163], v[58:61]
	v_mfma_f32_16x16x32_bf16 v[54:57], v[82:85], v[146:149], v[54:57]
	v_mfma_f32_16x16x32_bf16 v[50:53], v[82:85], v[156:159], v[50:53]
	v_mfma_f32_16x16x32_bf16 v[46:49], v[190:193], v[152:155], v[46:49]
	v_mfma_f32_16x16x32_bf16 v[42:45], v[186:189], v[156:159], v[42:45]
	v_mfma_f32_16x16x32_bf16 v[38:41], v[198:201], v[152:155], v[38:41]
	v_mfma_f32_16x16x32_bf16 v[34:37], v[194:197], v[156:159], v[34:37]
	v_mfma_f32_16x16x32_bf16 v[218:221], v[86:89], v[152:155], v[54:57]
	v_mfma_f32_16x16x32_bf16 v[222:225], v[86:89], v[160:163], v[50:53]
	v_mfma_f32_16x16x32_bf16 v[226:229], v[190:193], v[160:163], v[42:45]
	v_mfma_f32_16x16x32_bf16 v[144:147], v[198:201], v[160:163], v[34:37]
	v_mfma_f32_16x16x32_bf16 v[30:33], v[66:69], v[98:101], v[30:33]
	v_mfma_f32_16x16x32_bf16 v[26:29], v[66:69], v[114:117], v[26:29]
	v_mfma_f32_16x16x32_bf16 v[14:17], v[186:189], v[98:101], v[14:17]
	v_mfma_f32_16x16x32_bf16 v[6:9], v[194:197], v[98:101], v[6:9]
	v_mfma_f32_16x16x32_bf16 v[30:33], v[70:73], v[102:105], v[30:33]
	v_mfma_f32_16x16x32_bf16 v[26:29], v[70:73], v[118:121], v[26:29]
	v_mfma_f32_16x16x32_bf16 v[22:25], v[82:85], v[98:101], v[22:25]
	v_mfma_f32_16x16x32_bf16 v[18:21], v[82:85], v[114:117], v[18:21]
	v_mfma_f32_16x16x32_bf16 v[14:17], v[190:193], v[102:105], v[14:17]
	v_mfma_f32_16x16x32_bf16 v[10:13], v[186:189], v[114:117], v[10:13]
	v_mfma_f32_16x16x32_bf16 v[6:9], v[198:201], v[102:105], v[6:9]
	v_mfma_f32_16x16x32_bf16 v[2:5], v[194:197], v[114:117], v[2:5]
	v_mfma_f32_16x16x32_bf16 v[148:151], v[86:89], v[102:105], v[22:25]
	v_mfma_f32_16x16x32_bf16 v[152:155], v[86:89], v[118:121], v[18:21]
	v_mfma_f32_16x16x32_bf16 v[156:159], v[190:193], v[118:121], v[10:13]
	v_mfma_f32_16x16x32_bf16 v[160:163], v[198:201], v[118:121], v[2:5]
	s_barrier
; #define WAIT_V(n) asm volatile("s_waitcnt vmcnt(" #n ")" ::: "memory")
; #define WAIT_L(n) asm volatile("s_waitcnt lgkmcnt(" #n ")" ::: "memory")
; #define BAR __builtin_amdgcn_s_barrier()
; #define LDA(dst, b, h) for (int m = 0; m < 4; ++m) for (int k = 0; k < 2; ++k) \
;     dst[m][k] = *reinterpret_cast<const bf16x8*>((char*)SA(b, h) + lds_byte(wr * 64 + m * 16 + fr, k * 32 + fq * 8))
; #define LDB(dst, b, h) for (int n = 0; n < 2; ++n) for (int k = 0; k < 2; ++k) \
;     dst[n][k] = *reinterpret_cast<const bf16x8*>((char*)SB(b, h) + lds_byte(wc * 32 + n * 16 + fr, k * 32 + fq * 8))
; #define MMA(ai, bj, At_, Bt_) do { __builtin_amdgcn_s_setprio(1); \
;     for (int m = 0; m < 4; ++m) for (int n = 0; n < 2; ++n) for (int k = 0; k < 2; ++k) \
;       acc[ai][bj][m][n] = __builtin_amdgcn_mfma_f32_16x16x32_bf16(At_[m][k], Bt_[n][k], acc[ai][bj][m][n], 0, 0, 0); \
;     __builtin_amdgcn_s_setprio(0); } while (0)
; template <int K, int LD = K>
; __device__ __forceinline__ void gemm_main(const GAS bf16* A, const GAS bf16* Bt, int brow, int bcol, f32x4 (&acc)[2][2][4][2]) {
;     ...
;   { LDB(B0, 1, 0); LDA(At, 1, 0); WAIT_V(2); BAR; WAIT_L(0); MMA(0, 0, At, B0); BAR;
;     LDB(B1, 1, 1); WAIT_V(0); BAR; WAIT_L(0); MMA(0, 1, At, B1); BAR;
;     LDA(At, 1, 1); BAR; WAIT_L(0); MMA(1, 0, At, B0); MMA(1, 1, At, B1); BAR; }
;   if (wr == 0) BAR;
	s_nop 1
	ds_read_b128 v[2:5], v142
	ds_read_b128 v[10:13], v142 offset:1024
	ds_read_b128 v[186:189], v142 offset:2048
	ds_read_b128 v[190:193], v142 offset:3072
	ds_read_b128 v[18:21], v140 offset:32768
	ds_read_b128 v[22:25], v140 offset:33792
	ds_read_b128 v[34:37], v139 offset:32768
	ds_read_b128 v[42:45], v139 offset:33792
	ds_read_b128 v[50:53], v138 offset:32768
	ds_read_b128 v[54:57], v138 offset:33792
	ds_read_b128 v[194:197], v137 offset:32768
	ds_read_b128 v[198:201], v137 offset:33792
	s_waitcnt vmcnt(2)
	s_barrier
	s_waitcnt lgkmcnt(0)
	s_waitcnt lgkmcnt(0)
	v_mfma_f32_16x16x32_bf16 v[66:69], v[18:21], v[2:5], v[126:129]
	v_mfma_f32_16x16x32_bf16 v[118:121], v[22:25], v[10:13], v[66:69]
	v_mfma_f32_16x16x32_bf16 v[66:69], v[18:21], v[186:189], v[122:125]
	v_mfma_f32_16x16x32_bf16 v[114:117], v[22:25], v[190:193], v[66:69]
	v_mfma_f32_16x16x32_bf16 v[66:69], v[34:37], v[2:5], v[202:205]
	v_mfma_f32_16x16x32_bf16 v[102:105], v[42:45], v[10:13], v[66:69]
	v_mfma_f32_16x16x32_bf16 v[66:69], v[34:37], v[186:189], v[206:209]
	v_mfma_f32_16x16x32_bf16 v[98:101], v[42:45], v[190:193], v[66:69]
	v_mfma_f32_16x16x32_bf16 v[66:69], v[50:53], v[2:5], v[110:113]
	v_mfma_f32_16x16x32_bf16 v[86:89], v[54:57], v[10:13], v[66:69]
	v_mfma_f32_16x16x32_bf16 v[66:69], v[50:53], v[186:189], v[106:109]
	v_mfma_f32_16x16x32_bf16 v[82:85], v[54:57], v[190:193], v[66:69]
	v_mfma_f32_16x16x32_bf16 v[66:69], v[194:197], v[2:5], v[210:213]
	v_mfma_f32_16x16x32_bf16 v[70:73], v[198:201], v[10:13], v[66:69]
	v_mfma_f32_16x16x32_bf16 v[66:69], v[194:197], v[186:189], v[214:217]
	v_mfma_f32_16x16x32_bf16 v[66:69], v[198:201], v[190:193], v[66:69]
	s_barrier
	ds_read_b128 v[202:205], v141
	ds_read_b128 v[206:209], v141 offset:1024
	ds_read_b128 v[210:213], v141 offset:2048
	ds_read_b128 v[214:217], v141 offset:3072
	s_waitcnt vmcnt(0)
	s_barrier
	s_waitcnt lgkmcnt(0)
	s_waitcnt lgkmcnt(0)
	v_mfma_f32_16x16x32_bf16 v[94:97], v[18:21], v[202:205], v[94:97]
	v_mfma_f32_16x16x32_bf16 v[18:21], v[18:21], v[210:213], v[90:93]
	v_mfma_f32_16x16x32_bf16 v[122:125], v[22:25], v[214:217], v[18:21]
	v_mfma_f32_16x16x32_bf16 v[18:21], v[34:37], v[202:205], v[164:167]
	v_mfma_f32_16x16x32_bf16 v[110:113], v[42:45], v[206:209], v[18:21]
	v_mfma_f32_16x16x32_bf16 v[18:21], v[34:37], v[210:213], v[174:177]
	v_mfma_f32_16x16x32_bf16 v[106:109], v[42:45], v[214:217], v[18:21]
	v_mfma_f32_16x16x32_bf16 v[18:21], v[50:53], v[202:205], v[78:81]
	v_mfma_f32_16x16x32_bf16 v[126:129], v[22:25], v[206:209], v[94:97]
	v_mfma_f32_16x16x32_bf16 v[94:97], v[54:57], v[206:209], v[18:21]
	v_mfma_f32_16x16x32_bf16 v[18:21], v[50:53], v[210:213], v[74:77]
	v_mfma_f32_16x16x32_bf16 v[90:93], v[54:57], v[214:217], v[18:21]
	v_mfma_f32_16x16x32_bf16 v[18:21], v[194:197], v[202:205], v[178:181]
	v_mfma_f32_16x16x32_bf16 v[78:81], v[198:201], v[206:209], v[18:21]
	v_mfma_f32_16x16x32_bf16 v[18:21], v[194:197], v[210:213], v[182:185]
	v_mfma_f32_16x16x32_bf16 v[74:77], v[198:201], v[214:217], v[18:21]
	s_barrier
	ds_read_b128 v[164:167], v140 offset:49152
	ds_read_b128 v[140:143], v140 offset:50176
	ds_read_b128 v[174:177], v139 offset:49152
	ds_read_b128 v[178:181], v139 offset:50176
	ds_read_b128 v[182:185], v138 offset:49152
	ds_read_b128 v[194:197], v138 offset:50176
	ds_read_b128 v[198:201], v137 offset:49152
	ds_read_b128 v[230:233], v137 offset:50176
	s_barrier
	s_waitcnt lgkmcnt(0)
	s_waitcnt lgkmcnt(0)
	v_mfma_f32_16x16x32_bf16 v[18:21], v[164:167], v[2:5], v[62:65]
	v_mfma_f32_16x16x32_bf16 v[54:57], v[140:143], v[10:13], v[18:21]
	v_mfma_f32_16x16x32_bf16 v[18:21], v[164:167], v[186:189], v[58:61]
	v_mfma_f32_16x16x32_bf16 v[50:53], v[140:143], v[190:193], v[18:21]
	v_mfma_f32_16x16x32_bf16 v[18:21], v[174:177], v[2:5], v[218:221]
	v_mfma_f32_16x16x32_bf16 v[42:45], v[178:181], v[10:13], v[18:21]
	v_mfma_f32_16x16x32_bf16 v[18:21], v[174:177], v[186:189], v[222:225]
	v_mfma_f32_16x16x32_bf16 v[34:37], v[178:181], v[190:193], v[18:21]
	v_mfma_f32_16x16x32_bf16 v[18:21], v[182:185], v[2:5], v[46:49]
	v_mfma_f32_16x16x32_bf16 v[2:5], v[198:201], v[2:5], v[38:41]
	v_mfma_f32_16x16x32_bf16 v[22:25], v[194:197], v[10:13], v[18:21]
	v_mfma_f32_16x16x32_bf16 v[18:21], v[182:185], v[186:189], v[226:229]
	v_mfma_f32_16x16x32_bf16 v[10:13], v[230:233], v[10:13], v[2:5]
	v_mfma_f32_16x16x32_bf16 v[2:5], v[198:201], v[186:189], v[144:147]
	v_mfma_f32_16x16x32_bf16 v[18:21], v[194:197], v[190:193], v[18:21]
	v_mfma_f32_16x16x32_bf16 v[2:5], v[230:233], v[190:193], v[2:5]
	v_mfma_f32_16x16x32_bf16 v[26:29], v[164:167], v[210:213], v[26:29]
	v_mfma_f32_16x16x32_bf16 v[30:33], v[164:167], v[202:205], v[30:33]
	v_mfma_f32_16x16x32_bf16 v[58:61], v[140:143], v[214:217], v[26:29]
	v_mfma_f32_16x16x32_bf16 v[26:29], v[174:177], v[202:205], v[148:151]
	v_mfma_f32_16x16x32_bf16 v[14:17], v[182:185], v[202:205], v[14:17]
	v_mfma_f32_16x16x32_bf16 v[62:65], v[140:143], v[206:209], v[30:33]
	v_mfma_f32_16x16x32_bf16 v[46:49], v[178:181], v[206:209], v[26:29]
	v_mfma_f32_16x16x32_bf16 v[26:29], v[174:177], v[210:213], v[152:155]
	v_mfma_f32_16x16x32_bf16 v[30:33], v[194:197], v[206:209], v[14:17]
	v_mfma_f32_16x16x32_bf16 v[14:17], v[182:185], v[210:213], v[156:159]
	v_mfma_f32_16x16x32_bf16 v[6:9], v[198:201], v[202:205], v[6:9]
	v_mfma_f32_16x16x32_bf16 v[38:41], v[178:181], v[214:217], v[26:29]
	v_mfma_f32_16x16x32_bf16 v[26:29], v[194:197], v[214:217], v[14:17]
	v_mfma_f32_16x16x32_bf16 v[14:17], v[230:233], v[206:209], v[6:9]
	v_mfma_f32_16x16x32_bf16 v[6:9], v[198:201], v[210:213], v[160:163]
	v_mfma_f32_16x16x32_bf16 v[6:9], v[230:233], v[214:217], v[6:9]
	v_cmp_gt_u32_e32 vcc, s34, v136
	s_barrier
	s_and_saveexec_b64 s[14:15], vcc
	s_cbranch_execz .LBB0_92
	s_barrier

; #define GAS __attribute__((address_space(1)))
; #define STAGE(P, GP, ktrel) do { const GAS char* _g = (GP) + (ktrel) * (BK * 2); \
;     __builtin_amdgcn_global_load_lds((const GAS unsigned*)(_g + so0), (unsigned*)((char*)(P) + tid_ * 16), 16, 0, 0); \
;     __builtin_amdgcn_global_load_lds((const GAS unsigned*)(_g + so1), (unsigned*)((char*)(P) + tid_ * 16 + 8192), 16, 0, 0); } while (0)
; #define WAIT_V(n) asm volatile("s_waitcnt vmcnt(" #n ")" ::: "memory")
; #define WAIT_L(n) asm volatile("s_waitcnt lgkmcnt(" #n ")" ::: "memory")
; #define BAR __builtin_amdgcn_s_barrier()
; #define SCHED __builtin_amdgcn_sched_barrier(0)
; #define LDA(dst, b, h) for (int m = 0; m < 4; ++m) for (int k = 0; k < 2; ++k) \
;     dst[m][k] = *reinterpret_cast<const bf16x8*>((char*)SA(b, h) + lds_byte(wr * 64 + m * 16 + fr, k * 32 + fq * 8))
; #define LDB(dst, b, h) for (int n = 0; n < 2; ++n) for (int k = 0; k < 2; ++k) \
;     dst[n][k] = *reinterpret_cast<const bf16x8*>((char*)SB(b, h) + lds_byte(wc * 32 + n * 16 + fr, k * 32 + fq * 8))
; template <int K, int LD = K>
; __device__ __forceinline__ void gemm_main(const GAS bf16* A, const GAS bf16* Bt, int brow, int bcol, f32x4 (&acc)[2][2][4][2]) {
;     ...
;   bf16x8 At[4][2], B0[2][2], B1[2][2];
;   unsigned so0, so1;
;   { int r_, c_; stage_rc(tid_ * 16, r_, c_); so0 = (unsigned)(r_ * LD + c_) * 2u; stage_rc(tid_ * 16 + 8192, r_, c_); so1 = (unsigned)(r_ * LD + c_) * 2u; }
;   const GAS char* pA0 = (const GAS char*)A + (long)brow * LD * 2; const GAS char* pA1 = pA0 + (long)HALF * LD * 2;
;   const GAS char* pB0 = (const GAS char*)Bt + (long)bcol * LD * 2; const GAS char* pB1 = pB0 + (long)HALF * LD * 2;
;   asm volatile("" : "+s"(pA0), "+s"(pA1), "+s"(pB0), "+s"(pB1));
;   constexpr int nt = K / BK;
;   static_assert(K % 128 == 0 && K >= 256, "K");
;   if (wr == 1) BAR;
;   WAIT_V(0); BAR;
;   BAR;
;   for (int t = 0; t < nt - 2; t += 2) {
;     LDB(B0, 0, 0); SCHED; LDA(At, 0, 0); STAGE(SA(1, 1), pA1, 1);
;     WAIT_L(8); BAR; WAIT_L(0); MMA(0, 0, At, B0); BAR; SCHED;
;     LDB(B1, 0, 1); STAGE(SB(0, 0), pB0, 2);
;     BAR; WAIT_L(0); MMA(0, 1, At, B1); BAR;
;     LDA(At, 0, 1); STAGE(SA(0, 0), pA0, 2);
;     BAR; WAIT_L(0); MMA(1, 0, At, B0); BAR; SCHED;
;     STAGE(SB(0, 1), pB1, 2);
;     WAIT_V(6); BAR; MMA(1, 1, At, B1); BAR;
.LBB0_229:
	s_or_b64 exec, exec, s[22:23]
	v_bfe_i32 v7, v134, 27, 1
	v_lshlrev_b32_e32 v5, 4, v134
	v_lshrrev_b32_e32 v7, 22, v7
	v_add_u32_e32 v7, v5, v7
	v_and_b32_e32 v7, 0xfffffc00, v7
	v_ashrrev_i32_e32 v6, 31, v134
	v_sub_u32_e32 v7, v5, v7
	v_lshrrev_b32_e32 v6, 26, v6
	v_lshrrev_b32_e32 v8, 4, v7
	v_add_u32_e32 v6, v134, v6
	v_bitop3_b32 v8, v8, v7, 32 bitop3:0x6c
	v_ashrrev_i32_e32 v7, 31, v7
	v_ashrrev_i32_e32 v6, 6, v6
	v_lshrrev_b32_e32 v7, 26, v7
	v_lshlrev_b32_e32 v9, 3, v6
	v_add_u32_e32 v7, v8, v7
	v_and_b32_e32 v9, 0x3fffff0, v9
	v_ashrrev_i32_e32 v7, 6, v7
	v_add_u32_e32 v9, v7, v9
	v_mul_i32_i24_e32 v7, 64, v7
	v_sub_u32_e32 v7, v8, v7
	v_lshlrev_b32_e32 v6, 5, v6
	v_ashrrev_i16_sdwa v7, v154, sext(v7) dst_sel:DWORD dst_unused:UNUSED_PAD src0_sel:DWORD src1_sel:BYTE_0
	v_mul_lo_u32 v8, v9, s34
	v_bfe_i32 v7, v7, 0, 16
	v_and_or_b32 v6, v6, 32, v8
	v_add_lshl_u32 v130, v6, v7, 1
	v_add_u32_e32 v6, 0x2000, v5
	v_ashrrev_i32_e32 v7, 31, v6
	v_lshrrev_b32_e32 v7, 22, v7
	v_add_u32_e32 v7, v6, v7
	v_ashrrev_i32_e32 v7, 10, v7
	v_mul_i32_i24_e32 v8, 0x400, v7
	v_sub_u32_e32 v6, v6, v8
	v_lshrrev_b32_e32 v8, 4, v6
	v_bitop3_b32 v6, v8, v6, 32 bitop3:0x6c
	v_ashrrev_i32_e32 v9, 31, v6
	v_lshrrev_b32_e32 v9, 26, v9
	v_lshlrev_b32_e32 v8, 3, v7
	v_add_u32_e32 v9, v6, v9
	v_and_b32_e32 v8, 0x3fffff0, v8
	v_lshrrev_b32_e32 v10, 6, v9
	v_and_b32_e32 v9, 0xc0, v9
	v_add_u32_e32 v8, v10, v8
	v_sub_u32_e32 v6, v6, v9
	v_lshlrev_b32_e32 v7, 5, v7
	v_ashrrev_i16_sdwa v6, v154, sext(v6) dst_sel:DWORD dst_unused:UNUSED_PAD src0_sel:DWORD src1_sel:BYTE_0
	v_mul_lo_u32 v8, v8, s34
	v_bfe_i32 v6, v6, 0, 16
	v_and_or_b32 v7, v7, 32, v8
	v_and_b32_e32 v3, 15, v134
	v_add_lshl_u32 v132, v7, v6, 1
	v_lshlrev_b32_e32 v6, 2, v134
	v_and_b32_e32 v4, 48, v134
	v_lshlrev_b32_e32 v3, 6, v3
	v_and_b32_e32 v6, 32, v6
	v_lshlrev_b32_e32 v11, 6, v134
	v_bitop3_b32 v3, v3, v6, v4 bitop3:0x36
	v_lshlrev_b32_e32 v13, 13, v2
	v_and_or_b32 v2, v11, s40, v4
	v_add_u32_e32 v7, s36, v3
	v_add_u32_e32 v8, s37, v3
	v_add_u32_e32 v9, s38, v3
	v_add_u32_e32 v10, s39, v3
	v_and_b32_e32 v12, 0x3000, v11
	v_add_u32_e32 v3, 0x100, v3
	v_xad_u32 v4, v2, v6, s35
	v_or_b32_e32 v6, 0x800, v13
	v_or_b32_e32 v11, 0x1000, v13
	v_or_b32_e32 v14, 0x1800, v13
	v_mov_b32_e32 v2, 0
	v_add_u32_e32 v145, 0x100, v5
	v_add_u32_e32 v151, s36, v5
	v_add_u32_e32 v153, s37, v5
	v_add_u32_e32 v156, s38, v5
	v_add_u32_e32 v158, s39, v5
	v_mov_b32_e32 v133, v131
	s_mov_b32 s22, -2
	v_add_u32_e32 v144, v7, v12
	v_add_u32_e32 v138, v3, v13
	v_add_u32_e32 v137, v4, v6
	v_add_u32_e32 v136, v4, v11
	v_add_u32_e32 v135, v4, v14
	v_add_u32_e32 v143, 0xc000, v145
	v_add_u32_e32 v142, 0xe000, v145
	v_add_u32_e32 v141, v8, v12
	v_add_u32_e32 v146, 0x2000, v145
	v_add_u32_e32 v140, v9, v12
	v_add_u32_e32 v147, 0x4000, v145
	v_add_u32_e32 v148, 0x6000, v145
	v_add_u32_e32 v139, v10, v12
	v_add_u32_e32 v149, 0x8000, v145
	v_add_u32_e32 v150, 0xa000, v145
	v_add_u32_e32 v152, 0x2000, v151
	v_add_u32_e32 v155, 0x2000, v153
	v_add_u32_e32 v157, 0x2000, v156
	v_add_u32_e32 v159, 0x2000, v158
	s_waitcnt vmcnt(0)
	s_barrier
	s_barrier
	ds_read_b128 v[160:163], v144
	ds_read_b128 v[164:167], v144 offset:1024
	ds_read_b128 v[174:177], v144 offset:2048
	ds_read_b128 v[178:181], v144 offset:3072
	v_lshl_add_u64 v[168:169], s[12:13], 0, v[130:131]
	v_readfirstlane_b32 s23, v143
	v_lshl_add_u64 v[214:215], v[168:169], 0, s[6:7]
	s_mov_b32 m0, s23
	v_lshl_add_u64 v[230:231], s[12:13], 0, v[132:133]
	v_readfirstlane_b32 s23, v142
	ds_read_b128 v[182:185], v138
	ds_read_b128 v[186:189], v138 offset:1024
	ds_read_b128 v[190:193], v137
	ds_read_b128 v[194:197], v137 offset:1024
	ds_read_b128 v[198:201], v136
	ds_read_b128 v[202:205], v136 offset:1024
	ds_read_b128 v[206:209], v135
	ds_read_b128 v[210:213], v135 offset:1024
	global_load_lds_dwordx4 v[214:215], off
	v_lshl_add_u64 v[214:215], v[230:231], 0, s[6:7]
	s_mov_b32 m0, s23
	s_nop 0
	global_load_lds_dwordx4 v[214:215], off
	s_waitcnt lgkmcnt(8)
	s_waitcnt vmcnt(10)
	s_barrier
	s_waitcnt lgkmcnt(0)
	s_waitcnt lgkmcnt(0)
	v_mfma_f32_16x16x32_bf16 v[126:129], v[182:185], v[160:163], 0
	v_mfma_f32_16x16x32_bf16 v[122:125], v[182:185], v[174:177], 0
	v_mfma_f32_16x16x32_bf16 v[118:121], v[190:193], v[160:163], 0
	v_mfma_f32_16x16x32_bf16 v[114:117], v[190:193], v[174:177], 0
	v_mfma_f32_16x16x32_bf16 v[110:113], v[198:201], v[160:163], 0
	v_mfma_f32_16x16x32_bf16 v[106:109], v[198:201], v[174:177], 0
	v_mfma_f32_16x16x32_bf16 v[102:105], v[206:209], v[160:163], 0
	v_mfma_f32_16x16x32_bf16 v[98:101], v[206:209], v[174:177], 0
	v_mfma_f32_16x16x32_bf16 v[126:129], v[186:189], v[164:167], v[126:129]
	v_mfma_f32_16x16x32_bf16 v[122:125], v[186:189], v[178:181], v[122:125]
	v_mfma_f32_16x16x32_bf16 v[118:121], v[194:197], v[164:167], v[118:121]
	v_mfma_f32_16x16x32_bf16 v[114:117], v[194:197], v[178:181], v[114:117]
	v_mfma_f32_16x16x32_bf16 v[110:113], v[202:205], v[164:167], v[110:113]
	v_mfma_f32_16x16x32_bf16 v[106:109], v[202:205], v[178:181], v[106:109]
	v_mfma_f32_16x16x32_bf16 v[102:105], v[210:213], v[164:167], v[102:105]
	v_mfma_f32_16x16x32_bf16 v[98:101], v[210:213], v[178:181], v[98:101]
	s_barrier
	v_lshl_add_u64 v[232:233], s[20:21], 0, v[130:131]
	v_readfirstlane_b32 s23, v151
	v_lshl_add_u64 v[234:235], v[232:233], 0, s[8:9]
	s_mov_b32 m0, s23
	ds_read_b128 v[214:217], v141
	ds_read_b128 v[218:221], v141 offset:1024
	ds_read_b128 v[222:225], v141 offset:2048
	ds_read_b128 v[226:229], v141 offset:3072
	global_load_lds_dwordx4 v[234:235], off
	v_lshl_add_u64 v[234:235], s[20:21], 0, v[132:133]
	v_readfirstlane_b32 s23, v152
	v_lshl_add_u64 v[236:237], v[234:235], 0, s[8:9]
	s_mov_b32 m0, s23
	s_add_u32 s20, s20, 0x100
	global_load_lds_dwordx4 v[236:237], off
	s_waitcnt vmcnt(10)
	s_barrier
; #define STAGE(P, GP, ktrel) do { const GAS char* _g = (GP) + (ktrel) * (BK * 2); \
;     __builtin_amdgcn_global_load_lds((const GAS unsigned*)(_g + so0), (unsigned*)((char*)(P) + tid_ * 16), 16, 0, 0); \
;     __builtin_amdgcn_global_load_lds((const GAS unsigned*)(_g + so1), (unsigned*)((char*)(P) + tid_ * 16 + 8192), 16, 0, 0); } while (0)
; #define WAIT_V(n) asm volatile("s_waitcnt vmcnt(" #n ")" ::: "memory")
; #define WAIT_L(n) asm volatile("s_waitcnt lgkmcnt(" #n ")" ::: "memory")
; #define BAR __builtin_amdgcn_s_barrier()
; #define SCHED __builtin_amdgcn_sched_barrier(0)
; #define LDA(dst, b, h) for (int m = 0; m < 4; ++m) for (int k = 0; k < 2; ++k) \
;     dst[m][k] = *reinterpret_cast<const bf16x8*>((char*)SA(b, h) + lds_byte(wr * 64 + m * 16 + fr, k * 32 + fq * 8))
; #define LDB(dst, b, h) for (int n = 0; n < 2; ++n) for (int k = 0; k < 2; ++k) \
;     dst[n][k] = *reinterpret_cast<const bf16x8*>((char*)SB(b, h) + lds_byte(wc * 32 + n * 16 + fr, k * 32 + fq * 8))
; #define MMA(ai, bj, At_, Bt_) do { __builtin_amdgcn_s_setprio(1); \
;     for (int m = 0; m < 4; ++m) for (int n = 0; n < 2; ++n) for (int k = 0; k < 2; ++k) \
;       acc[ai][bj][m][n] = __builtin_amdgcn_mfma_f32_16x16x32_bf16(At_[m][k], Bt_[n][k], acc[ai][bj][m][n], 0, 0, 0); \
;     __builtin_amdgcn_s_setprio(0); } while (0)
; template <int K, int LD = K>
; __device__ __forceinline__ void gemm_main(const GAS bf16* A, const GAS bf16* Bt, int brow, int bcol, f32x4 (&acc)[2][2][4][2]) {
;     ...
;     LDB(B1, 0, 1); STAGE(SB(0, 0), pB0, 2);
;     BAR; WAIT_L(0); MMA(0, 1, At, B1); BAR;
;     LDA(At, 0, 1); STAGE(SA(0, 0), pA0, 2);
;     BAR; WAIT_L(0); MMA(1, 0, At, B0); BAR; SCHED;
;     STAGE(SB(0, 1), pB1, 2);
;     WAIT_V(6); BAR; MMA(1, 1, At, B1); BAR;
;     LDB(B0, 1, 0); SCHED; LDA(At, 1, 0); STAGE(SA(0, 1), pA1, 2);
;     WAIT_L(8); BAR; WAIT_L(0); MMA(0, 0, At, B0); BAR; SCHED;
	s_waitcnt lgkmcnt(0)
	s_addc_u32 s21, s21, 0
	s_waitcnt lgkmcnt(0)
	v_mfma_f32_16x16x32_bf16 v[94:97], v[182:185], v[214:217], 0
	v_mfma_f32_16x16x32_bf16 v[90:93], v[182:185], v[222:225], 0
	v_mfma_f32_16x16x32_bf16 v[86:89], v[190:193], v[214:217], 0
	v_mfma_f32_16x16x32_bf16 v[82:85], v[190:193], v[222:225], 0
	v_mfma_f32_16x16x32_bf16 v[78:81], v[198:201], v[214:217], 0
	v_mfma_f32_16x16x32_bf16 v[74:77], v[198:201], v[222:225], 0
	v_mfma_f32_16x16x32_bf16 v[70:73], v[206:209], v[214:217], 0
	v_mfma_f32_16x16x32_bf16 v[66:69], v[206:209], v[222:225], 0
	v_mfma_f32_16x16x32_bf16 v[94:97], v[186:189], v[218:221], v[94:97]
	v_mfma_f32_16x16x32_bf16 v[90:93], v[186:189], v[226:229], v[90:93]
	v_mfma_f32_16x16x32_bf16 v[86:89], v[194:197], v[218:221], v[86:89]
	v_mfma_f32_16x16x32_bf16 v[82:85], v[194:197], v[226:229], v[82:85]
	v_mfma_f32_16x16x32_bf16 v[78:81], v[202:205], v[218:221], v[78:81]
	v_mfma_f32_16x16x32_bf16 v[74:77], v[202:205], v[226:229], v[74:77]
	v_mfma_f32_16x16x32_bf16 v[70:73], v[210:213], v[218:221], v[70:73]
	v_mfma_f32_16x16x32_bf16 v[66:69], v[210:213], v[226:229], v[66:69]
	v_lshl_add_u64 v[236:237], s[18:19], 0, v[130:131]
	v_readfirstlane_b32 s23, v145
	v_lshl_add_u64 v[238:239], v[236:237], 0, s[8:9]
	s_mov_b32 m0, s23
	s_barrier
	ds_read_b128 v[182:185], v138 offset:16384
	ds_read_b128 v[186:189], v138 offset:17408
	ds_read_b128 v[190:193], v137 offset:16384
	ds_read_b128 v[194:197], v137 offset:17408
	ds_read_b128 v[198:201], v136 offset:16384
	ds_read_b128 v[202:205], v136 offset:17408
	ds_read_b128 v[206:209], v135 offset:16384
	ds_read_b128 v[210:213], v135 offset:17408
	global_load_lds_dwordx4 v[238:239], off
	v_lshl_add_u64 v[238:239], s[18:19], 0, v[132:133]
	v_readfirstlane_b32 s23, v146
	v_lshl_add_u64 v[240:241], v[238:239], 0, s[8:9]
	s_mov_b32 m0, s23
	s_add_u32 s18, s18, 0x100
	global_load_lds_dwordx4 v[240:241], off
	s_barrier
	s_waitcnt lgkmcnt(0)
	s_addc_u32 s19, s19, 0
	s_waitcnt lgkmcnt(0)
	v_mfma_f32_16x16x32_bf16 v[62:65], v[182:185], v[160:163], 0
	v_mfma_f32_16x16x32_bf16 v[58:61], v[182:185], v[174:177], 0
	v_mfma_f32_16x16x32_bf16 v[54:57], v[190:193], v[160:163], 0
	v_mfma_f32_16x16x32_bf16 v[50:53], v[190:193], v[174:177], 0
	v_mfma_f32_16x16x32_bf16 v[46:49], v[198:201], v[160:163], 0
	v_mfma_f32_16x16x32_bf16 v[42:45], v[198:201], v[174:177], 0
	v_mfma_f32_16x16x32_bf16 v[38:41], v[206:209], v[160:163], 0
	v_mfma_f32_16x16x32_bf16 v[34:37], v[206:209], v[174:177], 0
	v_mfma_f32_16x16x32_bf16 v[62:65], v[186:189], v[164:167], v[62:65]
	v_mfma_f32_16x16x32_bf16 v[58:61], v[186:189], v[178:181], v[58:61]
	v_mfma_f32_16x16x32_bf16 v[54:57], v[194:197], v[164:167], v[54:57]
	v_mfma_f32_16x16x32_bf16 v[50:53], v[194:197], v[178:181], v[50:53]
	v_mfma_f32_16x16x32_bf16 v[46:49], v[202:205], v[164:167], v[46:49]
	v_mfma_f32_16x16x32_bf16 v[42:45], v[202:205], v[178:181], v[42:45]
	v_mfma_f32_16x16x32_bf16 v[38:41], v[210:213], v[164:167], v[38:41]
	v_mfma_f32_16x16x32_bf16 v[34:37], v[210:213], v[178:181], v[34:37]
	s_barrier
	v_lshl_add_u64 v[240:241], s[16:17], 0, v[130:131]
	v_readfirstlane_b32 s23, v153
	v_lshl_add_u64 v[160:161], v[240:241], 0, s[8:9]
	s_mov_b32 m0, s23
	v_lshl_add_u64 v[242:243], s[16:17], 0, v[132:133]
	v_readfirstlane_b32 s23, v155
	global_load_lds_dwordx4 v[160:161], off
	v_lshl_add_u64 v[160:161], v[242:243], 0, s[8:9]
	s_mov_b32 m0, s23
	s_add_u32 s16, s16, 0x100
	global_load_lds_dwordx4 v[160:161], off
	s_waitcnt vmcnt(10)
	s_addc_u32 s17, s17, 0
	s_barrier
	v_mfma_f32_16x16x32_bf16 v[30:33], v[182:185], v[214:217], 0
	v_mfma_f32_16x16x32_bf16 v[26:29], v[182:185], v[222:225], 0
	v_mfma_f32_16x16x32_bf16 v[22:25], v[190:193], v[214:217], 0
	v_mfma_f32_16x16x32_bf16 v[18:21], v[190:193], v[222:225], 0
	v_mfma_f32_16x16x32_bf16 v[14:17], v[198:201], v[214:217], 0
	v_mfma_f32_16x16x32_bf16 v[10:13], v[198:201], v[222:225], 0
	v_mfma_f32_16x16x32_bf16 v[6:9], v[206:209], v[214:217], 0
	v_mfma_f32_16x16x32_bf16 v[2:5], v[206:209], v[222:225], 0
	v_mfma_f32_16x16x32_bf16 v[30:33], v[186:189], v[218:221], v[30:33]
	v_mfma_f32_16x16x32_bf16 v[26:29], v[186:189], v[226:229], v[26:29]
	v_mfma_f32_16x16x32_bf16 v[22:25], v[194:197], v[218:221], v[22:25]
	v_mfma_f32_16x16x32_bf16 v[18:21], v[194:197], v[226:229], v[18:21]
	v_mfma_f32_16x16x32_bf16 v[14:17], v[202:205], v[218:221], v[14:17]
	v_mfma_f32_16x16x32_bf16 v[10:13], v[202:205], v[226:229], v[10:13]
	v_mfma_f32_16x16x32_bf16 v[6:9], v[210:213], v[218:221], v[6:9]
	v_mfma_f32_16x16x32_bf16 v[2:5], v[210:213], v[226:229], v[2:5]
	s_barrier
	ds_read_b128 v[160:163], v140
	ds_read_b128 v[164:167], v140 offset:1024
	ds_read_b128 v[174:177], v140 offset:2048
	ds_read_b128 v[178:181], v140 offset:3072
	v_readfirstlane_b32 s23, v147
	v_lshl_add_u64 v[168:169], v[168:169], 0, s[8:9]
	s_mov_b32 m0, s23
	v_readfirstlane_b32 s23, v148
	ds_read_b128 v[182:185], v138 offset:32768
	ds_read_b128 v[186:189], v138 offset:33792
	ds_read_b128 v[190:193], v137 offset:32768
	ds_read_b128 v[194:197], v137 offset:33792
	ds_read_b128 v[198:201], v136 offset:32768
	ds_read_b128 v[202:205], v136 offset:33792
	ds_read_b128 v[206:209], v135 offset:32768
	ds_read_b128 v[210:213], v135 offset:33792
	global_load_lds_dwordx4 v[168:169], off
	v_lshl_add_u64 v[168:169], v[230:231], 0, s[8:9]
	s_mov_b32 m0, s23
	s_add_u32 s12, s12, 0x100
	global_load_lds_dwordx4 v[168:169], off
	s_waitcnt lgkmcnt(8)
	s_waitcnt vmcnt(10)
	s_barrier
; #define STAGE(P, GP, ktrel) do { const GAS char* _g = (GP) + (ktrel) * (BK * 2); \
;     __builtin_amdgcn_global_load_lds((const GAS unsigned*)(_g + so0), (unsigned*)((char*)(P) + tid_ * 16), 16, 0, 0); \
;     __builtin_amdgcn_global_load_lds((const GAS unsigned*)(_g + so1), (unsigned*)((char*)(P) + tid_ * 16 + 8192), 16, 0, 0); } while (0)
; #define WAIT_V(n) asm volatile("s_waitcnt vmcnt(" #n ")" ::: "memory")
; #define WAIT_L(n) asm volatile("s_waitcnt lgkmcnt(" #n ")" ::: "memory")
; #define BAR __builtin_amdgcn_s_barrier()
; #define SCHED __builtin_amdgcn_sched_barrier(0)
; #define LDA(dst, b, h) for (int m = 0; m < 4; ++m) for (int k = 0; k < 2; ++k) \
;     dst[m][k] = *reinterpret_cast<const bf16x8*>((char*)SA(b, h) + lds_byte(wr * 64 + m * 16 + fr, k * 32 + fq * 8))
; #define LDB(dst, b, h) for (int n = 0; n < 2; ++n) for (int k = 0; k < 2; ++k) \
;     dst[n][k] = *reinterpret_cast<const bf16x8*>((char*)SB(b, h) + lds_byte(wc * 32 + n * 16 + fr, k * 32 + fq * 8))
; #define MMA(ai, bj, At_, Bt_) do { __builtin_amdgcn_s_setprio(1); \
;     for (int m = 0; m < 4; ++m) for (int n = 0; n < 2; ++n) for (int k = 0; k < 2; ++k) \
;       acc[ai][bj][m][n] = __builtin_amdgcn_mfma_f32_16x16x32_bf16(At_[m][k], Bt_[n][k], acc[ai][bj][m][n], 0, 0, 0); \
;     __builtin_amdgcn_s_setprio(0); } while (0)
; template <int K, int LD = K>
; __device__ __forceinline__ void gemm_main(const GAS bf16* A, const GAS bf16* Bt, int brow, int bcol, f32x4 (&acc)[2][2][4][2]) {
;     ...
;     LDB(B0, 1, 0); SCHED; LDA(At, 1, 0); STAGE(SA(0, 1), pA1, 2);
;     WAIT_L(8); BAR; WAIT_L(0); MMA(0, 0, At, B0); BAR; SCHED;
;     LDB(B1, 1, 1); STAGE(SB(1, 0), pB0, 3);
;     BAR; WAIT_L(0); MMA(0, 1, At, B1); BAR;
;     LDA(At, 1, 1); STAGE(SA(1, 0), pA0, 3);
;     BAR; WAIT_L(0); MMA(1, 0, At, B0); BAR; SCHED;
;     STAGE(SB(1, 1), pB1, 3);
;     WAIT_V(6); BAR; MMA(1, 1, At, B1); BAR;
;     pA0 += 4 * BK; pA1 += 4 * BK; pB0 += 4 * BK; pB1 += 4 * BK;
;     asm volatile("" : "+s"(pA0), "+s"(pA1), "+s"(pB0), "+s"(pB1));
	s_waitcnt lgkmcnt(0)
	s_addc_u32 s13, s13, 0
	s_waitcnt lgkmcnt(0)
	v_mfma_f32_16x16x32_bf16 v[126:129], v[182:185], v[160:163], v[126:129]
	v_mfma_f32_16x16x32_bf16 v[122:125], v[182:185], v[174:177], v[122:125]
	v_mfma_f32_16x16x32_bf16 v[118:121], v[190:193], v[160:163], v[118:121]
	v_mfma_f32_16x16x32_bf16 v[114:117], v[190:193], v[174:177], v[114:117]
	v_mfma_f32_16x16x32_bf16 v[110:113], v[198:201], v[160:163], v[110:113]
	v_mfma_f32_16x16x32_bf16 v[106:109], v[198:201], v[174:177], v[106:109]
	v_mfma_f32_16x16x32_bf16 v[102:105], v[206:209], v[160:163], v[102:105]
	v_mfma_f32_16x16x32_bf16 v[98:101], v[206:209], v[174:177], v[98:101]
	v_mfma_f32_16x16x32_bf16 v[126:129], v[186:189], v[164:167], v[126:129]
	v_mfma_f32_16x16x32_bf16 v[122:125], v[186:189], v[178:181], v[122:125]
	v_mfma_f32_16x16x32_bf16 v[118:121], v[194:197], v[164:167], v[118:121]
	v_mfma_f32_16x16x32_bf16 v[114:117], v[194:197], v[178:181], v[114:117]
	v_mfma_f32_16x16x32_bf16 v[110:113], v[202:205], v[164:167], v[110:113]
	v_mfma_f32_16x16x32_bf16 v[106:109], v[202:205], v[178:181], v[106:109]
	v_mfma_f32_16x16x32_bf16 v[102:105], v[210:213], v[164:167], v[102:105]
	v_mfma_f32_16x16x32_bf16 v[98:101], v[210:213], v[178:181], v[98:101]
	s_barrier
	v_readfirstlane_b32 s23, v156
	v_lshl_add_u64 v[168:169], v[232:233], 0, s[10:11]
	s_mov_b32 m0, s23
	v_readfirstlane_b32 s23, v157
	ds_read_b128 v[214:217], v139
	ds_read_b128 v[218:221], v139 offset:1024
	ds_read_b128 v[222:225], v139 offset:2048
	ds_read_b128 v[226:229], v139 offset:3072
	global_load_lds_dwordx4 v[168:169], off
	v_lshl_add_u64 v[168:169], v[234:235], 0, s[10:11]
	s_mov_b32 m0, s23
	s_nop 0
	global_load_lds_dwordx4 v[168:169], off
	s_waitcnt vmcnt(10)
	s_barrier
	s_waitcnt lgkmcnt(0)
	s_waitcnt lgkmcnt(0)
	v_mfma_f32_16x16x32_bf16 v[94:97], v[182:185], v[214:217], v[94:97]
	v_mfma_f32_16x16x32_bf16 v[90:93], v[182:185], v[222:225], v[90:93]
	v_mfma_f32_16x16x32_bf16 v[86:89], v[190:193], v[214:217], v[86:89]
	v_mfma_f32_16x16x32_bf16 v[82:85], v[190:193], v[222:225], v[82:85]
	v_mfma_f32_16x16x32_bf16 v[78:81], v[198:201], v[214:217], v[78:81]
	v_mfma_f32_16x16x32_bf16 v[74:77], v[198:201], v[222:225], v[74:77]
	v_mfma_f32_16x16x32_bf16 v[70:73], v[206:209], v[214:217], v[70:73]
	v_mfma_f32_16x16x32_bf16 v[66:69], v[206:209], v[222:225], v[66:69]
	v_mfma_f32_16x16x32_bf16 v[94:97], v[186:189], v[218:221], v[94:97]
	v_mfma_f32_16x16x32_bf16 v[90:93], v[186:189], v[226:229], v[90:93]
	v_mfma_f32_16x16x32_bf16 v[86:89], v[194:197], v[218:221], v[86:89]
	v_mfma_f32_16x16x32_bf16 v[82:85], v[194:197], v[226:229], v[82:85]
	v_mfma_f32_16x16x32_bf16 v[78:81], v[202:205], v[218:221], v[78:81]
	v_mfma_f32_16x16x32_bf16 v[74:77], v[202:205], v[226:229], v[74:77]
	v_mfma_f32_16x16x32_bf16 v[70:73], v[210:213], v[218:221], v[70:73]
	v_mfma_f32_16x16x32_bf16 v[66:69], v[210:213], v[226:229], v[66:69]
	v_readfirstlane_b32 s23, v149
	v_lshl_add_u64 v[168:169], v[236:237], 0, s[10:11]
	s_mov_b32 m0, s23
	v_readfirstlane_b32 s23, v150
	s_barrier
	ds_read_b128 v[182:185], v138 offset:49152
	ds_read_b128 v[186:189], v138 offset:50176
	ds_read_b128 v[190:193], v137 offset:49152
	ds_read_b128 v[194:197], v137 offset:50176
	ds_read_b128 v[198:201], v136 offset:49152
	ds_read_b128 v[202:205], v136 offset:50176
	ds_read_b128 v[206:209], v135 offset:49152
	ds_read_b128 v[210:213], v135 offset:50176
	global_load_lds_dwordx4 v[168:169], off
	v_lshl_add_u64 v[168:169], v[238:239], 0, s[10:11]
	s_mov_b32 m0, s23
	s_nop 0
	global_load_lds_dwordx4 v[168:169], off
	s_barrier
	s_waitcnt lgkmcnt(0)
	s_waitcnt lgkmcnt(0)
	v_mfma_f32_16x16x32_bf16 v[62:65], v[182:185], v[160:163], v[62:65]
	v_mfma_f32_16x16x32_bf16 v[58:61], v[182:185], v[174:177], v[58:61]
	v_mfma_f32_16x16x32_bf16 v[54:57], v[190:193], v[160:163], v[54:57]
	v_mfma_f32_16x16x32_bf16 v[50:53], v[190:193], v[174:177], v[50:53]
	v_mfma_f32_16x16x32_bf16 v[46:49], v[198:201], v[160:163], v[46:49]
	v_mfma_f32_16x16x32_bf16 v[42:45], v[198:201], v[174:177], v[42:45]
	v_mfma_f32_16x16x32_bf16 v[38:41], v[206:209], v[160:163], v[38:41]
	v_mfma_f32_16x16x32_bf16 v[34:37], v[206:209], v[174:177], v[34:37]
	v_mfma_f32_16x16x32_bf16 v[62:65], v[186:189], v[164:167], v[62:65]
	v_mfma_f32_16x16x32_bf16 v[58:61], v[186:189], v[178:181], v[58:61]
	v_mfma_f32_16x16x32_bf16 v[54:57], v[194:197], v[164:167], v[54:57]
	v_mfma_f32_16x16x32_bf16 v[50:53], v[194:197], v[178:181], v[50:53]
	v_mfma_f32_16x16x32_bf16 v[46:49], v[202:205], v[164:167], v[46:49]
	v_mfma_f32_16x16x32_bf16 v[42:45], v[202:205], v[178:181], v[42:45]
	v_mfma_f32_16x16x32_bf16 v[38:41], v[210:213], v[164:167], v[38:41]
	v_mfma_f32_16x16x32_bf16 v[34:37], v[210:213], v[178:181], v[34:37]
	s_barrier
	v_readfirstlane_b32 s23, v158
	v_lshl_add_u64 v[160:161], v[240:241], 0, s[10:11]
	s_mov_b32 m0, s23
	v_readfirstlane_b32 s23, v159
	global_load_lds_dwordx4 v[160:161], off
	v_lshl_add_u64 v[160:161], v[242:243], 0, s[10:11]
	s_mov_b32 m0, s23
	s_nop 0
	global_load_lds_dwordx4 v[160:161], off
	s_waitcnt vmcnt(10)
	s_barrier
	v_mfma_f32_16x16x32_bf16 v[30:33], v[182:185], v[214:217], v[30:33]
	v_mfma_f32_16x16x32_bf16 v[26:29], v[182:185], v[222:225], v[26:29]
	v_mfma_f32_16x16x32_bf16 v[22:25], v[190:193], v[214:217], v[22:25]
	v_mfma_f32_16x16x32_bf16 v[18:21], v[190:193], v[222:225], v[18:21]
	v_mfma_f32_16x16x32_bf16 v[14:17], v[198:201], v[214:217], v[14:17]
	v_mfma_f32_16x16x32_bf16 v[10:13], v[198:201], v[222:225], v[10:13]
	v_mfma_f32_16x16x32_bf16 v[6:9], v[206:209], v[214:217], v[6:9]
	v_mfma_f32_16x16x32_bf16 v[2:5], v[206:209], v[222:225], v[2:5]
	v_mfma_f32_16x16x32_bf16 v[30:33], v[186:189], v[218:221], v[30:33]
	v_mfma_f32_16x16x32_bf16 v[26:29], v[186:189], v[226:229], v[26:29]
	v_mfma_f32_16x16x32_bf16 v[22:25], v[194:197], v[218:221], v[22:25]
	v_mfma_f32_16x16x32_bf16 v[18:21], v[194:197], v[226:229], v[18:21]
	v_mfma_f32_16x16x32_bf16 v[14:17], v[202:205], v[218:221], v[14:17]
	v_mfma_f32_16x16x32_bf16 v[10:13], v[202:205], v[226:229], v[10:13]
	v_mfma_f32_16x16x32_bf16 v[6:9], v[210:213], v[218:221], v[6:9]
	v_mfma_f32_16x16x32_bf16 v[2:5], v[210:213], v[226:229], v[2:5]
	s_add_i32 s22, s22, 2
	s_cmp_lt_u32 s22, 40
	s_barrier
	s_cbranch_scc1 .LBB0_230
	s_branch .Lpeel7_exit

; #define STAGE(P, GP, ktrel) do { const GAS char* _g = (GP) + (ktrel) * (BK * 2); \
;     __builtin_amdgcn_global_load_lds((const GAS unsigned*)(_g + so0), (unsigned*)((char*)(P) + tid_ * 16), 16, 0, 0); \
;     __builtin_amdgcn_global_load_lds((const GAS unsigned*)(_g + so1), (unsigned*)((char*)(P) + tid_ * 16 + 8192), 16, 0, 0); } while (0)
; #define WAIT_V(n) asm volatile("s_waitcnt vmcnt(" #n ")" ::: "memory")
; #define WAIT_L(n) asm volatile("s_waitcnt lgkmcnt(" #n ")" ::: "memory")
; #define BAR __builtin_amdgcn_s_barrier()
; #define LDA(dst, b, h) for (int m = 0; m < 4; ++m) for (int k = 0; k < 2; ++k) \
;     dst[m][k] = *reinterpret_cast<const bf16x8*>((char*)SA(b, h) + lds_byte(wr * 64 + m * 16 + fr, k * 32 + fq * 8))
; #define LDB(dst, b, h) for (int n = 0; n < 2; ++n) for (int k = 0; k < 2; ++k) \
;     dst[n][k] = *reinterpret_cast<const bf16x8*>((char*)SB(b, h) + lds_byte(wc * 32 + n * 16 + fr, k * 32 + fq * 8))
; #define MMA(ai, bj, At_, Bt_) do { __builtin_amdgcn_s_setprio(1); \
;     for (int m = 0; m < 4; ++m) for (int n = 0; n < 2; ++n) for (int k = 0; k < 2; ++k) \
;       acc[ai][bj][m][n] = __builtin_amdgcn_mfma_f32_16x16x32_bf16(At_[m][k], Bt_[n][k], acc[ai][bj][m][n], 0, 0, 0); \
;     __builtin_amdgcn_s_setprio(0); } while (0)
; template <int K, int LD = K>
; __device__ __forceinline__ void gemm_main(const GAS bf16* A, const GAS bf16* Bt, int brow, int bcol, f32x4 (&acc)[2][2][4][2]) {
;     ...
;   { LDB(B0, 0, 0); LDA(At, 0, 0); STAGE(SA(1, 1), pA1, 1);
;     BAR; WAIT_L(0); MMA(0, 0, At, B0); BAR;
;     LDB(B1, 0, 1); BAR; WAIT_L(0); MMA(0, 1, At, B1); BAR;
;     LDA(At, 0, 1); WAIT_V(4); BAR; WAIT_L(0); MMA(1, 0, At, B0); MMA(1, 1, At, B1); BAR; }
.Lpeel7_exit:
	ds_read_b128 v[146:149], v144
	ds_read_b128 v[150:153], v144 offset:1024
	ds_read_b128 v[156:159], v144 offset:2048
	ds_read_b128 v[160:163], v144 offset:3072
	ds_read_b128 v[164:167], v138
	ds_read_b128 v[174:177], v138 offset:1024
	ds_read_b128 v[178:181], v137
	ds_read_b128 v[182:185], v137 offset:1024
	ds_read_b128 v[186:189], v136
	ds_read_b128 v[190:193], v136 offset:1024
	ds_read_b128 v[194:197], v135
	ds_read_b128 v[198:201], v135 offset:1024
	v_lshl_add_u64 v[144:145], s[12:13], 0, v[130:131]
	v_readfirstlane_b32 s16, v143
	v_lshl_add_u64 v[144:145], v[144:145], 0, s[6:7]
	s_mov_b32 m0, s16
	v_lshl_add_u64 v[132:133], s[12:13], 0, v[132:133]
	v_readfirstlane_b32 s12, v142
	global_load_lds_dwordx4 v[144:145], off
	v_lshl_add_u64 v[132:133], v[132:133], 0, s[6:7]
	s_mov_b32 m0, s12
	s_nop 0
	global_load_lds_dwordx4 v[132:133], off
	s_waitcnt vmcnt(10)
	s_barrier
	s_waitcnt lgkmcnt(0)
	s_waitcnt lgkmcnt(0)
	v_mfma_f32_16x16x32_bf16 v[126:129], v[164:167], v[146:149], v[126:129]
	v_mfma_f32_16x16x32_bf16 v[122:125], v[164:167], v[156:159], v[122:125]
	v_mfma_f32_16x16x32_bf16 v[110:113], v[186:189], v[146:149], v[110:113]
	v_mfma_f32_16x16x32_bf16 v[106:109], v[186:189], v[156:159], v[106:109]
	v_mfma_f32_16x16x32_bf16 v[126:129], v[174:177], v[150:153], v[126:129]
	v_mfma_f32_16x16x32_bf16 v[122:125], v[174:177], v[160:163], v[122:125]
	v_mfma_f32_16x16x32_bf16 v[118:121], v[178:181], v[146:149], v[118:121]
	v_mfma_f32_16x16x32_bf16 v[114:117], v[178:181], v[156:159], v[114:117]
	v_mfma_f32_16x16x32_bf16 v[110:113], v[190:193], v[150:153], v[110:113]
	v_mfma_f32_16x16x32_bf16 v[106:109], v[190:193], v[160:163], v[106:109]
	v_mfma_f32_16x16x32_bf16 v[102:105], v[194:197], v[146:149], v[102:105]
	v_mfma_f32_16x16x32_bf16 v[98:101], v[194:197], v[156:159], v[98:101]
	v_mfma_f32_16x16x32_bf16 v[142:145], v[182:185], v[150:153], v[118:121]
	v_mfma_f32_16x16x32_bf16 v[202:205], v[182:185], v[160:163], v[114:117]
	v_mfma_f32_16x16x32_bf16 v[206:209], v[198:201], v[150:153], v[102:105]
	v_mfma_f32_16x16x32_bf16 v[210:213], v[198:201], v[160:163], v[98:101]
	s_barrier
	s_nop 1
	ds_read_b128 v[98:101], v141
	ds_read_b128 v[102:105], v141 offset:1024
	ds_read_b128 v[114:117], v141 offset:2048
	ds_read_b128 v[118:121], v141 offset:3072
	s_waitcnt vmcnt(8)
	s_barrier
	s_waitcnt lgkmcnt(0)
	s_waitcnt lgkmcnt(0)
	v_mfma_f32_16x16x32_bf16 v[94:97], v[164:167], v[98:101], v[94:97]
	v_mfma_f32_16x16x32_bf16 v[90:93], v[164:167], v[114:117], v[90:93]
	v_mfma_f32_16x16x32_bf16 v[78:81], v[186:189], v[98:101], v[78:81]
	v_mfma_f32_16x16x32_bf16 v[74:77], v[186:189], v[114:117], v[74:77]
	v_mfma_f32_16x16x32_bf16 v[94:97], v[174:177], v[102:105], v[94:97]
	v_mfma_f32_16x16x32_bf16 v[90:93], v[174:177], v[118:121], v[90:93]
	v_mfma_f32_16x16x32_bf16 v[86:89], v[178:181], v[98:101], v[86:89]
	v_mfma_f32_16x16x32_bf16 v[82:85], v[178:181], v[114:117], v[82:85]
	v_mfma_f32_16x16x32_bf16 v[78:81], v[190:193], v[102:105], v[78:81]
	v_mfma_f32_16x16x32_bf16 v[74:77], v[190:193], v[118:121], v[74:77]
	v_mfma_f32_16x16x32_bf16 v[70:73], v[194:197], v[98:101], v[70:73]
	v_mfma_f32_16x16x32_bf16 v[66:69], v[194:197], v[114:117], v[66:69]
	v_mfma_f32_16x16x32_bf16 v[164:167], v[182:185], v[102:105], v[86:89]
	v_mfma_f32_16x16x32_bf16 v[174:177], v[182:185], v[118:121], v[82:85]
	v_mfma_f32_16x16x32_bf16 v[178:181], v[198:201], v[102:105], v[70:73]
	v_mfma_f32_16x16x32_bf16 v[182:185], v[198:201], v[118:121], v[66:69]
	s_barrier
	s_nop 1
	ds_read_b128 v[66:69], v138 offset:16384
	ds_read_b128 v[70:73], v138 offset:17408
	ds_read_b128 v[82:85], v137 offset:16384
	ds_read_b128 v[86:89], v137 offset:17408
	ds_read_b128 v[186:189], v136 offset:16384
	ds_read_b128 v[190:193], v136 offset:17408
	ds_read_b128 v[194:197], v135 offset:16384
	ds_read_b128 v[198:201], v135 offset:17408
	s_waitcnt vmcnt(4)
	s_barrier
	s_waitcnt lgkmcnt(0)
	s_waitcnt lgkmcnt(0)
	v_mfma_f32_16x16x32_bf16 v[62:65], v[66:69], v[146:149], v[62:65]
	v_mfma_f32_16x16x32_bf16 v[58:61], v[66:69], v[156:159], v[58:61]
	v_mfma_f32_16x16x32_bf16 v[46:49], v[186:189], v[146:149], v[46:49]
	v_mfma_f32_16x16x32_bf16 v[42:45], v[186:189], v[156:159], v[42:45]
	v_mfma_f32_16x16x32_bf16 v[62:65], v[70:73], v[150:153], v[62:65]
	v_mfma_f32_16x16x32_bf16 v[58:61], v[70:73], v[160:163], v[58:61]
	v_mfma_f32_16x16x32_bf16 v[54:57], v[82:85], v[146:149], v[54:57]
	v_mfma_f32_16x16x32_bf16 v[50:53], v[82:85], v[156:159], v[50:53]
	v_mfma_f32_16x16x32_bf16 v[46:49], v[190:193], v[150:153], v[46:49]
	v_mfma_f32_16x16x32_bf16 v[42:45], v[190:193], v[160:163], v[42:45]
	v_mfma_f32_16x16x32_bf16 v[38:41], v[194:197], v[146:149], v[38:41]
	v_mfma_f32_16x16x32_bf16 v[34:37], v[194:197], v[156:159], v[34:37]
	v_mfma_f32_16x16x32_bf16 v[214:217], v[86:89], v[150:153], v[54:57]
	v_mfma_f32_16x16x32_bf16 v[218:221], v[86:89], v[160:163], v[50:53]
	v_mfma_f32_16x16x32_bf16 v[146:149], v[198:201], v[150:153], v[38:41]
	v_mfma_f32_16x16x32_bf16 v[150:153], v[198:201], v[160:163], v[34:37]
	v_mfma_f32_16x16x32_bf16 v[30:33], v[66:69], v[98:101], v[30:33]
	v_mfma_f32_16x16x32_bf16 v[26:29], v[66:69], v[114:117], v[26:29]
	v_mfma_f32_16x16x32_bf16 v[14:17], v[186:189], v[98:101], v[14:17]
	v_mfma_f32_16x16x32_bf16 v[10:13], v[186:189], v[114:117], v[10:13]
	v_mfma_f32_16x16x32_bf16 v[30:33], v[70:73], v[102:105], v[30:33]
	v_mfma_f32_16x16x32_bf16 v[26:29], v[70:73], v[118:121], v[26:29]
	v_mfma_f32_16x16x32_bf16 v[22:25], v[82:85], v[98:101], v[22:25]
	v_mfma_f32_16x16x32_bf16 v[18:21], v[82:85], v[114:117], v[18:21]
	v_mfma_f32_16x16x32_bf16 v[14:17], v[190:193], v[102:105], v[14:17]
	v_mfma_f32_16x16x32_bf16 v[10:13], v[190:193], v[118:121], v[10:13]
	v_mfma_f32_16x16x32_bf16 v[6:9], v[194:197], v[98:101], v[6:9]
	v_mfma_f32_16x16x32_bf16 v[2:5], v[194:197], v[114:117], v[2:5]
	v_mfma_f32_16x16x32_bf16 v[156:159], v[86:89], v[102:105], v[22:25]
	v_mfma_f32_16x16x32_bf16 v[160:163], v[86:89], v[118:121], v[18:21]
	v_mfma_f32_16x16x32_bf16 v[186:189], v[198:201], v[102:105], v[6:9]
	v_mfma_f32_16x16x32_bf16 v[190:193], v[198:201], v[118:121], v[2:5]
	s_barrier
; #define WAIT_V(n) asm volatile("s_waitcnt vmcnt(" #n ")" ::: "memory")
; #define WAIT_L(n) asm volatile("s_waitcnt lgkmcnt(" #n ")" ::: "memory")
; #define BAR __builtin_amdgcn_s_barrier()
; #define LDA(dst, b, h) for (int m = 0; m < 4; ++m) for (int k = 0; k < 2; ++k) \
;     dst[m][k] = *reinterpret_cast<const bf16x8*>((char*)SA(b, h) + lds_byte(wr * 64 + m * 16 + fr, k * 32 + fq * 8))
; #define LDB(dst, b, h) for (int n = 0; n < 2; ++n) for (int k = 0; k < 2; ++k) \
;     dst[n][k] = *reinterpret_cast<const bf16x8*>((char*)SB(b, h) + lds_byte(wc * 32 + n * 16 + fr, k * 32 + fq * 8))
; #define MMA(ai, bj, At_, Bt_) do { __builtin_amdgcn_s_setprio(1); \
;     for (int m = 0; m < 4; ++m) for (int n = 0; n < 2; ++n) for (int k = 0; k < 2; ++k) \
;       acc[ai][bj][m][n] = __builtin_amdgcn_mfma_f32_16x16x32_bf16(At_[m][k], Bt_[n][k], acc[ai][bj][m][n], 0, 0, 0); \
;     __builtin_amdgcn_s_setprio(0); } while (0)
; template <int K, int LD = K>
; __device__ __forceinline__ void gemm_main(const GAS bf16* A, const GAS bf16* Bt, int brow, int bcol, f32x4 (&acc)[2][2][4][2]) {
;     ...
;   { LDB(B0, 1, 0); LDA(At, 1, 0); WAIT_V(2); BAR; WAIT_L(0); MMA(0, 0, At, B0); BAR;
;     LDB(B1, 1, 1); WAIT_V(0); BAR; WAIT_L(0); MMA(0, 1, At, B1); BAR;
;     LDA(At, 1, 1); BAR; WAIT_L(0); MMA(1, 0, At, B0); MMA(1, 1, At, B1); BAR; }
;   if (wr == 0) BAR;
	s_nop 1
	ds_read_b128 v[2:5], v140
	ds_read_b128 v[6:9], v140 offset:1024
	ds_read_b128 v[194:197], v140 offset:2048
	ds_read_b128 v[198:201], v140 offset:3072
	ds_read_b128 v[18:21], v138 offset:32768
	ds_read_b128 v[22:25], v138 offset:33792
	ds_read_b128 v[34:37], v137 offset:32768
	ds_read_b128 v[38:41], v137 offset:33792
	ds_read_b128 v[50:53], v136 offset:32768
	ds_read_b128 v[54:57], v136 offset:33792
	ds_read_b128 v[222:225], v135 offset:32768
	ds_read_b128 v[226:229], v135 offset:33792
	s_waitcnt vmcnt(2)
	s_barrier
	s_waitcnt lgkmcnt(0)
	s_waitcnt lgkmcnt(0)
	v_mfma_f32_16x16x32_bf16 v[66:69], v[18:21], v[2:5], v[126:129]
	v_mfma_f32_16x16x32_bf16 v[118:121], v[22:25], v[6:9], v[66:69]
	v_mfma_f32_16x16x32_bf16 v[66:69], v[18:21], v[194:197], v[122:125]
	v_mfma_f32_16x16x32_bf16 v[114:117], v[22:25], v[198:201], v[66:69]
	v_mfma_f32_16x16x32_bf16 v[66:69], v[34:37], v[2:5], v[142:145]
	v_mfma_f32_16x16x32_bf16 v[102:105], v[38:41], v[6:9], v[66:69]
	v_mfma_f32_16x16x32_bf16 v[66:69], v[34:37], v[194:197], v[202:205]
	v_mfma_f32_16x16x32_bf16 v[98:101], v[38:41], v[198:201], v[66:69]
	v_mfma_f32_16x16x32_bf16 v[66:69], v[50:53], v[2:5], v[110:113]
	v_mfma_f32_16x16x32_bf16 v[86:89], v[54:57], v[6:9], v[66:69]
	v_mfma_f32_16x16x32_bf16 v[66:69], v[50:53], v[194:197], v[106:109]
	v_mfma_f32_16x16x32_bf16 v[82:85], v[54:57], v[198:201], v[66:69]
	v_mfma_f32_16x16x32_bf16 v[66:69], v[222:225], v[2:5], v[206:209]
	v_mfma_f32_16x16x32_bf16 v[70:73], v[226:229], v[6:9], v[66:69]
	v_mfma_f32_16x16x32_bf16 v[66:69], v[222:225], v[194:197], v[210:213]
	v_mfma_f32_16x16x32_bf16 v[66:69], v[226:229], v[198:201], v[66:69]
	s_barrier
	ds_read_b128 v[140:143], v139
	ds_read_b128 v[202:205], v139 offset:1024
	ds_read_b128 v[206:209], v139 offset:2048
	ds_read_b128 v[210:213], v139 offset:3072
	s_waitcnt vmcnt(0)
	s_barrier
	s_waitcnt lgkmcnt(0)
	s_waitcnt lgkmcnt(0)
	v_mfma_f32_16x16x32_bf16 v[94:97], v[18:21], v[140:143], v[94:97]
	v_mfma_f32_16x16x32_bf16 v[18:21], v[18:21], v[206:209], v[90:93]
	v_mfma_f32_16x16x32_bf16 v[122:125], v[22:25], v[210:213], v[18:21]
	v_mfma_f32_16x16x32_bf16 v[18:21], v[34:37], v[140:143], v[164:167]
	v_mfma_f32_16x16x32_bf16 v[110:113], v[38:41], v[202:205], v[18:21]
	v_mfma_f32_16x16x32_bf16 v[18:21], v[34:37], v[206:209], v[174:177]
	v_mfma_f32_16x16x32_bf16 v[106:109], v[38:41], v[210:213], v[18:21]
	v_mfma_f32_16x16x32_bf16 v[18:21], v[50:53], v[140:143], v[78:81]
	v_mfma_f32_16x16x32_bf16 v[126:129], v[22:25], v[202:205], v[94:97]
	v_mfma_f32_16x16x32_bf16 v[94:97], v[54:57], v[202:205], v[18:21]
	v_mfma_f32_16x16x32_bf16 v[18:21], v[50:53], v[206:209], v[74:77]
	v_mfma_f32_16x16x32_bf16 v[90:93], v[54:57], v[210:213], v[18:21]
	v_mfma_f32_16x16x32_bf16 v[18:21], v[222:225], v[140:143], v[178:181]
	v_mfma_f32_16x16x32_bf16 v[78:81], v[226:229], v[202:205], v[18:21]
	v_mfma_f32_16x16x32_bf16 v[18:21], v[222:225], v[206:209], v[182:185]
	v_mfma_f32_16x16x32_bf16 v[74:77], v[226:229], v[210:213], v[18:21]
	s_barrier
	ds_read_b128 v[164:167], v138 offset:49152
	ds_read_b128 v[174:177], v138 offset:50176
	ds_read_b128 v[178:181], v137 offset:49152
	ds_read_b128 v[182:185], v137 offset:50176
	ds_read_b128 v[222:225], v136 offset:49152
	ds_read_b128 v[136:139], v136 offset:50176
	ds_read_b128 v[226:229], v135 offset:49152
	ds_read_b128 v[230:233], v135 offset:50176
	s_barrier
	s_waitcnt lgkmcnt(0)
	s_waitcnt lgkmcnt(0)
	v_mfma_f32_16x16x32_bf16 v[18:21], v[164:167], v[2:5], v[62:65]
	v_mfma_f32_16x16x32_bf16 v[54:57], v[174:177], v[6:9], v[18:21]
	v_mfma_f32_16x16x32_bf16 v[18:21], v[164:167], v[194:197], v[58:61]
	v_mfma_f32_16x16x32_bf16 v[50:53], v[174:177], v[198:201], v[18:21]
	v_mfma_f32_16x16x32_bf16 v[18:21], v[178:181], v[2:5], v[214:217]
	v_mfma_f32_16x16x32_bf16 v[38:41], v[182:185], v[6:9], v[18:21]
	v_mfma_f32_16x16x32_bf16 v[18:21], v[178:181], v[194:197], v[218:221]
	v_mfma_f32_16x16x32_bf16 v[34:37], v[182:185], v[198:201], v[18:21]
	v_mfma_f32_16x16x32_bf16 v[18:21], v[222:225], v[2:5], v[46:49]
	v_mfma_f32_16x16x32_bf16 v[2:5], v[226:229], v[2:5], v[146:149]
	v_mfma_f32_16x16x32_bf16 v[22:25], v[136:139], v[6:9], v[18:21]
	v_mfma_f32_16x16x32_bf16 v[18:21], v[222:225], v[194:197], v[42:45]
	v_mfma_f32_16x16x32_bf16 v[6:9], v[230:233], v[6:9], v[2:5]
	v_mfma_f32_16x16x32_bf16 v[2:5], v[226:229], v[194:197], v[150:153]
	v_mfma_f32_16x16x32_bf16 v[18:21], v[136:139], v[198:201], v[18:21]
	v_mfma_f32_16x16x32_bf16 v[2:5], v[230:233], v[198:201], v[2:5]
	v_mfma_f32_16x16x32_bf16 v[26:29], v[164:167], v[206:209], v[26:29]
	v_mfma_f32_16x16x32_bf16 v[58:61], v[174:177], v[210:213], v[26:29]
	v_mfma_f32_16x16x32_bf16 v[26:29], v[178:181], v[140:143], v[156:159]
	v_mfma_f32_16x16x32_bf16 v[46:49], v[182:185], v[202:205], v[26:29]
	v_mfma_f32_16x16x32_bf16 v[26:29], v[178:181], v[206:209], v[160:163]
	v_mfma_f32_16x16x32_bf16 v[10:13], v[222:225], v[206:209], v[10:13]
	v_mfma_f32_16x16x32_bf16 v[30:33], v[164:167], v[140:143], v[30:33]
	v_mfma_f32_16x16x32_bf16 v[42:45], v[182:185], v[210:213], v[26:29]
	v_mfma_f32_16x16x32_bf16 v[14:17], v[222:225], v[140:143], v[14:17]
	v_mfma_f32_16x16x32_bf16 v[26:29], v[136:139], v[210:213], v[10:13]
	v_mfma_f32_16x16x32_bf16 v[10:13], v[226:229], v[140:143], v[186:189]
	v_mfma_f32_16x16x32_bf16 v[62:65], v[174:177], v[202:205], v[30:33]
	v_mfma_f32_16x16x32_bf16 v[30:33], v[136:139], v[202:205], v[14:17]
	v_mfma_f32_16x16x32_bf16 v[14:17], v[230:233], v[202:205], v[10:13]
	v_mfma_f32_16x16x32_bf16 v[10:13], v[226:229], v[206:209], v[190:193]
	v_mfma_f32_16x16x32_bf16 v[10:13], v[230:233], v[210:213], v[10:13]
	v_cmp_gt_u32_e32 vcc, s35, v134
	s_barrier
	s_and_saveexec_b64 s[12:13], vcc
	s_cbranch_execz .LBB0_233
	s_barrier

; #define GAS __attribute__((address_space(1)))
; __device__ __forceinline__ int otid() { int t = threadIdx.x; asm volatile("" : "+v"(t)); return t; }
; #define STAGE(P, GP, ktrel) do { const GAS char* _g = (GP) + (ktrel) * (BK * 2); \
;     __builtin_amdgcn_global_load_lds((const GAS unsigned*)(_g + so0), (unsigned*)((char*)(P) + tid_ * 16), 16, 0, 0); \
;     __builtin_amdgcn_global_load_lds((const GAS unsigned*)(_g + so1), (unsigned*)((char*)(P) + tid_ * 16 + 8192), 16, 0, 0); } while (0)
; #define WAIT_V(n) asm volatile("s_waitcnt vmcnt(" #n ")" ::: "memory")
; #define WAIT_L(n) asm volatile("s_waitcnt lgkmcnt(" #n ")" ::: "memory")
; #define BAR __builtin_amdgcn_s_barrier()
; #define SCHED __builtin_amdgcn_sched_barrier(0)
; #define LDA(dst, b, h) for (int m = 0; m < 4; ++m) for (int k = 0; k < 2; ++k) \
;     dst[m][k] = *reinterpret_cast<const bf16x8*>((char*)SA(b, h) + lds_byte(wr * 64 + m * 16 + fr, k * 32 + fq * 8))
; template <int K, int LD = K>
; __device__ __forceinline__ void gemm_main(const GAS bf16* A, const GAS bf16* Bt, int brow, int bcol, f32x4 (&acc)[2][2][4][2]) {
;     ...
;   const int tid_ = otid();
;     ...
;   const int wid = tid_ >> 6, lane = tid_ & 63, wr = wid >> 2, wc = wid & 3, fr = lane & 15, fq = lane >> 4;
; #pragma unroll
;   for (int a = 0; a < 2; ++a)
; #pragma unroll
;     for (int b = 0; b < 2; ++b)
; #pragma unroll
;       for (int m = 0; m < 4; ++m)
; #pragma unroll
;         for (int n = 0; n < 2; ++n) acc[a][b][m][n] = f32x4{0.f, 0.f, 0.f, 0.f};
;   bf16x8 At[4][2], B0[2][2], B1[2][2];
;   unsigned so0, so1;
;   { int r_, c_; stage_rc(tid_ * 16, r_, c_); so0 = (unsigned)(r_ * LD + c_) * 2u; stage_rc(tid_ * 16 + 8192, r_, c_); so1 = (unsigned)(r_ * LD + c_) * 2u; }
;   const GAS char* pA0 = (const GAS char*)A + (long)brow * LD * 2; const GAS char* pA1 = pA0 + (long)HALF * LD * 2;
;   const GAS char* pB0 = (const GAS char*)Bt + (long)bcol * LD * 2; const GAS char* pB1 = pB0 + (long)HALF * LD * 2;
;   asm volatile("" : "+s"(pA0), "+s"(pA1), "+s"(pB0), "+s"(pB1));
;   constexpr int nt = K / BK;
;   static_assert(K % 128 == 0 && K >= 256, "K");
;   if (wr == 1) BAR;
;   WAIT_V(0); BAR;
;   BAR;
;   for (int t = 0; t < nt - 2; t += 2) {
;     LDB(B0, 0, 0); SCHED; LDA(At, 0, 0); STAGE(SA(1, 1), pA1, 1);
;     WAIT_L(8); BAR; WAIT_L(0); MMA(0, 0, At, B0); BAR; SCHED;
;     LDB(B1, 0, 1); STAGE(SB(0, 0), pB0, 2);
.LBB0_345:
	s_or_b64 exec, exec, s[38:39]
	v_bfe_i32 v7, v134, 27, 1
	v_lshlrev_b32_e32 v5, 4, v134
	v_lshrrev_b32_e32 v7, 22, v7
	v_add_u32_e32 v7, v5, v7
	v_and_b32_e32 v7, 0xfffffc00, v7
	v_sub_u32_e32 v7, v5, v7
	v_lshrrev_b32_e32 v8, 4, v7
	v_bitop3_b32 v8, v8, v7, 32 bitop3:0x6c
	v_ashrrev_i32_e32 v7, 31, v7
	v_ashrrev_i32_e32 v6, 31, v134
	v_lshrrev_b32_e32 v7, 26, v7
	v_lshrrev_b32_e32 v6, 26, v6
	v_add_u32_e32 v7, v8, v7
	v_add_u32_e32 v6, v134, v6
	v_ashrrev_i32_e32 v7, 6, v7
	v_ashrrev_i32_e32 v6, 6, v6
	v_mul_i32_i24_e32 v10, 64, v7
	v_lshlrev_b32_e32 v9, 3, v6
	v_lshlrev_b32_e32 v6, 5, v6
	v_sub_u32_e32 v8, v8, v10
	v_and_b32_e32 v9, 0x1ffff0, v9
	v_and_b32_e32 v6, 32, v6
	v_ashrrev_i16_sdwa v8, v144, sext(v8) dst_sel:DWORD dst_unused:UNUSED_PAD src0_sel:DWORD src1_sel:BYTE_0
	v_add_u32_sdwa v6, v6, sext(v8) dst_sel:DWORD dst_unused:UNUSED_PAD src0_sel:DWORD src1_sel:WORD_0
	v_add_lshl_u32 v7, v7, v9, 11
	v_lshl_add_u32 v130, v6, 1, v7
	v_add_u32_e32 v6, 0x2000, v5
	v_ashrrev_i32_e32 v7, 31, v6
	v_lshrrev_b32_e32 v7, 22, v7
	v_add_u32_e32 v7, v6, v7
	v_ashrrev_i32_e32 v7, 10, v7
	v_mul_i32_i24_e32 v8, 0x400, v7
	v_sub_u32_e32 v6, v6, v8
	v_lshrrev_b32_e32 v8, 4, v6
	v_bitop3_b32 v6, v8, v6, 32 bitop3:0x6c
	v_ashrrev_i32_e32 v9, 31, v6
	v_lshrrev_b32_e32 v9, 26, v9
	v_add_u32_e32 v9, v6, v9
	v_lshrrev_b32_e32 v10, 6, v9
	v_and_b32_e32 v9, 0xc0, v9
	v_lshlrev_b32_e32 v8, 3, v7
	v_lshlrev_b32_e32 v7, 5, v7
	v_sub_u32_e32 v6, v6, v9
	v_and_b32_e32 v8, 0x1ffff0, v8
	v_and_b32_e32 v7, 32, v7
	v_ashrrev_i16_sdwa v6, v144, sext(v6) dst_sel:DWORD dst_unused:UNUSED_PAD src0_sel:DWORD src1_sel:BYTE_0
	v_add_u32_sdwa v6, v7, sext(v6) dst_sel:DWORD dst_unused:UNUSED_PAD src0_sel:DWORD src1_sel:WORD_0
	v_add_lshl_u32 v7, v10, v8, 11
	v_and_b32_e32 v3, 15, v134
	v_lshl_add_u32 v132, v6, 1, v7
	v_lshlrev_b32_e32 v6, 2, v134
	v_and_b32_e32 v4, 48, v134
	v_lshlrev_b32_e32 v3, 6, v3
	v_and_b32_e32 v6, 32, v6
	v_lshlrev_b32_e32 v11, 6, v134
	v_bitop3_b32 v3, v3, v6, v4 bitop3:0x36
	v_lshlrev_b32_e32 v13, 13, v2
	v_and_or_b32 v2, v11, s51, v4
	v_add_u32_e32 v7, s42, v3
	v_add_u32_e32 v8, s43, v3
	v_add_u32_e32 v9, s46, v3
	v_add_u32_e32 v10, s47, v3
	v_and_b32_e32 v12, 0x3000, v11
	v_add_u32_e32 v3, 0x100, v3
	v_xad_u32 v4, v2, v6, s48
	v_or_b32_e32 v6, 0x800, v13
	v_or_b32_e32 v11, 0x1000, v13
	v_or_b32_e32 v14, 0x1800, v13
	v_mov_b32_e32 v2, 0
	v_add_u32_e32 v147, 0x100, v5
	v_add_u32_e32 v153, s42, v5
	v_add_u32_e32 v155, s43, v5
	v_add_u32_e32 v157, s46, v5
	v_add_u32_e32 v159, s47, v5
	v_mov_b32_e32 v133, v131
	s_mov_b32 s5, -2
	v_add_u32_e32 v146, v7, v12
	v_add_u32_e32 v138, v3, v13
	v_add_u32_e32 v137, v4, v6
	v_add_u32_e32 v136, v4, v11
	v_add_u32_e32 v135, v4, v14
	v_add_u32_e32 v143, 0xc000, v147
	v_add_u32_e32 v142, 0xe000, v147
	v_add_u32_e32 v141, v8, v12
	v_add_u32_e32 v148, 0x2000, v147
	v_add_u32_e32 v140, v9, v12
	v_add_u32_e32 v149, 0x4000, v147
	v_add_u32_e32 v150, 0x6000, v147
	v_add_u32_e32 v139, v10, v12
	v_add_u32_e32 v151, 0x8000, v147
	v_add_u32_e32 v152, 0xa000, v147
	v_add_u32_e32 v154, 0x2000, v153
	v_add_u32_e32 v156, 0x2000, v155
	v_add_u32_e32 v158, 0x2000, v157
	v_add_u32_e32 v160, 0x2000, v159
	s_waitcnt vmcnt(0)
	s_barrier
	s_barrier
	ds_read_b128 v[162:165], v146
	ds_read_b128 v[166:169], v146 offset:1024
	ds_read_b128 v[174:177], v146 offset:2048
	ds_read_b128 v[178:181], v146 offset:3072
	v_lshl_add_u64 v[230:231], s[26:27], 0, v[130:131]
	v_readfirstlane_b32 s20, v143
	v_lshl_add_u64 v[214:215], v[230:231], 0, s[14:15]
	s_mov_b32 m0, s20
	v_lshl_add_u64 v[232:233], s[26:27], 0, v[132:133]
	v_readfirstlane_b32 s20, v142
	ds_read_b128 v[182:185], v138
	ds_read_b128 v[186:189], v138 offset:1024
	ds_read_b128 v[190:193], v137
	ds_read_b128 v[194:197], v137 offset:1024
	ds_read_b128 v[198:201], v136
	ds_read_b128 v[202:205], v136 offset:1024
	ds_read_b128 v[206:209], v135
	ds_read_b128 v[210:213], v135 offset:1024
	global_load_lds_dwordx4 v[214:215], off
	v_lshl_add_u64 v[214:215], v[232:233], 0, s[14:15]
	s_mov_b32 m0, s20
	s_nop 0
	global_load_lds_dwordx4 v[214:215], off
	s_waitcnt lgkmcnt(8)
	s_waitcnt vmcnt(10)
	s_barrier
	s_waitcnt lgkmcnt(0)
	s_waitcnt lgkmcnt(0)
	v_mfma_f32_16x16x32_bf16 v[126:129], v[182:185], v[162:165], 0
	v_mfma_f32_16x16x32_bf16 v[122:125], v[182:185], v[174:177], 0
	v_mfma_f32_16x16x32_bf16 v[118:121], v[190:193], v[162:165], 0
	v_mfma_f32_16x16x32_bf16 v[114:117], v[190:193], v[174:177], 0
	v_mfma_f32_16x16x32_bf16 v[110:113], v[198:201], v[162:165], 0
	v_mfma_f32_16x16x32_bf16 v[106:109], v[198:201], v[174:177], 0
	v_mfma_f32_16x16x32_bf16 v[102:105], v[206:209], v[162:165], 0
	v_mfma_f32_16x16x32_bf16 v[98:101], v[206:209], v[174:177], 0
	v_mfma_f32_16x16x32_bf16 v[126:129], v[186:189], v[166:169], v[126:129]
	v_mfma_f32_16x16x32_bf16 v[122:125], v[186:189], v[178:181], v[122:125]
	v_mfma_f32_16x16x32_bf16 v[118:121], v[194:197], v[166:169], v[118:121]
	v_mfma_f32_16x16x32_bf16 v[114:117], v[194:197], v[178:181], v[114:117]
	v_mfma_f32_16x16x32_bf16 v[110:113], v[202:205], v[166:169], v[110:113]
	v_mfma_f32_16x16x32_bf16 v[106:109], v[202:205], v[178:181], v[106:109]
	v_mfma_f32_16x16x32_bf16 v[102:105], v[210:213], v[166:169], v[102:105]
	v_mfma_f32_16x16x32_bf16 v[98:101], v[210:213], v[178:181], v[98:101]
	s_barrier
	v_lshl_add_u64 v[234:235], s[36:37], 0, v[130:131]
	v_readfirstlane_b32 s20, v153
	v_lshl_add_u64 v[236:237], v[234:235], 0, s[22:23]
	s_mov_b32 m0, s20
	ds_read_b128 v[214:217], v141
	ds_read_b128 v[218:221], v141 offset:1024
	ds_read_b128 v[222:225], v141 offset:2048
	ds_read_b128 v[226:229], v141 offset:3072
	global_load_lds_dwordx4 v[236:237], off
	v_lshl_add_u64 v[236:237], s[36:37], 0, v[132:133]
	v_readfirstlane_b32 s20, v154
	v_lshl_add_u64 v[238:239], v[236:237], 0, s[22:23]
	s_mov_b32 m0, s20
	s_add_u32 s36, s36, 0x100
	global_load_lds_dwordx4 v[238:239], off
	s_waitcnt vmcnt(10)
	s_barrier
; #define STAGE(P, GP, ktrel) do { const GAS char* _g = (GP) + (ktrel) * (BK * 2); \
;     __builtin_amdgcn_global_load_lds((const GAS unsigned*)(_g + so0), (unsigned*)((char*)(P) + tid_ * 16), 16, 0, 0); \
;     __builtin_amdgcn_global_load_lds((const GAS unsigned*)(_g + so1), (unsigned*)((char*)(P) + tid_ * 16 + 8192), 16, 0, 0); } while (0)
; #define WAIT_V(n) asm volatile("s_waitcnt vmcnt(" #n ")" ::: "memory")
; #define WAIT_L(n) asm volatile("s_waitcnt lgkmcnt(" #n ")" ::: "memory")
; #define BAR __builtin_amdgcn_s_barrier()
; #define SCHED __builtin_amdgcn_sched_barrier(0)
; #define LDA(dst, b, h) for (int m = 0; m < 4; ++m) for (int k = 0; k < 2; ++k) \
;     dst[m][k] = *reinterpret_cast<const bf16x8*>((char*)SA(b, h) + lds_byte(wr * 64 + m * 16 + fr, k * 32 + fq * 8))
; #define LDB(dst, b, h) for (int n = 0; n < 2; ++n) for (int k = 0; k < 2; ++k) \
;     dst[n][k] = *reinterpret_cast<const bf16x8*>((char*)SB(b, h) + lds_byte(wc * 32 + n * 16 + fr, k * 32 + fq * 8))
; #define MMA(ai, bj, At_, Bt_) do { __builtin_amdgcn_s_setprio(1); \
;     for (int m = 0; m < 4; ++m) for (int n = 0; n < 2; ++n) for (int k = 0; k < 2; ++k) \
;       acc[ai][bj][m][n] = __builtin_amdgcn_mfma_f32_16x16x32_bf16(At_[m][k], Bt_[n][k], acc[ai][bj][m][n], 0, 0, 0); \
;     __builtin_amdgcn_s_setprio(0); } while (0)
; template <int K, int LD = K>
; __device__ __forceinline__ void gemm_main(const GAS bf16* A, const GAS bf16* Bt, int brow, int bcol, f32x4 (&acc)[2][2][4][2]) {
;     ...
;     BAR; WAIT_L(0); MMA(0, 1, At, B1); BAR;
;     LDA(At, 0, 1); STAGE(SA(0, 0), pA0, 2);
;     BAR; WAIT_L(0); MMA(1, 0, At, B0); BAR; SCHED;
;     STAGE(SB(0, 1), pB1, 2);
;     WAIT_V(6); BAR; MMA(1, 1, At, B1); BAR;
;     LDB(B0, 1, 0); SCHED; LDA(At, 1, 0); STAGE(SA(0, 1), pA1, 2);
;     WAIT_L(8); BAR; WAIT_L(0); MMA(0, 0, At, B0); BAR; SCHED;
	s_waitcnt lgkmcnt(0)
	s_addc_u32 s37, s37, 0
	s_waitcnt lgkmcnt(0)
	v_mfma_f32_16x16x32_bf16 v[94:97], v[182:185], v[214:217], 0
	v_mfma_f32_16x16x32_bf16 v[90:93], v[182:185], v[222:225], 0
	v_mfma_f32_16x16x32_bf16 v[86:89], v[190:193], v[214:217], 0
	v_mfma_f32_16x16x32_bf16 v[82:85], v[190:193], v[222:225], 0
	v_mfma_f32_16x16x32_bf16 v[78:81], v[198:201], v[214:217], 0
	v_mfma_f32_16x16x32_bf16 v[74:77], v[198:201], v[222:225], 0
	v_mfma_f32_16x16x32_bf16 v[70:73], v[206:209], v[214:217], 0
	v_mfma_f32_16x16x32_bf16 v[66:69], v[206:209], v[222:225], 0
	v_mfma_f32_16x16x32_bf16 v[94:97], v[186:189], v[218:221], v[94:97]
	v_mfma_f32_16x16x32_bf16 v[90:93], v[186:189], v[226:229], v[90:93]
	v_mfma_f32_16x16x32_bf16 v[86:89], v[194:197], v[218:221], v[86:89]
	v_mfma_f32_16x16x32_bf16 v[82:85], v[194:197], v[226:229], v[82:85]
	v_mfma_f32_16x16x32_bf16 v[78:81], v[202:205], v[218:221], v[78:81]
	v_mfma_f32_16x16x32_bf16 v[74:77], v[202:205], v[226:229], v[74:77]
	v_mfma_f32_16x16x32_bf16 v[70:73], v[210:213], v[218:221], v[70:73]
	v_mfma_f32_16x16x32_bf16 v[66:69], v[210:213], v[226:229], v[66:69]
	v_lshl_add_u64 v[238:239], s[34:35], 0, v[130:131]
	v_readfirstlane_b32 s20, v147
	v_lshl_add_u64 v[240:241], v[238:239], 0, s[22:23]
	s_mov_b32 m0, s20
	s_barrier
	ds_read_b128 v[182:185], v138 offset:16384
	ds_read_b128 v[186:189], v138 offset:17408
	ds_read_b128 v[190:193], v137 offset:16384
	ds_read_b128 v[194:197], v137 offset:17408
	ds_read_b128 v[198:201], v136 offset:16384
	ds_read_b128 v[202:205], v136 offset:17408
	ds_read_b128 v[206:209], v135 offset:16384
	ds_read_b128 v[210:213], v135 offset:17408
	global_load_lds_dwordx4 v[240:241], off
	v_lshl_add_u64 v[240:241], s[34:35], 0, v[132:133]
	v_readfirstlane_b32 s20, v148
	v_lshl_add_u64 v[242:243], v[240:241], 0, s[22:23]
	s_mov_b32 m0, s20
	s_add_u32 s34, s34, 0x100
	global_load_lds_dwordx4 v[242:243], off
	s_barrier
	s_waitcnt lgkmcnt(0)
	s_addc_u32 s35, s35, 0
	s_waitcnt lgkmcnt(0)
	v_mfma_f32_16x16x32_bf16 v[62:65], v[182:185], v[162:165], 0
	v_mfma_f32_16x16x32_bf16 v[58:61], v[182:185], v[174:177], 0
	v_mfma_f32_16x16x32_bf16 v[54:57], v[190:193], v[162:165], 0
	v_mfma_f32_16x16x32_bf16 v[50:53], v[190:193], v[174:177], 0
	v_mfma_f32_16x16x32_bf16 v[46:49], v[198:201], v[162:165], 0
	v_mfma_f32_16x16x32_bf16 v[42:45], v[198:201], v[174:177], 0
	v_mfma_f32_16x16x32_bf16 v[38:41], v[206:209], v[162:165], 0
	v_mfma_f32_16x16x32_bf16 v[34:37], v[206:209], v[174:177], 0
	v_mfma_f32_16x16x32_bf16 v[62:65], v[186:189], v[166:169], v[62:65]
	v_mfma_f32_16x16x32_bf16 v[58:61], v[186:189], v[178:181], v[58:61]
	v_mfma_f32_16x16x32_bf16 v[54:57], v[194:197], v[166:169], v[54:57]
	v_mfma_f32_16x16x32_bf16 v[50:53], v[194:197], v[178:181], v[50:53]
	v_mfma_f32_16x16x32_bf16 v[46:49], v[202:205], v[166:169], v[46:49]
	v_mfma_f32_16x16x32_bf16 v[42:45], v[202:205], v[178:181], v[42:45]
	v_mfma_f32_16x16x32_bf16 v[38:41], v[210:213], v[166:169], v[38:41]
	v_mfma_f32_16x16x32_bf16 v[34:37], v[210:213], v[178:181], v[34:37]
	s_barrier
	v_lshl_add_u64 v[242:243], s[28:29], 0, v[130:131]
	v_readfirstlane_b32 s20, v155
	v_lshl_add_u64 v[162:163], v[242:243], 0, s[22:23]
	s_mov_b32 m0, s20
	v_lshl_add_u64 v[244:245], s[28:29], 0, v[132:133]
	v_readfirstlane_b32 s20, v156
	global_load_lds_dwordx4 v[162:163], off
	v_lshl_add_u64 v[162:163], v[244:245], 0, s[22:23]
	s_mov_b32 m0, s20
	s_add_u32 s28, s28, 0x100
	global_load_lds_dwordx4 v[162:163], off
	s_waitcnt vmcnt(10)
	s_addc_u32 s29, s29, 0
	s_barrier
	v_mfma_f32_16x16x32_bf16 v[30:33], v[182:185], v[214:217], 0
	v_mfma_f32_16x16x32_bf16 v[26:29], v[182:185], v[222:225], 0
	v_mfma_f32_16x16x32_bf16 v[22:25], v[190:193], v[214:217], 0
	v_mfma_f32_16x16x32_bf16 v[18:21], v[190:193], v[222:225], 0
	v_mfma_f32_16x16x32_bf16 v[14:17], v[198:201], v[214:217], 0
	v_mfma_f32_16x16x32_bf16 v[10:13], v[198:201], v[222:225], 0
	v_mfma_f32_16x16x32_bf16 v[6:9], v[206:209], v[214:217], 0
	v_mfma_f32_16x16x32_bf16 v[2:5], v[206:209], v[222:225], 0
	v_mfma_f32_16x16x32_bf16 v[30:33], v[186:189], v[218:221], v[30:33]
	v_mfma_f32_16x16x32_bf16 v[26:29], v[186:189], v[226:229], v[26:29]
	v_mfma_f32_16x16x32_bf16 v[22:25], v[194:197], v[218:221], v[22:25]
	v_mfma_f32_16x16x32_bf16 v[18:21], v[194:197], v[226:229], v[18:21]
	v_mfma_f32_16x16x32_bf16 v[14:17], v[202:205], v[218:221], v[14:17]
	v_mfma_f32_16x16x32_bf16 v[10:13], v[202:205], v[226:229], v[10:13]
	v_mfma_f32_16x16x32_bf16 v[6:9], v[210:213], v[218:221], v[6:9]
	v_mfma_f32_16x16x32_bf16 v[2:5], v[210:213], v[226:229], v[2:5]
	s_barrier
	ds_read_b128 v[162:165], v140
	ds_read_b128 v[166:169], v140 offset:1024
	ds_read_b128 v[174:177], v140 offset:2048
	ds_read_b128 v[178:181], v140 offset:3072
	v_readfirstlane_b32 s20, v149
	v_lshl_add_u64 v[214:215], v[230:231], 0, s[22:23]
	s_mov_b32 m0, s20
	v_readfirstlane_b32 s20, v150
	ds_read_b128 v[182:185], v138 offset:32768
	ds_read_b128 v[186:189], v138 offset:33792
	ds_read_b128 v[190:193], v137 offset:32768
	ds_read_b128 v[194:197], v137 offset:33792
	ds_read_b128 v[198:201], v136 offset:32768
	ds_read_b128 v[202:205], v136 offset:33792
	ds_read_b128 v[206:209], v135 offset:32768
	ds_read_b128 v[210:213], v135 offset:33792
	global_load_lds_dwordx4 v[214:215], off
	v_lshl_add_u64 v[214:215], v[232:233], 0, s[22:23]
	s_mov_b32 m0, s20
	s_add_u32 s26, s26, 0x100
	global_load_lds_dwordx4 v[214:215], off
	s_waitcnt lgkmcnt(8)
	s_waitcnt vmcnt(10)
	s_barrier
; #define STAGE(P, GP, ktrel) do { const GAS char* _g = (GP) + (ktrel) * (BK * 2); \
;     __builtin_amdgcn_global_load_lds((const GAS unsigned*)(_g + so0), (unsigned*)((char*)(P) + tid_ * 16), 16, 0, 0); \
;     __builtin_amdgcn_global_load_lds((const GAS unsigned*)(_g + so1), (unsigned*)((char*)(P) + tid_ * 16 + 8192), 16, 0, 0); } while (0)
; #define WAIT_V(n) asm volatile("s_waitcnt vmcnt(" #n ")" ::: "memory")
; #define WAIT_L(n) asm volatile("s_waitcnt lgkmcnt(" #n ")" ::: "memory")
; #define BAR __builtin_amdgcn_s_barrier()
; #define SCHED __builtin_amdgcn_sched_barrier(0)
; #define LDA(dst, b, h) for (int m = 0; m < 4; ++m) for (int k = 0; k < 2; ++k) \
;     dst[m][k] = *reinterpret_cast<const bf16x8*>((char*)SA(b, h) + lds_byte(wr * 64 + m * 16 + fr, k * 32 + fq * 8))
; #define LDB(dst, b, h) for (int n = 0; n < 2; ++n) for (int k = 0; k < 2; ++k) \
;     dst[n][k] = *reinterpret_cast<const bf16x8*>((char*)SB(b, h) + lds_byte(wc * 32 + n * 16 + fr, k * 32 + fq * 8))
; #define MMA(ai, bj, At_, Bt_) do { __builtin_amdgcn_s_setprio(1); \
;     for (int m = 0; m < 4; ++m) for (int n = 0; n < 2; ++n) for (int k = 0; k < 2; ++k) \
;       acc[ai][bj][m][n] = __builtin_amdgcn_mfma_f32_16x16x32_bf16(At_[m][k], Bt_[n][k], acc[ai][bj][m][n], 0, 0, 0); \
;     __builtin_amdgcn_s_setprio(0); } while (0)
; template <int K, int LD = K>
; __device__ __forceinline__ void gemm_main(const GAS bf16* A, const GAS bf16* Bt, int brow, int bcol, f32x4 (&acc)[2][2][4][2]) {
;     ...
;     WAIT_L(8); BAR; WAIT_L(0); MMA(0, 0, At, B0); BAR; SCHED;
;     LDB(B1, 1, 1); STAGE(SB(1, 0), pB0, 3);
;     BAR; WAIT_L(0); MMA(0, 1, At, B1); BAR;
;     LDA(At, 1, 1); STAGE(SA(1, 0), pA0, 3);
;     BAR; WAIT_L(0); MMA(1, 0, At, B0); BAR; SCHED;
;     STAGE(SB(1, 1), pB1, 3);
;     WAIT_V(6); BAR; MMA(1, 1, At, B1); BAR;
;     pA0 += 4 * BK; pA1 += 4 * BK; pB0 += 4 * BK; pB1 += 4 * BK;
;     asm volatile("" : "+s"(pA0), "+s"(pA1), "+s"(pB0), "+s"(pB1));
	s_waitcnt lgkmcnt(0)
	s_addc_u32 s27, s27, 0
	s_waitcnt lgkmcnt(0)
	v_mfma_f32_16x16x32_bf16 v[126:129], v[182:185], v[162:165], v[126:129]
	v_mfma_f32_16x16x32_bf16 v[122:125], v[182:185], v[174:177], v[122:125]
	v_mfma_f32_16x16x32_bf16 v[118:121], v[190:193], v[162:165], v[118:121]
	v_mfma_f32_16x16x32_bf16 v[114:117], v[190:193], v[174:177], v[114:117]
	v_mfma_f32_16x16x32_bf16 v[110:113], v[198:201], v[162:165], v[110:113]
	v_mfma_f32_16x16x32_bf16 v[106:109], v[198:201], v[174:177], v[106:109]
	v_mfma_f32_16x16x32_bf16 v[102:105], v[206:209], v[162:165], v[102:105]
	v_mfma_f32_16x16x32_bf16 v[98:101], v[206:209], v[174:177], v[98:101]
	v_mfma_f32_16x16x32_bf16 v[126:129], v[186:189], v[166:169], v[126:129]
	v_mfma_f32_16x16x32_bf16 v[122:125], v[186:189], v[178:181], v[122:125]
	v_mfma_f32_16x16x32_bf16 v[118:121], v[194:197], v[166:169], v[118:121]
	v_mfma_f32_16x16x32_bf16 v[114:117], v[194:197], v[178:181], v[114:117]
	v_mfma_f32_16x16x32_bf16 v[110:113], v[202:205], v[166:169], v[110:113]
	v_mfma_f32_16x16x32_bf16 v[106:109], v[202:205], v[178:181], v[106:109]
	v_mfma_f32_16x16x32_bf16 v[102:105], v[210:213], v[166:169], v[102:105]
	v_mfma_f32_16x16x32_bf16 v[98:101], v[210:213], v[178:181], v[98:101]
	s_barrier
	v_readfirstlane_b32 s20, v157
	v_lshl_add_u64 v[230:231], v[234:235], 0, s[24:25]
	s_mov_b32 m0, s20
	v_readfirstlane_b32 s20, v158
	ds_read_b128 v[214:217], v139
	ds_read_b128 v[218:221], v139 offset:1024
	ds_read_b128 v[222:225], v139 offset:2048
	ds_read_b128 v[226:229], v139 offset:3072
	global_load_lds_dwordx4 v[230:231], off
	v_lshl_add_u64 v[230:231], v[236:237], 0, s[24:25]
	s_mov_b32 m0, s20
	s_nop 0
	global_load_lds_dwordx4 v[230:231], off
	s_waitcnt vmcnt(10)
	s_barrier
	s_waitcnt lgkmcnt(0)
	s_waitcnt lgkmcnt(0)
	v_mfma_f32_16x16x32_bf16 v[94:97], v[182:185], v[214:217], v[94:97]
	v_mfma_f32_16x16x32_bf16 v[90:93], v[182:185], v[222:225], v[90:93]
	v_mfma_f32_16x16x32_bf16 v[86:89], v[190:193], v[214:217], v[86:89]
	v_mfma_f32_16x16x32_bf16 v[82:85], v[190:193], v[222:225], v[82:85]
	v_mfma_f32_16x16x32_bf16 v[78:81], v[198:201], v[214:217], v[78:81]
	v_mfma_f32_16x16x32_bf16 v[74:77], v[198:201], v[222:225], v[74:77]
	v_mfma_f32_16x16x32_bf16 v[70:73], v[206:209], v[214:217], v[70:73]
	v_mfma_f32_16x16x32_bf16 v[66:69], v[206:209], v[222:225], v[66:69]
	v_mfma_f32_16x16x32_bf16 v[94:97], v[186:189], v[218:221], v[94:97]
	v_mfma_f32_16x16x32_bf16 v[90:93], v[186:189], v[226:229], v[90:93]
	v_mfma_f32_16x16x32_bf16 v[86:89], v[194:197], v[218:221], v[86:89]
	v_mfma_f32_16x16x32_bf16 v[82:85], v[194:197], v[226:229], v[82:85]
	v_mfma_f32_16x16x32_bf16 v[78:81], v[202:205], v[218:221], v[78:81]
	v_mfma_f32_16x16x32_bf16 v[74:77], v[202:205], v[226:229], v[74:77]
	v_mfma_f32_16x16x32_bf16 v[70:73], v[210:213], v[218:221], v[70:73]
	v_mfma_f32_16x16x32_bf16 v[66:69], v[210:213], v[226:229], v[66:69]
	v_readfirstlane_b32 s20, v151
	v_lshl_add_u64 v[230:231], v[238:239], 0, s[24:25]
	s_mov_b32 m0, s20
	v_readfirstlane_b32 s20, v152
	s_barrier
	ds_read_b128 v[182:185], v138 offset:49152
	ds_read_b128 v[186:189], v138 offset:50176
	ds_read_b128 v[190:193], v137 offset:49152
	ds_read_b128 v[194:197], v137 offset:50176
	ds_read_b128 v[198:201], v136 offset:49152
	ds_read_b128 v[202:205], v136 offset:50176
	ds_read_b128 v[206:209], v135 offset:49152
	ds_read_b128 v[210:213], v135 offset:50176
	global_load_lds_dwordx4 v[230:231], off
	v_lshl_add_u64 v[230:231], v[240:241], 0, s[24:25]
	s_mov_b32 m0, s20
	s_nop 0
	global_load_lds_dwordx4 v[230:231], off
	s_barrier
	s_waitcnt lgkmcnt(0)
	s_waitcnt lgkmcnt(0)
	v_mfma_f32_16x16x32_bf16 v[62:65], v[182:185], v[162:165], v[62:65]
	v_mfma_f32_16x16x32_bf16 v[58:61], v[182:185], v[174:177], v[58:61]
	v_mfma_f32_16x16x32_bf16 v[54:57], v[190:193], v[162:165], v[54:57]
	v_mfma_f32_16x16x32_bf16 v[50:53], v[190:193], v[174:177], v[50:53]
	v_mfma_f32_16x16x32_bf16 v[46:49], v[198:201], v[162:165], v[46:49]
	v_mfma_f32_16x16x32_bf16 v[42:45], v[198:201], v[174:177], v[42:45]
	v_mfma_f32_16x16x32_bf16 v[38:41], v[206:209], v[162:165], v[38:41]
	v_mfma_f32_16x16x32_bf16 v[34:37], v[206:209], v[174:177], v[34:37]
	v_mfma_f32_16x16x32_bf16 v[62:65], v[186:189], v[166:169], v[62:65]
	v_mfma_f32_16x16x32_bf16 v[58:61], v[186:189], v[178:181], v[58:61]
	v_mfma_f32_16x16x32_bf16 v[54:57], v[194:197], v[166:169], v[54:57]
	v_mfma_f32_16x16x32_bf16 v[50:53], v[194:197], v[178:181], v[50:53]
	v_mfma_f32_16x16x32_bf16 v[46:49], v[202:205], v[166:169], v[46:49]
	v_mfma_f32_16x16x32_bf16 v[42:45], v[202:205], v[178:181], v[42:45]
	v_mfma_f32_16x16x32_bf16 v[38:41], v[210:213], v[166:169], v[38:41]
	v_mfma_f32_16x16x32_bf16 v[34:37], v[210:213], v[178:181], v[34:37]
	s_barrier
	v_readfirstlane_b32 s20, v159
	v_lshl_add_u64 v[162:163], v[242:243], 0, s[24:25]
	s_mov_b32 m0, s20
	v_readfirstlane_b32 s20, v160
	global_load_lds_dwordx4 v[162:163], off
	v_lshl_add_u64 v[162:163], v[244:245], 0, s[24:25]
	s_mov_b32 m0, s20
	s_nop 0
	global_load_lds_dwordx4 v[162:163], off
	s_waitcnt vmcnt(10)
	s_barrier
	v_mfma_f32_16x16x32_bf16 v[30:33], v[182:185], v[214:217], v[30:33]
	v_mfma_f32_16x16x32_bf16 v[26:29], v[182:185], v[222:225], v[26:29]
	v_mfma_f32_16x16x32_bf16 v[22:25], v[190:193], v[214:217], v[22:25]
	v_mfma_f32_16x16x32_bf16 v[18:21], v[190:193], v[222:225], v[18:21]
	v_mfma_f32_16x16x32_bf16 v[14:17], v[198:201], v[214:217], v[14:17]
	v_mfma_f32_16x16x32_bf16 v[10:13], v[198:201], v[222:225], v[10:13]
	v_mfma_f32_16x16x32_bf16 v[6:9], v[206:209], v[214:217], v[6:9]
	v_mfma_f32_16x16x32_bf16 v[2:5], v[206:209], v[222:225], v[2:5]
	v_mfma_f32_16x16x32_bf16 v[30:33], v[186:189], v[218:221], v[30:33]
	v_mfma_f32_16x16x32_bf16 v[26:29], v[186:189], v[226:229], v[26:29]
	v_mfma_f32_16x16x32_bf16 v[22:25], v[194:197], v[218:221], v[22:25]
	v_mfma_f32_16x16x32_bf16 v[18:21], v[194:197], v[226:229], v[18:21]
	v_mfma_f32_16x16x32_bf16 v[14:17], v[202:205], v[218:221], v[14:17]
	v_mfma_f32_16x16x32_bf16 v[10:13], v[202:205], v[226:229], v[10:13]
	v_mfma_f32_16x16x32_bf16 v[6:9], v[210:213], v[218:221], v[6:9]
	v_mfma_f32_16x16x32_bf16 v[2:5], v[210:213], v[226:229], v[2:5]
	s_add_i32 s5, s5, 2
	s_cmp_lt_u32 s5, 12
	s_barrier
	s_cbranch_scc1 .LBB0_346
	s_branch .Lpeel6_exit

; #define STAGE(P, GP, ktrel) do { const GAS char* _g = (GP) + (ktrel) * (BK * 2); \
;     __builtin_amdgcn_global_load_lds((const GAS unsigned*)(_g + so0), (unsigned*)((char*)(P) + tid_ * 16), 16, 0, 0); \
;     __builtin_amdgcn_global_load_lds((const GAS unsigned*)(_g + so1), (unsigned*)((char*)(P) + tid_ * 16 + 8192), 16, 0, 0); } while (0)
; #define WAIT_V(n) asm volatile("s_waitcnt vmcnt(" #n ")" ::: "memory")
; #define WAIT_L(n) asm volatile("s_waitcnt lgkmcnt(" #n ")" ::: "memory")
; #define BAR __builtin_amdgcn_s_barrier()
; #define LDA(dst, b, h) for (int m = 0; m < 4; ++m) for (int k = 0; k < 2; ++k) \
;     dst[m][k] = *reinterpret_cast<const bf16x8*>((char*)SA(b, h) + lds_byte(wr * 64 + m * 16 + fr, k * 32 + fq * 8))
; #define LDB(dst, b, h) for (int n = 0; n < 2; ++n) for (int k = 0; k < 2; ++k) \
;     dst[n][k] = *reinterpret_cast<const bf16x8*>((char*)SB(b, h) + lds_byte(wc * 32 + n * 16 + fr, k * 32 + fq * 8))
; #define MMA(ai, bj, At_, Bt_) do { __builtin_amdgcn_s_setprio(1); \
;     for (int m = 0; m < 4; ++m) for (int n = 0; n < 2; ++n) for (int k = 0; k < 2; ++k) \
;       acc[ai][bj][m][n] = __builtin_amdgcn_mfma_f32_16x16x32_bf16(At_[m][k], Bt_[n][k], acc[ai][bj][m][n], 0, 0, 0); \
;     __builtin_amdgcn_s_setprio(0); } while (0)
; template <int K, int LD = K>
; __device__ __forceinline__ void gemm_main(const GAS bf16* A, const GAS bf16* Bt, int brow, int bcol, f32x4 (&acc)[2][2][4][2]) {
;     ...
;   { LDB(B0, 0, 0); LDA(At, 0, 0); STAGE(SA(1, 1), pA1, 1);
;     BAR; WAIT_L(0); MMA(0, 0, At, B0); BAR;
;     LDB(B1, 0, 1); BAR; WAIT_L(0); MMA(0, 1, At, B1); BAR;
;     LDA(At, 0, 1); WAIT_V(4); BAR; WAIT_L(0); MMA(1, 0, At, B0); MMA(1, 1, At, B1); BAR; }
.Lpeel6_exit:
	ds_read_b128 v[148:151], v146
	ds_read_b128 v[152:155], v146 offset:1024
	ds_read_b128 v[156:159], v146 offset:2048
	ds_read_b128 v[160:163], v146 offset:3072
	ds_read_b128 v[164:167], v138
	ds_read_b128 v[174:177], v138 offset:1024
	ds_read_b128 v[178:181], v137
	ds_read_b128 v[182:185], v137 offset:1024
	ds_read_b128 v[186:189], v136
	ds_read_b128 v[190:193], v136 offset:1024
	ds_read_b128 v[194:197], v135
	ds_read_b128 v[198:201], v135 offset:1024
	v_lshl_add_u64 v[146:147], s[26:27], 0, v[130:131]
	v_readfirstlane_b32 s5, v143
	v_lshl_add_u64 v[146:147], v[146:147], 0, s[14:15]
	s_mov_b32 m0, s5
	v_lshl_add_u64 v[132:133], s[26:27], 0, v[132:133]
	v_readfirstlane_b32 s5, v142
	global_load_lds_dwordx4 v[146:147], off
	v_lshl_add_u64 v[132:133], v[132:133], 0, s[14:15]
	s_mov_b32 m0, s5
	s_nop 0
	global_load_lds_dwordx4 v[132:133], off
	s_waitcnt vmcnt(10)
	s_barrier
	s_waitcnt lgkmcnt(0)
	s_waitcnt lgkmcnt(0)
	v_mfma_f32_16x16x32_bf16 v[126:129], v[164:167], v[148:151], v[126:129]
	v_mfma_f32_16x16x32_bf16 v[122:125], v[164:167], v[156:159], v[122:125]
	v_mfma_f32_16x16x32_bf16 v[110:113], v[186:189], v[148:151], v[110:113]
	v_mfma_f32_16x16x32_bf16 v[106:109], v[186:189], v[156:159], v[106:109]
	v_mfma_f32_16x16x32_bf16 v[126:129], v[174:177], v[152:155], v[126:129]
	v_mfma_f32_16x16x32_bf16 v[122:125], v[174:177], v[160:163], v[122:125]
	v_mfma_f32_16x16x32_bf16 v[118:121], v[178:181], v[148:151], v[118:121]
	v_mfma_f32_16x16x32_bf16 v[114:117], v[178:181], v[156:159], v[114:117]
	v_mfma_f32_16x16x32_bf16 v[110:113], v[190:193], v[152:155], v[110:113]
	v_mfma_f32_16x16x32_bf16 v[106:109], v[190:193], v[160:163], v[106:109]
	v_mfma_f32_16x16x32_bf16 v[102:105], v[194:197], v[148:151], v[102:105]
	v_mfma_f32_16x16x32_bf16 v[98:101], v[194:197], v[156:159], v[98:101]
	v_mfma_f32_16x16x32_bf16 v[202:205], v[182:185], v[152:155], v[118:121]
	v_mfma_f32_16x16x32_bf16 v[206:209], v[182:185], v[160:163], v[114:117]
	v_mfma_f32_16x16x32_bf16 v[210:213], v[198:201], v[152:155], v[102:105]
	v_mfma_f32_16x16x32_bf16 v[214:217], v[198:201], v[160:163], v[98:101]
	s_barrier
	s_nop 1
	ds_read_b128 v[98:101], v141
	ds_read_b128 v[102:105], v141 offset:1024
	ds_read_b128 v[114:117], v141 offset:2048
	ds_read_b128 v[118:121], v141 offset:3072
	s_waitcnt vmcnt(8)
	s_barrier
	s_waitcnt lgkmcnt(0)
	s_waitcnt lgkmcnt(0)
	v_mfma_f32_16x16x32_bf16 v[94:97], v[164:167], v[98:101], v[94:97]
	v_mfma_f32_16x16x32_bf16 v[90:93], v[164:167], v[114:117], v[90:93]
	v_mfma_f32_16x16x32_bf16 v[78:81], v[186:189], v[98:101], v[78:81]
	v_mfma_f32_16x16x32_bf16 v[74:77], v[186:189], v[114:117], v[74:77]
	v_mfma_f32_16x16x32_bf16 v[94:97], v[174:177], v[102:105], v[94:97]
	v_mfma_f32_16x16x32_bf16 v[90:93], v[174:177], v[118:121], v[90:93]
	v_mfma_f32_16x16x32_bf16 v[86:89], v[178:181], v[98:101], v[86:89]
	v_mfma_f32_16x16x32_bf16 v[82:85], v[178:181], v[114:117], v[82:85]
	v_mfma_f32_16x16x32_bf16 v[78:81], v[190:193], v[102:105], v[78:81]
	v_mfma_f32_16x16x32_bf16 v[74:77], v[190:193], v[118:121], v[74:77]
	v_mfma_f32_16x16x32_bf16 v[70:73], v[194:197], v[98:101], v[70:73]
	v_mfma_f32_16x16x32_bf16 v[66:69], v[194:197], v[114:117], v[66:69]
	v_mfma_f32_16x16x32_bf16 v[164:167], v[182:185], v[102:105], v[86:89]
	v_mfma_f32_16x16x32_bf16 v[174:177], v[182:185], v[118:121], v[82:85]
	v_mfma_f32_16x16x32_bf16 v[178:181], v[198:201], v[102:105], v[70:73]
	v_mfma_f32_16x16x32_bf16 v[182:185], v[198:201], v[118:121], v[66:69]
	s_barrier
	s_nop 1
	ds_read_b128 v[66:69], v138 offset:16384
	ds_read_b128 v[70:73], v138 offset:17408
	ds_read_b128 v[82:85], v137 offset:16384
	ds_read_b128 v[86:89], v137 offset:17408
	ds_read_b128 v[186:189], v136 offset:16384
	ds_read_b128 v[190:193], v136 offset:17408
	ds_read_b128 v[194:197], v135 offset:16384
	ds_read_b128 v[198:201], v135 offset:17408
	s_waitcnt vmcnt(4)
	s_barrier
	s_waitcnt lgkmcnt(0)
	s_waitcnt lgkmcnt(0)
	v_mfma_f32_16x16x32_bf16 v[62:65], v[66:69], v[148:151], v[62:65]
	v_mfma_f32_16x16x32_bf16 v[58:61], v[66:69], v[156:159], v[58:61]
	v_mfma_f32_16x16x32_bf16 v[46:49], v[186:189], v[148:151], v[46:49]
	v_mfma_f32_16x16x32_bf16 v[42:45], v[186:189], v[156:159], v[42:45]
	v_mfma_f32_16x16x32_bf16 v[62:65], v[70:73], v[152:155], v[62:65]
	v_mfma_f32_16x16x32_bf16 v[58:61], v[70:73], v[160:163], v[58:61]
	v_mfma_f32_16x16x32_bf16 v[54:57], v[82:85], v[148:151], v[54:57]
	v_mfma_f32_16x16x32_bf16 v[50:53], v[82:85], v[156:159], v[50:53]
	v_mfma_f32_16x16x32_bf16 v[46:49], v[190:193], v[152:155], v[46:49]
	v_mfma_f32_16x16x32_bf16 v[42:45], v[190:193], v[160:163], v[42:45]
	v_mfma_f32_16x16x32_bf16 v[38:41], v[194:197], v[148:151], v[38:41]
	v_mfma_f32_16x16x32_bf16 v[34:37], v[194:197], v[156:159], v[34:37]
	v_mfma_f32_16x16x32_bf16 v[218:221], v[86:89], v[152:155], v[54:57]
	v_mfma_f32_16x16x32_bf16 v[222:225], v[86:89], v[160:163], v[50:53]
	v_mfma_f32_16x16x32_bf16 v[146:149], v[198:201], v[152:155], v[38:41]
	v_mfma_f32_16x16x32_bf16 v[150:153], v[198:201], v[160:163], v[34:37]
	v_mfma_f32_16x16x32_bf16 v[30:33], v[66:69], v[98:101], v[30:33]
	v_mfma_f32_16x16x32_bf16 v[26:29], v[66:69], v[114:117], v[26:29]
	v_mfma_f32_16x16x32_bf16 v[14:17], v[186:189], v[98:101], v[14:17]
	v_mfma_f32_16x16x32_bf16 v[10:13], v[186:189], v[114:117], v[10:13]
	v_mfma_f32_16x16x32_bf16 v[30:33], v[70:73], v[102:105], v[30:33]
	v_mfma_f32_16x16x32_bf16 v[26:29], v[70:73], v[118:121], v[26:29]
	v_mfma_f32_16x16x32_bf16 v[22:25], v[82:85], v[98:101], v[22:25]
	v_mfma_f32_16x16x32_bf16 v[18:21], v[82:85], v[114:117], v[18:21]
	v_mfma_f32_16x16x32_bf16 v[14:17], v[190:193], v[102:105], v[14:17]
	v_mfma_f32_16x16x32_bf16 v[10:13], v[190:193], v[118:121], v[10:13]
	v_mfma_f32_16x16x32_bf16 v[6:9], v[194:197], v[98:101], v[6:9]
	v_mfma_f32_16x16x32_bf16 v[2:5], v[194:197], v[114:117], v[2:5]
	v_mfma_f32_16x16x32_bf16 v[154:157], v[86:89], v[102:105], v[22:25]
	v_mfma_f32_16x16x32_bf16 v[158:161], v[86:89], v[118:121], v[18:21]
	v_mfma_f32_16x16x32_bf16 v[186:189], v[198:201], v[102:105], v[6:9]
	v_mfma_f32_16x16x32_bf16 v[190:193], v[198:201], v[118:121], v[2:5]
	s_barrier
; #define WAIT_V(n) asm volatile("s_waitcnt vmcnt(" #n ")" ::: "memory")
; #define WAIT_L(n) asm volatile("s_waitcnt lgkmcnt(" #n ")" ::: "memory")
; #define BAR __builtin_amdgcn_s_barrier()
; #define LDA(dst, b, h) for (int m = 0; m < 4; ++m) for (int k = 0; k < 2; ++k) \
;     dst[m][k] = *reinterpret_cast<const bf16x8*>((char*)SA(b, h) + lds_byte(wr * 64 + m * 16 + fr, k * 32 + fq * 8))
; #define LDB(dst, b, h) for (int n = 0; n < 2; ++n) for (int k = 0; k < 2; ++k) \
;     dst[n][k] = *reinterpret_cast<const bf16x8*>((char*)SB(b, h) + lds_byte(wc * 32 + n * 16 + fr, k * 32 + fq * 8))
; #define MMA(ai, bj, At_, Bt_) do { __builtin_amdgcn_s_setprio(1); \
;     for (int m = 0; m < 4; ++m) for (int n = 0; n < 2; ++n) for (int k = 0; k < 2; ++k) \
;       acc[ai][bj][m][n] = __builtin_amdgcn_mfma_f32_16x16x32_bf16(At_[m][k], Bt_[n][k], acc[ai][bj][m][n], 0, 0, 0); \
;     __builtin_amdgcn_s_setprio(0); } while (0)
; template <int K, int LD = K>
; __device__ __forceinline__ void gemm_main(const GAS bf16* A, const GAS bf16* Bt, int brow, int bcol, f32x4 (&acc)[2][2][4][2]) {
;     ...
;   { LDB(B0, 1, 0); LDA(At, 1, 0); WAIT_V(2); BAR; WAIT_L(0); MMA(0, 0, At, B0); BAR;
;     LDB(B1, 1, 1); WAIT_V(0); BAR; WAIT_L(0); MMA(0, 1, At, B1); BAR;
;     LDA(At, 1, 1); BAR; WAIT_L(0); MMA(1, 0, At, B0); MMA(1, 1, At, B1); BAR; }
;   if (wr == 0) BAR;
	s_nop 1
	ds_read_b128 v[2:5], v140
	ds_read_b128 v[6:9], v140 offset:1024
	ds_read_b128 v[194:197], v140 offset:2048
	ds_read_b128 v[140:143], v140 offset:3072
	ds_read_b128 v[18:21], v138 offset:32768
	ds_read_b128 v[22:25], v138 offset:33792
	ds_read_b128 v[34:37], v137 offset:32768
	ds_read_b128 v[38:41], v137 offset:33792
	ds_read_b128 v[50:53], v136 offset:32768
	ds_read_b128 v[54:57], v136 offset:33792
	ds_read_b128 v[198:201], v135 offset:32768
	ds_read_b128 v[226:229], v135 offset:33792
	s_waitcnt vmcnt(2)
	s_barrier
	s_waitcnt lgkmcnt(0)
	s_waitcnt lgkmcnt(0)
	v_mfma_f32_16x16x32_bf16 v[66:69], v[18:21], v[2:5], v[126:129]
	v_mfma_f32_16x16x32_bf16 v[114:117], v[22:25], v[6:9], v[66:69]
	v_mfma_f32_16x16x32_bf16 v[66:69], v[18:21], v[194:197], v[122:125]
	v_mfma_f32_16x16x32_bf16 v[118:121], v[22:25], v[140:143], v[66:69]
	v_mfma_f32_16x16x32_bf16 v[66:69], v[34:37], v[2:5], v[202:205]
	v_mfma_f32_16x16x32_bf16 v[102:105], v[38:41], v[6:9], v[66:69]
	v_mfma_f32_16x16x32_bf16 v[66:69], v[34:37], v[194:197], v[206:209]
	v_mfma_f32_16x16x32_bf16 v[98:101], v[38:41], v[140:143], v[66:69]
	v_mfma_f32_16x16x32_bf16 v[66:69], v[50:53], v[2:5], v[110:113]
	v_mfma_f32_16x16x32_bf16 v[82:85], v[54:57], v[6:9], v[66:69]
	v_mfma_f32_16x16x32_bf16 v[66:69], v[50:53], v[194:197], v[106:109]
	v_mfma_f32_16x16x32_bf16 v[86:89], v[54:57], v[140:143], v[66:69]
	v_mfma_f32_16x16x32_bf16 v[66:69], v[198:201], v[2:5], v[210:213]
	v_mfma_f32_16x16x32_bf16 v[70:73], v[226:229], v[6:9], v[66:69]
	v_mfma_f32_16x16x32_bf16 v[66:69], v[198:201], v[194:197], v[214:217]
	v_mfma_f32_16x16x32_bf16 v[66:69], v[226:229], v[140:143], v[66:69]
	s_barrier
	ds_read_b128 v[202:205], v139
	ds_read_b128 v[206:209], v139 offset:1024
	ds_read_b128 v[210:213], v139 offset:2048
	ds_read_b128 v[214:217], v139 offset:3072
	s_waitcnt vmcnt(0)
	s_barrier
	s_waitcnt lgkmcnt(0)
	s_waitcnt lgkmcnt(0)
	v_mfma_f32_16x16x32_bf16 v[94:97], v[18:21], v[202:205], v[94:97]
	v_mfma_f32_16x16x32_bf16 v[18:21], v[18:21], v[210:213], v[90:93]
	v_mfma_f32_16x16x32_bf16 v[126:129], v[22:25], v[214:217], v[18:21]
	v_mfma_f32_16x16x32_bf16 v[18:21], v[34:37], v[202:205], v[164:167]
	v_mfma_f32_16x16x32_bf16 v[106:109], v[38:41], v[206:209], v[18:21]
	v_mfma_f32_16x16x32_bf16 v[18:21], v[34:37], v[210:213], v[174:177]
	v_mfma_f32_16x16x32_bf16 v[110:113], v[38:41], v[214:217], v[18:21]
	v_mfma_f32_16x16x32_bf16 v[18:21], v[50:53], v[202:205], v[78:81]
	v_mfma_f32_16x16x32_bf16 v[90:93], v[54:57], v[206:209], v[18:21]
	v_mfma_f32_16x16x32_bf16 v[18:21], v[50:53], v[210:213], v[74:77]
	v_mfma_f32_16x16x32_bf16 v[122:125], v[22:25], v[206:209], v[94:97]
	v_mfma_f32_16x16x32_bf16 v[94:97], v[54:57], v[214:217], v[18:21]
	v_mfma_f32_16x16x32_bf16 v[18:21], v[198:201], v[202:205], v[178:181]
	v_mfma_f32_16x16x32_bf16 v[74:77], v[226:229], v[206:209], v[18:21]
	v_mfma_f32_16x16x32_bf16 v[18:21], v[198:201], v[210:213], v[182:185]
	v_mfma_f32_16x16x32_bf16 v[78:81], v[226:229], v[214:217], v[18:21]
	s_barrier
	ds_read_b128 v[162:165], v138 offset:49152
	ds_read_b128 v[166:169], v138 offset:50176
	ds_read_b128 v[174:177], v137 offset:49152
	ds_read_b128 v[178:181], v137 offset:50176
	ds_read_b128 v[182:185], v136 offset:49152
	ds_read_b128 v[136:139], v136 offset:50176
	ds_read_b128 v[198:201], v135 offset:49152
	ds_read_b128 v[226:229], v135 offset:50176
	s_barrier
	s_waitcnt lgkmcnt(0)
	s_waitcnt lgkmcnt(0)
	v_mfma_f32_16x16x32_bf16 v[18:21], v[162:165], v[2:5], v[62:65]
	v_mfma_f32_16x16x32_bf16 v[50:53], v[166:169], v[6:9], v[18:21]
	v_mfma_f32_16x16x32_bf16 v[18:21], v[162:165], v[194:197], v[58:61]
	v_mfma_f32_16x16x32_bf16 v[54:57], v[166:169], v[140:143], v[18:21]
	v_mfma_f32_16x16x32_bf16 v[18:21], v[174:177], v[2:5], v[218:221]
	v_mfma_f32_16x16x32_bf16 v[38:41], v[178:181], v[6:9], v[18:21]
	v_mfma_f32_16x16x32_bf16 v[18:21], v[174:177], v[194:197], v[222:225]
	v_mfma_f32_16x16x32_bf16 v[34:37], v[178:181], v[140:143], v[18:21]
	v_mfma_f32_16x16x32_bf16 v[18:21], v[182:185], v[2:5], v[46:49]
	v_mfma_f32_16x16x32_bf16 v[2:5], v[198:201], v[2:5], v[146:149]
	v_mfma_f32_16x16x32_bf16 v[18:21], v[136:139], v[6:9], v[18:21]
	v_mfma_f32_16x16x32_bf16 v[22:25], v[182:185], v[194:197], v[42:45]
	v_mfma_f32_16x16x32_bf16 v[6:9], v[226:229], v[6:9], v[2:5]
	v_mfma_f32_16x16x32_bf16 v[2:5], v[198:201], v[194:197], v[150:153]
	v_mfma_f32_16x16x32_bf16 v[22:25], v[136:139], v[140:143], v[22:25]
	v_mfma_f32_16x16x32_bf16 v[2:5], v[226:229], v[140:143], v[2:5]
	v_mfma_f32_16x16x32_bf16 v[26:29], v[162:165], v[210:213], v[26:29]
	v_mfma_f32_16x16x32_bf16 v[62:65], v[166:169], v[214:217], v[26:29]
	v_mfma_f32_16x16x32_bf16 v[26:29], v[174:177], v[202:205], v[154:157]
	v_mfma_f32_16x16x32_bf16 v[30:33], v[162:165], v[202:205], v[30:33]
	v_mfma_f32_16x16x32_bf16 v[42:45], v[178:181], v[206:209], v[26:29]
	v_mfma_f32_16x16x32_bf16 v[26:29], v[174:177], v[210:213], v[158:161]
	v_mfma_f32_16x16x32_bf16 v[14:17], v[182:185], v[202:205], v[14:17]
	v_mfma_f32_16x16x32_bf16 v[10:13], v[182:185], v[210:213], v[10:13]
	v_mfma_f32_16x16x32_bf16 v[58:61], v[166:169], v[206:209], v[30:33]
	v_mfma_f32_16x16x32_bf16 v[46:49], v[178:181], v[214:217], v[26:29]
	v_mfma_f32_16x16x32_bf16 v[26:29], v[136:139], v[206:209], v[14:17]
	v_mfma_f32_16x16x32_bf16 v[30:33], v[136:139], v[214:217], v[10:13]
	v_mfma_f32_16x16x32_bf16 v[10:13], v[198:201], v[202:205], v[186:189]
	v_mfma_f32_16x16x32_bf16 v[14:17], v[198:201], v[210:213], v[190:193]
	v_mfma_f32_16x16x32_bf16 v[10:13], v[226:229], v[206:209], v[10:13]
	v_mfma_f32_16x16x32_bf16 v[14:17], v[226:229], v[214:217], v[14:17]
	v_cmp_gt_u32_e32 vcc, s48, v134
	s_barrier
	s_and_saveexec_b64 s[26:27], vcc
	s_cbranch_execz .LBB0_349
	s_barrier

; #define GAS __attribute__((address_space(1)))
; __device__ __forceinline__ int otid() { int t = threadIdx.x; asm volatile("" : "+v"(t)); return t; }
; #define STAGE(P, GP, ktrel) do { const GAS char* _g = (GP) + (ktrel) * (BK * 2); \
;     __builtin_amdgcn_global_load_lds((const GAS unsigned*)(_g + so0), (unsigned*)((char*)(P) + tid_ * 16), 16, 0, 0); \
;     __builtin_amdgcn_global_load_lds((const GAS unsigned*)(_g + so1), (unsigned*)((char*)(P) + tid_ * 16 + 8192), 16, 0, 0); } while (0)
; #define WAIT_V(n) asm volatile("s_waitcnt vmcnt(" #n ")" ::: "memory")
; #define WAIT_L(n) asm volatile("s_waitcnt lgkmcnt(" #n ")" ::: "memory")
; #define BAR __builtin_amdgcn_s_barrier()
; #define SCHED __builtin_amdgcn_sched_barrier(0)
; #define LDA(dst, b, h) for (int m = 0; m < 4; ++m) for (int k = 0; k < 2; ++k) \
;     dst[m][k] = *reinterpret_cast<const bf16x8*>((char*)SA(b, h) + lds_byte(wr * 64 + m * 16 + fr, k * 32 + fq * 8))
; template <int K, int LD = K>
; __device__ __forceinline__ void gemm_main(const GAS bf16* A, const GAS bf16* Bt, int brow, int bcol, f32x4 (&acc)[2][2][4][2]) {
;     ...
;   const int tid_ = otid();
;     ...
;   const int wid = tid_ >> 6, lane = tid_ & 63, wr = wid >> 2, wc = wid & 3, fr = lane & 15, fq = lane >> 4;
; #pragma unroll
;   for (int a = 0; a < 2; ++a)
; #pragma unroll
;     for (int b = 0; b < 2; ++b)
; #pragma unroll
;       for (int m = 0; m < 4; ++m)
; #pragma unroll
;         for (int n = 0; n < 2; ++n) acc[a][b][m][n] = f32x4{0.f, 0.f, 0.f, 0.f};
;   bf16x8 At[4][2], B0[2][2], B1[2][2];
;   unsigned so0, so1;
;   { int r_, c_; stage_rc(tid_ * 16, r_, c_); so0 = (unsigned)(r_ * LD + c_) * 2u; stage_rc(tid_ * 16 + 8192, r_, c_); so1 = (unsigned)(r_ * LD + c_) * 2u; }
;   const GAS char* pA0 = (const GAS char*)A + (long)brow * LD * 2; const GAS char* pA1 = pA0 + (long)HALF * LD * 2;
;   const GAS char* pB0 = (const GAS char*)Bt + (long)bcol * LD * 2; const GAS char* pB1 = pB0 + (long)HALF * LD * 2;
;   asm volatile("" : "+s"(pA0), "+s"(pA1), "+s"(pB0), "+s"(pB1));
;   constexpr int nt = K / BK;
;   static_assert(K % 128 == 0 && K >= 256, "K");
;   if (wr == 1) BAR;
;   WAIT_V(0); BAR;
;   BAR;
;   for (int t = 0; t < nt - 2; t += 2) {
;     LDB(B0, 0, 0); SCHED; LDA(At, 0, 0); STAGE(SA(1, 1), pA1, 1);
;     WAIT_L(8); BAR; WAIT_L(0); MMA(0, 0, At, B0); BAR; SCHED;
;     LDB(B1, 0, 1); STAGE(SB(0, 0), pB0, 2);
.LBB0_708:
	s_or_b64 exec, exec, s[30:31]
	v_bfe_i32 v6, v134, 27, 1
	v_lshlrev_b32_e32 v141, 4, v134
	v_lshrrev_b32_e32 v6, 22, v6
	v_add_u32_e32 v6, v141, v6
	v_and_b32_e32 v6, 0xfffffc00, v6
	v_sub_u32_e32 v6, v141, v6
	v_lshrrev_b32_e32 v7, 4, v6
	v_bitop3_b32 v7, v7, v6, 32 bitop3:0x6c
	v_ashrrev_i32_e32 v6, 31, v6
	v_ashrrev_i32_e32 v5, 31, v134
	v_lshrrev_b32_e32 v6, 26, v6
	v_lshrrev_b32_e32 v5, 26, v5
	v_add_u32_e32 v6, v7, v6
	v_add_u32_e32 v5, v134, v5
	v_ashrrev_i32_e32 v6, 6, v6
	v_ashrrev_i32_e32 v5, 6, v5
	v_mul_i32_i24_e32 v9, 64, v6
	v_lshlrev_b32_e32 v8, 3, v5
	v_lshlrev_b32_e32 v5, 5, v5
	v_sub_u32_e32 v7, v7, v9
	v_and_b32_e32 v8, 0x3ffff0, v8
	v_and_b32_e32 v5, 32, v5
	v_ashrrev_i16_sdwa v7, v1, sext(v7) dst_sel:DWORD dst_unused:UNUSED_PAD src0_sel:DWORD src1_sel:BYTE_0
	v_add_u32_sdwa v5, v5, sext(v7) dst_sel:DWORD dst_unused:UNUSED_PAD src0_sel:DWORD src1_sel:WORD_0
	v_add_lshl_u32 v6, v6, v8, 10
	v_lshl_add_u32 v130, v5, 1, v6
	v_add_u32_e32 v5, 0x2000, v141
	v_ashrrev_i32_e32 v6, 31, v5
	v_lshrrev_b32_e32 v6, 22, v6
	v_add_u32_e32 v6, v5, v6
	v_ashrrev_i32_e32 v6, 10, v6
	v_mul_i32_i24_e32 v7, 0x400, v6
	v_sub_u32_e32 v5, v5, v7
	v_lshrrev_b32_e32 v7, 4, v5
	v_bitop3_b32 v5, v7, v5, 32 bitop3:0x6c
	v_ashrrev_i32_e32 v8, 31, v5
	v_lshrrev_b32_e32 v8, 26, v8
	v_add_u32_e32 v8, v5, v8
	v_lshrrev_b32_e32 v9, 6, v8
	v_and_b32_e32 v8, 0xc0, v8
	v_lshlrev_b32_e32 v7, 3, v6
	v_lshlrev_b32_e32 v6, 5, v6
	v_sub_u32_e32 v5, v5, v8
	v_and_b32_e32 v7, 0x3ffff0, v7
	v_and_b32_e32 v6, 32, v6
	v_ashrrev_i16_sdwa v5, v1, sext(v5) dst_sel:DWORD dst_unused:UNUSED_PAD src0_sel:DWORD src1_sel:BYTE_0
	v_add_u32_sdwa v5, v6, sext(v5) dst_sel:DWORD dst_unused:UNUSED_PAD src0_sel:DWORD src1_sel:WORD_0
	v_add_lshl_u32 v6, v9, v7, 10
	v_and_b32_e32 v3, 15, v134
	v_lshl_add_u32 v132, v5, 1, v6
	v_lshlrev_b32_e32 v5, 2, v134
	v_and_b32_e32 v4, 48, v134
	v_lshlrev_b32_e32 v3, 6, v3
	v_and_b32_e32 v5, 32, v5
	v_lshlrev_b32_e32 v10, 6, v134
	v_bitop3_b32 v3, v3, v5, v4 bitop3:0x36
	v_lshlrev_b32_e32 v12, 13, v2
	v_and_or_b32 v2, v10, s54, v4
	v_add_u32_e32 v6, s47, v3
	v_add_u32_e32 v7, s48, v3
	v_add_u32_e32 v8, s49, v3
	v_add_u32_e32 v9, s50, v3
	v_and_b32_e32 v11, 0x3000, v10
	v_add_u32_e32 v3, 0x100, v3
	v_xad_u32 v4, v2, v5, s51
	v_or_b32_e32 v5, 0x800, v12
	v_or_b32_e32 v10, 0x1000, v12
	v_or_b32_e32 v13, 0x1800, v12
	v_mov_b32_e32 v2, 0
	v_mov_b32_e32 v133, v131
	s_mov_b32 s17, -2
	v_add_u32_e32 v143, v6, v11
	v_add_u32_e32 v138, v3, v12
	v_add_u32_e32 v137, v4, v5
	v_add_u32_e32 v136, v4, v10
	v_add_u32_e32 v135, v4, v13
	v_add_u32_e32 v142, v7, v11
	v_add_u32_e32 v140, v8, v11
	v_add_u32_e32 v139, v9, v11
	s_waitcnt vmcnt(0)
	s_barrier
	s_barrier
	ds_read_b128 v[146:149], v143
	ds_read_b128 v[150:153], v143 offset:1024
	ds_read_b128 v[154:157], v143 offset:2048
	ds_read_b128 v[158:161], v143 offset:3072
	v_add_u32_e32 v230, 0x100, v141
	v_add_u32_e32 v144, 0xc000, v230
	v_lshl_add_u64 v[214:215], s[20:21], 0, v[130:131]
	v_readfirstlane_b32 s30, v144
	v_add_u32_e32 v145, 0xe000, v230
	v_lshl_add_u64 v[198:199], v[214:215], 0, s[6:7]
	s_mov_b32 m0, s30
	v_lshl_add_u64 v[216:217], s[20:21], 0, v[132:133]
	v_readfirstlane_b32 s30, v145
	ds_read_b128 v[162:165], v138
	ds_read_b128 v[166:169], v138 offset:1024
	ds_read_b128 v[174:177], v137
	ds_read_b128 v[178:181], v137 offset:1024
	ds_read_b128 v[182:185], v136
	ds_read_b128 v[186:189], v136 offset:1024
	ds_read_b128 v[190:193], v135
	ds_read_b128 v[194:197], v135 offset:1024
	global_load_lds_dwordx4 v[198:199], off
	v_lshl_add_u64 v[198:199], v[216:217], 0, s[6:7]
	s_mov_b32 m0, s30
	s_nop 0
	global_load_lds_dwordx4 v[198:199], off
	s_waitcnt lgkmcnt(8)
	s_waitcnt vmcnt(10)
	s_barrier
	s_waitcnt lgkmcnt(0)
	s_waitcnt lgkmcnt(0)
	v_mfma_f32_16x16x32_bf16 v[126:129], v[162:165], v[146:149], 0
	v_mfma_f32_16x16x32_bf16 v[122:125], v[162:165], v[154:157], 0
	v_mfma_f32_16x16x32_bf16 v[118:121], v[174:177], v[146:149], 0
	v_mfma_f32_16x16x32_bf16 v[114:117], v[174:177], v[154:157], 0
	v_mfma_f32_16x16x32_bf16 v[110:113], v[182:185], v[146:149], 0
	v_mfma_f32_16x16x32_bf16 v[106:109], v[182:185], v[154:157], 0
	v_mfma_f32_16x16x32_bf16 v[102:105], v[190:193], v[146:149], 0
	v_mfma_f32_16x16x32_bf16 v[98:101], v[190:193], v[154:157], 0
	v_mfma_f32_16x16x32_bf16 v[126:129], v[166:169], v[150:153], v[126:129]
	v_mfma_f32_16x16x32_bf16 v[122:125], v[166:169], v[158:161], v[122:125]
	v_mfma_f32_16x16x32_bf16 v[118:121], v[178:181], v[150:153], v[118:121]
	v_mfma_f32_16x16x32_bf16 v[114:117], v[178:181], v[158:161], v[114:117]
	v_mfma_f32_16x16x32_bf16 v[110:113], v[186:189], v[150:153], v[110:113]
	v_mfma_f32_16x16x32_bf16 v[106:109], v[186:189], v[158:161], v[106:109]
	v_mfma_f32_16x16x32_bf16 v[102:105], v[194:197], v[150:153], v[102:105]
	v_mfma_f32_16x16x32_bf16 v[98:101], v[194:197], v[158:161], v[98:101]
	s_barrier
	v_add_u32_e32 v224, s47, v141
	v_lshl_add_u64 v[218:219], s[28:29], 0, v[130:131]
	v_readfirstlane_b32 s30, v224
	v_lshl_add_u64 v[220:221], v[218:219], 0, s[10:11]
	s_mov_b32 m0, s30
	v_add_u32_e32 v224, 0x2000, v224
	ds_read_b128 v[198:201], v142
	ds_read_b128 v[202:205], v142 offset:1024
	ds_read_b128 v[206:209], v142 offset:2048
	ds_read_b128 v[210:213], v142 offset:3072
	global_load_lds_dwordx4 v[220:221], off
	v_lshl_add_u64 v[220:221], s[28:29], 0, v[132:133]
	v_readfirstlane_b32 s30, v224
	v_lshl_add_u64 v[222:223], v[220:221], 0, s[10:11]
	s_mov_b32 m0, s30
	s_add_u32 s28, s28, 0x100
	global_load_lds_dwordx4 v[222:223], off
	s_waitcnt vmcnt(10)
	s_barrier
; #define STAGE(P, GP, ktrel) do { const GAS char* _g = (GP) + (ktrel) * (BK * 2); \
;     __builtin_amdgcn_global_load_lds((const GAS unsigned*)(_g + so0), (unsigned*)((char*)(P) + tid_ * 16), 16, 0, 0); \
;     __builtin_amdgcn_global_load_lds((const GAS unsigned*)(_g + so1), (unsigned*)((char*)(P) + tid_ * 16 + 8192), 16, 0, 0); } while (0)
; #define WAIT_V(n) asm volatile("s_waitcnt vmcnt(" #n ")" ::: "memory")
; #define WAIT_L(n) asm volatile("s_waitcnt lgkmcnt(" #n ")" ::: "memory")
; #define BAR __builtin_amdgcn_s_barrier()
; #define SCHED __builtin_amdgcn_sched_barrier(0)
; #define LDA(dst, b, h) for (int m = 0; m < 4; ++m) for (int k = 0; k < 2; ++k) \
;     dst[m][k] = *reinterpret_cast<const bf16x8*>((char*)SA(b, h) + lds_byte(wr * 64 + m * 16 + fr, k * 32 + fq * 8))
; #define LDB(dst, b, h) for (int n = 0; n < 2; ++n) for (int k = 0; k < 2; ++k) \
;     dst[n][k] = *reinterpret_cast<const bf16x8*>((char*)SB(b, h) + lds_byte(wc * 32 + n * 16 + fr, k * 32 + fq * 8))
; #define MMA(ai, bj, At_, Bt_) do { __builtin_amdgcn_s_setprio(1); \
;     for (int m = 0; m < 4; ++m) for (int n = 0; n < 2; ++n) for (int k = 0; k < 2; ++k) \
;       acc[ai][bj][m][n] = __builtin_amdgcn_mfma_f32_16x16x32_bf16(At_[m][k], Bt_[n][k], acc[ai][bj][m][n], 0, 0, 0); \
;     __builtin_amdgcn_s_setprio(0); } while (0)
; template <int K, int LD = K>
; __device__ __forceinline__ void gemm_main(const GAS bf16* A, const GAS bf16* Bt, int brow, int bcol, f32x4 (&acc)[2][2][4][2]) {
;     ...
;     BAR; WAIT_L(0); MMA(0, 1, At, B1); BAR;
;     LDA(At, 0, 1); STAGE(SA(0, 0), pA0, 2);
;     BAR; WAIT_L(0); MMA(1, 0, At, B0); BAR; SCHED;
;     STAGE(SB(0, 1), pB1, 2);
;     WAIT_V(6); BAR; MMA(1, 1, At, B1); BAR;
;     LDB(B0, 1, 0); SCHED; LDA(At, 1, 0); STAGE(SA(0, 1), pA1, 2);
;     WAIT_L(8); BAR; WAIT_L(0); MMA(0, 0, At, B0); BAR; SCHED;
	s_waitcnt lgkmcnt(0)
	s_addc_u32 s29, s29, 0
	s_waitcnt lgkmcnt(0)
	v_mfma_f32_16x16x32_bf16 v[94:97], v[162:165], v[198:201], 0
	v_mfma_f32_16x16x32_bf16 v[90:93], v[162:165], v[206:209], 0
	v_mfma_f32_16x16x32_bf16 v[86:89], v[174:177], v[198:201], 0
	v_mfma_f32_16x16x32_bf16 v[82:85], v[174:177], v[206:209], 0
	v_mfma_f32_16x16x32_bf16 v[78:81], v[182:185], v[198:201], 0
	v_mfma_f32_16x16x32_bf16 v[74:77], v[182:185], v[206:209], 0
	v_mfma_f32_16x16x32_bf16 v[70:73], v[190:193], v[198:201], 0
	v_mfma_f32_16x16x32_bf16 v[66:69], v[190:193], v[206:209], 0
	v_mfma_f32_16x16x32_bf16 v[94:97], v[166:169], v[202:205], v[94:97]
	v_mfma_f32_16x16x32_bf16 v[90:93], v[166:169], v[210:213], v[90:93]
	v_mfma_f32_16x16x32_bf16 v[86:89], v[178:181], v[202:205], v[86:89]
	v_mfma_f32_16x16x32_bf16 v[82:85], v[178:181], v[210:213], v[82:85]
	v_mfma_f32_16x16x32_bf16 v[78:81], v[186:189], v[202:205], v[78:81]
	v_mfma_f32_16x16x32_bf16 v[74:77], v[186:189], v[210:213], v[74:77]
	v_mfma_f32_16x16x32_bf16 v[70:73], v[194:197], v[202:205], v[70:73]
	v_mfma_f32_16x16x32_bf16 v[66:69], v[194:197], v[210:213], v[66:69]
	v_lshl_add_u64 v[222:223], s[26:27], 0, v[130:131]
	v_readfirstlane_b32 s30, v230
	v_lshl_add_u64 v[224:225], v[222:223], 0, s[10:11]
	s_mov_b32 m0, s30
	v_add_u32_e32 v228, 0x2000, v230
	s_barrier
	ds_read_b128 v[162:165], v138 offset:16384
	ds_read_b128 v[166:169], v138 offset:17408
	ds_read_b128 v[174:177], v137 offset:16384
	ds_read_b128 v[178:181], v137 offset:17408
	ds_read_b128 v[182:185], v136 offset:16384
	ds_read_b128 v[186:189], v136 offset:17408
	ds_read_b128 v[190:193], v135 offset:16384
	ds_read_b128 v[194:197], v135 offset:17408
	global_load_lds_dwordx4 v[224:225], off
	v_lshl_add_u64 v[224:225], s[26:27], 0, v[132:133]
	v_readfirstlane_b32 s30, v228
	v_lshl_add_u64 v[226:227], v[224:225], 0, s[10:11]
	s_mov_b32 m0, s30
	s_add_u32 s26, s26, 0x100
	global_load_lds_dwordx4 v[226:227], off
	s_barrier
	s_waitcnt lgkmcnt(0)
	s_addc_u32 s27, s27, 0
	s_waitcnt lgkmcnt(0)
	v_mfma_f32_16x16x32_bf16 v[62:65], v[162:165], v[146:149], 0
	v_mfma_f32_16x16x32_bf16 v[58:61], v[162:165], v[154:157], 0
	v_mfma_f32_16x16x32_bf16 v[54:57], v[174:177], v[146:149], 0
	v_mfma_f32_16x16x32_bf16 v[50:53], v[174:177], v[154:157], 0
	v_mfma_f32_16x16x32_bf16 v[46:49], v[182:185], v[146:149], 0
	v_mfma_f32_16x16x32_bf16 v[42:45], v[182:185], v[154:157], 0
	v_mfma_f32_16x16x32_bf16 v[38:41], v[190:193], v[146:149], 0
	v_mfma_f32_16x16x32_bf16 v[34:37], v[190:193], v[154:157], 0
	v_mfma_f32_16x16x32_bf16 v[62:65], v[166:169], v[150:153], v[62:65]
	v_mfma_f32_16x16x32_bf16 v[58:61], v[166:169], v[158:161], v[58:61]
	v_mfma_f32_16x16x32_bf16 v[54:57], v[178:181], v[150:153], v[54:57]
	v_mfma_f32_16x16x32_bf16 v[50:53], v[178:181], v[158:161], v[50:53]
	v_mfma_f32_16x16x32_bf16 v[46:49], v[186:189], v[150:153], v[46:49]
	v_mfma_f32_16x16x32_bf16 v[42:45], v[186:189], v[158:161], v[42:45]
	v_mfma_f32_16x16x32_bf16 v[38:41], v[194:197], v[150:153], v[38:41]
	v_mfma_f32_16x16x32_bf16 v[34:37], v[194:197], v[158:161], v[34:37]
	s_barrier
	v_add_u32_e32 v148, s48, v141
	v_lshl_add_u64 v[226:227], s[24:25], 0, v[130:131]
	v_readfirstlane_b32 s30, v148
	v_add_u32_e32 v148, 0x2000, v148
	v_lshl_add_u64 v[146:147], v[226:227], 0, s[10:11]
	s_mov_b32 m0, s30
	v_lshl_add_u64 v[228:229], s[24:25], 0, v[132:133]
	v_readfirstlane_b32 s30, v148
	global_load_lds_dwordx4 v[146:147], off
	v_lshl_add_u64 v[146:147], v[228:229], 0, s[10:11]
	s_mov_b32 m0, s30
	s_add_u32 s24, s24, 0x100
	global_load_lds_dwordx4 v[146:147], off
	s_waitcnt vmcnt(10)
	s_addc_u32 s25, s25, 0
	s_barrier
	v_mfma_f32_16x16x32_bf16 v[30:33], v[162:165], v[198:201], 0
	v_mfma_f32_16x16x32_bf16 v[26:29], v[162:165], v[206:209], 0
	v_mfma_f32_16x16x32_bf16 v[22:25], v[174:177], v[198:201], 0
	v_mfma_f32_16x16x32_bf16 v[18:21], v[174:177], v[206:209], 0
	v_mfma_f32_16x16x32_bf16 v[14:17], v[182:185], v[198:201], 0
	v_mfma_f32_16x16x32_bf16 v[10:13], v[182:185], v[206:209], 0
	v_mfma_f32_16x16x32_bf16 v[6:9], v[190:193], v[198:201], 0
	v_mfma_f32_16x16x32_bf16 v[2:5], v[190:193], v[206:209], 0
	v_mfma_f32_16x16x32_bf16 v[30:33], v[166:169], v[202:205], v[30:33]
	v_mfma_f32_16x16x32_bf16 v[26:29], v[166:169], v[210:213], v[26:29]
	v_mfma_f32_16x16x32_bf16 v[22:25], v[178:181], v[202:205], v[22:25]
	v_mfma_f32_16x16x32_bf16 v[18:21], v[178:181], v[210:213], v[18:21]
	v_mfma_f32_16x16x32_bf16 v[14:17], v[186:189], v[202:205], v[14:17]
	v_mfma_f32_16x16x32_bf16 v[10:13], v[186:189], v[210:213], v[10:13]
	v_mfma_f32_16x16x32_bf16 v[6:9], v[194:197], v[202:205], v[6:9]
	v_mfma_f32_16x16x32_bf16 v[2:5], v[194:197], v[210:213], v[2:5]
	s_barrier
	ds_read_b128 v[146:149], v140
	ds_read_b128 v[150:153], v140 offset:1024
	ds_read_b128 v[154:157], v140 offset:2048
	ds_read_b128 v[158:161], v140 offset:3072
	v_add_u32_e32 v200, 0x4000, v230
	v_lshl_add_u64 v[198:199], v[214:215], 0, s[10:11]
	v_readfirstlane_b32 s30, v200
	v_add_u32_e32 v200, 0x6000, v230
	s_mov_b32 m0, s30
	v_readfirstlane_b32 s30, v200
	ds_read_b128 v[162:165], v138 offset:32768
	ds_read_b128 v[166:169], v138 offset:33792
	ds_read_b128 v[174:177], v137 offset:32768
	ds_read_b128 v[178:181], v137 offset:33792
	ds_read_b128 v[182:185], v136 offset:32768
	ds_read_b128 v[186:189], v136 offset:33792
	ds_read_b128 v[190:193], v135 offset:32768
	ds_read_b128 v[194:197], v135 offset:33792
	global_load_lds_dwordx4 v[198:199], off
	v_lshl_add_u64 v[198:199], v[216:217], 0, s[10:11]
	s_mov_b32 m0, s30
	s_add_u32 s20, s20, 0x100
	global_load_lds_dwordx4 v[198:199], off
	s_waitcnt lgkmcnt(8)
	s_waitcnt vmcnt(10)
	s_barrier
; #define STAGE(P, GP, ktrel) do { const GAS char* _g = (GP) + (ktrel) * (BK * 2); \
;     __builtin_amdgcn_global_load_lds((const GAS unsigned*)(_g + so0), (unsigned*)((char*)(P) + tid_ * 16), 16, 0, 0); \
;     __builtin_amdgcn_global_load_lds((const GAS unsigned*)(_g + so1), (unsigned*)((char*)(P) + tid_ * 16 + 8192), 16, 0, 0); } while (0)
; #define WAIT_V(n) asm volatile("s_waitcnt vmcnt(" #n ")" ::: "memory")
; #define WAIT_L(n) asm volatile("s_waitcnt lgkmcnt(" #n ")" ::: "memory")
; #define BAR __builtin_amdgcn_s_barrier()
; #define SCHED __builtin_amdgcn_sched_barrier(0)
; #define LDA(dst, b, h) for (int m = 0; m < 4; ++m) for (int k = 0; k < 2; ++k) \
;     dst[m][k] = *reinterpret_cast<const bf16x8*>((char*)SA(b, h) + lds_byte(wr * 64 + m * 16 + fr, k * 32 + fq * 8))
; #define LDB(dst, b, h) for (int n = 0; n < 2; ++n) for (int k = 0; k < 2; ++k) \
;     dst[n][k] = *reinterpret_cast<const bf16x8*>((char*)SB(b, h) + lds_byte(wc * 32 + n * 16 + fr, k * 32 + fq * 8))
; #define MMA(ai, bj, At_, Bt_) do { __builtin_amdgcn_s_setprio(1); \
;     for (int m = 0; m < 4; ++m) for (int n = 0; n < 2; ++n) for (int k = 0; k < 2; ++k) \
;       acc[ai][bj][m][n] = __builtin_amdgcn_mfma_f32_16x16x32_bf16(At_[m][k], Bt_[n][k], acc[ai][bj][m][n], 0, 0, 0); \
;     __builtin_amdgcn_s_setprio(0); } while (0)
; template <int K, int LD = K>
; __device__ __forceinline__ void gemm_main(const GAS bf16* A, const GAS bf16* Bt, int brow, int bcol, f32x4 (&acc)[2][2][4][2]) {
;     ...
;     WAIT_L(8); BAR; WAIT_L(0); MMA(0, 0, At, B0); BAR; SCHED;
;     LDB(B1, 1, 1); STAGE(SB(1, 0), pB0, 3);
;     BAR; WAIT_L(0); MMA(0, 1, At, B1); BAR;
;     LDA(At, 1, 1); STAGE(SA(1, 0), pA0, 3);
;     BAR; WAIT_L(0); MMA(1, 0, At, B0); BAR; SCHED;
;     STAGE(SB(1, 1), pB1, 3);
;     WAIT_V(6); BAR; MMA(1, 1, At, B1); BAR;
;     pA0 += 4 * BK; pA1 += 4 * BK; pB0 += 4 * BK; pB1 += 4 * BK;
;     asm volatile("" : "+s"(pA0), "+s"(pA1), "+s"(pB0), "+s"(pB1));
	s_waitcnt lgkmcnt(0)
	s_addc_u32 s21, s21, 0
	s_waitcnt lgkmcnt(0)
	v_mfma_f32_16x16x32_bf16 v[126:129], v[162:165], v[146:149], v[126:129]
	v_mfma_f32_16x16x32_bf16 v[122:125], v[162:165], v[154:157], v[122:125]
	v_mfma_f32_16x16x32_bf16 v[118:121], v[174:177], v[146:149], v[118:121]
	v_mfma_f32_16x16x32_bf16 v[114:117], v[174:177], v[154:157], v[114:117]
	v_mfma_f32_16x16x32_bf16 v[110:113], v[182:185], v[146:149], v[110:113]
	v_mfma_f32_16x16x32_bf16 v[106:109], v[182:185], v[154:157], v[106:109]
	v_mfma_f32_16x16x32_bf16 v[102:105], v[190:193], v[146:149], v[102:105]
	v_mfma_f32_16x16x32_bf16 v[98:101], v[190:193], v[154:157], v[98:101]
	v_mfma_f32_16x16x32_bf16 v[126:129], v[166:169], v[150:153], v[126:129]
	v_mfma_f32_16x16x32_bf16 v[122:125], v[166:169], v[158:161], v[122:125]
	v_mfma_f32_16x16x32_bf16 v[118:121], v[178:181], v[150:153], v[118:121]
	v_mfma_f32_16x16x32_bf16 v[114:117], v[178:181], v[158:161], v[114:117]
	v_mfma_f32_16x16x32_bf16 v[110:113], v[186:189], v[150:153], v[110:113]
	v_mfma_f32_16x16x32_bf16 v[106:109], v[186:189], v[158:161], v[106:109]
	v_mfma_f32_16x16x32_bf16 v[102:105], v[194:197], v[150:153], v[102:105]
	v_mfma_f32_16x16x32_bf16 v[98:101], v[194:197], v[158:161], v[98:101]
	s_barrier
	v_add_u32_e32 v216, s49, v141
	v_lshl_add_u64 v[214:215], v[218:219], 0, s[12:13]
	v_readfirstlane_b32 s30, v216
	v_add_u32_e32 v216, 0x2000, v216
	s_mov_b32 m0, s30
	v_readfirstlane_b32 s30, v216
	ds_read_b128 v[198:201], v139
	ds_read_b128 v[202:205], v139 offset:1024
	ds_read_b128 v[206:209], v139 offset:2048
	ds_read_b128 v[210:213], v139 offset:3072
	global_load_lds_dwordx4 v[214:215], off
	v_lshl_add_u64 v[214:215], v[220:221], 0, s[12:13]
	s_mov_b32 m0, s30
	s_nop 0
	global_load_lds_dwordx4 v[214:215], off
	s_waitcnt vmcnt(10)
	s_barrier
	s_waitcnt lgkmcnt(0)
	s_waitcnt lgkmcnt(0)
	v_mfma_f32_16x16x32_bf16 v[94:97], v[162:165], v[198:201], v[94:97]
	v_mfma_f32_16x16x32_bf16 v[90:93], v[162:165], v[206:209], v[90:93]
	v_mfma_f32_16x16x32_bf16 v[86:89], v[174:177], v[198:201], v[86:89]
	v_mfma_f32_16x16x32_bf16 v[82:85], v[174:177], v[206:209], v[82:85]
	v_mfma_f32_16x16x32_bf16 v[78:81], v[182:185], v[198:201], v[78:81]
	v_mfma_f32_16x16x32_bf16 v[74:77], v[182:185], v[206:209], v[74:77]
	v_mfma_f32_16x16x32_bf16 v[70:73], v[190:193], v[198:201], v[70:73]
	v_mfma_f32_16x16x32_bf16 v[66:69], v[190:193], v[206:209], v[66:69]
	v_mfma_f32_16x16x32_bf16 v[94:97], v[166:169], v[202:205], v[94:97]
	v_mfma_f32_16x16x32_bf16 v[90:93], v[166:169], v[210:213], v[90:93]
	v_mfma_f32_16x16x32_bf16 v[86:89], v[178:181], v[202:205], v[86:89]
	v_mfma_f32_16x16x32_bf16 v[82:85], v[178:181], v[210:213], v[82:85]
	v_mfma_f32_16x16x32_bf16 v[78:81], v[186:189], v[202:205], v[78:81]
	v_mfma_f32_16x16x32_bf16 v[74:77], v[186:189], v[210:213], v[74:77]
	v_mfma_f32_16x16x32_bf16 v[70:73], v[194:197], v[202:205], v[70:73]
	v_mfma_f32_16x16x32_bf16 v[66:69], v[194:197], v[210:213], v[66:69]
	v_add_u32_e32 v216, 0x8000, v230
	v_lshl_add_u64 v[214:215], v[222:223], 0, s[12:13]
	v_readfirstlane_b32 s30, v216
	v_add_u32_e32 v216, 0xa000, v230
	s_mov_b32 m0, s30
	v_readfirstlane_b32 s30, v216
	s_barrier
	ds_read_b128 v[162:165], v138 offset:49152
	ds_read_b128 v[166:169], v138 offset:50176
	ds_read_b128 v[174:177], v137 offset:49152
	ds_read_b128 v[178:181], v137 offset:50176
	ds_read_b128 v[182:185], v136 offset:49152
	ds_read_b128 v[186:189], v136 offset:50176
	ds_read_b128 v[190:193], v135 offset:49152
	ds_read_b128 v[194:197], v135 offset:50176
	global_load_lds_dwordx4 v[214:215], off
	v_lshl_add_u64 v[214:215], v[224:225], 0, s[12:13]
	s_mov_b32 m0, s30
	s_nop 0
	global_load_lds_dwordx4 v[214:215], off
	s_barrier
	s_waitcnt lgkmcnt(0)
	s_waitcnt lgkmcnt(0)
	v_mfma_f32_16x16x32_bf16 v[62:65], v[162:165], v[146:149], v[62:65]
	v_mfma_f32_16x16x32_bf16 v[58:61], v[162:165], v[154:157], v[58:61]
	v_mfma_f32_16x16x32_bf16 v[54:57], v[174:177], v[146:149], v[54:57]
	v_mfma_f32_16x16x32_bf16 v[50:53], v[174:177], v[154:157], v[50:53]
	v_mfma_f32_16x16x32_bf16 v[46:49], v[182:185], v[146:149], v[46:49]
	v_mfma_f32_16x16x32_bf16 v[42:45], v[182:185], v[154:157], v[42:45]
	v_mfma_f32_16x16x32_bf16 v[38:41], v[190:193], v[146:149], v[38:41]
	v_mfma_f32_16x16x32_bf16 v[34:37], v[190:193], v[154:157], v[34:37]
	v_mfma_f32_16x16x32_bf16 v[62:65], v[166:169], v[150:153], v[62:65]
	v_mfma_f32_16x16x32_bf16 v[58:61], v[166:169], v[158:161], v[58:61]
	v_mfma_f32_16x16x32_bf16 v[54:57], v[178:181], v[150:153], v[54:57]
	v_mfma_f32_16x16x32_bf16 v[50:53], v[178:181], v[158:161], v[50:53]
	v_mfma_f32_16x16x32_bf16 v[46:49], v[186:189], v[150:153], v[46:49]
	v_mfma_f32_16x16x32_bf16 v[42:45], v[186:189], v[158:161], v[42:45]
	v_mfma_f32_16x16x32_bf16 v[38:41], v[194:197], v[150:153], v[38:41]
	v_mfma_f32_16x16x32_bf16 v[34:37], v[194:197], v[158:161], v[34:37]
	s_barrier
	v_add_u32_e32 v148, s50, v141
	v_lshl_add_u64 v[146:147], v[226:227], 0, s[12:13]
	v_readfirstlane_b32 s30, v148
	v_add_u32_e32 v148, 0x2000, v148
	s_mov_b32 m0, s30
	v_readfirstlane_b32 s30, v148
	global_load_lds_dwordx4 v[146:147], off
	v_lshl_add_u64 v[146:147], v[228:229], 0, s[12:13]
	s_mov_b32 m0, s30
	s_nop 0
	global_load_lds_dwordx4 v[146:147], off
	s_waitcnt vmcnt(10)
	s_barrier
	v_mfma_f32_16x16x32_bf16 v[30:33], v[162:165], v[198:201], v[30:33]
	v_mfma_f32_16x16x32_bf16 v[26:29], v[162:165], v[206:209], v[26:29]
	v_mfma_f32_16x16x32_bf16 v[22:25], v[174:177], v[198:201], v[22:25]
	v_mfma_f32_16x16x32_bf16 v[18:21], v[174:177], v[206:209], v[18:21]
	v_mfma_f32_16x16x32_bf16 v[14:17], v[182:185], v[198:201], v[14:17]
	v_mfma_f32_16x16x32_bf16 v[10:13], v[182:185], v[206:209], v[10:13]
	v_mfma_f32_16x16x32_bf16 v[6:9], v[190:193], v[198:201], v[6:9]
	v_mfma_f32_16x16x32_bf16 v[2:5], v[190:193], v[206:209], v[2:5]
	v_mfma_f32_16x16x32_bf16 v[30:33], v[166:169], v[202:205], v[30:33]
	v_mfma_f32_16x16x32_bf16 v[26:29], v[166:169], v[210:213], v[26:29]
	v_mfma_f32_16x16x32_bf16 v[22:25], v[178:181], v[202:205], v[22:25]
	v_mfma_f32_16x16x32_bf16 v[18:21], v[178:181], v[210:213], v[18:21]
	v_mfma_f32_16x16x32_bf16 v[14:17], v[186:189], v[202:205], v[14:17]
	v_mfma_f32_16x16x32_bf16 v[10:13], v[186:189], v[210:213], v[10:13]
	v_mfma_f32_16x16x32_bf16 v[6:9], v[194:197], v[202:205], v[6:9]
	v_mfma_f32_16x16x32_bf16 v[2:5], v[194:197], v[210:213], v[2:5]
	s_add_i32 s17, s17, 2
	s_cmp_lt_u32 s17, 4
	s_barrier
	s_cbranch_scc1 .LBB0_709
	s_branch .Lpeel5_exit

; #define STAGE(P, GP, ktrel) do { const GAS char* _g = (GP) + (ktrel) * (BK * 2); \
;     __builtin_amdgcn_global_load_lds((const GAS unsigned*)(_g + so0), (unsigned*)((char*)(P) + tid_ * 16), 16, 0, 0); \
;     __builtin_amdgcn_global_load_lds((const GAS unsigned*)(_g + so1), (unsigned*)((char*)(P) + tid_ * 16 + 8192), 16, 0, 0); } while (0)
; #define WAIT_V(n) asm volatile("s_waitcnt vmcnt(" #n ")" ::: "memory")
; #define WAIT_L(n) asm volatile("s_waitcnt lgkmcnt(" #n ")" ::: "memory")
; #define BAR __builtin_amdgcn_s_barrier()
; #define LDA(dst, b, h) for (int m = 0; m < 4; ++m) for (int k = 0; k < 2; ++k) \
;     dst[m][k] = *reinterpret_cast<const bf16x8*>((char*)SA(b, h) + lds_byte(wr * 64 + m * 16 + fr, k * 32 + fq * 8))
; #define LDB(dst, b, h) for (int n = 0; n < 2; ++n) for (int k = 0; k < 2; ++k) \
;     dst[n][k] = *reinterpret_cast<const bf16x8*>((char*)SB(b, h) + lds_byte(wc * 32 + n * 16 + fr, k * 32 + fq * 8))
; #define MMA(ai, bj, At_, Bt_) do { __builtin_amdgcn_s_setprio(1); \
;     for (int m = 0; m < 4; ++m) for (int n = 0; n < 2; ++n) for (int k = 0; k < 2; ++k) \
;       acc[ai][bj][m][n] = __builtin_amdgcn_mfma_f32_16x16x32_bf16(At_[m][k], Bt_[n][k], acc[ai][bj][m][n], 0, 0, 0); \
;     __builtin_amdgcn_s_setprio(0); } while (0)
; template <int K, int LD = K>
; __device__ __forceinline__ void gemm_main(const GAS bf16* A, const GAS bf16* Bt, int brow, int bcol, f32x4 (&acc)[2][2][4][2]) {
;     ...
;   { LDB(B0, 0, 0); LDA(At, 0, 0); STAGE(SA(1, 1), pA1, 1);
;     BAR; WAIT_L(0); MMA(0, 0, At, B0); BAR;
;     LDB(B1, 0, 1); BAR; WAIT_L(0); MMA(0, 1, At, B1); BAR;
;     LDA(At, 0, 1); WAIT_V(4); BAR; WAIT_L(0); MMA(1, 0, At, B0); MMA(1, 1, At, B1); BAR; }
.Lpeel5_exit:
	v_lshl_add_u64 v[198:199], s[20:21], 0, v[130:131]
	v_readfirstlane_b32 s17, v144
	v_lshl_add_u64 v[198:199], v[198:199], 0, s[6:7]
	s_mov_b32 m0, s17
	v_lshl_add_u64 v[132:133], s[20:21], 0, v[132:133]
	v_readfirstlane_b32 s17, v145
	ds_read_b128 v[146:149], v143
	ds_read_b128 v[150:153], v143 offset:1024
	ds_read_b128 v[154:157], v143 offset:2048
	ds_read_b128 v[158:161], v143 offset:3072
	ds_read_b128 v[162:165], v138
	ds_read_b128 v[166:169], v138 offset:1024
	ds_read_b128 v[174:177], v137
	ds_read_b128 v[178:181], v137 offset:1024
	ds_read_b128 v[182:185], v136
	ds_read_b128 v[186:189], v136 offset:1024
	ds_read_b128 v[190:193], v135
	ds_read_b128 v[194:197], v135 offset:1024
	global_load_lds_dwordx4 v[198:199], off
	v_lshl_add_u64 v[132:133], v[132:133], 0, s[6:7]
	s_mov_b32 m0, s17
	s_nop 0
	global_load_lds_dwordx4 v[132:133], off
	s_waitcnt vmcnt(10)
	s_barrier
	s_waitcnt lgkmcnt(0)
	s_waitcnt lgkmcnt(0)
	v_mfma_f32_16x16x32_bf16 v[126:129], v[162:165], v[146:149], v[126:129]
	v_mfma_f32_16x16x32_bf16 v[122:125], v[162:165], v[154:157], v[122:125]
	v_mfma_f32_16x16x32_bf16 v[110:113], v[182:185], v[146:149], v[110:113]
	v_mfma_f32_16x16x32_bf16 v[106:109], v[182:185], v[154:157], v[106:109]
	v_mfma_f32_16x16x32_bf16 v[126:129], v[166:169], v[150:153], v[126:129]
	v_mfma_f32_16x16x32_bf16 v[122:125], v[166:169], v[158:161], v[122:125]
	v_mfma_f32_16x16x32_bf16 v[118:121], v[174:177], v[146:149], v[118:121]
	v_mfma_f32_16x16x32_bf16 v[114:117], v[174:177], v[154:157], v[114:117]
	v_mfma_f32_16x16x32_bf16 v[110:113], v[186:189], v[150:153], v[110:113]
	v_mfma_f32_16x16x32_bf16 v[106:109], v[186:189], v[158:161], v[106:109]
	v_mfma_f32_16x16x32_bf16 v[102:105], v[190:193], v[146:149], v[102:105]
	v_mfma_f32_16x16x32_bf16 v[98:101], v[190:193], v[154:157], v[98:101]
	v_mfma_f32_16x16x32_bf16 v[198:201], v[178:181], v[150:153], v[118:121]
	v_mfma_f32_16x16x32_bf16 v[202:205], v[178:181], v[158:161], v[114:117]
	v_mfma_f32_16x16x32_bf16 v[206:209], v[194:197], v[150:153], v[102:105]
	v_mfma_f32_16x16x32_bf16 v[210:213], v[194:197], v[158:161], v[98:101]
	s_barrier
	s_nop 1
	ds_read_b128 v[98:101], v142
	ds_read_b128 v[102:105], v142 offset:1024
	ds_read_b128 v[114:117], v142 offset:2048
	ds_read_b128 v[118:121], v142 offset:3072
	s_waitcnt vmcnt(8)
	s_barrier
	s_waitcnt lgkmcnt(0)
	s_waitcnt lgkmcnt(0)
	v_mfma_f32_16x16x32_bf16 v[94:97], v[162:165], v[98:101], v[94:97]
	v_mfma_f32_16x16x32_bf16 v[90:93], v[162:165], v[114:117], v[90:93]
	v_mfma_f32_16x16x32_bf16 v[70:73], v[190:193], v[98:101], v[70:73]
	v_mfma_f32_16x16x32_bf16 v[66:69], v[190:193], v[114:117], v[66:69]
	v_mfma_f32_16x16x32_bf16 v[94:97], v[166:169], v[102:105], v[94:97]
	v_mfma_f32_16x16x32_bf16 v[90:93], v[166:169], v[118:121], v[90:93]
	v_mfma_f32_16x16x32_bf16 v[86:89], v[174:177], v[98:101], v[86:89]
	v_mfma_f32_16x16x32_bf16 v[82:85], v[174:177], v[114:117], v[82:85]
	v_mfma_f32_16x16x32_bf16 v[78:81], v[182:185], v[98:101], v[78:81]
	v_mfma_f32_16x16x32_bf16 v[74:77], v[182:185], v[114:117], v[74:77]
	v_mfma_f32_16x16x32_bf16 v[70:73], v[194:197], v[102:105], v[70:73]
	v_mfma_f32_16x16x32_bf16 v[66:69], v[194:197], v[118:121], v[66:69]
	v_mfma_f32_16x16x32_bf16 v[142:145], v[178:181], v[102:105], v[86:89]
	v_mfma_f32_16x16x32_bf16 v[162:165], v[178:181], v[118:121], v[82:85]
	v_mfma_f32_16x16x32_bf16 v[166:169], v[186:189], v[102:105], v[78:81]
	v_mfma_f32_16x16x32_bf16 v[174:177], v[186:189], v[118:121], v[74:77]
	s_barrier
	s_nop 0
	ds_read_b128 v[74:77], v138 offset:16384
	ds_read_b128 v[78:81], v138 offset:17408
	ds_read_b128 v[82:85], v137 offset:16384
	ds_read_b128 v[86:89], v137 offset:17408
	ds_read_b128 v[178:181], v136 offset:16384
	ds_read_b128 v[182:185], v136 offset:17408
	ds_read_b128 v[186:189], v135 offset:16384
	ds_read_b128 v[190:193], v135 offset:17408
	s_waitcnt vmcnt(4)
	s_barrier
	s_waitcnt lgkmcnt(0)
	s_waitcnt lgkmcnt(0)
	v_mfma_f32_16x16x32_bf16 v[62:65], v[74:77], v[146:149], v[62:65]
	v_mfma_f32_16x16x32_bf16 v[58:61], v[74:77], v[154:157], v[58:61]
	v_mfma_f32_16x16x32_bf16 v[54:57], v[82:85], v[146:149], v[54:57]
	v_mfma_f32_16x16x32_bf16 v[50:53], v[82:85], v[154:157], v[50:53]
	v_mfma_f32_16x16x32_bf16 v[38:41], v[186:189], v[146:149], v[38:41]
	v_mfma_f32_16x16x32_bf16 v[34:37], v[186:189], v[154:157], v[34:37]
	v_mfma_f32_16x16x32_bf16 v[62:65], v[78:81], v[150:153], v[62:65]
	v_mfma_f32_16x16x32_bf16 v[58:61], v[78:81], v[158:161], v[58:61]
	v_mfma_f32_16x16x32_bf16 v[54:57], v[86:89], v[150:153], v[54:57]
	v_mfma_f32_16x16x32_bf16 v[50:53], v[86:89], v[158:161], v[50:53]
	v_mfma_f32_16x16x32_bf16 v[46:49], v[178:181], v[146:149], v[46:49]
	v_mfma_f32_16x16x32_bf16 v[42:45], v[178:181], v[154:157], v[42:45]
	v_mfma_f32_16x16x32_bf16 v[38:41], v[190:193], v[150:153], v[38:41]
	v_mfma_f32_16x16x32_bf16 v[34:37], v[190:193], v[158:161], v[34:37]
	v_mfma_f32_16x16x32_bf16 v[194:197], v[182:185], v[150:153], v[46:49]
	v_mfma_f32_16x16x32_bf16 v[214:217], v[182:185], v[158:161], v[42:45]
	v_mfma_f32_16x16x32_bf16 v[22:25], v[82:85], v[98:101], v[22:25]
	v_mfma_f32_16x16x32_bf16 v[18:21], v[82:85], v[114:117], v[18:21]
	v_mfma_f32_16x16x32_bf16 v[14:17], v[178:181], v[98:101], v[14:17]
	v_mfma_f32_16x16x32_bf16 v[10:13], v[178:181], v[114:117], v[10:13]
	v_mfma_f32_16x16x32_bf16 v[30:33], v[74:77], v[98:101], v[30:33]
	v_mfma_f32_16x16x32_bf16 v[26:29], v[74:77], v[114:117], v[26:29]
	v_mfma_f32_16x16x32_bf16 v[22:25], v[86:89], v[102:105], v[22:25]
	v_mfma_f32_16x16x32_bf16 v[18:21], v[86:89], v[118:121], v[18:21]
	v_mfma_f32_16x16x32_bf16 v[14:17], v[182:185], v[102:105], v[14:17]
	v_mfma_f32_16x16x32_bf16 v[10:13], v[182:185], v[118:121], v[10:13]
	v_mfma_f32_16x16x32_bf16 v[6:9], v[186:189], v[98:101], v[6:9]
	v_mfma_f32_16x16x32_bf16 v[2:5], v[186:189], v[114:117], v[2:5]
	v_mfma_f32_16x16x32_bf16 v[146:149], v[78:81], v[102:105], v[30:33]
	v_mfma_f32_16x16x32_bf16 v[150:153], v[78:81], v[118:121], v[26:29]
	v_mfma_f32_16x16x32_bf16 v[154:157], v[190:193], v[102:105], v[6:9]
	v_mfma_f32_16x16x32_bf16 v[158:161], v[190:193], v[118:121], v[2:5]
	s_barrier
; #define WAIT_V(n) asm volatile("s_waitcnt vmcnt(" #n ")" ::: "memory")
; #define WAIT_L(n) asm volatile("s_waitcnt lgkmcnt(" #n ")" ::: "memory")
; #define BAR __builtin_amdgcn_s_barrier()
; #define LDA(dst, b, h) for (int m = 0; m < 4; ++m) for (int k = 0; k < 2; ++k) \
;     dst[m][k] = *reinterpret_cast<const bf16x8*>((char*)SA(b, h) + lds_byte(wr * 64 + m * 16 + fr, k * 32 + fq * 8))
; #define LDB(dst, b, h) for (int n = 0; n < 2; ++n) for (int k = 0; k < 2; ++k) \
;     dst[n][k] = *reinterpret_cast<const bf16x8*>((char*)SB(b, h) + lds_byte(wc * 32 + n * 16 + fr, k * 32 + fq * 8))
; #define MMA(ai, bj, At_, Bt_) do { __builtin_amdgcn_s_setprio(1); \
;     for (int m = 0; m < 4; ++m) for (int n = 0; n < 2; ++n) for (int k = 0; k < 2; ++k) \
;       acc[ai][bj][m][n] = __builtin_amdgcn_mfma_f32_16x16x32_bf16(At_[m][k], Bt_[n][k], acc[ai][bj][m][n], 0, 0, 0); \
;     __builtin_amdgcn_s_setprio(0); } while (0)
; template <int K, int LD = K>
; __device__ __forceinline__ void gemm_main(const GAS bf16* A, const GAS bf16* Bt, int brow, int bcol, f32x4 (&acc)[2][2][4][2]) {
;     ...
;   { LDB(B0, 1, 0); LDA(At, 1, 0); WAIT_V(2); BAR; WAIT_L(0); MMA(0, 0, At, B0); BAR;
;     LDB(B1, 1, 1); WAIT_V(0); BAR; WAIT_L(0); MMA(0, 1, At, B1); BAR;
;     LDA(At, 1, 1); BAR; WAIT_L(0); MMA(1, 0, At, B0); MMA(1, 1, At, B1); BAR; }
;   if (wr == 0) BAR;
	s_nop 1
	ds_read_b128 v[2:5], v140
	ds_read_b128 v[6:9], v140 offset:1024
	ds_read_b128 v[178:181], v140 offset:2048
	ds_read_b128 v[182:185], v140 offset:3072
	ds_read_b128 v[26:29], v138 offset:32768
	ds_read_b128 v[30:33], v138 offset:33792
	ds_read_b128 v[42:45], v137 offset:32768
	ds_read_b128 v[46:49], v137 offset:33792
	ds_read_b128 v[186:189], v136 offset:32768
	ds_read_b128 v[190:193], v136 offset:33792
	ds_read_b128 v[218:221], v135 offset:32768
	ds_read_b128 v[222:225], v135 offset:33792
	s_waitcnt vmcnt(2)
	s_barrier
	s_waitcnt lgkmcnt(0)
	s_waitcnt lgkmcnt(0)
	v_mfma_f32_16x16x32_bf16 v[74:77], v[26:29], v[2:5], v[126:129]
	v_mfma_f32_16x16x32_bf16 v[118:121], v[30:33], v[6:9], v[74:77]
	v_mfma_f32_16x16x32_bf16 v[74:77], v[26:29], v[178:181], v[122:125]
	v_mfma_f32_16x16x32_bf16 v[114:117], v[30:33], v[182:185], v[74:77]
	v_mfma_f32_16x16x32_bf16 v[74:77], v[42:45], v[2:5], v[198:201]
	v_mfma_f32_16x16x32_bf16 v[102:105], v[46:49], v[6:9], v[74:77]
	v_mfma_f32_16x16x32_bf16 v[74:77], v[42:45], v[178:181], v[202:205]
	v_mfma_f32_16x16x32_bf16 v[98:101], v[46:49], v[182:185], v[74:77]
	v_mfma_f32_16x16x32_bf16 v[74:77], v[186:189], v[2:5], v[110:113]
	v_mfma_f32_16x16x32_bf16 v[86:89], v[190:193], v[6:9], v[74:77]
	v_mfma_f32_16x16x32_bf16 v[74:77], v[186:189], v[178:181], v[106:109]
	v_mfma_f32_16x16x32_bf16 v[82:85], v[190:193], v[182:185], v[74:77]
	v_mfma_f32_16x16x32_bf16 v[74:77], v[218:221], v[2:5], v[206:209]
	v_mfma_f32_16x16x32_bf16 v[78:81], v[222:225], v[6:9], v[74:77]
	v_mfma_f32_16x16x32_bf16 v[74:77], v[218:221], v[178:181], v[210:213]
	v_mfma_f32_16x16x32_bf16 v[74:77], v[222:225], v[182:185], v[74:77]
	s_barrier
	ds_read_b128 v[198:201], v139
	ds_read_b128 v[202:205], v139 offset:1024
	ds_read_b128 v[206:209], v139 offset:2048
	ds_read_b128 v[210:213], v139 offset:3072
	s_waitcnt vmcnt(0)
	s_barrier
	s_waitcnt lgkmcnt(0)
	s_waitcnt lgkmcnt(0)
	v_mfma_f32_16x16x32_bf16 v[94:97], v[26:29], v[198:201], v[94:97]
	v_mfma_f32_16x16x32_bf16 v[26:29], v[26:29], v[206:209], v[90:93]
	v_mfma_f32_16x16x32_bf16 v[122:125], v[30:33], v[210:213], v[26:29]
	v_mfma_f32_16x16x32_bf16 v[26:29], v[42:45], v[198:201], v[142:145]
	v_mfma_f32_16x16x32_bf16 v[110:113], v[46:49], v[202:205], v[26:29]
	v_mfma_f32_16x16x32_bf16 v[26:29], v[42:45], v[206:209], v[162:165]
	v_mfma_f32_16x16x32_bf16 v[106:109], v[46:49], v[210:213], v[26:29]
	v_mfma_f32_16x16x32_bf16 v[26:29], v[186:189], v[198:201], v[166:169]
	v_mfma_f32_16x16x32_bf16 v[126:129], v[30:33], v[202:205], v[94:97]
	v_mfma_f32_16x16x32_bf16 v[94:97], v[190:193], v[202:205], v[26:29]
	v_mfma_f32_16x16x32_bf16 v[26:29], v[186:189], v[206:209], v[174:177]
	v_mfma_f32_16x16x32_bf16 v[90:93], v[190:193], v[210:213], v[26:29]
	v_mfma_f32_16x16x32_bf16 v[26:29], v[218:221], v[198:201], v[70:73]
	v_mfma_f32_16x16x32_bf16 v[70:73], v[222:225], v[202:205], v[26:29]
	v_mfma_f32_16x16x32_bf16 v[26:29], v[218:221], v[206:209], v[66:69]
	v_mfma_f32_16x16x32_bf16 v[66:69], v[222:225], v[210:213], v[26:29]
	s_barrier
	ds_read_b128 v[140:143], v138 offset:49152
	ds_read_b128 v[162:165], v138 offset:50176
	ds_read_b128 v[166:169], v137 offset:49152
	ds_read_b128 v[174:177], v137 offset:50176
	ds_read_b128 v[186:189], v136 offset:49152
	ds_read_b128 v[136:139], v136 offset:50176
	ds_read_b128 v[190:193], v135 offset:49152
	ds_read_b128 v[218:221], v135 offset:50176
	s_barrier
	s_waitcnt lgkmcnt(0)
	s_waitcnt lgkmcnt(0)
	v_mfma_f32_16x16x32_bf16 v[26:29], v[140:143], v[2:5], v[62:65]
	v_mfma_f32_16x16x32_bf16 v[62:65], v[162:165], v[6:9], v[26:29]
	v_mfma_f32_16x16x32_bf16 v[26:29], v[140:143], v[178:181], v[58:61]
	v_mfma_f32_16x16x32_bf16 v[58:61], v[162:165], v[182:185], v[26:29]
	v_mfma_f32_16x16x32_bf16 v[26:29], v[166:169], v[2:5], v[54:57]
	v_mfma_f32_16x16x32_bf16 v[46:49], v[174:177], v[6:9], v[26:29]
	v_mfma_f32_16x16x32_bf16 v[26:29], v[166:169], v[178:181], v[50:53]
	v_mfma_f32_16x16x32_bf16 v[42:45], v[174:177], v[182:185], v[26:29]
	v_mfma_f32_16x16x32_bf16 v[26:29], v[186:189], v[2:5], v[194:197]
	v_mfma_f32_16x16x32_bf16 v[2:5], v[190:193], v[2:5], v[38:41]
	v_mfma_f32_16x16x32_bf16 v[30:33], v[136:139], v[6:9], v[26:29]
	v_mfma_f32_16x16x32_bf16 v[26:29], v[186:189], v[178:181], v[214:217]
	v_mfma_f32_16x16x32_bf16 v[6:9], v[218:221], v[6:9], v[2:5]
	v_mfma_f32_16x16x32_bf16 v[2:5], v[190:193], v[178:181], v[34:37]
	v_mfma_f32_16x16x32_bf16 v[26:29], v[136:139], v[182:185], v[26:29]
	v_mfma_f32_16x16x32_bf16 v[2:5], v[218:221], v[182:185], v[2:5]
	v_mfma_f32_16x16x32_bf16 v[34:37], v[140:143], v[198:201], v[146:149]
	v_mfma_f32_16x16x32_bf16 v[54:57], v[162:165], v[202:205], v[34:37]
	v_mfma_f32_16x16x32_bf16 v[34:37], v[140:143], v[206:209], v[150:153]
	v_mfma_f32_16x16x32_bf16 v[18:21], v[166:169], v[206:209], v[18:21]
	v_mfma_f32_16x16x32_bf16 v[10:13], v[186:189], v[206:209], v[10:13]
	v_mfma_f32_16x16x32_bf16 v[50:53], v[162:165], v[210:213], v[34:37]
	v_mfma_f32_16x16x32_bf16 v[22:25], v[166:169], v[198:201], v[22:25]
	v_mfma_f32_16x16x32_bf16 v[34:37], v[174:177], v[210:213], v[18:21]
	v_mfma_f32_16x16x32_bf16 v[14:17], v[186:189], v[198:201], v[14:17]
	v_mfma_f32_16x16x32_bf16 v[18:21], v[136:139], v[210:213], v[10:13]
	v_mfma_f32_16x16x32_bf16 v[10:13], v[190:193], v[198:201], v[154:157]
	v_mfma_f32_16x16x32_bf16 v[38:41], v[174:177], v[202:205], v[22:25]
	v_mfma_f32_16x16x32_bf16 v[22:25], v[136:139], v[202:205], v[14:17]
	v_mfma_f32_16x16x32_bf16 v[14:17], v[218:221], v[202:205], v[10:13]
	v_mfma_f32_16x16x32_bf16 v[10:13], v[190:193], v[206:209], v[158:161]
	v_mfma_f32_16x16x32_bf16 v[10:13], v[218:221], v[210:213], v[10:13]
	v_cmp_gt_u32_e32 vcc, s51, v134
	s_barrier
	s_and_saveexec_b64 s[20:21], vcc
	s_cbranch_execz .LBB0_712
	s_barrier

; #define GAS __attribute__((address_space(1)))
; __device__ __forceinline__ int otid() { int t = threadIdx.x; asm volatile("" : "+v"(t)); return t; }
; #define STAGE(P, GP, ktrel) do { const GAS char* _g = (GP) + (ktrel) * (BK * 2); \
;     __builtin_amdgcn_global_load_lds((const GAS unsigned*)(_g + so0), (unsigned*)((char*)(P) + tid_ * 16), 16, 0, 0); \
;     __builtin_amdgcn_global_load_lds((const GAS unsigned*)(_g + so1), (unsigned*)((char*)(P) + tid_ * 16 + 8192), 16, 0, 0); } while (0)
; #define WAIT_V(n) asm volatile("s_waitcnt vmcnt(" #n ")" ::: "memory")
; #define WAIT_L(n) asm volatile("s_waitcnt lgkmcnt(" #n ")" ::: "memory")
; #define BAR __builtin_amdgcn_s_barrier()
; #define SCHED __builtin_amdgcn_sched_barrier(0)
; #define LDA(dst, b, h) for (int m = 0; m < 4; ++m) for (int k = 0; k < 2; ++k) \
;     dst[m][k] = *reinterpret_cast<const bf16x8*>((char*)SA(b, h) + lds_byte(wr * 64 + m * 16 + fr, k * 32 + fq * 8))
; template <int K, int LD = K>
; __device__ __forceinline__ void gemm_main(const GAS bf16* A, const GAS bf16* Bt, int brow, int bcol, f32x4 (&acc)[2][2][4][2]) {
;     ...
;   const int tid_ = otid();
;     ...
;   const int wid = tid_ >> 6, lane = tid_ & 63, wr = wid >> 2, wc = wid & 3, fr = lane & 15, fq = lane >> 4;
; #pragma unroll
;   for (int a = 0; a < 2; ++a)
; #pragma unroll
;     for (int b = 0; b < 2; ++b)
; #pragma unroll
;       for (int m = 0; m < 4; ++m)
; #pragma unroll
;         for (int n = 0; n < 2; ++n) acc[a][b][m][n] = f32x4{0.f, 0.f, 0.f, 0.f};
;   bf16x8 At[4][2], B0[2][2], B1[2][2];
;   unsigned so0, so1;
;   { int r_, c_; stage_rc(tid_ * 16, r_, c_); so0 = (unsigned)(r_ * LD + c_) * 2u; stage_rc(tid_ * 16 + 8192, r_, c_); so1 = (unsigned)(r_ * LD + c_) * 2u; }
;   const GAS char* pA0 = (const GAS char*)A + (long)brow * LD * 2; const GAS char* pA1 = pA0 + (long)HALF * LD * 2;
;   const GAS char* pB0 = (const GAS char*)Bt + (long)bcol * LD * 2; const GAS char* pB1 = pB0 + (long)HALF * LD * 2;
;   asm volatile("" : "+s"(pA0), "+s"(pA1), "+s"(pB0), "+s"(pB1));
;   constexpr int nt = K / BK;
;   static_assert(K % 128 == 0 && K >= 256, "K");
;   if (wr == 1) BAR;
;   WAIT_V(0); BAR;
;   BAR;
;   for (int t = 0; t < nt - 2; t += 2) {
;     LDB(B0, 0, 0); SCHED; LDA(At, 0, 0); STAGE(SA(1, 1), pA1, 1);
;     WAIT_L(8); BAR; WAIT_L(0); MMA(0, 0, At, B0); BAR; SCHED;
;     LDB(B1, 0, 1); STAGE(SB(0, 0), pB0, 2);
.LBB0_714:
	s_or_b64 exec, exec, s[28:29]
	v_bfe_i32 v6, v134, 27, 1
	v_lshlrev_b32_e32 v141, 4, v134
	v_lshrrev_b32_e32 v6, 22, v6
	v_add_u32_e32 v6, v141, v6
	v_and_b32_e32 v6, 0xfffffc00, v6
	v_sub_u32_e32 v6, v141, v6
	v_lshrrev_b32_e32 v7, 4, v6
	v_bitop3_b32 v7, v7, v6, 32 bitop3:0x6c
	v_ashrrev_i32_e32 v6, 31, v6
	v_ashrrev_i32_e32 v5, 31, v134
	v_lshrrev_b32_e32 v6, 26, v6
	v_lshrrev_b32_e32 v5, 26, v5
	v_add_u32_e32 v6, v7, v6
	v_add_u32_e32 v5, v134, v5
	v_ashrrev_i32_e32 v6, 6, v6
	v_ashrrev_i32_e32 v5, 6, v5
	v_mul_i32_i24_e32 v9, 64, v6
	v_lshlrev_b32_e32 v8, 3, v5
	v_lshlrev_b32_e32 v5, 5, v5
	v_sub_u32_e32 v7, v7, v9
	v_and_b32_e32 v8, 0x3ffff0, v8
	v_and_b32_e32 v5, 32, v5
	v_ashrrev_i16_sdwa v7, v1, sext(v7) dst_sel:DWORD dst_unused:UNUSED_PAD src0_sel:DWORD src1_sel:BYTE_0
	v_add_u32_sdwa v5, v5, sext(v7) dst_sel:DWORD dst_unused:UNUSED_PAD src0_sel:DWORD src1_sel:WORD_0
	v_add_lshl_u32 v6, v6, v8, 10
	v_lshl_add_u32 v130, v5, 1, v6
	v_add_u32_e32 v5, 0x2000, v141
	v_ashrrev_i32_e32 v6, 31, v5
	v_lshrrev_b32_e32 v6, 22, v6
	v_add_u32_e32 v6, v5, v6
	v_ashrrev_i32_e32 v6, 10, v6
	v_mul_i32_i24_e32 v7, 0x400, v6
	v_sub_u32_e32 v5, v5, v7
	v_lshrrev_b32_e32 v7, 4, v5
	v_bitop3_b32 v5, v7, v5, 32 bitop3:0x6c
	v_ashrrev_i32_e32 v8, 31, v5
	v_lshrrev_b32_e32 v8, 26, v8
	v_add_u32_e32 v8, v5, v8
	v_lshrrev_b32_e32 v9, 6, v8
	v_and_b32_e32 v8, 0xc0, v8
	v_lshlrev_b32_e32 v7, 3, v6
	v_lshlrev_b32_e32 v6, 5, v6
	v_sub_u32_e32 v5, v5, v8
	v_and_b32_e32 v7, 0x3ffff0, v7
	v_and_b32_e32 v6, 32, v6
	v_ashrrev_i16_sdwa v5, v1, sext(v5) dst_sel:DWORD dst_unused:UNUSED_PAD src0_sel:DWORD src1_sel:BYTE_0
	v_add_u32_sdwa v5, v6, sext(v5) dst_sel:DWORD dst_unused:UNUSED_PAD src0_sel:DWORD src1_sel:WORD_0
	v_add_lshl_u32 v6, v9, v7, 10
	v_and_b32_e32 v3, 15, v134
	v_lshl_add_u32 v132, v5, 1, v6
	v_lshlrev_b32_e32 v5, 2, v134
	v_and_b32_e32 v4, 48, v134
	v_lshlrev_b32_e32 v3, 6, v3
	v_and_b32_e32 v5, 32, v5
	v_lshlrev_b32_e32 v10, 6, v134
	v_bitop3_b32 v3, v3, v5, v4 bitop3:0x36
	v_lshlrev_b32_e32 v12, 13, v2
	v_and_or_b32 v2, v10, s54, v4
	v_add_u32_e32 v6, s47, v3
	v_add_u32_e32 v7, s48, v3
	v_add_u32_e32 v8, s49, v3
	v_add_u32_e32 v9, s50, v3
	v_and_b32_e32 v11, 0x3000, v10
	v_add_u32_e32 v3, 0x100, v3
	v_xad_u32 v4, v2, v5, s51
	v_or_b32_e32 v5, 0x800, v12
	v_or_b32_e32 v10, 0x1000, v12
	v_or_b32_e32 v13, 0x1800, v12
	v_mov_b32_e32 v2, 0
	v_mov_b32_e32 v133, v131
	s_mov_b32 s17, -2
	v_add_u32_e32 v143, v6, v11
	v_add_u32_e32 v138, v3, v12
	v_add_u32_e32 v137, v4, v5
	v_add_u32_e32 v136, v4, v10
	v_add_u32_e32 v135, v4, v13
	v_add_u32_e32 v142, v7, v11
	v_add_u32_e32 v140, v8, v11
	v_add_u32_e32 v139, v9, v11
	s_waitcnt vmcnt(0)
	s_barrier
	s_barrier
	ds_read_b128 v[146:149], v143
	ds_read_b128 v[150:153], v143 offset:1024
	ds_read_b128 v[154:157], v143 offset:2048
	ds_read_b128 v[158:161], v143 offset:3072
	v_add_u32_e32 v230, 0x100, v141
	v_add_u32_e32 v144, 0xc000, v230
	v_lshl_add_u64 v[214:215], s[20:21], 0, v[130:131]
	v_readfirstlane_b32 s28, v144
	v_add_u32_e32 v145, 0xe000, v230
	v_lshl_add_u64 v[198:199], v[214:215], 0, s[6:7]
	s_mov_b32 m0, s28
	v_lshl_add_u64 v[216:217], s[20:21], 0, v[132:133]
	v_readfirstlane_b32 s28, v145
	ds_read_b128 v[162:165], v138
	ds_read_b128 v[166:169], v138 offset:1024
	ds_read_b128 v[174:177], v137
	ds_read_b128 v[178:181], v137 offset:1024
	ds_read_b128 v[182:185], v136
	ds_read_b128 v[186:189], v136 offset:1024
	ds_read_b128 v[190:193], v135
	ds_read_b128 v[194:197], v135 offset:1024
	global_load_lds_dwordx4 v[198:199], off
	v_lshl_add_u64 v[198:199], v[216:217], 0, s[6:7]
	s_mov_b32 m0, s28
	s_nop 0
	global_load_lds_dwordx4 v[198:199], off
	s_waitcnt lgkmcnt(8)
	s_waitcnt vmcnt(10)
	s_barrier
	s_waitcnt lgkmcnt(0)
	s_waitcnt lgkmcnt(0)
	v_mfma_f32_16x16x32_bf16 v[126:129], v[162:165], v[146:149], 0
	v_mfma_f32_16x16x32_bf16 v[122:125], v[162:165], v[154:157], 0
	v_mfma_f32_16x16x32_bf16 v[118:121], v[174:177], v[146:149], 0
	v_mfma_f32_16x16x32_bf16 v[114:117], v[174:177], v[154:157], 0
	v_mfma_f32_16x16x32_bf16 v[110:113], v[182:185], v[146:149], 0
	v_mfma_f32_16x16x32_bf16 v[106:109], v[182:185], v[154:157], 0
	v_mfma_f32_16x16x32_bf16 v[102:105], v[190:193], v[146:149], 0
	v_mfma_f32_16x16x32_bf16 v[98:101], v[190:193], v[154:157], 0
	v_mfma_f32_16x16x32_bf16 v[126:129], v[166:169], v[150:153], v[126:129]
	v_mfma_f32_16x16x32_bf16 v[122:125], v[166:169], v[158:161], v[122:125]
	v_mfma_f32_16x16x32_bf16 v[118:121], v[178:181], v[150:153], v[118:121]
	v_mfma_f32_16x16x32_bf16 v[114:117], v[178:181], v[158:161], v[114:117]
	v_mfma_f32_16x16x32_bf16 v[110:113], v[186:189], v[150:153], v[110:113]
	v_mfma_f32_16x16x32_bf16 v[106:109], v[186:189], v[158:161], v[106:109]
	v_mfma_f32_16x16x32_bf16 v[102:105], v[194:197], v[150:153], v[102:105]
	v_mfma_f32_16x16x32_bf16 v[98:101], v[194:197], v[158:161], v[98:101]
	s_barrier
	v_add_u32_e32 v224, s47, v141
	v_lshl_add_u64 v[218:219], s[26:27], 0, v[130:131]
	v_readfirstlane_b32 s28, v224
	v_lshl_add_u64 v[220:221], v[218:219], 0, s[10:11]
	s_mov_b32 m0, s28
	v_add_u32_e32 v224, 0x2000, v224
	ds_read_b128 v[198:201], v142
	ds_read_b128 v[202:205], v142 offset:1024
	ds_read_b128 v[206:209], v142 offset:2048
	ds_read_b128 v[210:213], v142 offset:3072
	global_load_lds_dwordx4 v[220:221], off
	v_lshl_add_u64 v[220:221], s[26:27], 0, v[132:133]
	v_readfirstlane_b32 s28, v224
	v_lshl_add_u64 v[222:223], v[220:221], 0, s[10:11]
	s_mov_b32 m0, s28
	s_add_u32 s26, s26, 0x100
	global_load_lds_dwordx4 v[222:223], off
	s_waitcnt vmcnt(10)
	s_barrier
; #define STAGE(P, GP, ktrel) do { const GAS char* _g = (GP) + (ktrel) * (BK * 2); \
;     __builtin_amdgcn_global_load_lds((const GAS unsigned*)(_g + so0), (unsigned*)((char*)(P) + tid_ * 16), 16, 0, 0); \
;     __builtin_amdgcn_global_load_lds((const GAS unsigned*)(_g + so1), (unsigned*)((char*)(P) + tid_ * 16 + 8192), 16, 0, 0); } while (0)
; #define WAIT_V(n) asm volatile("s_waitcnt vmcnt(" #n ")" ::: "memory")
; #define WAIT_L(n) asm volatile("s_waitcnt lgkmcnt(" #n ")" ::: "memory")
; #define BAR __builtin_amdgcn_s_barrier()
; #define SCHED __builtin_amdgcn_sched_barrier(0)
; #define LDA(dst, b, h) for (int m = 0; m < 4; ++m) for (int k = 0; k < 2; ++k) \
;     dst[m][k] = *reinterpret_cast<const bf16x8*>((char*)SA(b, h) + lds_byte(wr * 64 + m * 16 + fr, k * 32 + fq * 8))
; #define LDB(dst, b, h) for (int n = 0; n < 2; ++n) for (int k = 0; k < 2; ++k) \
;     dst[n][k] = *reinterpret_cast<const bf16x8*>((char*)SB(b, h) + lds_byte(wc * 32 + n * 16 + fr, k * 32 + fq * 8))
; #define MMA(ai, bj, At_, Bt_) do { __builtin_amdgcn_s_setprio(1); \
;     for (int m = 0; m < 4; ++m) for (int n = 0; n < 2; ++n) for (int k = 0; k < 2; ++k) \
;       acc[ai][bj][m][n] = __builtin_amdgcn_mfma_f32_16x16x32_bf16(At_[m][k], Bt_[n][k], acc[ai][bj][m][n], 0, 0, 0); \
;     __builtin_amdgcn_s_setprio(0); } while (0)
; template <int K, int LD = K>
; __device__ __forceinline__ void gemm_main(const GAS bf16* A, const GAS bf16* Bt, int brow, int bcol, f32x4 (&acc)[2][2][4][2]) {
;     ...
;     BAR; WAIT_L(0); MMA(0, 1, At, B1); BAR;
;     LDA(At, 0, 1); STAGE(SA(0, 0), pA0, 2);
;     BAR; WAIT_L(0); MMA(1, 0, At, B0); BAR; SCHED;
;     STAGE(SB(0, 1), pB1, 2);
;     WAIT_V(6); BAR; MMA(1, 1, At, B1); BAR;
;     LDB(B0, 1, 0); SCHED; LDA(At, 1, 0); STAGE(SA(0, 1), pA1, 2);
;     WAIT_L(8); BAR; WAIT_L(0); MMA(0, 0, At, B0); BAR; SCHED;
	s_waitcnt lgkmcnt(0)
	s_addc_u32 s27, s27, 0
	s_waitcnt lgkmcnt(0)
	v_mfma_f32_16x16x32_bf16 v[94:97], v[162:165], v[198:201], 0
	v_mfma_f32_16x16x32_bf16 v[90:93], v[162:165], v[206:209], 0
	v_mfma_f32_16x16x32_bf16 v[86:89], v[174:177], v[198:201], 0
	v_mfma_f32_16x16x32_bf16 v[82:85], v[174:177], v[206:209], 0
	v_mfma_f32_16x16x32_bf16 v[78:81], v[182:185], v[198:201], 0
	v_mfma_f32_16x16x32_bf16 v[74:77], v[182:185], v[206:209], 0
	v_mfma_f32_16x16x32_bf16 v[70:73], v[190:193], v[198:201], 0
	v_mfma_f32_16x16x32_bf16 v[66:69], v[190:193], v[206:209], 0
	v_mfma_f32_16x16x32_bf16 v[94:97], v[166:169], v[202:205], v[94:97]
	v_mfma_f32_16x16x32_bf16 v[90:93], v[166:169], v[210:213], v[90:93]
	v_mfma_f32_16x16x32_bf16 v[86:89], v[178:181], v[202:205], v[86:89]
	v_mfma_f32_16x16x32_bf16 v[82:85], v[178:181], v[210:213], v[82:85]
	v_mfma_f32_16x16x32_bf16 v[78:81], v[186:189], v[202:205], v[78:81]
	v_mfma_f32_16x16x32_bf16 v[74:77], v[186:189], v[210:213], v[74:77]
	v_mfma_f32_16x16x32_bf16 v[70:73], v[194:197], v[202:205], v[70:73]
	v_mfma_f32_16x16x32_bf16 v[66:69], v[194:197], v[210:213], v[66:69]
	v_lshl_add_u64 v[222:223], s[24:25], 0, v[130:131]
	v_readfirstlane_b32 s28, v230
	v_lshl_add_u64 v[224:225], v[222:223], 0, s[10:11]
	s_mov_b32 m0, s28
	v_add_u32_e32 v228, 0x2000, v230
	s_barrier
	ds_read_b128 v[162:165], v138 offset:16384
	ds_read_b128 v[166:169], v138 offset:17408
	ds_read_b128 v[174:177], v137 offset:16384
	ds_read_b128 v[178:181], v137 offset:17408
	ds_read_b128 v[182:185], v136 offset:16384
	ds_read_b128 v[186:189], v136 offset:17408
	ds_read_b128 v[190:193], v135 offset:16384
	ds_read_b128 v[194:197], v135 offset:17408
	global_load_lds_dwordx4 v[224:225], off
	v_lshl_add_u64 v[224:225], s[24:25], 0, v[132:133]
	v_readfirstlane_b32 s28, v228
	v_lshl_add_u64 v[226:227], v[224:225], 0, s[10:11]
	s_mov_b32 m0, s28
	s_add_u32 s24, s24, 0x100
	global_load_lds_dwordx4 v[226:227], off
	s_barrier
	s_waitcnt lgkmcnt(0)
	s_addc_u32 s25, s25, 0
	s_waitcnt lgkmcnt(0)
	v_mfma_f32_16x16x32_bf16 v[62:65], v[162:165], v[146:149], 0
	v_mfma_f32_16x16x32_bf16 v[58:61], v[162:165], v[154:157], 0
	v_mfma_f32_16x16x32_bf16 v[54:57], v[174:177], v[146:149], 0
	v_mfma_f32_16x16x32_bf16 v[50:53], v[174:177], v[154:157], 0
	v_mfma_f32_16x16x32_bf16 v[46:49], v[182:185], v[146:149], 0
	v_mfma_f32_16x16x32_bf16 v[42:45], v[182:185], v[154:157], 0
	v_mfma_f32_16x16x32_bf16 v[38:41], v[190:193], v[146:149], 0
	v_mfma_f32_16x16x32_bf16 v[34:37], v[190:193], v[154:157], 0
	v_mfma_f32_16x16x32_bf16 v[62:65], v[166:169], v[150:153], v[62:65]
	v_mfma_f32_16x16x32_bf16 v[58:61], v[166:169], v[158:161], v[58:61]
	v_mfma_f32_16x16x32_bf16 v[54:57], v[178:181], v[150:153], v[54:57]
	v_mfma_f32_16x16x32_bf16 v[50:53], v[178:181], v[158:161], v[50:53]
	v_mfma_f32_16x16x32_bf16 v[46:49], v[186:189], v[150:153], v[46:49]
	v_mfma_f32_16x16x32_bf16 v[42:45], v[186:189], v[158:161], v[42:45]
	v_mfma_f32_16x16x32_bf16 v[38:41], v[194:197], v[150:153], v[38:41]
	v_mfma_f32_16x16x32_bf16 v[34:37], v[194:197], v[158:161], v[34:37]
	s_barrier
	v_add_u32_e32 v148, s48, v141
	v_lshl_add_u64 v[226:227], s[22:23], 0, v[130:131]
	v_readfirstlane_b32 s28, v148
	v_add_u32_e32 v148, 0x2000, v148
	v_lshl_add_u64 v[146:147], v[226:227], 0, s[10:11]
	s_mov_b32 m0, s28
	v_lshl_add_u64 v[228:229], s[22:23], 0, v[132:133]
	v_readfirstlane_b32 s28, v148
	global_load_lds_dwordx4 v[146:147], off
	v_lshl_add_u64 v[146:147], v[228:229], 0, s[10:11]
	s_mov_b32 m0, s28
	s_add_u32 s22, s22, 0x100
	global_load_lds_dwordx4 v[146:147], off
	s_waitcnt vmcnt(10)
	s_addc_u32 s23, s23, 0
	s_barrier
	v_mfma_f32_16x16x32_bf16 v[30:33], v[162:165], v[198:201], 0
	v_mfma_f32_16x16x32_bf16 v[26:29], v[162:165], v[206:209], 0
	v_mfma_f32_16x16x32_bf16 v[22:25], v[174:177], v[198:201], 0
	v_mfma_f32_16x16x32_bf16 v[18:21], v[174:177], v[206:209], 0
	v_mfma_f32_16x16x32_bf16 v[14:17], v[182:185], v[198:201], 0
	v_mfma_f32_16x16x32_bf16 v[10:13], v[182:185], v[206:209], 0
	v_mfma_f32_16x16x32_bf16 v[6:9], v[190:193], v[198:201], 0
	v_mfma_f32_16x16x32_bf16 v[2:5], v[190:193], v[206:209], 0
	v_mfma_f32_16x16x32_bf16 v[30:33], v[166:169], v[202:205], v[30:33]
	v_mfma_f32_16x16x32_bf16 v[26:29], v[166:169], v[210:213], v[26:29]
	v_mfma_f32_16x16x32_bf16 v[22:25], v[178:181], v[202:205], v[22:25]
	v_mfma_f32_16x16x32_bf16 v[18:21], v[178:181], v[210:213], v[18:21]
	v_mfma_f32_16x16x32_bf16 v[14:17], v[186:189], v[202:205], v[14:17]
	v_mfma_f32_16x16x32_bf16 v[10:13], v[186:189], v[210:213], v[10:13]
	v_mfma_f32_16x16x32_bf16 v[6:9], v[194:197], v[202:205], v[6:9]
	v_mfma_f32_16x16x32_bf16 v[2:5], v[194:197], v[210:213], v[2:5]
	s_barrier
	ds_read_b128 v[146:149], v140
	ds_read_b128 v[150:153], v140 offset:1024
	ds_read_b128 v[154:157], v140 offset:2048
	ds_read_b128 v[158:161], v140 offset:3072
	v_add_u32_e32 v200, 0x4000, v230
	v_lshl_add_u64 v[198:199], v[214:215], 0, s[10:11]
	v_readfirstlane_b32 s28, v200
	v_add_u32_e32 v200, 0x6000, v230
	s_mov_b32 m0, s28
	v_readfirstlane_b32 s28, v200
	ds_read_b128 v[162:165], v138 offset:32768
	ds_read_b128 v[166:169], v138 offset:33792
	ds_read_b128 v[174:177], v137 offset:32768
	ds_read_b128 v[178:181], v137 offset:33792
	ds_read_b128 v[182:185], v136 offset:32768
	ds_read_b128 v[186:189], v136 offset:33792
	ds_read_b128 v[190:193], v135 offset:32768
	ds_read_b128 v[194:197], v135 offset:33792
	global_load_lds_dwordx4 v[198:199], off
	v_lshl_add_u64 v[198:199], v[216:217], 0, s[10:11]
	s_mov_b32 m0, s28
	s_add_u32 s20, s20, 0x100
	global_load_lds_dwordx4 v[198:199], off
	s_waitcnt lgkmcnt(8)
	s_waitcnt vmcnt(10)
	s_barrier
; #define STAGE(P, GP, ktrel) do { const GAS char* _g = (GP) + (ktrel) * (BK * 2); \
;     __builtin_amdgcn_global_load_lds((const GAS unsigned*)(_g + so0), (unsigned*)((char*)(P) + tid_ * 16), 16, 0, 0); \
;     __builtin_amdgcn_global_load_lds((const GAS unsigned*)(_g + so1), (unsigned*)((char*)(P) + tid_ * 16 + 8192), 16, 0, 0); } while (0)
; #define WAIT_V(n) asm volatile("s_waitcnt vmcnt(" #n ")" ::: "memory")
; #define WAIT_L(n) asm volatile("s_waitcnt lgkmcnt(" #n ")" ::: "memory")
; #define BAR __builtin_amdgcn_s_barrier()
; #define SCHED __builtin_amdgcn_sched_barrier(0)
; #define LDA(dst, b, h) for (int m = 0; m < 4; ++m) for (int k = 0; k < 2; ++k) \
;     dst[m][k] = *reinterpret_cast<const bf16x8*>((char*)SA(b, h) + lds_byte(wr * 64 + m * 16 + fr, k * 32 + fq * 8))
; #define LDB(dst, b, h) for (int n = 0; n < 2; ++n) for (int k = 0; k < 2; ++k) \
;     dst[n][k] = *reinterpret_cast<const bf16x8*>((char*)SB(b, h) + lds_byte(wc * 32 + n * 16 + fr, k * 32 + fq * 8))
; #define MMA(ai, bj, At_, Bt_) do { __builtin_amdgcn_s_setprio(1); \
;     for (int m = 0; m < 4; ++m) for (int n = 0; n < 2; ++n) for (int k = 0; k < 2; ++k) \
;       acc[ai][bj][m][n] = __builtin_amdgcn_mfma_f32_16x16x32_bf16(At_[m][k], Bt_[n][k], acc[ai][bj][m][n], 0, 0, 0); \
;     __builtin_amdgcn_s_setprio(0); } while (0)
; template <int K, int LD = K>
; __device__ __forceinline__ void gemm_main(const GAS bf16* A, const GAS bf16* Bt, int brow, int bcol, f32x4 (&acc)[2][2][4][2]) {
;     ...
;     WAIT_L(8); BAR; WAIT_L(0); MMA(0, 0, At, B0); BAR; SCHED;
;     LDB(B1, 1, 1); STAGE(SB(1, 0), pB0, 3);
;     BAR; WAIT_L(0); MMA(0, 1, At, B1); BAR;
;     LDA(At, 1, 1); STAGE(SA(1, 0), pA0, 3);
;     BAR; WAIT_L(0); MMA(1, 0, At, B0); BAR; SCHED;
;     STAGE(SB(1, 1), pB1, 3);
;     WAIT_V(6); BAR; MMA(1, 1, At, B1); BAR;
;     pA0 += 4 * BK; pA1 += 4 * BK; pB0 += 4 * BK; pB1 += 4 * BK;
;     asm volatile("" : "+s"(pA0), "+s"(pA1), "+s"(pB0), "+s"(pB1));
	s_waitcnt lgkmcnt(0)
	s_addc_u32 s21, s21, 0
	s_waitcnt lgkmcnt(0)
	v_mfma_f32_16x16x32_bf16 v[126:129], v[162:165], v[146:149], v[126:129]
	v_mfma_f32_16x16x32_bf16 v[122:125], v[162:165], v[154:157], v[122:125]
	v_mfma_f32_16x16x32_bf16 v[118:121], v[174:177], v[146:149], v[118:121]
	v_mfma_f32_16x16x32_bf16 v[114:117], v[174:177], v[154:157], v[114:117]
	v_mfma_f32_16x16x32_bf16 v[110:113], v[182:185], v[146:149], v[110:113]
	v_mfma_f32_16x16x32_bf16 v[106:109], v[182:185], v[154:157], v[106:109]
	v_mfma_f32_16x16x32_bf16 v[102:105], v[190:193], v[146:149], v[102:105]
	v_mfma_f32_16x16x32_bf16 v[98:101], v[190:193], v[154:157], v[98:101]
	v_mfma_f32_16x16x32_bf16 v[126:129], v[166:169], v[150:153], v[126:129]
	v_mfma_f32_16x16x32_bf16 v[122:125], v[166:169], v[158:161], v[122:125]
	v_mfma_f32_16x16x32_bf16 v[118:121], v[178:181], v[150:153], v[118:121]
	v_mfma_f32_16x16x32_bf16 v[114:117], v[178:181], v[158:161], v[114:117]
	v_mfma_f32_16x16x32_bf16 v[110:113], v[186:189], v[150:153], v[110:113]
	v_mfma_f32_16x16x32_bf16 v[106:109], v[186:189], v[158:161], v[106:109]
	v_mfma_f32_16x16x32_bf16 v[102:105], v[194:197], v[150:153], v[102:105]
	v_mfma_f32_16x16x32_bf16 v[98:101], v[194:197], v[158:161], v[98:101]
	s_barrier
	v_add_u32_e32 v216, s49, v141
	v_lshl_add_u64 v[214:215], v[218:219], 0, s[12:13]
	v_readfirstlane_b32 s28, v216
	v_add_u32_e32 v216, 0x2000, v216
	s_mov_b32 m0, s28
	v_readfirstlane_b32 s28, v216
	ds_read_b128 v[198:201], v139
	ds_read_b128 v[202:205], v139 offset:1024
	ds_read_b128 v[206:209], v139 offset:2048
	ds_read_b128 v[210:213], v139 offset:3072
	global_load_lds_dwordx4 v[214:215], off
	v_lshl_add_u64 v[214:215], v[220:221], 0, s[12:13]
	s_mov_b32 m0, s28
	s_nop 0
	global_load_lds_dwordx4 v[214:215], off
	s_waitcnt vmcnt(10)
	s_barrier
	s_waitcnt lgkmcnt(0)
	s_waitcnt lgkmcnt(0)
	v_mfma_f32_16x16x32_bf16 v[94:97], v[162:165], v[198:201], v[94:97]
	v_mfma_f32_16x16x32_bf16 v[90:93], v[162:165], v[206:209], v[90:93]
	v_mfma_f32_16x16x32_bf16 v[86:89], v[174:177], v[198:201], v[86:89]
	v_mfma_f32_16x16x32_bf16 v[82:85], v[174:177], v[206:209], v[82:85]
	v_mfma_f32_16x16x32_bf16 v[78:81], v[182:185], v[198:201], v[78:81]
	v_mfma_f32_16x16x32_bf16 v[74:77], v[182:185], v[206:209], v[74:77]
	v_mfma_f32_16x16x32_bf16 v[70:73], v[190:193], v[198:201], v[70:73]
	v_mfma_f32_16x16x32_bf16 v[66:69], v[190:193], v[206:209], v[66:69]
	v_mfma_f32_16x16x32_bf16 v[94:97], v[166:169], v[202:205], v[94:97]
	v_mfma_f32_16x16x32_bf16 v[90:93], v[166:169], v[210:213], v[90:93]
	v_mfma_f32_16x16x32_bf16 v[86:89], v[178:181], v[202:205], v[86:89]
	v_mfma_f32_16x16x32_bf16 v[82:85], v[178:181], v[210:213], v[82:85]
	v_mfma_f32_16x16x32_bf16 v[78:81], v[186:189], v[202:205], v[78:81]
	v_mfma_f32_16x16x32_bf16 v[74:77], v[186:189], v[210:213], v[74:77]
	v_mfma_f32_16x16x32_bf16 v[70:73], v[194:197], v[202:205], v[70:73]
	v_mfma_f32_16x16x32_bf16 v[66:69], v[194:197], v[210:213], v[66:69]
	v_add_u32_e32 v216, 0x8000, v230
	v_lshl_add_u64 v[214:215], v[222:223], 0, s[12:13]
	v_readfirstlane_b32 s28, v216
	v_add_u32_e32 v216, 0xa000, v230
	s_mov_b32 m0, s28
	v_readfirstlane_b32 s28, v216
	s_barrier
	ds_read_b128 v[162:165], v138 offset:49152
	ds_read_b128 v[166:169], v138 offset:50176
	ds_read_b128 v[174:177], v137 offset:49152
	ds_read_b128 v[178:181], v137 offset:50176
	ds_read_b128 v[182:185], v136 offset:49152
	ds_read_b128 v[186:189], v136 offset:50176
	ds_read_b128 v[190:193], v135 offset:49152
	ds_read_b128 v[194:197], v135 offset:50176
	global_load_lds_dwordx4 v[214:215], off
	v_lshl_add_u64 v[214:215], v[224:225], 0, s[12:13]
	s_mov_b32 m0, s28
	s_nop 0
	global_load_lds_dwordx4 v[214:215], off
	s_barrier
	s_waitcnt lgkmcnt(0)
	s_waitcnt lgkmcnt(0)
	v_mfma_f32_16x16x32_bf16 v[62:65], v[162:165], v[146:149], v[62:65]
	v_mfma_f32_16x16x32_bf16 v[58:61], v[162:165], v[154:157], v[58:61]
	v_mfma_f32_16x16x32_bf16 v[54:57], v[174:177], v[146:149], v[54:57]
	v_mfma_f32_16x16x32_bf16 v[50:53], v[174:177], v[154:157], v[50:53]
	v_mfma_f32_16x16x32_bf16 v[46:49], v[182:185], v[146:149], v[46:49]
	v_mfma_f32_16x16x32_bf16 v[42:45], v[182:185], v[154:157], v[42:45]
	v_mfma_f32_16x16x32_bf16 v[38:41], v[190:193], v[146:149], v[38:41]
	v_mfma_f32_16x16x32_bf16 v[34:37], v[190:193], v[154:157], v[34:37]
	v_mfma_f32_16x16x32_bf16 v[62:65], v[166:169], v[150:153], v[62:65]
	v_mfma_f32_16x16x32_bf16 v[58:61], v[166:169], v[158:161], v[58:61]
	v_mfma_f32_16x16x32_bf16 v[54:57], v[178:181], v[150:153], v[54:57]
	v_mfma_f32_16x16x32_bf16 v[50:53], v[178:181], v[158:161], v[50:53]
	v_mfma_f32_16x16x32_bf16 v[46:49], v[186:189], v[150:153], v[46:49]
	v_mfma_f32_16x16x32_bf16 v[42:45], v[186:189], v[158:161], v[42:45]
	v_mfma_f32_16x16x32_bf16 v[38:41], v[194:197], v[150:153], v[38:41]
	v_mfma_f32_16x16x32_bf16 v[34:37], v[194:197], v[158:161], v[34:37]
	s_barrier
	v_add_u32_e32 v148, s50, v141
	v_lshl_add_u64 v[146:147], v[226:227], 0, s[12:13]
	v_readfirstlane_b32 s28, v148
	v_add_u32_e32 v148, 0x2000, v148
	s_mov_b32 m0, s28
	v_readfirstlane_b32 s28, v148
	global_load_lds_dwordx4 v[146:147], off
	v_lshl_add_u64 v[146:147], v[228:229], 0, s[12:13]
	s_mov_b32 m0, s28
	s_nop 0
	global_load_lds_dwordx4 v[146:147], off
	s_waitcnt vmcnt(10)
	s_barrier
	v_mfma_f32_16x16x32_bf16 v[30:33], v[162:165], v[198:201], v[30:33]
	v_mfma_f32_16x16x32_bf16 v[26:29], v[162:165], v[206:209], v[26:29]
	v_mfma_f32_16x16x32_bf16 v[22:25], v[174:177], v[198:201], v[22:25]
	v_mfma_f32_16x16x32_bf16 v[18:21], v[174:177], v[206:209], v[18:21]
	v_mfma_f32_16x16x32_bf16 v[14:17], v[182:185], v[198:201], v[14:17]
	v_mfma_f32_16x16x32_bf16 v[10:13], v[182:185], v[206:209], v[10:13]
	v_mfma_f32_16x16x32_bf16 v[6:9], v[190:193], v[198:201], v[6:9]
	v_mfma_f32_16x16x32_bf16 v[2:5], v[190:193], v[206:209], v[2:5]
	v_mfma_f32_16x16x32_bf16 v[30:33], v[166:169], v[202:205], v[30:33]
	v_mfma_f32_16x16x32_bf16 v[26:29], v[166:169], v[210:213], v[26:29]
	v_mfma_f32_16x16x32_bf16 v[22:25], v[178:181], v[202:205], v[22:25]
	v_mfma_f32_16x16x32_bf16 v[18:21], v[178:181], v[210:213], v[18:21]
	v_mfma_f32_16x16x32_bf16 v[14:17], v[186:189], v[202:205], v[14:17]
	v_mfma_f32_16x16x32_bf16 v[10:13], v[186:189], v[210:213], v[10:13]
	v_mfma_f32_16x16x32_bf16 v[6:9], v[194:197], v[202:205], v[6:9]
	v_mfma_f32_16x16x32_bf16 v[2:5], v[194:197], v[210:213], v[2:5]
	s_add_i32 s17, s17, 2
	s_cmp_lt_u32 s17, 4
	s_barrier
	s_cbranch_scc1 .LBB0_715
	s_branch .Lpeel4_exit

; #define STAGE(P, GP, ktrel) do { const GAS char* _g = (GP) + (ktrel) * (BK * 2); \
;     __builtin_amdgcn_global_load_lds((const GAS unsigned*)(_g + so0), (unsigned*)((char*)(P) + tid_ * 16), 16, 0, 0); \
;     __builtin_amdgcn_global_load_lds((const GAS unsigned*)(_g + so1), (unsigned*)((char*)(P) + tid_ * 16 + 8192), 16, 0, 0); } while (0)
; #define WAIT_V(n) asm volatile("s_waitcnt vmcnt(" #n ")" ::: "memory")
; #define WAIT_L(n) asm volatile("s_waitcnt lgkmcnt(" #n ")" ::: "memory")
; #define BAR __builtin_amdgcn_s_barrier()
; #define LDA(dst, b, h) for (int m = 0; m < 4; ++m) for (int k = 0; k < 2; ++k) \
;     dst[m][k] = *reinterpret_cast<const bf16x8*>((char*)SA(b, h) + lds_byte(wr * 64 + m * 16 + fr, k * 32 + fq * 8))
; #define LDB(dst, b, h) for (int n = 0; n < 2; ++n) for (int k = 0; k < 2; ++k) \
;     dst[n][k] = *reinterpret_cast<const bf16x8*>((char*)SB(b, h) + lds_byte(wc * 32 + n * 16 + fr, k * 32 + fq * 8))
; #define MMA(ai, bj, At_, Bt_) do { __builtin_amdgcn_s_setprio(1); \
;     for (int m = 0; m < 4; ++m) for (int n = 0; n < 2; ++n) for (int k = 0; k < 2; ++k) \
;       acc[ai][bj][m][n] = __builtin_amdgcn_mfma_f32_16x16x32_bf16(At_[m][k], Bt_[n][k], acc[ai][bj][m][n], 0, 0, 0); \
;     __builtin_amdgcn_s_setprio(0); } while (0)
; template <int K, int LD = K>
; __device__ __forceinline__ void gemm_main(const GAS bf16* A, const GAS bf16* Bt, int brow, int bcol, f32x4 (&acc)[2][2][4][2]) {
;     ...
;   { LDB(B0, 0, 0); LDA(At, 0, 0); STAGE(SA(1, 1), pA1, 1);
;     BAR; WAIT_L(0); MMA(0, 0, At, B0); BAR;
;     LDB(B1, 0, 1); BAR; WAIT_L(0); MMA(0, 1, At, B1); BAR;
;     LDA(At, 0, 1); WAIT_V(4); BAR; WAIT_L(0); MMA(1, 0, At, B0); MMA(1, 1, At, B1); BAR; }
.Lpeel4_exit:
	v_lshl_add_u64 v[198:199], s[20:21], 0, v[130:131]
	v_readfirstlane_b32 s17, v144
	v_lshl_add_u64 v[198:199], v[198:199], 0, s[6:7]
	s_mov_b32 m0, s17
	v_lshl_add_u64 v[132:133], s[20:21], 0, v[132:133]
	v_readfirstlane_b32 s17, v145
	ds_read_b128 v[146:149], v143
	ds_read_b128 v[150:153], v143 offset:1024
	ds_read_b128 v[154:157], v143 offset:2048
	ds_read_b128 v[158:161], v143 offset:3072
	ds_read_b128 v[162:165], v138
	ds_read_b128 v[166:169], v138 offset:1024
	ds_read_b128 v[174:177], v137
	ds_read_b128 v[178:181], v137 offset:1024
	ds_read_b128 v[182:185], v136
	ds_read_b128 v[186:189], v136 offset:1024
	ds_read_b128 v[190:193], v135
	ds_read_b128 v[194:197], v135 offset:1024
	global_load_lds_dwordx4 v[198:199], off
	v_lshl_add_u64 v[132:133], v[132:133], 0, s[6:7]
	s_mov_b32 m0, s17
	s_nop 0
	global_load_lds_dwordx4 v[132:133], off
	s_waitcnt vmcnt(10)
	s_barrier
	s_waitcnt lgkmcnt(0)
	s_waitcnt lgkmcnt(0)
	v_mfma_f32_16x16x32_bf16 v[126:129], v[162:165], v[146:149], v[126:129]
	v_mfma_f32_16x16x32_bf16 v[122:125], v[162:165], v[154:157], v[122:125]
	v_mfma_f32_16x16x32_bf16 v[110:113], v[182:185], v[146:149], v[110:113]
	v_mfma_f32_16x16x32_bf16 v[106:109], v[182:185], v[154:157], v[106:109]
	v_mfma_f32_16x16x32_bf16 v[126:129], v[166:169], v[150:153], v[126:129]
	v_mfma_f32_16x16x32_bf16 v[122:125], v[166:169], v[158:161], v[122:125]
	v_mfma_f32_16x16x32_bf16 v[118:121], v[174:177], v[146:149], v[118:121]
	v_mfma_f32_16x16x32_bf16 v[114:117], v[174:177], v[154:157], v[114:117]
	v_mfma_f32_16x16x32_bf16 v[110:113], v[186:189], v[150:153], v[110:113]
	v_mfma_f32_16x16x32_bf16 v[106:109], v[186:189], v[158:161], v[106:109]
	v_mfma_f32_16x16x32_bf16 v[102:105], v[190:193], v[146:149], v[102:105]
	v_mfma_f32_16x16x32_bf16 v[98:101], v[190:193], v[154:157], v[98:101]
	v_mfma_f32_16x16x32_bf16 v[198:201], v[178:181], v[150:153], v[118:121]
	v_mfma_f32_16x16x32_bf16 v[202:205], v[178:181], v[158:161], v[114:117]
	v_mfma_f32_16x16x32_bf16 v[206:209], v[194:197], v[150:153], v[102:105]
	v_mfma_f32_16x16x32_bf16 v[210:213], v[194:197], v[158:161], v[98:101]
	s_barrier
	s_nop 1
	ds_read_b128 v[98:101], v142
	ds_read_b128 v[102:105], v142 offset:1024
	ds_read_b128 v[114:117], v142 offset:2048
	ds_read_b128 v[118:121], v142 offset:3072
	s_waitcnt vmcnt(8)
	s_barrier
	s_waitcnt lgkmcnt(0)
	s_waitcnt lgkmcnt(0)
	v_mfma_f32_16x16x32_bf16 v[94:97], v[162:165], v[98:101], v[94:97]
	v_mfma_f32_16x16x32_bf16 v[90:93], v[162:165], v[114:117], v[90:93]
	v_mfma_f32_16x16x32_bf16 v[78:81], v[182:185], v[98:101], v[78:81]
	v_mfma_f32_16x16x32_bf16 v[74:77], v[182:185], v[114:117], v[74:77]
	v_mfma_f32_16x16x32_bf16 v[94:97], v[166:169], v[102:105], v[94:97]
	v_mfma_f32_16x16x32_bf16 v[90:93], v[166:169], v[118:121], v[90:93]
	v_mfma_f32_16x16x32_bf16 v[86:89], v[174:177], v[98:101], v[86:89]
	v_mfma_f32_16x16x32_bf16 v[82:85], v[174:177], v[114:117], v[82:85]
	v_mfma_f32_16x16x32_bf16 v[78:81], v[186:189], v[102:105], v[78:81]
	v_mfma_f32_16x16x32_bf16 v[74:77], v[186:189], v[118:121], v[74:77]
	v_mfma_f32_16x16x32_bf16 v[70:73], v[190:193], v[98:101], v[70:73]
	v_mfma_f32_16x16x32_bf16 v[66:69], v[190:193], v[114:117], v[66:69]
	v_mfma_f32_16x16x32_bf16 v[142:145], v[178:181], v[102:105], v[86:89]
	v_mfma_f32_16x16x32_bf16 v[162:165], v[178:181], v[118:121], v[82:85]
	v_mfma_f32_16x16x32_bf16 v[166:169], v[194:197], v[102:105], v[70:73]
	v_mfma_f32_16x16x32_bf16 v[174:177], v[194:197], v[118:121], v[66:69]
	s_barrier
	s_nop 1
	ds_read_b128 v[66:69], v138 offset:16384
	ds_read_b128 v[70:73], v138 offset:17408
	ds_read_b128 v[82:85], v137 offset:16384
	ds_read_b128 v[86:89], v137 offset:17408
	ds_read_b128 v[178:181], v136 offset:16384
	ds_read_b128 v[182:185], v136 offset:17408
	ds_read_b128 v[186:189], v135 offset:16384
	ds_read_b128 v[190:193], v135 offset:17408
	s_waitcnt vmcnt(4)
	s_barrier
	s_waitcnt lgkmcnt(0)
	s_waitcnt lgkmcnt(0)
	v_mfma_f32_16x16x32_bf16 v[62:65], v[66:69], v[146:149], v[62:65]
	v_mfma_f32_16x16x32_bf16 v[54:57], v[82:85], v[146:149], v[54:57]
	v_mfma_f32_16x16x32_bf16 v[46:49], v[178:181], v[146:149], v[46:49]
	v_mfma_f32_16x16x32_bf16 v[38:41], v[186:189], v[146:149], v[38:41]
	v_mfma_f32_16x16x32_bf16 v[62:65], v[70:73], v[150:153], v[62:65]
	v_mfma_f32_16x16x32_bf16 v[58:61], v[66:69], v[154:157], v[58:61]
	v_mfma_f32_16x16x32_bf16 v[54:57], v[86:89], v[150:153], v[54:57]
	v_mfma_f32_16x16x32_bf16 v[50:53], v[82:85], v[154:157], v[50:53]
	v_mfma_f32_16x16x32_bf16 v[46:49], v[182:185], v[150:153], v[46:49]
	v_mfma_f32_16x16x32_bf16 v[42:45], v[178:181], v[154:157], v[42:45]
	v_mfma_f32_16x16x32_bf16 v[38:41], v[190:193], v[150:153], v[38:41]
	v_mfma_f32_16x16x32_bf16 v[34:37], v[186:189], v[154:157], v[34:37]
	v_mfma_f32_16x16x32_bf16 v[194:197], v[70:73], v[158:161], v[58:61]
	v_mfma_f32_16x16x32_bf16 v[214:217], v[86:89], v[158:161], v[50:53]
	v_mfma_f32_16x16x32_bf16 v[218:221], v[182:185], v[158:161], v[42:45]
	v_mfma_f32_16x16x32_bf16 v[146:149], v[190:193], v[158:161], v[34:37]
	v_mfma_f32_16x16x32_bf16 v[30:33], v[66:69], v[98:101], v[30:33]
	v_mfma_f32_16x16x32_bf16 v[22:25], v[82:85], v[98:101], v[22:25]
	v_mfma_f32_16x16x32_bf16 v[14:17], v[178:181], v[98:101], v[14:17]
	v_mfma_f32_16x16x32_bf16 v[6:9], v[186:189], v[98:101], v[6:9]
	v_mfma_f32_16x16x32_bf16 v[30:33], v[70:73], v[102:105], v[30:33]
	v_mfma_f32_16x16x32_bf16 v[26:29], v[66:69], v[114:117], v[26:29]
	v_mfma_f32_16x16x32_bf16 v[22:25], v[86:89], v[102:105], v[22:25]
	v_mfma_f32_16x16x32_bf16 v[18:21], v[82:85], v[114:117], v[18:21]
	v_mfma_f32_16x16x32_bf16 v[14:17], v[182:185], v[102:105], v[14:17]
	v_mfma_f32_16x16x32_bf16 v[10:13], v[178:181], v[114:117], v[10:13]
	v_mfma_f32_16x16x32_bf16 v[6:9], v[190:193], v[102:105], v[6:9]
	v_mfma_f32_16x16x32_bf16 v[2:5], v[186:189], v[114:117], v[2:5]
	v_mfma_f32_16x16x32_bf16 v[150:153], v[70:73], v[118:121], v[26:29]
	v_mfma_f32_16x16x32_bf16 v[154:157], v[86:89], v[118:121], v[18:21]
	v_mfma_f32_16x16x32_bf16 v[158:161], v[182:185], v[118:121], v[10:13]
	v_mfma_f32_16x16x32_bf16 v[178:181], v[190:193], v[118:121], v[2:5]
	s_barrier
; #define WAIT_V(n) asm volatile("s_waitcnt vmcnt(" #n ")" ::: "memory")
; #define WAIT_L(n) asm volatile("s_waitcnt lgkmcnt(" #n ")" ::: "memory")
; #define BAR __builtin_amdgcn_s_barrier()
; #define LDA(dst, b, h) for (int m = 0; m < 4; ++m) for (int k = 0; k < 2; ++k) \
;     dst[m][k] = *reinterpret_cast<const bf16x8*>((char*)SA(b, h) + lds_byte(wr * 64 + m * 16 + fr, k * 32 + fq * 8))
; #define LDB(dst, b, h) for (int n = 0; n < 2; ++n) for (int k = 0; k < 2; ++k) \
;     dst[n][k] = *reinterpret_cast<const bf16x8*>((char*)SB(b, h) + lds_byte(wc * 32 + n * 16 + fr, k * 32 + fq * 8))
; #define MMA(ai, bj, At_, Bt_) do { __builtin_amdgcn_s_setprio(1); \
;     for (int m = 0; m < 4; ++m) for (int n = 0; n < 2; ++n) for (int k = 0; k < 2; ++k) \
;       acc[ai][bj][m][n] = __builtin_amdgcn_mfma_f32_16x16x32_bf16(At_[m][k], Bt_[n][k], acc[ai][bj][m][n], 0, 0, 0); \
;     __builtin_amdgcn_s_setprio(0); } while (0)
; template <int K, int LD = K>
; __device__ __forceinline__ void gemm_main(const GAS bf16* A, const GAS bf16* Bt, int brow, int bcol, f32x4 (&acc)[2][2][4][2]) {
;     ...
;   { LDB(B0, 1, 0); LDA(At, 1, 0); WAIT_V(2); BAR; WAIT_L(0); MMA(0, 0, At, B0); BAR;
;     LDB(B1, 1, 1); WAIT_V(0); BAR; WAIT_L(0); MMA(0, 1, At, B1); BAR;
;     LDA(At, 1, 1); BAR; WAIT_L(0); MMA(1, 0, At, B0); MMA(1, 1, At, B1); BAR; }
;   if (wr == 0) BAR;
	s_nop 1
	ds_read_b128 v[2:5], v140
	ds_read_b128 v[10:13], v140 offset:1024
	ds_read_b128 v[182:185], v140 offset:2048
	ds_read_b128 v[186:189], v140 offset:3072
	ds_read_b128 v[18:21], v138 offset:32768
	ds_read_b128 v[26:29], v138 offset:33792
	ds_read_b128 v[34:37], v137 offset:32768
	ds_read_b128 v[42:45], v137 offset:33792
	ds_read_b128 v[50:53], v136 offset:32768
	ds_read_b128 v[58:61], v136 offset:33792
	ds_read_b128 v[190:193], v135 offset:32768
	ds_read_b128 v[222:225], v135 offset:33792
	s_waitcnt vmcnt(2)
	s_barrier
	s_waitcnt lgkmcnt(0)
	s_waitcnt lgkmcnt(0)
	v_mfma_f32_16x16x32_bf16 v[66:69], v[18:21], v[2:5], v[126:129]
	v_mfma_f32_16x16x32_bf16 v[118:121], v[26:29], v[10:13], v[66:69]
	v_mfma_f32_16x16x32_bf16 v[66:69], v[18:21], v[182:185], v[122:125]
	v_mfma_f32_16x16x32_bf16 v[114:117], v[26:29], v[186:189], v[66:69]
	v_mfma_f32_16x16x32_bf16 v[66:69], v[34:37], v[2:5], v[198:201]
	v_mfma_f32_16x16x32_bf16 v[102:105], v[42:45], v[10:13], v[66:69]
	v_mfma_f32_16x16x32_bf16 v[66:69], v[34:37], v[182:185], v[202:205]
	v_mfma_f32_16x16x32_bf16 v[98:101], v[42:45], v[186:189], v[66:69]
	v_mfma_f32_16x16x32_bf16 v[66:69], v[50:53], v[2:5], v[110:113]
	v_mfma_f32_16x16x32_bf16 v[86:89], v[58:61], v[10:13], v[66:69]
	v_mfma_f32_16x16x32_bf16 v[66:69], v[50:53], v[182:185], v[106:109]
	v_mfma_f32_16x16x32_bf16 v[82:85], v[58:61], v[186:189], v[66:69]
	v_mfma_f32_16x16x32_bf16 v[66:69], v[190:193], v[2:5], v[206:209]
	v_mfma_f32_16x16x32_bf16 v[70:73], v[222:225], v[10:13], v[66:69]
	v_mfma_f32_16x16x32_bf16 v[66:69], v[190:193], v[182:185], v[210:213]
	v_mfma_f32_16x16x32_bf16 v[66:69], v[222:225], v[186:189], v[66:69]
	s_barrier
	ds_read_b128 v[198:201], v139
	ds_read_b128 v[202:205], v139 offset:1024
	ds_read_b128 v[206:209], v139 offset:2048
	ds_read_b128 v[210:213], v139 offset:3072
	s_waitcnt vmcnt(0)
	s_barrier
	s_waitcnt lgkmcnt(0)
	s_waitcnt lgkmcnt(0)
	v_mfma_f32_16x16x32_bf16 v[94:97], v[18:21], v[198:201], v[94:97]
	v_mfma_f32_16x16x32_bf16 v[18:21], v[18:21], v[206:209], v[90:93]
	v_mfma_f32_16x16x32_bf16 v[122:125], v[26:29], v[210:213], v[18:21]
	v_mfma_f32_16x16x32_bf16 v[18:21], v[34:37], v[198:201], v[142:145]
	v_mfma_f32_16x16x32_bf16 v[110:113], v[42:45], v[202:205], v[18:21]
	v_mfma_f32_16x16x32_bf16 v[18:21], v[34:37], v[206:209], v[162:165]
	v_mfma_f32_16x16x32_bf16 v[106:109], v[42:45], v[210:213], v[18:21]
	v_mfma_f32_16x16x32_bf16 v[18:21], v[50:53], v[198:201], v[78:81]
	v_mfma_f32_16x16x32_bf16 v[126:129], v[26:29], v[202:205], v[94:97]
	v_mfma_f32_16x16x32_bf16 v[94:97], v[58:61], v[202:205], v[18:21]
	v_mfma_f32_16x16x32_bf16 v[18:21], v[50:53], v[206:209], v[74:77]
	v_mfma_f32_16x16x32_bf16 v[90:93], v[58:61], v[210:213], v[18:21]
	v_mfma_f32_16x16x32_bf16 v[18:21], v[190:193], v[198:201], v[166:169]
	v_mfma_f32_16x16x32_bf16 v[78:81], v[222:225], v[202:205], v[18:21]
	v_mfma_f32_16x16x32_bf16 v[18:21], v[190:193], v[206:209], v[174:177]
	v_mfma_f32_16x16x32_bf16 v[74:77], v[222:225], v[210:213], v[18:21]
	s_barrier
	ds_read_b128 v[140:143], v138 offset:49152
	ds_read_b128 v[162:165], v138 offset:50176
	ds_read_b128 v[166:169], v137 offset:49152
	ds_read_b128 v[174:177], v137 offset:50176
	ds_read_b128 v[190:193], v136 offset:49152
	ds_read_b128 v[136:139], v136 offset:50176
	ds_read_b128 v[222:225], v135 offset:49152
	ds_read_b128 v[226:229], v135 offset:50176
	s_barrier
	s_waitcnt lgkmcnt(0)
	s_waitcnt lgkmcnt(0)
	v_mfma_f32_16x16x32_bf16 v[18:21], v[140:143], v[2:5], v[62:65]
	v_mfma_f32_16x16x32_bf16 v[58:61], v[162:165], v[10:13], v[18:21]
	v_mfma_f32_16x16x32_bf16 v[18:21], v[140:143], v[182:185], v[194:197]
	v_mfma_f32_16x16x32_bf16 v[50:53], v[162:165], v[186:189], v[18:21]
	v_mfma_f32_16x16x32_bf16 v[18:21], v[166:169], v[2:5], v[54:57]
	v_mfma_f32_16x16x32_bf16 v[42:45], v[174:177], v[10:13], v[18:21]
	v_mfma_f32_16x16x32_bf16 v[18:21], v[166:169], v[182:185], v[214:217]
	v_mfma_f32_16x16x32_bf16 v[34:37], v[174:177], v[186:189], v[18:21]
	v_mfma_f32_16x16x32_bf16 v[18:21], v[190:193], v[2:5], v[46:49]
	v_mfma_f32_16x16x32_bf16 v[2:5], v[222:225], v[2:5], v[38:41]
	v_mfma_f32_16x16x32_bf16 v[26:29], v[136:139], v[10:13], v[18:21]
	v_mfma_f32_16x16x32_bf16 v[18:21], v[190:193], v[182:185], v[218:221]
	v_mfma_f32_16x16x32_bf16 v[10:13], v[226:229], v[10:13], v[2:5]
	v_mfma_f32_16x16x32_bf16 v[2:5], v[222:225], v[182:185], v[146:149]
	v_mfma_f32_16x16x32_bf16 v[18:21], v[136:139], v[186:189], v[18:21]
	v_mfma_f32_16x16x32_bf16 v[2:5], v[226:229], v[186:189], v[2:5]
	v_mfma_f32_16x16x32_bf16 v[30:33], v[140:143], v[198:201], v[30:33]
	v_mfma_f32_16x16x32_bf16 v[62:65], v[162:165], v[202:205], v[30:33]
	v_mfma_f32_16x16x32_bf16 v[30:33], v[140:143], v[206:209], v[150:153]
	v_mfma_f32_16x16x32_bf16 v[22:25], v[166:169], v[198:201], v[22:25]
	v_mfma_f32_16x16x32_bf16 v[14:17], v[190:193], v[198:201], v[14:17]
	v_mfma_f32_16x16x32_bf16 v[54:57], v[162:165], v[210:213], v[30:33]
	v_mfma_f32_16x16x32_bf16 v[46:49], v[174:177], v[202:205], v[22:25]
	v_mfma_f32_16x16x32_bf16 v[22:25], v[166:169], v[206:209], v[154:157]
	v_mfma_f32_16x16x32_bf16 v[30:33], v[136:139], v[202:205], v[14:17]
	v_mfma_f32_16x16x32_bf16 v[14:17], v[190:193], v[206:209], v[158:161]
	v_mfma_f32_16x16x32_bf16 v[6:9], v[222:225], v[198:201], v[6:9]
	v_mfma_f32_16x16x32_bf16 v[38:41], v[174:177], v[210:213], v[22:25]
	v_mfma_f32_16x16x32_bf16 v[22:25], v[136:139], v[210:213], v[14:17]
	v_mfma_f32_16x16x32_bf16 v[14:17], v[226:229], v[202:205], v[6:9]
	v_mfma_f32_16x16x32_bf16 v[6:9], v[222:225], v[206:209], v[178:181]
	v_mfma_f32_16x16x32_bf16 v[6:9], v[226:229], v[210:213], v[6:9]
	v_cmp_gt_u32_e32 vcc, s51, v134
	s_barrier
	s_and_saveexec_b64 s[20:21], vcc
	s_cbranch_execz .LBB0_718
	s_barrier

; #define GAS __attribute__((address_space(1)))
; __device__ __forceinline__ int otid() { int t = threadIdx.x; asm volatile("" : "+v"(t)); return t; }
; #define STAGE(P, GP, ktrel) do { const GAS char* _g = (GP) + (ktrel) * (BK * 2); \
;     __builtin_amdgcn_global_load_lds((const GAS unsigned*)(_g + so0), (unsigned*)((char*)(P) + tid_ * 16), 16, 0, 0); \
;     __builtin_amdgcn_global_load_lds((const GAS unsigned*)(_g + so1), (unsigned*)((char*)(P) + tid_ * 16 + 8192), 16, 0, 0); } while (0)
; #define WAIT_V(n) asm volatile("s_waitcnt vmcnt(" #n ")" ::: "memory")
; #define WAIT_L(n) asm volatile("s_waitcnt lgkmcnt(" #n ")" ::: "memory")
; #define BAR __builtin_amdgcn_s_barrier()
; #define SCHED __builtin_amdgcn_sched_barrier(0)
; #define LDA(dst, b, h) for (int m = 0; m < 4; ++m) for (int k = 0; k < 2; ++k) \
;     dst[m][k] = *reinterpret_cast<const bf16x8*>((char*)SA(b, h) + lds_byte(wr * 64 + m * 16 + fr, k * 32 + fq * 8))
; template <int K, int LD = K>
; __device__ __forceinline__ void gemm_main(const GAS bf16* A, const GAS bf16* Bt, int brow, int bcol, f32x4 (&acc)[2][2][4][2]) {
;     ...
;   const int tid_ = otid();
;     ...
;   const int wid = tid_ >> 6, lane = tid_ & 63, wr = wid >> 2, wc = wid & 3, fr = lane & 15, fq = lane >> 4;
; #pragma unroll
;   for (int a = 0; a < 2; ++a)
; #pragma unroll
;     for (int b = 0; b < 2; ++b)
; #pragma unroll
;       for (int m = 0; m < 4; ++m)
; #pragma unroll
;         for (int n = 0; n < 2; ++n) acc[a][b][m][n] = f32x4{0.f, 0.f, 0.f, 0.f};
;   bf16x8 At[4][2], B0[2][2], B1[2][2];
;   unsigned so0, so1;
;   { int r_, c_; stage_rc(tid_ * 16, r_, c_); so0 = (unsigned)(r_ * LD + c_) * 2u; stage_rc(tid_ * 16 + 8192, r_, c_); so1 = (unsigned)(r_ * LD + c_) * 2u; }
;   const GAS char* pA0 = (const GAS char*)A + (long)brow * LD * 2; const GAS char* pA1 = pA0 + (long)HALF * LD * 2;
;   const GAS char* pB0 = (const GAS char*)Bt + (long)bcol * LD * 2; const GAS char* pB1 = pB0 + (long)HALF * LD * 2;
;   asm volatile("" : "+s"(pA0), "+s"(pA1), "+s"(pB0), "+s"(pB1));
;   constexpr int nt = K / BK;
;   static_assert(K % 128 == 0 && K >= 256, "K");
;   if (wr == 1) BAR;
;   WAIT_V(0); BAR;
;   BAR;
;   for (int t = 0; t < nt - 2; t += 2) {
;     LDB(B0, 0, 0); SCHED; LDA(At, 0, 0); STAGE(SA(1, 1), pA1, 1);
;     WAIT_L(8); BAR; WAIT_L(0); MMA(0, 0, At, B0); BAR; SCHED;
;     LDB(B1, 0, 1); STAGE(SB(0, 0), pB0, 2);
.LBB0_766:
	s_or_b64 exec, exec, s[22:23]
	v_bfe_i32 v7, v134, 27, 1
	v_lshlrev_b32_e32 v5, 4, v134
	v_lshrrev_b32_e32 v7, 22, v7
	v_add_u32_e32 v7, v5, v7
	v_and_b32_e32 v7, 0xfffffc00, v7
	v_sub_u32_e32 v7, v5, v7
	v_lshrrev_b32_e32 v8, 4, v7
	v_bitop3_b32 v8, v8, v7, 32 bitop3:0x6c
	v_ashrrev_i32_e32 v7, 31, v7
	v_ashrrev_i32_e32 v6, 31, v134
	v_lshrrev_b32_e32 v7, 26, v7
	v_lshrrev_b32_e32 v6, 26, v6
	v_add_u32_e32 v7, v8, v7
	v_add_u32_e32 v6, v134, v6
	v_ashrrev_i32_e32 v7, 6, v7
	v_ashrrev_i32_e32 v6, 6, v6
	v_mul_i32_i24_e32 v10, 64, v7
	v_lshlrev_b32_e32 v9, 3, v6
	v_lshlrev_b32_e32 v6, 5, v6
	v_sub_u32_e32 v8, v8, v10
	v_and_b32_e32 v9, 0x1ffff0, v9
	v_and_b32_e32 v6, 32, v6
	v_ashrrev_i16_sdwa v8, v1, sext(v8) dst_sel:DWORD dst_unused:UNUSED_PAD src0_sel:DWORD src1_sel:BYTE_0
	v_add_u32_sdwa v6, v6, sext(v8) dst_sel:DWORD dst_unused:UNUSED_PAD src0_sel:DWORD src1_sel:WORD_0
	v_add_lshl_u32 v7, v7, v9, 11
	v_lshl_add_u32 v130, v6, 1, v7
	v_add_u32_e32 v6, 0x2000, v5
	v_ashrrev_i32_e32 v7, 31, v6
	v_lshrrev_b32_e32 v7, 22, v7
	v_add_u32_e32 v7, v6, v7
	v_ashrrev_i32_e32 v7, 10, v7
	v_mul_i32_i24_e32 v8, 0x400, v7
	v_sub_u32_e32 v6, v6, v8
	v_lshrrev_b32_e32 v8, 4, v6
	v_bitop3_b32 v6, v8, v6, 32 bitop3:0x6c
	v_ashrrev_i32_e32 v9, 31, v6
	v_lshrrev_b32_e32 v9, 26, v9
	v_add_u32_e32 v9, v6, v9
	v_lshrrev_b32_e32 v10, 6, v9
	v_and_b32_e32 v9, 0xc0, v9
	v_lshlrev_b32_e32 v8, 3, v7
	v_lshlrev_b32_e32 v7, 5, v7
	v_sub_u32_e32 v6, v6, v9
	v_and_b32_e32 v8, 0x1ffff0, v8
	v_and_b32_e32 v7, 32, v7
	v_ashrrev_i16_sdwa v6, v1, sext(v6) dst_sel:DWORD dst_unused:UNUSED_PAD src0_sel:DWORD src1_sel:BYTE_0
	v_add_u32_sdwa v6, v7, sext(v6) dst_sel:DWORD dst_unused:UNUSED_PAD src0_sel:DWORD src1_sel:WORD_0
	v_add_lshl_u32 v7, v10, v8, 11
	v_and_b32_e32 v3, 15, v134
	v_lshl_add_u32 v132, v6, 1, v7
	v_lshlrev_b32_e32 v6, 2, v134
	v_and_b32_e32 v4, 48, v134
	v_lshlrev_b32_e32 v3, 6, v3
	v_and_b32_e32 v6, 32, v6
	v_lshlrev_b32_e32 v11, 6, v134
	v_bitop3_b32 v3, v3, v6, v4 bitop3:0x36
	v_lshlrev_b32_e32 v13, 13, v2
	v_and_or_b32 v2, v11, s39, v4
	v_add_u32_e32 v7, s35, v3
	v_add_u32_e32 v8, s36, v3
	v_add_u32_e32 v9, s37, v3
	v_add_u32_e32 v10, s38, v3
	v_and_b32_e32 v12, 0x3000, v11
	v_add_u32_e32 v3, 0x100, v3
	v_xad_u32 v4, v2, v6, s34
	v_or_b32_e32 v6, 0x800, v13
	v_or_b32_e32 v11, 0x1000, v13
	v_or_b32_e32 v14, 0x1800, v13
	v_mov_b32_e32 v2, 0
	v_add_u32_e32 v145, 0x100, v5
	v_add_u32_e32 v151, s35, v5
	v_add_u32_e32 v153, s36, v5
	v_add_u32_e32 v155, s37, v5
	v_add_u32_e32 v157, s38, v5
	v_mov_b32_e32 v133, v131
	s_mov_b32 s15, -2
	v_add_u32_e32 v144, v7, v12
	v_add_u32_e32 v138, v3, v13
	v_add_u32_e32 v137, v4, v6
	v_add_u32_e32 v136, v4, v11
	v_add_u32_e32 v135, v4, v14
	v_add_u32_e32 v143, 0xc000, v145
	v_add_u32_e32 v142, 0xe000, v145
	v_add_u32_e32 v141, v8, v12
	v_add_u32_e32 v146, 0x2000, v145
	v_add_u32_e32 v140, v9, v12
	v_add_u32_e32 v147, 0x4000, v145
	v_add_u32_e32 v148, 0x6000, v145
	v_add_u32_e32 v139, v10, v12
	v_add_u32_e32 v149, 0x8000, v145
	v_add_u32_e32 v150, 0xa000, v145
	v_add_u32_e32 v152, 0x2000, v151
	v_add_u32_e32 v154, 0x2000, v153
	v_add_u32_e32 v156, 0x2000, v155
	v_add_u32_e32 v158, 0x2000, v157
	s_waitcnt vmcnt(0)
	s_barrier
	s_barrier
	ds_read_b128 v[160:163], v144
	ds_read_b128 v[164:167], v144 offset:1024
	ds_read_b128 v[174:177], v144 offset:2048
	ds_read_b128 v[178:181], v144 offset:3072
	v_lshl_add_u64 v[168:169], s[10:11], 0, v[130:131]
	v_readfirstlane_b32 s22, v143
	v_lshl_add_u64 v[214:215], v[168:169], 0, s[4:5]
	s_mov_b32 m0, s22
	v_lshl_add_u64 v[230:231], s[10:11], 0, v[132:133]
	v_readfirstlane_b32 s22, v142
	ds_read_b128 v[182:185], v138
	ds_read_b128 v[186:189], v138 offset:1024
	ds_read_b128 v[190:193], v137
	ds_read_b128 v[194:197], v137 offset:1024
	ds_read_b128 v[198:201], v136
	ds_read_b128 v[202:205], v136 offset:1024
	ds_read_b128 v[206:209], v135
	ds_read_b128 v[210:213], v135 offset:1024
	global_load_lds_dwordx4 v[214:215], off
	v_lshl_add_u64 v[214:215], v[230:231], 0, s[4:5]
	s_mov_b32 m0, s22
	s_nop 0
	global_load_lds_dwordx4 v[214:215], off
	s_waitcnt lgkmcnt(8)
	s_waitcnt vmcnt(10)
	s_barrier
	s_waitcnt lgkmcnt(0)
	s_waitcnt lgkmcnt(0)
	v_mfma_f32_16x16x32_bf16 v[126:129], v[182:185], v[160:163], 0
	v_mfma_f32_16x16x32_bf16 v[122:125], v[182:185], v[174:177], 0
	v_mfma_f32_16x16x32_bf16 v[118:121], v[190:193], v[160:163], 0
	v_mfma_f32_16x16x32_bf16 v[114:117], v[190:193], v[174:177], 0
	v_mfma_f32_16x16x32_bf16 v[110:113], v[198:201], v[160:163], 0
	v_mfma_f32_16x16x32_bf16 v[106:109], v[198:201], v[174:177], 0
	v_mfma_f32_16x16x32_bf16 v[102:105], v[206:209], v[160:163], 0
	v_mfma_f32_16x16x32_bf16 v[98:101], v[206:209], v[174:177], 0
	v_mfma_f32_16x16x32_bf16 v[126:129], v[186:189], v[164:167], v[126:129]
	v_mfma_f32_16x16x32_bf16 v[122:125], v[186:189], v[178:181], v[122:125]
	v_mfma_f32_16x16x32_bf16 v[118:121], v[194:197], v[164:167], v[118:121]
	v_mfma_f32_16x16x32_bf16 v[114:117], v[194:197], v[178:181], v[114:117]
	v_mfma_f32_16x16x32_bf16 v[110:113], v[202:205], v[164:167], v[110:113]
	v_mfma_f32_16x16x32_bf16 v[106:109], v[202:205], v[178:181], v[106:109]
	v_mfma_f32_16x16x32_bf16 v[102:105], v[210:213], v[164:167], v[102:105]
	v_mfma_f32_16x16x32_bf16 v[98:101], v[210:213], v[178:181], v[98:101]
	s_barrier
	v_lshl_add_u64 v[232:233], s[20:21], 0, v[130:131]
	v_readfirstlane_b32 s22, v151
	v_lshl_add_u64 v[234:235], v[232:233], 0, s[6:7]
	s_mov_b32 m0, s22
	ds_read_b128 v[214:217], v141
	ds_read_b128 v[218:221], v141 offset:1024
	ds_read_b128 v[222:225], v141 offset:2048
	ds_read_b128 v[226:229], v141 offset:3072
	global_load_lds_dwordx4 v[234:235], off
	v_lshl_add_u64 v[234:235], s[20:21], 0, v[132:133]
	v_readfirstlane_b32 s22, v152
	v_lshl_add_u64 v[236:237], v[234:235], 0, s[6:7]
	s_mov_b32 m0, s22
	s_add_u32 s20, s20, 0x100
	global_load_lds_dwordx4 v[236:237], off
	s_waitcnt vmcnt(10)
	s_barrier
; #define STAGE(P, GP, ktrel) do { const GAS char* _g = (GP) + (ktrel) * (BK * 2); \
;     __builtin_amdgcn_global_load_lds((const GAS unsigned*)(_g + so0), (unsigned*)((char*)(P) + tid_ * 16), 16, 0, 0); \
;     __builtin_amdgcn_global_load_lds((const GAS unsigned*)(_g + so1), (unsigned*)((char*)(P) + tid_ * 16 + 8192), 16, 0, 0); } while (0)
; #define WAIT_V(n) asm volatile("s_waitcnt vmcnt(" #n ")" ::: "memory")
; #define WAIT_L(n) asm volatile("s_waitcnt lgkmcnt(" #n ")" ::: "memory")
; #define BAR __builtin_amdgcn_s_barrier()
; #define SCHED __builtin_amdgcn_sched_barrier(0)
; #define LDA(dst, b, h) for (int m = 0; m < 4; ++m) for (int k = 0; k < 2; ++k) \
;     dst[m][k] = *reinterpret_cast<const bf16x8*>((char*)SA(b, h) + lds_byte(wr * 64 + m * 16 + fr, k * 32 + fq * 8))
; #define LDB(dst, b, h) for (int n = 0; n < 2; ++n) for (int k = 0; k < 2; ++k) \
;     dst[n][k] = *reinterpret_cast<const bf16x8*>((char*)SB(b, h) + lds_byte(wc * 32 + n * 16 + fr, k * 32 + fq * 8))
; #define MMA(ai, bj, At_, Bt_) do { __builtin_amdgcn_s_setprio(1); \
;     for (int m = 0; m < 4; ++m) for (int n = 0; n < 2; ++n) for (int k = 0; k < 2; ++k) \
;       acc[ai][bj][m][n] = __builtin_amdgcn_mfma_f32_16x16x32_bf16(At_[m][k], Bt_[n][k], acc[ai][bj][m][n], 0, 0, 0); \
;     __builtin_amdgcn_s_setprio(0); } while (0)
; template <int K, int LD = K>
; __device__ __forceinline__ void gemm_main(const GAS bf16* A, const GAS bf16* Bt, int brow, int bcol, f32x4 (&acc)[2][2][4][2]) {
;     ...
;     BAR; WAIT_L(0); MMA(0, 1, At, B1); BAR;
;     LDA(At, 0, 1); STAGE(SA(0, 0), pA0, 2);
;     BAR; WAIT_L(0); MMA(1, 0, At, B0); BAR; SCHED;
;     STAGE(SB(0, 1), pB1, 2);
;     WAIT_V(6); BAR; MMA(1, 1, At, B1); BAR;
;     LDB(B0, 1, 0); SCHED; LDA(At, 1, 0); STAGE(SA(0, 1), pA1, 2);
;     WAIT_L(8); BAR; WAIT_L(0); MMA(0, 0, At, B0); BAR; SCHED;
	s_waitcnt lgkmcnt(0)
	s_addc_u32 s21, s21, 0
	s_waitcnt lgkmcnt(0)
	v_mfma_f32_16x16x32_bf16 v[94:97], v[182:185], v[214:217], 0
	v_mfma_f32_16x16x32_bf16 v[90:93], v[182:185], v[222:225], 0
	v_mfma_f32_16x16x32_bf16 v[86:89], v[190:193], v[214:217], 0
	v_mfma_f32_16x16x32_bf16 v[82:85], v[190:193], v[222:225], 0
	v_mfma_f32_16x16x32_bf16 v[78:81], v[198:201], v[214:217], 0
	v_mfma_f32_16x16x32_bf16 v[74:77], v[198:201], v[222:225], 0
	v_mfma_f32_16x16x32_bf16 v[70:73], v[206:209], v[214:217], 0
	v_mfma_f32_16x16x32_bf16 v[66:69], v[206:209], v[222:225], 0
	v_mfma_f32_16x16x32_bf16 v[94:97], v[186:189], v[218:221], v[94:97]
	v_mfma_f32_16x16x32_bf16 v[90:93], v[186:189], v[226:229], v[90:93]
	v_mfma_f32_16x16x32_bf16 v[86:89], v[194:197], v[218:221], v[86:89]
	v_mfma_f32_16x16x32_bf16 v[82:85], v[194:197], v[226:229], v[82:85]
	v_mfma_f32_16x16x32_bf16 v[78:81], v[202:205], v[218:221], v[78:81]
	v_mfma_f32_16x16x32_bf16 v[74:77], v[202:205], v[226:229], v[74:77]
	v_mfma_f32_16x16x32_bf16 v[70:73], v[210:213], v[218:221], v[70:73]
	v_mfma_f32_16x16x32_bf16 v[66:69], v[210:213], v[226:229], v[66:69]
	v_lshl_add_u64 v[236:237], s[18:19], 0, v[130:131]
	v_readfirstlane_b32 s22, v145
	v_lshl_add_u64 v[238:239], v[236:237], 0, s[6:7]
	s_mov_b32 m0, s22
	s_barrier
	ds_read_b128 v[182:185], v138 offset:16384
	ds_read_b128 v[186:189], v138 offset:17408
	ds_read_b128 v[190:193], v137 offset:16384
	ds_read_b128 v[194:197], v137 offset:17408
	ds_read_b128 v[198:201], v136 offset:16384
	ds_read_b128 v[202:205], v136 offset:17408
	ds_read_b128 v[206:209], v135 offset:16384
	ds_read_b128 v[210:213], v135 offset:17408
	global_load_lds_dwordx4 v[238:239], off
	v_lshl_add_u64 v[238:239], s[18:19], 0, v[132:133]
	v_readfirstlane_b32 s22, v146
	v_lshl_add_u64 v[240:241], v[238:239], 0, s[6:7]
	s_mov_b32 m0, s22
	s_add_u32 s18, s18, 0x100
	global_load_lds_dwordx4 v[240:241], off
	s_barrier
	s_waitcnt lgkmcnt(0)
	s_addc_u32 s19, s19, 0
	s_waitcnt lgkmcnt(0)
	v_mfma_f32_16x16x32_bf16 v[62:65], v[182:185], v[160:163], 0
	v_mfma_f32_16x16x32_bf16 v[58:61], v[182:185], v[174:177], 0
	v_mfma_f32_16x16x32_bf16 v[54:57], v[190:193], v[160:163], 0
	v_mfma_f32_16x16x32_bf16 v[50:53], v[190:193], v[174:177], 0
	v_mfma_f32_16x16x32_bf16 v[46:49], v[198:201], v[160:163], 0
	v_mfma_f32_16x16x32_bf16 v[42:45], v[198:201], v[174:177], 0
	v_mfma_f32_16x16x32_bf16 v[38:41], v[206:209], v[160:163], 0
	v_mfma_f32_16x16x32_bf16 v[34:37], v[206:209], v[174:177], 0
	v_mfma_f32_16x16x32_bf16 v[62:65], v[186:189], v[164:167], v[62:65]
	v_mfma_f32_16x16x32_bf16 v[58:61], v[186:189], v[178:181], v[58:61]
	v_mfma_f32_16x16x32_bf16 v[54:57], v[194:197], v[164:167], v[54:57]
	v_mfma_f32_16x16x32_bf16 v[50:53], v[194:197], v[178:181], v[50:53]
	v_mfma_f32_16x16x32_bf16 v[46:49], v[202:205], v[164:167], v[46:49]
	v_mfma_f32_16x16x32_bf16 v[42:45], v[202:205], v[178:181], v[42:45]
	v_mfma_f32_16x16x32_bf16 v[38:41], v[210:213], v[164:167], v[38:41]
	v_mfma_f32_16x16x32_bf16 v[34:37], v[210:213], v[178:181], v[34:37]
	s_barrier
	v_lshl_add_u64 v[240:241], s[16:17], 0, v[130:131]
	v_readfirstlane_b32 s22, v153
	v_lshl_add_u64 v[160:161], v[240:241], 0, s[6:7]
	s_mov_b32 m0, s22
	v_lshl_add_u64 v[242:243], s[16:17], 0, v[132:133]
	v_readfirstlane_b32 s22, v154
	global_load_lds_dwordx4 v[160:161], off
	v_lshl_add_u64 v[160:161], v[242:243], 0, s[6:7]
	s_mov_b32 m0, s22
	s_add_u32 s16, s16, 0x100
	global_load_lds_dwordx4 v[160:161], off
	s_waitcnt vmcnt(10)
	s_addc_u32 s17, s17, 0
	s_barrier
	v_mfma_f32_16x16x32_bf16 v[30:33], v[182:185], v[214:217], 0
	v_mfma_f32_16x16x32_bf16 v[26:29], v[182:185], v[222:225], 0
	v_mfma_f32_16x16x32_bf16 v[22:25], v[190:193], v[214:217], 0
	v_mfma_f32_16x16x32_bf16 v[18:21], v[190:193], v[222:225], 0
	v_mfma_f32_16x16x32_bf16 v[14:17], v[198:201], v[214:217], 0
	v_mfma_f32_16x16x32_bf16 v[10:13], v[198:201], v[222:225], 0
	v_mfma_f32_16x16x32_bf16 v[6:9], v[206:209], v[214:217], 0
	v_mfma_f32_16x16x32_bf16 v[2:5], v[206:209], v[222:225], 0
	v_mfma_f32_16x16x32_bf16 v[30:33], v[186:189], v[218:221], v[30:33]
	v_mfma_f32_16x16x32_bf16 v[26:29], v[186:189], v[226:229], v[26:29]
	v_mfma_f32_16x16x32_bf16 v[22:25], v[194:197], v[218:221], v[22:25]
	v_mfma_f32_16x16x32_bf16 v[18:21], v[194:197], v[226:229], v[18:21]
	v_mfma_f32_16x16x32_bf16 v[14:17], v[202:205], v[218:221], v[14:17]
	v_mfma_f32_16x16x32_bf16 v[10:13], v[202:205], v[226:229], v[10:13]
	v_mfma_f32_16x16x32_bf16 v[6:9], v[210:213], v[218:221], v[6:9]
	v_mfma_f32_16x16x32_bf16 v[2:5], v[210:213], v[226:229], v[2:5]
	s_barrier
	ds_read_b128 v[160:163], v140
	ds_read_b128 v[164:167], v140 offset:1024
	ds_read_b128 v[174:177], v140 offset:2048
	ds_read_b128 v[178:181], v140 offset:3072
	v_readfirstlane_b32 s22, v147
	v_lshl_add_u64 v[168:169], v[168:169], 0, s[6:7]
	s_mov_b32 m0, s22
	v_readfirstlane_b32 s22, v148
	ds_read_b128 v[182:185], v138 offset:32768
	ds_read_b128 v[186:189], v138 offset:33792
	ds_read_b128 v[190:193], v137 offset:32768
	ds_read_b128 v[194:197], v137 offset:33792
	ds_read_b128 v[198:201], v136 offset:32768
	ds_read_b128 v[202:205], v136 offset:33792
	ds_read_b128 v[206:209], v135 offset:32768
	ds_read_b128 v[210:213], v135 offset:33792
	global_load_lds_dwordx4 v[168:169], off
	v_lshl_add_u64 v[168:169], v[230:231], 0, s[6:7]
	s_mov_b32 m0, s22
	s_add_u32 s10, s10, 0x100
	global_load_lds_dwordx4 v[168:169], off
	s_waitcnt lgkmcnt(8)
	s_waitcnt vmcnt(10)
	s_barrier
; #define STAGE(P, GP, ktrel) do { const GAS char* _g = (GP) + (ktrel) * (BK * 2); \
;     __builtin_amdgcn_global_load_lds((const GAS unsigned*)(_g + so0), (unsigned*)((char*)(P) + tid_ * 16), 16, 0, 0); \
;     __builtin_amdgcn_global_load_lds((const GAS unsigned*)(_g + so1), (unsigned*)((char*)(P) + tid_ * 16 + 8192), 16, 0, 0); } while (0)
; #define WAIT_V(n) asm volatile("s_waitcnt vmcnt(" #n ")" ::: "memory")
; #define WAIT_L(n) asm volatile("s_waitcnt lgkmcnt(" #n ")" ::: "memory")
; #define BAR __builtin_amdgcn_s_barrier()
; #define SCHED __builtin_amdgcn_sched_barrier(0)
; #define LDA(dst, b, h) for (int m = 0; m < 4; ++m) for (int k = 0; k < 2; ++k) \
;     dst[m][k] = *reinterpret_cast<const bf16x8*>((char*)SA(b, h) + lds_byte(wr * 64 + m * 16 + fr, k * 32 + fq * 8))
; #define LDB(dst, b, h) for (int n = 0; n < 2; ++n) for (int k = 0; k < 2; ++k) \
;     dst[n][k] = *reinterpret_cast<const bf16x8*>((char*)SB(b, h) + lds_byte(wc * 32 + n * 16 + fr, k * 32 + fq * 8))
; #define MMA(ai, bj, At_, Bt_) do { __builtin_amdgcn_s_setprio(1); \
;     for (int m = 0; m < 4; ++m) for (int n = 0; n < 2; ++n) for (int k = 0; k < 2; ++k) \
;       acc[ai][bj][m][n] = __builtin_amdgcn_mfma_f32_16x16x32_bf16(At_[m][k], Bt_[n][k], acc[ai][bj][m][n], 0, 0, 0); \
;     __builtin_amdgcn_s_setprio(0); } while (0)
; template <int K, int LD = K>
; __device__ __forceinline__ void gemm_main(const GAS bf16* A, const GAS bf16* Bt, int brow, int bcol, f32x4 (&acc)[2][2][4][2]) {
;     ...
;     WAIT_L(8); BAR; WAIT_L(0); MMA(0, 0, At, B0); BAR; SCHED;
;     LDB(B1, 1, 1); STAGE(SB(1, 0), pB0, 3);
;     BAR; WAIT_L(0); MMA(0, 1, At, B1); BAR;
;     LDA(At, 1, 1); STAGE(SA(1, 0), pA0, 3);
;     BAR; WAIT_L(0); MMA(1, 0, At, B0); BAR; SCHED;
;     STAGE(SB(1, 1), pB1, 3);
;     WAIT_V(6); BAR; MMA(1, 1, At, B1); BAR;
;     pA0 += 4 * BK; pA1 += 4 * BK; pB0 += 4 * BK; pB1 += 4 * BK;
;     asm volatile("" : "+s"(pA0), "+s"(pA1), "+s"(pB0), "+s"(pB1));
	s_waitcnt lgkmcnt(0)
	s_addc_u32 s11, s11, 0
	s_waitcnt lgkmcnt(0)
	v_mfma_f32_16x16x32_bf16 v[126:129], v[182:185], v[160:163], v[126:129]
	v_mfma_f32_16x16x32_bf16 v[122:125], v[182:185], v[174:177], v[122:125]
	v_mfma_f32_16x16x32_bf16 v[118:121], v[190:193], v[160:163], v[118:121]
	v_mfma_f32_16x16x32_bf16 v[114:117], v[190:193], v[174:177], v[114:117]
	v_mfma_f32_16x16x32_bf16 v[110:113], v[198:201], v[160:163], v[110:113]
	v_mfma_f32_16x16x32_bf16 v[106:109], v[198:201], v[174:177], v[106:109]
	v_mfma_f32_16x16x32_bf16 v[102:105], v[206:209], v[160:163], v[102:105]
	v_mfma_f32_16x16x32_bf16 v[98:101], v[206:209], v[174:177], v[98:101]
	v_mfma_f32_16x16x32_bf16 v[126:129], v[186:189], v[164:167], v[126:129]
	v_mfma_f32_16x16x32_bf16 v[122:125], v[186:189], v[178:181], v[122:125]
	v_mfma_f32_16x16x32_bf16 v[118:121], v[194:197], v[164:167], v[118:121]
	v_mfma_f32_16x16x32_bf16 v[114:117], v[194:197], v[178:181], v[114:117]
	v_mfma_f32_16x16x32_bf16 v[110:113], v[202:205], v[164:167], v[110:113]
	v_mfma_f32_16x16x32_bf16 v[106:109], v[202:205], v[178:181], v[106:109]
	v_mfma_f32_16x16x32_bf16 v[102:105], v[210:213], v[164:167], v[102:105]
	v_mfma_f32_16x16x32_bf16 v[98:101], v[210:213], v[178:181], v[98:101]
	s_barrier
	v_readfirstlane_b32 s22, v155
	v_lshl_add_u64 v[168:169], v[232:233], 0, s[8:9]
	s_mov_b32 m0, s22
	v_readfirstlane_b32 s22, v156
	ds_read_b128 v[214:217], v139
	ds_read_b128 v[218:221], v139 offset:1024
	ds_read_b128 v[222:225], v139 offset:2048
	ds_read_b128 v[226:229], v139 offset:3072
	global_load_lds_dwordx4 v[168:169], off
	v_lshl_add_u64 v[168:169], v[234:235], 0, s[8:9]
	s_mov_b32 m0, s22
	s_nop 0
	global_load_lds_dwordx4 v[168:169], off
	s_waitcnt vmcnt(10)
	s_barrier
	s_waitcnt lgkmcnt(0)
	s_waitcnt lgkmcnt(0)
	v_mfma_f32_16x16x32_bf16 v[94:97], v[182:185], v[214:217], v[94:97]
	v_mfma_f32_16x16x32_bf16 v[90:93], v[182:185], v[222:225], v[90:93]
	v_mfma_f32_16x16x32_bf16 v[86:89], v[190:193], v[214:217], v[86:89]
	v_mfma_f32_16x16x32_bf16 v[82:85], v[190:193], v[222:225], v[82:85]
	v_mfma_f32_16x16x32_bf16 v[78:81], v[198:201], v[214:217], v[78:81]
	v_mfma_f32_16x16x32_bf16 v[74:77], v[198:201], v[222:225], v[74:77]
	v_mfma_f32_16x16x32_bf16 v[70:73], v[206:209], v[214:217], v[70:73]
	v_mfma_f32_16x16x32_bf16 v[66:69], v[206:209], v[222:225], v[66:69]
	v_mfma_f32_16x16x32_bf16 v[94:97], v[186:189], v[218:221], v[94:97]
	v_mfma_f32_16x16x32_bf16 v[90:93], v[186:189], v[226:229], v[90:93]
	v_mfma_f32_16x16x32_bf16 v[86:89], v[194:197], v[218:221], v[86:89]
	v_mfma_f32_16x16x32_bf16 v[82:85], v[194:197], v[226:229], v[82:85]
	v_mfma_f32_16x16x32_bf16 v[78:81], v[202:205], v[218:221], v[78:81]
	v_mfma_f32_16x16x32_bf16 v[74:77], v[202:205], v[226:229], v[74:77]
	v_mfma_f32_16x16x32_bf16 v[70:73], v[210:213], v[218:221], v[70:73]
	v_mfma_f32_16x16x32_bf16 v[66:69], v[210:213], v[226:229], v[66:69]
	v_readfirstlane_b32 s22, v149
	v_lshl_add_u64 v[168:169], v[236:237], 0, s[8:9]
	s_mov_b32 m0, s22
	v_readfirstlane_b32 s22, v150
	s_barrier
	ds_read_b128 v[182:185], v138 offset:49152
	ds_read_b128 v[186:189], v138 offset:50176
	ds_read_b128 v[190:193], v137 offset:49152
	ds_read_b128 v[194:197], v137 offset:50176
	ds_read_b128 v[198:201], v136 offset:49152
	ds_read_b128 v[202:205], v136 offset:50176
	ds_read_b128 v[206:209], v135 offset:49152
	ds_read_b128 v[210:213], v135 offset:50176
	global_load_lds_dwordx4 v[168:169], off
	v_lshl_add_u64 v[168:169], v[238:239], 0, s[8:9]
	s_mov_b32 m0, s22
	s_nop 0
	global_load_lds_dwordx4 v[168:169], off
	s_barrier
	s_waitcnt lgkmcnt(0)
	s_waitcnt lgkmcnt(0)
	v_mfma_f32_16x16x32_bf16 v[62:65], v[182:185], v[160:163], v[62:65]
	v_mfma_f32_16x16x32_bf16 v[58:61], v[182:185], v[174:177], v[58:61]
	v_mfma_f32_16x16x32_bf16 v[54:57], v[190:193], v[160:163], v[54:57]
	v_mfma_f32_16x16x32_bf16 v[50:53], v[190:193], v[174:177], v[50:53]
	v_mfma_f32_16x16x32_bf16 v[46:49], v[198:201], v[160:163], v[46:49]
	v_mfma_f32_16x16x32_bf16 v[42:45], v[198:201], v[174:177], v[42:45]
	v_mfma_f32_16x16x32_bf16 v[38:41], v[206:209], v[160:163], v[38:41]
	v_mfma_f32_16x16x32_bf16 v[34:37], v[206:209], v[174:177], v[34:37]
	v_mfma_f32_16x16x32_bf16 v[62:65], v[186:189], v[164:167], v[62:65]
	v_mfma_f32_16x16x32_bf16 v[58:61], v[186:189], v[178:181], v[58:61]
	v_mfma_f32_16x16x32_bf16 v[54:57], v[194:197], v[164:167], v[54:57]
	v_mfma_f32_16x16x32_bf16 v[50:53], v[194:197], v[178:181], v[50:53]
	v_mfma_f32_16x16x32_bf16 v[46:49], v[202:205], v[164:167], v[46:49]
	v_mfma_f32_16x16x32_bf16 v[42:45], v[202:205], v[178:181], v[42:45]
	v_mfma_f32_16x16x32_bf16 v[38:41], v[210:213], v[164:167], v[38:41]
	v_mfma_f32_16x16x32_bf16 v[34:37], v[210:213], v[178:181], v[34:37]
	s_barrier
	v_readfirstlane_b32 s22, v157
	v_lshl_add_u64 v[160:161], v[240:241], 0, s[8:9]
	s_mov_b32 m0, s22
	v_readfirstlane_b32 s22, v158
	global_load_lds_dwordx4 v[160:161], off
	v_lshl_add_u64 v[160:161], v[242:243], 0, s[8:9]
	s_mov_b32 m0, s22
	s_nop 0
	global_load_lds_dwordx4 v[160:161], off
	s_waitcnt vmcnt(10)
	s_barrier
	v_mfma_f32_16x16x32_bf16 v[30:33], v[182:185], v[214:217], v[30:33]
	v_mfma_f32_16x16x32_bf16 v[26:29], v[182:185], v[222:225], v[26:29]
	v_mfma_f32_16x16x32_bf16 v[22:25], v[190:193], v[214:217], v[22:25]
	v_mfma_f32_16x16x32_bf16 v[18:21], v[190:193], v[222:225], v[18:21]
	v_mfma_f32_16x16x32_bf16 v[14:17], v[198:201], v[214:217], v[14:17]
	v_mfma_f32_16x16x32_bf16 v[10:13], v[198:201], v[222:225], v[10:13]
	v_mfma_f32_16x16x32_bf16 v[6:9], v[206:209], v[214:217], v[6:9]
	v_mfma_f32_16x16x32_bf16 v[2:5], v[206:209], v[222:225], v[2:5]
	v_mfma_f32_16x16x32_bf16 v[30:33], v[186:189], v[218:221], v[30:33]
	v_mfma_f32_16x16x32_bf16 v[26:29], v[186:189], v[226:229], v[26:29]
	v_mfma_f32_16x16x32_bf16 v[22:25], v[194:197], v[218:221], v[22:25]
	v_mfma_f32_16x16x32_bf16 v[18:21], v[194:197], v[226:229], v[18:21]
	v_mfma_f32_16x16x32_bf16 v[14:17], v[202:205], v[218:221], v[14:17]
	v_mfma_f32_16x16x32_bf16 v[10:13], v[202:205], v[226:229], v[10:13]
	v_mfma_f32_16x16x32_bf16 v[6:9], v[210:213], v[218:221], v[6:9]
	v_mfma_f32_16x16x32_bf16 v[2:5], v[210:213], v[226:229], v[2:5]
	s_add_i32 s15, s15, 2
	s_cmp_lt_u32 s15, 12
	s_barrier
	s_cbranch_scc1 .LBB0_767
	s_branch .Lpeel3_exit

; #define STAGE(P, GP, ktrel) do { const GAS char* _g = (GP) + (ktrel) * (BK * 2); \
;     __builtin_amdgcn_global_load_lds((const GAS unsigned*)(_g + so0), (unsigned*)((char*)(P) + tid_ * 16), 16, 0, 0); \
;     __builtin_amdgcn_global_load_lds((const GAS unsigned*)(_g + so1), (unsigned*)((char*)(P) + tid_ * 16 + 8192), 16, 0, 0); } while (0)
; #define WAIT_V(n) asm volatile("s_waitcnt vmcnt(" #n ")" ::: "memory")
; #define WAIT_L(n) asm volatile("s_waitcnt lgkmcnt(" #n ")" ::: "memory")
; #define BAR __builtin_amdgcn_s_barrier()
; #define LDA(dst, b, h) for (int m = 0; m < 4; ++m) for (int k = 0; k < 2; ++k) \
;     dst[m][k] = *reinterpret_cast<const bf16x8*>((char*)SA(b, h) + lds_byte(wr * 64 + m * 16 + fr, k * 32 + fq * 8))
; #define LDB(dst, b, h) for (int n = 0; n < 2; ++n) for (int k = 0; k < 2; ++k) \
;     dst[n][k] = *reinterpret_cast<const bf16x8*>((char*)SB(b, h) + lds_byte(wc * 32 + n * 16 + fr, k * 32 + fq * 8))
; #define MMA(ai, bj, At_, Bt_) do { __builtin_amdgcn_s_setprio(1); \
;     for (int m = 0; m < 4; ++m) for (int n = 0; n < 2; ++n) for (int k = 0; k < 2; ++k) \
;       acc[ai][bj][m][n] = __builtin_amdgcn_mfma_f32_16x16x32_bf16(At_[m][k], Bt_[n][k], acc[ai][bj][m][n], 0, 0, 0); \
;     __builtin_amdgcn_s_setprio(0); } while (0)
; template <int K, int LD = K>
; __device__ __forceinline__ void gemm_main(const GAS bf16* A, const GAS bf16* Bt, int brow, int bcol, f32x4 (&acc)[2][2][4][2]) {
;     ...
;   { LDB(B0, 0, 0); LDA(At, 0, 0); STAGE(SA(1, 1), pA1, 1);
;     BAR; WAIT_L(0); MMA(0, 0, At, B0); BAR;
;     LDB(B1, 0, 1); BAR; WAIT_L(0); MMA(0, 1, At, B1); BAR;
;     LDA(At, 0, 1); WAIT_V(4); BAR; WAIT_L(0); MMA(1, 0, At, B0); MMA(1, 1, At, B1); BAR; }
.Lpeel3_exit:
	ds_read_b128 v[146:149], v144
	ds_read_b128 v[150:153], v144 offset:1024
	ds_read_b128 v[154:157], v144 offset:2048
	ds_read_b128 v[158:161], v144 offset:3072
	ds_read_b128 v[162:165], v138
	ds_read_b128 v[166:169], v138 offset:1024
	ds_read_b128 v[174:177], v137
	ds_read_b128 v[178:181], v137 offset:1024
	ds_read_b128 v[182:185], v136
	ds_read_b128 v[186:189], v136 offset:1024
	ds_read_b128 v[190:193], v135
	ds_read_b128 v[194:197], v135 offset:1024
	v_lshl_add_u64 v[144:145], s[10:11], 0, v[130:131]
	v_readfirstlane_b32 s15, v143
	v_lshl_add_u64 v[144:145], v[144:145], 0, s[4:5]
	s_mov_b32 m0, s15
	v_lshl_add_u64 v[132:133], s[10:11], 0, v[132:133]
	v_readfirstlane_b32 s10, v142
	global_load_lds_dwordx4 v[144:145], off
	v_lshl_add_u64 v[132:133], v[132:133], 0, s[4:5]
	s_mov_b32 m0, s10
	s_nop 0
	global_load_lds_dwordx4 v[132:133], off
	s_waitcnt vmcnt(10)
	s_barrier
	s_waitcnt lgkmcnt(0)
	s_waitcnt lgkmcnt(0)
	v_mfma_f32_16x16x32_bf16 v[126:129], v[162:165], v[146:149], v[126:129]
	v_mfma_f32_16x16x32_bf16 v[122:125], v[162:165], v[154:157], v[122:125]
	v_mfma_f32_16x16x32_bf16 v[110:113], v[182:185], v[146:149], v[110:113]
	v_mfma_f32_16x16x32_bf16 v[106:109], v[182:185], v[154:157], v[106:109]
	v_mfma_f32_16x16x32_bf16 v[126:129], v[166:169], v[150:153], v[126:129]
	v_mfma_f32_16x16x32_bf16 v[122:125], v[166:169], v[158:161], v[122:125]
	v_mfma_f32_16x16x32_bf16 v[118:121], v[174:177], v[146:149], v[118:121]
	v_mfma_f32_16x16x32_bf16 v[114:117], v[174:177], v[154:157], v[114:117]
	v_mfma_f32_16x16x32_bf16 v[110:113], v[186:189], v[150:153], v[110:113]
	v_mfma_f32_16x16x32_bf16 v[106:109], v[186:189], v[158:161], v[106:109]
	v_mfma_f32_16x16x32_bf16 v[102:105], v[190:193], v[146:149], v[102:105]
	v_mfma_f32_16x16x32_bf16 v[98:101], v[190:193], v[154:157], v[98:101]
	v_mfma_f32_16x16x32_bf16 v[142:145], v[178:181], v[150:153], v[118:121]
	v_mfma_f32_16x16x32_bf16 v[198:201], v[178:181], v[158:161], v[114:117]
	v_mfma_f32_16x16x32_bf16 v[202:205], v[194:197], v[150:153], v[102:105]
	v_mfma_f32_16x16x32_bf16 v[206:209], v[194:197], v[158:161], v[98:101]
	s_barrier
	s_nop 1
	ds_read_b128 v[98:101], v141
	ds_read_b128 v[102:105], v141 offset:1024
	ds_read_b128 v[114:117], v141 offset:2048
	ds_read_b128 v[118:121], v141 offset:3072
	s_waitcnt vmcnt(8)
	s_barrier
	s_waitcnt lgkmcnt(0)
	s_waitcnt lgkmcnt(0)
	v_mfma_f32_16x16x32_bf16 v[94:97], v[162:165], v[98:101], v[94:97]
	v_mfma_f32_16x16x32_bf16 v[90:93], v[162:165], v[114:117], v[90:93]
	v_mfma_f32_16x16x32_bf16 v[78:81], v[182:185], v[98:101], v[78:81]
	v_mfma_f32_16x16x32_bf16 v[74:77], v[182:185], v[114:117], v[74:77]
	v_mfma_f32_16x16x32_bf16 v[94:97], v[166:169], v[102:105], v[94:97]
	v_mfma_f32_16x16x32_bf16 v[90:93], v[166:169], v[118:121], v[90:93]
	v_mfma_f32_16x16x32_bf16 v[86:89], v[174:177], v[98:101], v[86:89]
	v_mfma_f32_16x16x32_bf16 v[82:85], v[174:177], v[114:117], v[82:85]
	v_mfma_f32_16x16x32_bf16 v[78:81], v[186:189], v[102:105], v[78:81]
	v_mfma_f32_16x16x32_bf16 v[74:77], v[186:189], v[118:121], v[74:77]
	v_mfma_f32_16x16x32_bf16 v[70:73], v[190:193], v[98:101], v[70:73]
	v_mfma_f32_16x16x32_bf16 v[66:69], v[190:193], v[114:117], v[66:69]
	v_mfma_f32_16x16x32_bf16 v[162:165], v[178:181], v[102:105], v[86:89]
	v_mfma_f32_16x16x32_bf16 v[166:169], v[178:181], v[118:121], v[82:85]
	v_mfma_f32_16x16x32_bf16 v[174:177], v[194:197], v[102:105], v[70:73]
	v_mfma_f32_16x16x32_bf16 v[178:181], v[194:197], v[118:121], v[66:69]
	s_barrier
	s_nop 1
	ds_read_b128 v[66:69], v138 offset:16384
	ds_read_b128 v[70:73], v138 offset:17408
	ds_read_b128 v[82:85], v137 offset:16384
	ds_read_b128 v[86:89], v137 offset:17408
	ds_read_b128 v[182:185], v136 offset:16384
	ds_read_b128 v[186:189], v136 offset:17408
	ds_read_b128 v[190:193], v135 offset:16384
	ds_read_b128 v[194:197], v135 offset:17408
	s_waitcnt vmcnt(4)
	s_barrier
	s_waitcnt lgkmcnt(0)
	s_waitcnt lgkmcnt(0)
	v_mfma_f32_16x16x32_bf16 v[62:65], v[66:69], v[146:149], v[62:65]
	v_mfma_f32_16x16x32_bf16 v[58:61], v[66:69], v[154:157], v[58:61]
	v_mfma_f32_16x16x32_bf16 v[46:49], v[182:185], v[146:149], v[46:49]
	v_mfma_f32_16x16x32_bf16 v[42:45], v[182:185], v[154:157], v[42:45]
	v_mfma_f32_16x16x32_bf16 v[62:65], v[70:73], v[150:153], v[62:65]
	v_mfma_f32_16x16x32_bf16 v[58:61], v[70:73], v[158:161], v[58:61]
	v_mfma_f32_16x16x32_bf16 v[54:57], v[82:85], v[146:149], v[54:57]
	v_mfma_f32_16x16x32_bf16 v[50:53], v[82:85], v[154:157], v[50:53]
	v_mfma_f32_16x16x32_bf16 v[46:49], v[186:189], v[150:153], v[46:49]
	v_mfma_f32_16x16x32_bf16 v[42:45], v[186:189], v[158:161], v[42:45]
	v_mfma_f32_16x16x32_bf16 v[38:41], v[190:193], v[146:149], v[38:41]
	v_mfma_f32_16x16x32_bf16 v[34:37], v[190:193], v[154:157], v[34:37]
	v_mfma_f32_16x16x32_bf16 v[210:213], v[86:89], v[150:153], v[54:57]
	v_mfma_f32_16x16x32_bf16 v[214:217], v[86:89], v[158:161], v[50:53]
	v_mfma_f32_16x16x32_bf16 v[146:149], v[194:197], v[150:153], v[38:41]
	v_mfma_f32_16x16x32_bf16 v[150:153], v[194:197], v[158:161], v[34:37]
	v_mfma_f32_16x16x32_bf16 v[30:33], v[66:69], v[98:101], v[30:33]
	v_mfma_f32_16x16x32_bf16 v[26:29], v[66:69], v[114:117], v[26:29]
	v_mfma_f32_16x16x32_bf16 v[14:17], v[182:185], v[98:101], v[14:17]
	v_mfma_f32_16x16x32_bf16 v[10:13], v[182:185], v[114:117], v[10:13]
	v_mfma_f32_16x16x32_bf16 v[30:33], v[70:73], v[102:105], v[30:33]
	v_mfma_f32_16x16x32_bf16 v[26:29], v[70:73], v[118:121], v[26:29]
	v_mfma_f32_16x16x32_bf16 v[22:25], v[82:85], v[98:101], v[22:25]
	v_mfma_f32_16x16x32_bf16 v[18:21], v[82:85], v[114:117], v[18:21]
	v_mfma_f32_16x16x32_bf16 v[14:17], v[186:189], v[102:105], v[14:17]
	v_mfma_f32_16x16x32_bf16 v[10:13], v[186:189], v[118:121], v[10:13]
	v_mfma_f32_16x16x32_bf16 v[6:9], v[190:193], v[98:101], v[6:9]
	v_mfma_f32_16x16x32_bf16 v[2:5], v[190:193], v[114:117], v[2:5]
	v_mfma_f32_16x16x32_bf16 v[154:157], v[86:89], v[102:105], v[22:25]
	v_mfma_f32_16x16x32_bf16 v[158:161], v[86:89], v[118:121], v[18:21]
	v_mfma_f32_16x16x32_bf16 v[182:185], v[194:197], v[102:105], v[6:9]
	v_mfma_f32_16x16x32_bf16 v[186:189], v[194:197], v[118:121], v[2:5]
	s_barrier
; #define WAIT_V(n) asm volatile("s_waitcnt vmcnt(" #n ")" ::: "memory")
; #define WAIT_L(n) asm volatile("s_waitcnt lgkmcnt(" #n ")" ::: "memory")
; #define BAR __builtin_amdgcn_s_barrier()
; #define LDA(dst, b, h) for (int m = 0; m < 4; ++m) for (int k = 0; k < 2; ++k) \
;     dst[m][k] = *reinterpret_cast<const bf16x8*>((char*)SA(b, h) + lds_byte(wr * 64 + m * 16 + fr, k * 32 + fq * 8))
; #define LDB(dst, b, h) for (int n = 0; n < 2; ++n) for (int k = 0; k < 2; ++k) \
;     dst[n][k] = *reinterpret_cast<const bf16x8*>((char*)SB(b, h) + lds_byte(wc * 32 + n * 16 + fr, k * 32 + fq * 8))
; #define MMA(ai, bj, At_, Bt_) do { __builtin_amdgcn_s_setprio(1); \
;     for (int m = 0; m < 4; ++m) for (int n = 0; n < 2; ++n) for (int k = 0; k < 2; ++k) \
;       acc[ai][bj][m][n] = __builtin_amdgcn_mfma_f32_16x16x32_bf16(At_[m][k], Bt_[n][k], acc[ai][bj][m][n], 0, 0, 0); \
;     __builtin_amdgcn_s_setprio(0); } while (0)
; template <int K, int LD = K>
; __device__ __forceinline__ void gemm_main(const GAS bf16* A, const GAS bf16* Bt, int brow, int bcol, f32x4 (&acc)[2][2][4][2]) {
;     ...
;   { LDB(B0, 1, 0); LDA(At, 1, 0); WAIT_V(2); BAR; WAIT_L(0); MMA(0, 0, At, B0); BAR;
;     LDB(B1, 1, 1); WAIT_V(0); BAR; WAIT_L(0); MMA(0, 1, At, B1); BAR;
;     LDA(At, 1, 1); BAR; WAIT_L(0); MMA(1, 0, At, B0); MMA(1, 1, At, B1); BAR; }
;   if (wr == 0) BAR;
	s_nop 1
	ds_read_b128 v[2:5], v140
	ds_read_b128 v[6:9], v140 offset:1024
	ds_read_b128 v[190:193], v140 offset:2048
	ds_read_b128 v[194:197], v140 offset:3072
	ds_read_b128 v[18:21], v138 offset:32768
	ds_read_b128 v[22:25], v138 offset:33792
	ds_read_b128 v[34:37], v137 offset:32768
	ds_read_b128 v[38:41], v137 offset:33792
	ds_read_b128 v[50:53], v136 offset:32768
	ds_read_b128 v[54:57], v136 offset:33792
	ds_read_b128 v[218:221], v135 offset:32768
	ds_read_b128 v[222:225], v135 offset:33792
	s_waitcnt vmcnt(2)
	s_barrier
	s_waitcnt lgkmcnt(0)
	s_waitcnt lgkmcnt(0)
	v_mfma_f32_16x16x32_bf16 v[66:69], v[18:21], v[2:5], v[126:129]
	v_mfma_f32_16x16x32_bf16 v[118:121], v[22:25], v[6:9], v[66:69]
	v_mfma_f32_16x16x32_bf16 v[66:69], v[18:21], v[190:193], v[122:125]
	v_mfma_f32_16x16x32_bf16 v[114:117], v[22:25], v[194:197], v[66:69]
	v_mfma_f32_16x16x32_bf16 v[66:69], v[34:37], v[2:5], v[142:145]
	v_mfma_f32_16x16x32_bf16 v[102:105], v[38:41], v[6:9], v[66:69]
	v_mfma_f32_16x16x32_bf16 v[66:69], v[34:37], v[190:193], v[198:201]
	v_mfma_f32_16x16x32_bf16 v[98:101], v[38:41], v[194:197], v[66:69]
	v_mfma_f32_16x16x32_bf16 v[66:69], v[50:53], v[2:5], v[110:113]
	v_mfma_f32_16x16x32_bf16 v[86:89], v[54:57], v[6:9], v[66:69]
	v_mfma_f32_16x16x32_bf16 v[66:69], v[50:53], v[190:193], v[106:109]
	v_mfma_f32_16x16x32_bf16 v[82:85], v[54:57], v[194:197], v[66:69]
	v_mfma_f32_16x16x32_bf16 v[66:69], v[218:221], v[2:5], v[202:205]
	v_mfma_f32_16x16x32_bf16 v[70:73], v[222:225], v[6:9], v[66:69]
	v_mfma_f32_16x16x32_bf16 v[66:69], v[218:221], v[190:193], v[206:209]
	v_mfma_f32_16x16x32_bf16 v[66:69], v[222:225], v[194:197], v[66:69]
	s_barrier
	ds_read_b128 v[140:143], v139
	ds_read_b128 v[198:201], v139 offset:1024
	ds_read_b128 v[202:205], v139 offset:2048
	ds_read_b128 v[206:209], v139 offset:3072
	s_waitcnt vmcnt(0)
	s_barrier
	s_waitcnt lgkmcnt(0)
	s_waitcnt lgkmcnt(0)
	v_mfma_f32_16x16x32_bf16 v[94:97], v[18:21], v[140:143], v[94:97]
	v_mfma_f32_16x16x32_bf16 v[18:21], v[18:21], v[202:205], v[90:93]
	v_mfma_f32_16x16x32_bf16 v[122:125], v[22:25], v[206:209], v[18:21]
	v_mfma_f32_16x16x32_bf16 v[18:21], v[34:37], v[140:143], v[162:165]
	v_mfma_f32_16x16x32_bf16 v[110:113], v[38:41], v[198:201], v[18:21]
	v_mfma_f32_16x16x32_bf16 v[18:21], v[34:37], v[202:205], v[166:169]
	v_mfma_f32_16x16x32_bf16 v[106:109], v[38:41], v[206:209], v[18:21]
	v_mfma_f32_16x16x32_bf16 v[18:21], v[50:53], v[140:143], v[78:81]
	v_mfma_f32_16x16x32_bf16 v[126:129], v[22:25], v[198:201], v[94:97]
	v_mfma_f32_16x16x32_bf16 v[94:97], v[54:57], v[198:201], v[18:21]
	v_mfma_f32_16x16x32_bf16 v[18:21], v[50:53], v[202:205], v[74:77]
	v_mfma_f32_16x16x32_bf16 v[90:93], v[54:57], v[206:209], v[18:21]
	v_mfma_f32_16x16x32_bf16 v[18:21], v[218:221], v[140:143], v[174:177]
	v_mfma_f32_16x16x32_bf16 v[78:81], v[222:225], v[198:201], v[18:21]
	v_mfma_f32_16x16x32_bf16 v[18:21], v[218:221], v[202:205], v[178:181]
	v_mfma_f32_16x16x32_bf16 v[74:77], v[222:225], v[206:209], v[18:21]
	s_barrier
	ds_read_b128 v[162:165], v138 offset:49152
	ds_read_b128 v[166:169], v138 offset:50176
	ds_read_b128 v[174:177], v137 offset:49152
	ds_read_b128 v[178:181], v137 offset:50176
	ds_read_b128 v[218:221], v136 offset:49152
	ds_read_b128 v[136:139], v136 offset:50176
	ds_read_b128 v[222:225], v135 offset:49152
	ds_read_b128 v[226:229], v135 offset:50176
	s_barrier
	s_waitcnt lgkmcnt(0)
	s_waitcnt lgkmcnt(0)
	v_mfma_f32_16x16x32_bf16 v[18:21], v[162:165], v[2:5], v[62:65]
	v_mfma_f32_16x16x32_bf16 v[54:57], v[166:169], v[6:9], v[18:21]
	v_mfma_f32_16x16x32_bf16 v[18:21], v[162:165], v[190:193], v[58:61]
	v_mfma_f32_16x16x32_bf16 v[50:53], v[166:169], v[194:197], v[18:21]
	v_mfma_f32_16x16x32_bf16 v[18:21], v[174:177], v[2:5], v[210:213]
	v_mfma_f32_16x16x32_bf16 v[38:41], v[178:181], v[6:9], v[18:21]
	v_mfma_f32_16x16x32_bf16 v[18:21], v[174:177], v[190:193], v[214:217]
	v_mfma_f32_16x16x32_bf16 v[34:37], v[178:181], v[194:197], v[18:21]
	v_mfma_f32_16x16x32_bf16 v[18:21], v[218:221], v[2:5], v[46:49]
	v_mfma_f32_16x16x32_bf16 v[2:5], v[222:225], v[2:5], v[146:149]
	v_mfma_f32_16x16x32_bf16 v[22:25], v[136:139], v[6:9], v[18:21]
	v_mfma_f32_16x16x32_bf16 v[18:21], v[218:221], v[190:193], v[42:45]
	v_mfma_f32_16x16x32_bf16 v[6:9], v[226:229], v[6:9], v[2:5]
	v_mfma_f32_16x16x32_bf16 v[2:5], v[222:225], v[190:193], v[150:153]
	v_mfma_f32_16x16x32_bf16 v[18:21], v[136:139], v[194:197], v[18:21]
	v_mfma_f32_16x16x32_bf16 v[2:5], v[226:229], v[194:197], v[2:5]
	v_mfma_f32_16x16x32_bf16 v[26:29], v[162:165], v[202:205], v[26:29]
	v_mfma_f32_16x16x32_bf16 v[58:61], v[166:169], v[206:209], v[26:29]
	v_mfma_f32_16x16x32_bf16 v[26:29], v[174:177], v[140:143], v[154:157]
	v_mfma_f32_16x16x32_bf16 v[46:49], v[178:181], v[198:201], v[26:29]
	v_mfma_f32_16x16x32_bf16 v[26:29], v[174:177], v[202:205], v[158:161]
	v_mfma_f32_16x16x32_bf16 v[10:13], v[218:221], v[202:205], v[10:13]
	v_mfma_f32_16x16x32_bf16 v[30:33], v[162:165], v[140:143], v[30:33]
	v_mfma_f32_16x16x32_bf16 v[42:45], v[178:181], v[206:209], v[26:29]
	v_mfma_f32_16x16x32_bf16 v[14:17], v[218:221], v[140:143], v[14:17]
	v_mfma_f32_16x16x32_bf16 v[26:29], v[136:139], v[206:209], v[10:13]
	v_mfma_f32_16x16x32_bf16 v[10:13], v[222:225], v[140:143], v[182:185]
	v_mfma_f32_16x16x32_bf16 v[62:65], v[166:169], v[198:201], v[30:33]
	v_mfma_f32_16x16x32_bf16 v[30:33], v[136:139], v[198:201], v[14:17]
	v_mfma_f32_16x16x32_bf16 v[14:17], v[226:229], v[198:201], v[10:13]
	v_mfma_f32_16x16x32_bf16 v[10:13], v[222:225], v[202:205], v[186:189]
	v_mfma_f32_16x16x32_bf16 v[10:13], v[226:229], v[206:209], v[10:13]
	v_cmp_gt_u32_e32 vcc, s34, v134
	s_barrier
	s_and_saveexec_b64 s[10:11], vcc
	s_cbranch_execz .LBB0_770
	s_barrier

; #define GAS __attribute__((address_space(1)))
; #define STAGE(P, GP, ktrel) do { const GAS char* _g = (GP) + (ktrel) * (BK * 2); \
;     __builtin_amdgcn_global_load_lds((const GAS unsigned*)(_g + so0), (unsigned*)((char*)(P) + tid_ * 16), 16, 0, 0); \
;     __builtin_amdgcn_global_load_lds((const GAS unsigned*)(_g + so1), (unsigned*)((char*)(P) + tid_ * 16 + 8192), 16, 0, 0); } while (0)
; #define WAIT_V(n) asm volatile("s_waitcnt vmcnt(" #n ")" ::: "memory")
; #define WAIT_L(n) asm volatile("s_waitcnt lgkmcnt(" #n ")" ::: "memory")
; #define BAR __builtin_amdgcn_s_barrier()
; #define SCHED __builtin_amdgcn_sched_barrier(0)
; #define LDA(dst, b, h) for (int m = 0; m < 4; ++m) for (int k = 0; k < 2; ++k) \
;     dst[m][k] = *reinterpret_cast<const bf16x8*>((char*)SA(b, h) + lds_byte(wr * 64 + m * 16 + fr, k * 32 + fq * 8))
; #define LDB(dst, b, h) for (int n = 0; n < 2; ++n) for (int k = 0; k < 2; ++k) \
;     dst[n][k] = *reinterpret_cast<const bf16x8*>((char*)SB(b, h) + lds_byte(wc * 32 + n * 16 + fr, k * 32 + fq * 8))
; template <int K, int LD = K>
; __device__ __forceinline__ void gemm_main(const GAS bf16* A, const GAS bf16* Bt, int brow, int bcol, f32x4 (&acc)[2][2][4][2]) {
;     ...
;         for (int n = 0; n < 2; ++n) acc[a][b][m][n] = f32x4{0.f, 0.f, 0.f, 0.f};
;   bf16x8 At[4][2], B0[2][2], B1[2][2];
;   unsigned so0, so1;
;   { int r_, c_; stage_rc(tid_ * 16, r_, c_); so0 = (unsigned)(r_ * LD + c_) * 2u; stage_rc(tid_ * 16 + 8192, r_, c_); so1 = (unsigned)(r_ * LD + c_) * 2u; }
;   const GAS char* pA0 = (const GAS char*)A + (long)brow * LD * 2; const GAS char* pA1 = pA0 + (long)HALF * LD * 2;
;   const GAS char* pB0 = (const GAS char*)Bt + (long)bcol * LD * 2; const GAS char* pB1 = pB0 + (long)HALF * LD * 2;
;   asm volatile("" : "+s"(pA0), "+s"(pA1), "+s"(pB0), "+s"(pB1));
;   constexpr int nt = K / BK;
;   static_assert(K % 128 == 0 && K >= 256, "K");
;   if (wr == 1) BAR;
;   WAIT_V(0); BAR;
;   BAR;
;   for (int t = 0; t < nt - 2; t += 2) {
;     LDB(B0, 0, 0); SCHED; LDA(At, 0, 0); STAGE(SA(1, 1), pA1, 1);
;     WAIT_L(8); BAR; WAIT_L(0); MMA(0, 0, At, B0); BAR; SCHED;
;     LDB(B1, 0, 1); STAGE(SB(0, 0), pB0, 2);
;     BAR; WAIT_L(0); MMA(0, 1, At, B1); BAR;
.LBB0_883:
	s_or_b64 exec, exec, s[22:23]
	v_bfe_i32 v7, v135, 27, 1
	v_lshlrev_b32_e32 v5, 4, v135
	v_lshrrev_b32_e32 v7, 22, v7
	v_add_u32_e32 v7, v5, v7
	v_and_b32_e32 v7, 0xfffffc00, v7
	v_sub_u32_e32 v7, v5, v7
	v_lshrrev_b32_e32 v8, 4, v7
	v_bitop3_b32 v8, v8, v7, 32 bitop3:0x6c
	v_ashrrev_i32_e32 v7, 31, v7
	v_ashrrev_i32_e32 v6, 31, v135
	v_lshrrev_b32_e32 v7, 26, v7
	v_lshrrev_b32_e32 v6, 26, v6
	v_add_u32_e32 v7, v8, v7
	v_add_u32_e32 v6, v135, v6
	v_ashrrev_i32_e32 v7, 6, v7
	v_ashrrev_i32_e32 v6, 6, v6
	v_mul_i32_i24_e32 v10, 64, v7
	v_lshlrev_b32_e32 v9, 3, v6
	v_lshlrev_b32_e32 v6, 5, v6
	v_sub_u32_e32 v8, v8, v10
	v_and_b32_e32 v9, 0x1ffff0, v9
	v_and_b32_e32 v6, 32, v6
	v_ashrrev_i16_sdwa v8, v1, sext(v8) dst_sel:DWORD dst_unused:UNUSED_PAD src0_sel:DWORD src1_sel:BYTE_0
	v_add_u32_sdwa v6, v6, sext(v8) dst_sel:DWORD dst_unused:UNUSED_PAD src0_sel:DWORD src1_sel:WORD_0
	v_add_lshl_u32 v7, v7, v9, 11
	v_lshl_add_u32 v130, v6, 1, v7
	v_add_u32_e32 v6, 0x2000, v5
	v_ashrrev_i32_e32 v7, 31, v6
	v_lshrrev_b32_e32 v7, 22, v7
	v_add_u32_e32 v7, v6, v7
	v_ashrrev_i32_e32 v7, 10, v7
	v_mul_i32_i24_e32 v8, 0x400, v7
	v_sub_u32_e32 v6, v6, v8
	v_lshrrev_b32_e32 v8, 4, v6
	v_bitop3_b32 v6, v8, v6, 32 bitop3:0x6c
	v_ashrrev_i32_e32 v9, 31, v6
	v_lshrrev_b32_e32 v9, 26, v9
	v_add_u32_e32 v9, v6, v9
	v_lshrrev_b32_e32 v10, 6, v9
	v_and_b32_e32 v9, 0xc0, v9
	v_lshlrev_b32_e32 v8, 3, v7
	v_lshlrev_b32_e32 v7, 5, v7
	v_sub_u32_e32 v6, v6, v9
	v_and_b32_e32 v8, 0x1ffff0, v8
	v_and_b32_e32 v7, 32, v7
	v_ashrrev_i16_sdwa v6, v1, sext(v6) dst_sel:DWORD dst_unused:UNUSED_PAD src0_sel:DWORD src1_sel:BYTE_0
	v_add_u32_sdwa v6, v7, sext(v6) dst_sel:DWORD dst_unused:UNUSED_PAD src0_sel:DWORD src1_sel:WORD_0
	v_add_lshl_u32 v7, v10, v8, 11
	v_and_b32_e32 v3, 15, v135
	v_lshl_add_u32 v132, v6, 1, v7
	v_lshlrev_b32_e32 v6, 2, v135
	v_and_b32_e32 v4, 48, v135
	v_lshlrev_b32_e32 v3, 6, v3
	v_and_b32_e32 v6, 32, v6
	v_lshlrev_b32_e32 v11, 6, v135
	v_bitop3_b32 v3, v3, v6, v4 bitop3:0x36
	v_lshlrev_b32_e32 v13, 13, v2
	v_and_or_b32 v2, v11, s38, v4
	v_add_u32_e32 v7, s29, v3
	v_add_u32_e32 v8, s30, v3
	v_add_u32_e32 v9, s31, v3
	v_add_u32_e32 v10, s33, v3
	v_and_b32_e32 v12, 0x3000, v11
	v_add_u32_e32 v3, 0x100, v3
	v_xad_u32 v4, v2, v6, s34
	v_or_b32_e32 v6, 0x800, v13
	v_or_b32_e32 v11, 0x1000, v13
	v_or_b32_e32 v14, 0x1800, v13
	v_mov_b32_e32 v2, 0
	v_add_u32_e32 v146, 0x100, v5
	v_add_u32_e32 v152, s29, v5
	v_add_u32_e32 v154, s30, v5
	v_add_u32_e32 v156, s31, v5
	v_add_u32_e32 v158, s33, v5
	v_mov_b32_e32 v133, v131
	s_mov_b32 s15, -2
	v_add_u32_e32 v145, v7, v12
	v_add_u32_e32 v139, v3, v13
	v_add_u32_e32 v138, v4, v6
	v_add_u32_e32 v137, v4, v11
	v_add_u32_e32 v136, v4, v14
	v_add_u32_e32 v144, 0xc000, v146
	v_add_u32_e32 v143, 0xe000, v146
	v_add_u32_e32 v142, v8, v12
	v_add_u32_e32 v147, 0x2000, v146
	v_add_u32_e32 v141, v9, v12
	v_add_u32_e32 v148, 0x4000, v146
	v_add_u32_e32 v149, 0x6000, v146
	v_add_u32_e32 v140, v10, v12
	v_add_u32_e32 v150, 0x8000, v146
	v_add_u32_e32 v151, 0xa000, v146
	v_add_u32_e32 v153, 0x2000, v152
	v_add_u32_e32 v155, 0x2000, v154
	v_add_u32_e32 v157, 0x2000, v156
	v_add_u32_e32 v159, 0x2000, v158
	s_waitcnt vmcnt(0)
	s_barrier
	s_barrier
	ds_read_b128 v[160:163], v145
	ds_read_b128 v[164:167], v145 offset:1024
	ds_read_b128 v[174:177], v145 offset:2048
	ds_read_b128 v[178:181], v145 offset:3072
	v_lshl_add_u64 v[168:169], s[12:13], 0, v[130:131]
	v_readfirstlane_b32 s22, v144
	v_lshl_add_u64 v[214:215], v[168:169], 0, s[6:7]
	s_mov_b32 m0, s22
	v_lshl_add_u64 v[230:231], s[12:13], 0, v[132:133]
	v_readfirstlane_b32 s22, v143
	ds_read_b128 v[182:185], v139
	ds_read_b128 v[186:189], v139 offset:1024
	ds_read_b128 v[190:193], v138
	ds_read_b128 v[194:197], v138 offset:1024
	ds_read_b128 v[198:201], v137
	ds_read_b128 v[202:205], v137 offset:1024
	ds_read_b128 v[206:209], v136
	ds_read_b128 v[210:213], v136 offset:1024
	global_load_lds_dwordx4 v[214:215], off
	v_lshl_add_u64 v[214:215], v[230:231], 0, s[6:7]
	s_mov_b32 m0, s22
	s_nop 0
	global_load_lds_dwordx4 v[214:215], off
	s_waitcnt lgkmcnt(8)
	s_waitcnt vmcnt(10)
	s_barrier
	s_waitcnt lgkmcnt(0)
	s_waitcnt lgkmcnt(0)
	v_mfma_f32_16x16x32_bf16 v[126:129], v[182:185], v[160:163], 0
	v_mfma_f32_16x16x32_bf16 v[122:125], v[182:185], v[174:177], 0
	v_mfma_f32_16x16x32_bf16 v[118:121], v[190:193], v[160:163], 0
	v_mfma_f32_16x16x32_bf16 v[114:117], v[190:193], v[174:177], 0
	v_mfma_f32_16x16x32_bf16 v[110:113], v[198:201], v[160:163], 0
	v_mfma_f32_16x16x32_bf16 v[106:109], v[198:201], v[174:177], 0
	v_mfma_f32_16x16x32_bf16 v[102:105], v[206:209], v[160:163], 0
	v_mfma_f32_16x16x32_bf16 v[98:101], v[206:209], v[174:177], 0
	v_mfma_f32_16x16x32_bf16 v[126:129], v[186:189], v[164:167], v[126:129]
	v_mfma_f32_16x16x32_bf16 v[122:125], v[186:189], v[178:181], v[122:125]
	v_mfma_f32_16x16x32_bf16 v[118:121], v[194:197], v[164:167], v[118:121]
	v_mfma_f32_16x16x32_bf16 v[114:117], v[194:197], v[178:181], v[114:117]
	v_mfma_f32_16x16x32_bf16 v[110:113], v[202:205], v[164:167], v[110:113]
	v_mfma_f32_16x16x32_bf16 v[106:109], v[202:205], v[178:181], v[106:109]
	v_mfma_f32_16x16x32_bf16 v[102:105], v[210:213], v[164:167], v[102:105]
	v_mfma_f32_16x16x32_bf16 v[98:101], v[210:213], v[178:181], v[98:101]
	s_barrier
	v_lshl_add_u64 v[232:233], s[20:21], 0, v[130:131]
	v_readfirstlane_b32 s22, v152
	v_lshl_add_u64 v[234:235], v[232:233], 0, s[8:9]
	s_mov_b32 m0, s22
	ds_read_b128 v[214:217], v142
	ds_read_b128 v[218:221], v142 offset:1024
	ds_read_b128 v[222:225], v142 offset:2048
	ds_read_b128 v[226:229], v142 offset:3072
	global_load_lds_dwordx4 v[234:235], off
	v_lshl_add_u64 v[234:235], s[20:21], 0, v[132:133]
	v_readfirstlane_b32 s22, v153
	v_lshl_add_u64 v[236:237], v[234:235], 0, s[8:9]
	s_mov_b32 m0, s22
	s_add_u32 s20, s20, 0x100
	global_load_lds_dwordx4 v[236:237], off
	s_waitcnt vmcnt(10)
	s_barrier
; #define STAGE(P, GP, ktrel) do { const GAS char* _g = (GP) + (ktrel) * (BK * 2); \
;     __builtin_amdgcn_global_load_lds((const GAS unsigned*)(_g + so0), (unsigned*)((char*)(P) + tid_ * 16), 16, 0, 0); \
;     __builtin_amdgcn_global_load_lds((const GAS unsigned*)(_g + so1), (unsigned*)((char*)(P) + tid_ * 16 + 8192), 16, 0, 0); } while (0)
; #define WAIT_V(n) asm volatile("s_waitcnt vmcnt(" #n ")" ::: "memory")
; #define WAIT_L(n) asm volatile("s_waitcnt lgkmcnt(" #n ")" ::: "memory")
; #define BAR __builtin_amdgcn_s_barrier()
; #define SCHED __builtin_amdgcn_sched_barrier(0)
; #define LDA(dst, b, h) for (int m = 0; m < 4; ++m) for (int k = 0; k < 2; ++k) \
;     dst[m][k] = *reinterpret_cast<const bf16x8*>((char*)SA(b, h) + lds_byte(wr * 64 + m * 16 + fr, k * 32 + fq * 8))
; #define LDB(dst, b, h) for (int n = 0; n < 2; ++n) for (int k = 0; k < 2; ++k) \
;     dst[n][k] = *reinterpret_cast<const bf16x8*>((char*)SB(b, h) + lds_byte(wc * 32 + n * 16 + fr, k * 32 + fq * 8))
; #define MMA(ai, bj, At_, Bt_) do { __builtin_amdgcn_s_setprio(1); \
;     for (int m = 0; m < 4; ++m) for (int n = 0; n < 2; ++n) for (int k = 0; k < 2; ++k) \
;       acc[ai][bj][m][n] = __builtin_amdgcn_mfma_f32_16x16x32_bf16(At_[m][k], Bt_[n][k], acc[ai][bj][m][n], 0, 0, 0); \
;     __builtin_amdgcn_s_setprio(0); } while (0)
; template <int K, int LD = K>
; __device__ __forceinline__ void gemm_main(const GAS bf16* A, const GAS bf16* Bt, int brow, int bcol, f32x4 (&acc)[2][2][4][2]) {
;     ...
;     BAR; WAIT_L(0); MMA(0, 1, At, B1); BAR;
;     LDA(At, 0, 1); STAGE(SA(0, 0), pA0, 2);
;     BAR; WAIT_L(0); MMA(1, 0, At, B0); BAR; SCHED;
;     STAGE(SB(0, 1), pB1, 2);
;     WAIT_V(6); BAR; MMA(1, 1, At, B1); BAR;
;     LDB(B0, 1, 0); SCHED; LDA(At, 1, 0); STAGE(SA(0, 1), pA1, 2);
;     WAIT_L(8); BAR; WAIT_L(0); MMA(0, 0, At, B0); BAR; SCHED;
	s_waitcnt lgkmcnt(0)
	s_addc_u32 s21, s21, 0
	s_waitcnt lgkmcnt(0)
	v_mfma_f32_16x16x32_bf16 v[94:97], v[182:185], v[214:217], 0
	v_mfma_f32_16x16x32_bf16 v[90:93], v[182:185], v[222:225], 0
	v_mfma_f32_16x16x32_bf16 v[86:89], v[190:193], v[214:217], 0
	v_mfma_f32_16x16x32_bf16 v[82:85], v[190:193], v[222:225], 0
	v_mfma_f32_16x16x32_bf16 v[78:81], v[198:201], v[214:217], 0
	v_mfma_f32_16x16x32_bf16 v[74:77], v[198:201], v[222:225], 0
	v_mfma_f32_16x16x32_bf16 v[70:73], v[206:209], v[214:217], 0
	v_mfma_f32_16x16x32_bf16 v[66:69], v[206:209], v[222:225], 0
	v_mfma_f32_16x16x32_bf16 v[94:97], v[186:189], v[218:221], v[94:97]
	v_mfma_f32_16x16x32_bf16 v[90:93], v[186:189], v[226:229], v[90:93]
	v_mfma_f32_16x16x32_bf16 v[86:89], v[194:197], v[218:221], v[86:89]
	v_mfma_f32_16x16x32_bf16 v[82:85], v[194:197], v[226:229], v[82:85]
	v_mfma_f32_16x16x32_bf16 v[78:81], v[202:205], v[218:221], v[78:81]
	v_mfma_f32_16x16x32_bf16 v[74:77], v[202:205], v[226:229], v[74:77]
	v_mfma_f32_16x16x32_bf16 v[70:73], v[210:213], v[218:221], v[70:73]
	v_mfma_f32_16x16x32_bf16 v[66:69], v[210:213], v[226:229], v[66:69]
	v_lshl_add_u64 v[236:237], s[18:19], 0, v[130:131]
	v_readfirstlane_b32 s22, v146
	v_lshl_add_u64 v[238:239], v[236:237], 0, s[8:9]
	s_mov_b32 m0, s22
	s_barrier
	ds_read_b128 v[182:185], v139 offset:16384
	ds_read_b128 v[186:189], v139 offset:17408
	ds_read_b128 v[190:193], v138 offset:16384
	ds_read_b128 v[194:197], v138 offset:17408
	ds_read_b128 v[198:201], v137 offset:16384
	ds_read_b128 v[202:205], v137 offset:17408
	ds_read_b128 v[206:209], v136 offset:16384
	ds_read_b128 v[210:213], v136 offset:17408
	global_load_lds_dwordx4 v[238:239], off
	v_lshl_add_u64 v[238:239], s[18:19], 0, v[132:133]
	v_readfirstlane_b32 s22, v147
	v_lshl_add_u64 v[240:241], v[238:239], 0, s[8:9]
	s_mov_b32 m0, s22
	s_add_u32 s18, s18, 0x100
	global_load_lds_dwordx4 v[240:241], off
	s_barrier
	s_waitcnt lgkmcnt(0)
	s_addc_u32 s19, s19, 0
	s_waitcnt lgkmcnt(0)
	v_mfma_f32_16x16x32_bf16 v[62:65], v[182:185], v[160:163], 0
	v_mfma_f32_16x16x32_bf16 v[58:61], v[182:185], v[174:177], 0
	v_mfma_f32_16x16x32_bf16 v[54:57], v[190:193], v[160:163], 0
	v_mfma_f32_16x16x32_bf16 v[50:53], v[190:193], v[174:177], 0
	v_mfma_f32_16x16x32_bf16 v[46:49], v[198:201], v[160:163], 0
	v_mfma_f32_16x16x32_bf16 v[42:45], v[198:201], v[174:177], 0
	v_mfma_f32_16x16x32_bf16 v[38:41], v[206:209], v[160:163], 0
	v_mfma_f32_16x16x32_bf16 v[34:37], v[206:209], v[174:177], 0
	v_mfma_f32_16x16x32_bf16 v[62:65], v[186:189], v[164:167], v[62:65]
	v_mfma_f32_16x16x32_bf16 v[58:61], v[186:189], v[178:181], v[58:61]
	v_mfma_f32_16x16x32_bf16 v[54:57], v[194:197], v[164:167], v[54:57]
	v_mfma_f32_16x16x32_bf16 v[50:53], v[194:197], v[178:181], v[50:53]
	v_mfma_f32_16x16x32_bf16 v[46:49], v[202:205], v[164:167], v[46:49]
	v_mfma_f32_16x16x32_bf16 v[42:45], v[202:205], v[178:181], v[42:45]
	v_mfma_f32_16x16x32_bf16 v[38:41], v[210:213], v[164:167], v[38:41]
	v_mfma_f32_16x16x32_bf16 v[34:37], v[210:213], v[178:181], v[34:37]
	s_barrier
	v_lshl_add_u64 v[240:241], s[16:17], 0, v[130:131]
	v_readfirstlane_b32 s22, v154
	v_lshl_add_u64 v[160:161], v[240:241], 0, s[8:9]
	s_mov_b32 m0, s22
	v_lshl_add_u64 v[242:243], s[16:17], 0, v[132:133]
	v_readfirstlane_b32 s22, v155
	global_load_lds_dwordx4 v[160:161], off
	v_lshl_add_u64 v[160:161], v[242:243], 0, s[8:9]
	s_mov_b32 m0, s22
	s_add_u32 s16, s16, 0x100
	global_load_lds_dwordx4 v[160:161], off
	s_waitcnt vmcnt(10)
	s_addc_u32 s17, s17, 0
	s_barrier
	v_mfma_f32_16x16x32_bf16 v[30:33], v[182:185], v[214:217], 0
	v_mfma_f32_16x16x32_bf16 v[26:29], v[182:185], v[222:225], 0
	v_mfma_f32_16x16x32_bf16 v[22:25], v[190:193], v[214:217], 0
	v_mfma_f32_16x16x32_bf16 v[18:21], v[190:193], v[222:225], 0
	v_mfma_f32_16x16x32_bf16 v[14:17], v[198:201], v[214:217], 0
	v_mfma_f32_16x16x32_bf16 v[10:13], v[198:201], v[222:225], 0
	v_mfma_f32_16x16x32_bf16 v[6:9], v[206:209], v[214:217], 0
	v_mfma_f32_16x16x32_bf16 v[2:5], v[206:209], v[222:225], 0
	v_mfma_f32_16x16x32_bf16 v[30:33], v[186:189], v[218:221], v[30:33]
	v_mfma_f32_16x16x32_bf16 v[26:29], v[186:189], v[226:229], v[26:29]
	v_mfma_f32_16x16x32_bf16 v[22:25], v[194:197], v[218:221], v[22:25]
	v_mfma_f32_16x16x32_bf16 v[18:21], v[194:197], v[226:229], v[18:21]
	v_mfma_f32_16x16x32_bf16 v[14:17], v[202:205], v[218:221], v[14:17]
	v_mfma_f32_16x16x32_bf16 v[10:13], v[202:205], v[226:229], v[10:13]
	v_mfma_f32_16x16x32_bf16 v[6:9], v[210:213], v[218:221], v[6:9]
	v_mfma_f32_16x16x32_bf16 v[2:5], v[210:213], v[226:229], v[2:5]
	s_barrier
	ds_read_b128 v[160:163], v141
	ds_read_b128 v[164:167], v141 offset:1024
	ds_read_b128 v[174:177], v141 offset:2048
	ds_read_b128 v[178:181], v141 offset:3072
	v_readfirstlane_b32 s22, v148
	v_lshl_add_u64 v[168:169], v[168:169], 0, s[8:9]
	s_mov_b32 m0, s22
	v_readfirstlane_b32 s22, v149
	ds_read_b128 v[182:185], v139 offset:32768
	ds_read_b128 v[186:189], v139 offset:33792
	ds_read_b128 v[190:193], v138 offset:32768
	ds_read_b128 v[194:197], v138 offset:33792
	ds_read_b128 v[198:201], v137 offset:32768
	ds_read_b128 v[202:205], v137 offset:33792
	ds_read_b128 v[206:209], v136 offset:32768
	ds_read_b128 v[210:213], v136 offset:33792
	global_load_lds_dwordx4 v[168:169], off
	v_lshl_add_u64 v[168:169], v[230:231], 0, s[8:9]
	s_mov_b32 m0, s22
	s_add_u32 s12, s12, 0x100
	global_load_lds_dwordx4 v[168:169], off
	s_waitcnt lgkmcnt(8)
	s_waitcnt vmcnt(10)
	s_barrier
; #define STAGE(P, GP, ktrel) do { const GAS char* _g = (GP) + (ktrel) * (BK * 2); \
;     __builtin_amdgcn_global_load_lds((const GAS unsigned*)(_g + so0), (unsigned*)((char*)(P) + tid_ * 16), 16, 0, 0); \
;     __builtin_amdgcn_global_load_lds((const GAS unsigned*)(_g + so1), (unsigned*)((char*)(P) + tid_ * 16 + 8192), 16, 0, 0); } while (0)
; #define WAIT_V(n) asm volatile("s_waitcnt vmcnt(" #n ")" ::: "memory")
; #define WAIT_L(n) asm volatile("s_waitcnt lgkmcnt(" #n ")" ::: "memory")
; #define BAR __builtin_amdgcn_s_barrier()
; #define SCHED __builtin_amdgcn_sched_barrier(0)
; #define LDA(dst, b, h) for (int m = 0; m < 4; ++m) for (int k = 0; k < 2; ++k) \
;     dst[m][k] = *reinterpret_cast<const bf16x8*>((char*)SA(b, h) + lds_byte(wr * 64 + m * 16 + fr, k * 32 + fq * 8))
; #define LDB(dst, b, h) for (int n = 0; n < 2; ++n) for (int k = 0; k < 2; ++k) \
;     dst[n][k] = *reinterpret_cast<const bf16x8*>((char*)SB(b, h) + lds_byte(wc * 32 + n * 16 + fr, k * 32 + fq * 8))
; #define MMA(ai, bj, At_, Bt_) do { __builtin_amdgcn_s_setprio(1); \
;     for (int m = 0; m < 4; ++m) for (int n = 0; n < 2; ++n) for (int k = 0; k < 2; ++k) \
;       acc[ai][bj][m][n] = __builtin_amdgcn_mfma_f32_16x16x32_bf16(At_[m][k], Bt_[n][k], acc[ai][bj][m][n], 0, 0, 0); \
;     __builtin_amdgcn_s_setprio(0); } while (0)
; template <int K, int LD = K>
; __device__ __forceinline__ void gemm_main(const GAS bf16* A, const GAS bf16* Bt, int brow, int bcol, f32x4 (&acc)[2][2][4][2]) {
;     ...
;     WAIT_L(8); BAR; WAIT_L(0); MMA(0, 0, At, B0); BAR; SCHED;
;     LDB(B1, 1, 1); STAGE(SB(1, 0), pB0, 3);
;     BAR; WAIT_L(0); MMA(0, 1, At, B1); BAR;
;     LDA(At, 1, 1); STAGE(SA(1, 0), pA0, 3);
;     BAR; WAIT_L(0); MMA(1, 0, At, B0); BAR; SCHED;
;     STAGE(SB(1, 1), pB1, 3);
;     WAIT_V(6); BAR; MMA(1, 1, At, B1); BAR;
;     pA0 += 4 * BK; pA1 += 4 * BK; pB0 += 4 * BK; pB1 += 4 * BK;
;     asm volatile("" : "+s"(pA0), "+s"(pA1), "+s"(pB0), "+s"(pB1));
;   }
	s_waitcnt lgkmcnt(0)
	s_addc_u32 s13, s13, 0
	s_waitcnt lgkmcnt(0)
	v_mfma_f32_16x16x32_bf16 v[126:129], v[182:185], v[160:163], v[126:129]
	v_mfma_f32_16x16x32_bf16 v[122:125], v[182:185], v[174:177], v[122:125]
	v_mfma_f32_16x16x32_bf16 v[118:121], v[190:193], v[160:163], v[118:121]
	v_mfma_f32_16x16x32_bf16 v[114:117], v[190:193], v[174:177], v[114:117]
	v_mfma_f32_16x16x32_bf16 v[110:113], v[198:201], v[160:163], v[110:113]
	v_mfma_f32_16x16x32_bf16 v[106:109], v[198:201], v[174:177], v[106:109]
	v_mfma_f32_16x16x32_bf16 v[102:105], v[206:209], v[160:163], v[102:105]
	v_mfma_f32_16x16x32_bf16 v[98:101], v[206:209], v[174:177], v[98:101]
	v_mfma_f32_16x16x32_bf16 v[126:129], v[186:189], v[164:167], v[126:129]
	v_mfma_f32_16x16x32_bf16 v[122:125], v[186:189], v[178:181], v[122:125]
	v_mfma_f32_16x16x32_bf16 v[118:121], v[194:197], v[164:167], v[118:121]
	v_mfma_f32_16x16x32_bf16 v[114:117], v[194:197], v[178:181], v[114:117]
	v_mfma_f32_16x16x32_bf16 v[110:113], v[202:205], v[164:167], v[110:113]
	v_mfma_f32_16x16x32_bf16 v[106:109], v[202:205], v[178:181], v[106:109]
	v_mfma_f32_16x16x32_bf16 v[102:105], v[210:213], v[164:167], v[102:105]
	v_mfma_f32_16x16x32_bf16 v[98:101], v[210:213], v[178:181], v[98:101]
	s_barrier
	v_readfirstlane_b32 s22, v156
	v_lshl_add_u64 v[168:169], v[232:233], 0, s[10:11]
	s_mov_b32 m0, s22
	v_readfirstlane_b32 s22, v157
	ds_read_b128 v[214:217], v140
	ds_read_b128 v[218:221], v140 offset:1024
	ds_read_b128 v[222:225], v140 offset:2048
	ds_read_b128 v[226:229], v140 offset:3072
	global_load_lds_dwordx4 v[168:169], off
	v_lshl_add_u64 v[168:169], v[234:235], 0, s[10:11]
	s_mov_b32 m0, s22
	s_nop 0
	global_load_lds_dwordx4 v[168:169], off
	s_waitcnt vmcnt(10)
	s_barrier
	s_waitcnt lgkmcnt(0)
	s_waitcnt lgkmcnt(0)
	v_mfma_f32_16x16x32_bf16 v[94:97], v[182:185], v[214:217], v[94:97]
	v_mfma_f32_16x16x32_bf16 v[90:93], v[182:185], v[222:225], v[90:93]
	v_mfma_f32_16x16x32_bf16 v[86:89], v[190:193], v[214:217], v[86:89]
	v_mfma_f32_16x16x32_bf16 v[82:85], v[190:193], v[222:225], v[82:85]
	v_mfma_f32_16x16x32_bf16 v[78:81], v[198:201], v[214:217], v[78:81]
	v_mfma_f32_16x16x32_bf16 v[74:77], v[198:201], v[222:225], v[74:77]
	v_mfma_f32_16x16x32_bf16 v[70:73], v[206:209], v[214:217], v[70:73]
	v_mfma_f32_16x16x32_bf16 v[66:69], v[206:209], v[222:225], v[66:69]
	v_mfma_f32_16x16x32_bf16 v[94:97], v[186:189], v[218:221], v[94:97]
	v_mfma_f32_16x16x32_bf16 v[90:93], v[186:189], v[226:229], v[90:93]
	v_mfma_f32_16x16x32_bf16 v[86:89], v[194:197], v[218:221], v[86:89]
	v_mfma_f32_16x16x32_bf16 v[82:85], v[194:197], v[226:229], v[82:85]
	v_mfma_f32_16x16x32_bf16 v[78:81], v[202:205], v[218:221], v[78:81]
	v_mfma_f32_16x16x32_bf16 v[74:77], v[202:205], v[226:229], v[74:77]
	v_mfma_f32_16x16x32_bf16 v[70:73], v[210:213], v[218:221], v[70:73]
	v_mfma_f32_16x16x32_bf16 v[66:69], v[210:213], v[226:229], v[66:69]
	v_readfirstlane_b32 s22, v150
	v_lshl_add_u64 v[168:169], v[236:237], 0, s[10:11]
	s_mov_b32 m0, s22
	v_readfirstlane_b32 s22, v151
	s_barrier
	ds_read_b128 v[182:185], v139 offset:49152
	ds_read_b128 v[186:189], v139 offset:50176
	ds_read_b128 v[190:193], v138 offset:49152
	ds_read_b128 v[194:197], v138 offset:50176
	ds_read_b128 v[198:201], v137 offset:49152
	ds_read_b128 v[202:205], v137 offset:50176
	ds_read_b128 v[206:209], v136 offset:49152
	ds_read_b128 v[210:213], v136 offset:50176
	global_load_lds_dwordx4 v[168:169], off
	v_lshl_add_u64 v[168:169], v[238:239], 0, s[10:11]
	s_mov_b32 m0, s22
	s_nop 0
	global_load_lds_dwordx4 v[168:169], off
	s_barrier
	s_waitcnt lgkmcnt(0)
	s_waitcnt lgkmcnt(0)
	v_mfma_f32_16x16x32_bf16 v[62:65], v[182:185], v[160:163], v[62:65]
	v_mfma_f32_16x16x32_bf16 v[58:61], v[182:185], v[174:177], v[58:61]
	v_mfma_f32_16x16x32_bf16 v[54:57], v[190:193], v[160:163], v[54:57]
	v_mfma_f32_16x16x32_bf16 v[50:53], v[190:193], v[174:177], v[50:53]
	v_mfma_f32_16x16x32_bf16 v[46:49], v[198:201], v[160:163], v[46:49]
	v_mfma_f32_16x16x32_bf16 v[42:45], v[198:201], v[174:177], v[42:45]
	v_mfma_f32_16x16x32_bf16 v[38:41], v[206:209], v[160:163], v[38:41]
	v_mfma_f32_16x16x32_bf16 v[34:37], v[206:209], v[174:177], v[34:37]
	v_mfma_f32_16x16x32_bf16 v[62:65], v[186:189], v[164:167], v[62:65]
	v_mfma_f32_16x16x32_bf16 v[58:61], v[186:189], v[178:181], v[58:61]
	v_mfma_f32_16x16x32_bf16 v[54:57], v[194:197], v[164:167], v[54:57]
	v_mfma_f32_16x16x32_bf16 v[50:53], v[194:197], v[178:181], v[50:53]
	v_mfma_f32_16x16x32_bf16 v[46:49], v[202:205], v[164:167], v[46:49]
	v_mfma_f32_16x16x32_bf16 v[42:45], v[202:205], v[178:181], v[42:45]
	v_mfma_f32_16x16x32_bf16 v[38:41], v[210:213], v[164:167], v[38:41]
	v_mfma_f32_16x16x32_bf16 v[34:37], v[210:213], v[178:181], v[34:37]
	s_barrier
	v_readfirstlane_b32 s22, v158
	v_lshl_add_u64 v[160:161], v[240:241], 0, s[10:11]
	s_mov_b32 m0, s22
	v_readfirstlane_b32 s22, v159
	global_load_lds_dwordx4 v[160:161], off
	v_lshl_add_u64 v[160:161], v[242:243], 0, s[10:11]
	s_mov_b32 m0, s22
	s_nop 0
	global_load_lds_dwordx4 v[160:161], off
	s_waitcnt vmcnt(10)
	s_barrier
	v_mfma_f32_16x16x32_bf16 v[30:33], v[182:185], v[214:217], v[30:33]
	v_mfma_f32_16x16x32_bf16 v[26:29], v[182:185], v[222:225], v[26:29]
	v_mfma_f32_16x16x32_bf16 v[22:25], v[190:193], v[214:217], v[22:25]
	v_mfma_f32_16x16x32_bf16 v[18:21], v[190:193], v[222:225], v[18:21]
	v_mfma_f32_16x16x32_bf16 v[14:17], v[198:201], v[214:217], v[14:17]
	v_mfma_f32_16x16x32_bf16 v[10:13], v[198:201], v[222:225], v[10:13]
	v_mfma_f32_16x16x32_bf16 v[6:9], v[206:209], v[214:217], v[6:9]
	v_mfma_f32_16x16x32_bf16 v[2:5], v[206:209], v[222:225], v[2:5]
	v_mfma_f32_16x16x32_bf16 v[30:33], v[186:189], v[218:221], v[30:33]
	v_mfma_f32_16x16x32_bf16 v[26:29], v[186:189], v[226:229], v[26:29]
	v_mfma_f32_16x16x32_bf16 v[22:25], v[194:197], v[218:221], v[22:25]
	v_mfma_f32_16x16x32_bf16 v[18:21], v[194:197], v[226:229], v[18:21]
	v_mfma_f32_16x16x32_bf16 v[14:17], v[202:205], v[218:221], v[14:17]
	v_mfma_f32_16x16x32_bf16 v[10:13], v[202:205], v[226:229], v[10:13]
	v_mfma_f32_16x16x32_bf16 v[6:9], v[210:213], v[218:221], v[6:9]
	v_mfma_f32_16x16x32_bf16 v[2:5], v[210:213], v[226:229], v[2:5]
	s_add_i32 s15, s15, 2
	s_cmp_lt_u32 s15, 12
	s_barrier
	s_cbranch_scc1 .LBB0_884
	s_branch .Lpeel2_exit

; #define STAGE(P, GP, ktrel) do { const GAS char* _g = (GP) + (ktrel) * (BK * 2); \
;     __builtin_amdgcn_global_load_lds((const GAS unsigned*)(_g + so0), (unsigned*)((char*)(P) + tid_ * 16), 16, 0, 0); \
;     __builtin_amdgcn_global_load_lds((const GAS unsigned*)(_g + so1), (unsigned*)((char*)(P) + tid_ * 16 + 8192), 16, 0, 0); } while (0)
; #define WAIT_V(n) asm volatile("s_waitcnt vmcnt(" #n ")" ::: "memory")
; #define WAIT_L(n) asm volatile("s_waitcnt lgkmcnt(" #n ")" ::: "memory")
; #define BAR __builtin_amdgcn_s_barrier()
; #define LDA(dst, b, h) for (int m = 0; m < 4; ++m) for (int k = 0; k < 2; ++k) \
;     dst[m][k] = *reinterpret_cast<const bf16x8*>((char*)SA(b, h) + lds_byte(wr * 64 + m * 16 + fr, k * 32 + fq * 8))
; #define LDB(dst, b, h) for (int n = 0; n < 2; ++n) for (int k = 0; k < 2; ++k) \
;     dst[n][k] = *reinterpret_cast<const bf16x8*>((char*)SB(b, h) + lds_byte(wc * 32 + n * 16 + fr, k * 32 + fq * 8))
; #define MMA(ai, bj, At_, Bt_) do { __builtin_amdgcn_s_setprio(1); \
;     for (int m = 0; m < 4; ++m) for (int n = 0; n < 2; ++n) for (int k = 0; k < 2; ++k) \
;       acc[ai][bj][m][n] = __builtin_amdgcn_mfma_f32_16x16x32_bf16(At_[m][k], Bt_[n][k], acc[ai][bj][m][n], 0, 0, 0); \
;     __builtin_amdgcn_s_setprio(0); } while (0)
; template <int K, int LD = K>
; __device__ __forceinline__ void gemm_main(const GAS bf16* A, const GAS bf16* Bt, int brow, int bcol, f32x4 (&acc)[2][2][4][2]) {
;     ...
;   { LDB(B0, 0, 0); LDA(At, 0, 0); STAGE(SA(1, 1), pA1, 1);
;     BAR; WAIT_L(0); MMA(0, 0, At, B0); BAR;
;     LDB(B1, 0, 1); BAR; WAIT_L(0); MMA(0, 1, At, B1); BAR;
;     LDA(At, 0, 1); WAIT_V(4); BAR; WAIT_L(0); MMA(1, 0, At, B0); MMA(1, 1, At, B1); BAR; }
.Lpeel2_exit:
	v_lshl_add_u64 v[198:199], s[12:13], 0, v[130:131]
	v_readfirstlane_b32 s15, v144
	v_lshl_add_u64 v[198:199], v[198:199], 0, s[6:7]
	s_mov_b32 m0, s15
	v_lshl_add_u64 v[132:133], s[12:13], 0, v[132:133]
	v_readfirstlane_b32 s12, v143
	ds_read_b128 v[146:149], v145
	ds_read_b128 v[150:153], v145 offset:1024
	ds_read_b128 v[154:157], v145 offset:2048
	ds_read_b128 v[158:161], v145 offset:3072
	ds_read_b128 v[162:165], v139
	ds_read_b128 v[166:169], v139 offset:1024
	ds_read_b128 v[174:177], v138
	ds_read_b128 v[178:181], v138 offset:1024
	ds_read_b128 v[182:185], v137
	ds_read_b128 v[186:189], v137 offset:1024
	ds_read_b128 v[190:193], v136
	ds_read_b128 v[194:197], v136 offset:1024
	global_load_lds_dwordx4 v[198:199], off
	v_lshl_add_u64 v[132:133], v[132:133], 0, s[6:7]
	s_mov_b32 m0, s12
	s_nop 0
	global_load_lds_dwordx4 v[132:133], off
	s_waitcnt vmcnt(10)
	s_barrier
	s_waitcnt lgkmcnt(0)
	s_waitcnt lgkmcnt(0)
	v_mfma_f32_16x16x32_bf16 v[126:129], v[162:165], v[146:149], v[126:129]
	v_mfma_f32_16x16x32_bf16 v[122:125], v[162:165], v[154:157], v[122:125]
	v_mfma_f32_16x16x32_bf16 v[110:113], v[182:185], v[146:149], v[110:113]
	v_mfma_f32_16x16x32_bf16 v[106:109], v[182:185], v[154:157], v[106:109]
	v_mfma_f32_16x16x32_bf16 v[126:129], v[166:169], v[150:153], v[126:129]
	v_mfma_f32_16x16x32_bf16 v[122:125], v[166:169], v[158:161], v[122:125]
	v_mfma_f32_16x16x32_bf16 v[118:121], v[174:177], v[146:149], v[118:121]
	v_mfma_f32_16x16x32_bf16 v[114:117], v[174:177], v[154:157], v[114:117]
	v_mfma_f32_16x16x32_bf16 v[110:113], v[186:189], v[150:153], v[110:113]
	v_mfma_f32_16x16x32_bf16 v[106:109], v[186:189], v[158:161], v[106:109]
	v_mfma_f32_16x16x32_bf16 v[102:105], v[190:193], v[146:149], v[102:105]
	v_mfma_f32_16x16x32_bf16 v[98:101], v[190:193], v[154:157], v[98:101]
	v_mfma_f32_16x16x32_bf16 v[198:201], v[178:181], v[150:153], v[118:121]
	v_mfma_f32_16x16x32_bf16 v[202:205], v[178:181], v[158:161], v[114:117]
	v_mfma_f32_16x16x32_bf16 v[206:209], v[194:197], v[150:153], v[102:105]
	v_mfma_f32_16x16x32_bf16 v[210:213], v[194:197], v[158:161], v[98:101]
	s_barrier
	s_nop 1
	ds_read_b128 v[98:101], v142
	ds_read_b128 v[102:105], v142 offset:1024
	ds_read_b128 v[114:117], v142 offset:2048
	ds_read_b128 v[118:121], v142 offset:3072
	s_waitcnt vmcnt(8)
	s_barrier
	s_waitcnt lgkmcnt(0)
	s_waitcnt lgkmcnt(0)
	v_mfma_f32_16x16x32_bf16 v[94:97], v[162:165], v[98:101], v[94:97]
	v_mfma_f32_16x16x32_bf16 v[90:93], v[162:165], v[114:117], v[90:93]
	v_mfma_f32_16x16x32_bf16 v[78:81], v[182:185], v[98:101], v[78:81]
	v_mfma_f32_16x16x32_bf16 v[74:77], v[182:185], v[114:117], v[74:77]
	v_mfma_f32_16x16x32_bf16 v[94:97], v[166:169], v[102:105], v[94:97]
	v_mfma_f32_16x16x32_bf16 v[90:93], v[166:169], v[118:121], v[90:93]
	v_mfma_f32_16x16x32_bf16 v[86:89], v[174:177], v[98:101], v[86:89]
	v_mfma_f32_16x16x32_bf16 v[82:85], v[174:177], v[114:117], v[82:85]
	v_mfma_f32_16x16x32_bf16 v[78:81], v[186:189], v[102:105], v[78:81]
	v_mfma_f32_16x16x32_bf16 v[74:77], v[186:189], v[118:121], v[74:77]
	v_mfma_f32_16x16x32_bf16 v[70:73], v[190:193], v[98:101], v[70:73]
	v_mfma_f32_16x16x32_bf16 v[66:69], v[190:193], v[114:117], v[66:69]
	v_mfma_f32_16x16x32_bf16 v[142:145], v[178:181], v[102:105], v[86:89]
	v_mfma_f32_16x16x32_bf16 v[162:165], v[178:181], v[118:121], v[82:85]
	v_mfma_f32_16x16x32_bf16 v[166:169], v[194:197], v[102:105], v[70:73]
	v_mfma_f32_16x16x32_bf16 v[174:177], v[194:197], v[118:121], v[66:69]
	s_barrier
	s_nop 1
	ds_read_b128 v[66:69], v139 offset:16384
	ds_read_b128 v[70:73], v139 offset:17408
	ds_read_b128 v[82:85], v138 offset:16384
	ds_read_b128 v[86:89], v138 offset:17408
	ds_read_b128 v[178:181], v137 offset:16384
	ds_read_b128 v[182:185], v137 offset:17408
	ds_read_b128 v[186:189], v136 offset:16384
	ds_read_b128 v[190:193], v136 offset:17408
	s_waitcnt vmcnt(4)
	s_barrier
	s_waitcnt lgkmcnt(0)
	s_waitcnt lgkmcnt(0)
	v_mfma_f32_16x16x32_bf16 v[62:65], v[66:69], v[146:149], v[62:65]
	v_mfma_f32_16x16x32_bf16 v[58:61], v[66:69], v[154:157], v[58:61]
	v_mfma_f32_16x16x32_bf16 v[46:49], v[178:181], v[146:149], v[46:49]
	v_mfma_f32_16x16x32_bf16 v[38:41], v[186:189], v[146:149], v[38:41]
	v_mfma_f32_16x16x32_bf16 v[62:65], v[70:73], v[150:153], v[62:65]
	v_mfma_f32_16x16x32_bf16 v[58:61], v[70:73], v[158:161], v[58:61]
	v_mfma_f32_16x16x32_bf16 v[54:57], v[82:85], v[146:149], v[54:57]
	v_mfma_f32_16x16x32_bf16 v[50:53], v[82:85], v[154:157], v[50:53]
	v_mfma_f32_16x16x32_bf16 v[46:49], v[182:185], v[150:153], v[46:49]
	v_mfma_f32_16x16x32_bf16 v[42:45], v[178:181], v[154:157], v[42:45]
	v_mfma_f32_16x16x32_bf16 v[38:41], v[190:193], v[150:153], v[38:41]
	v_mfma_f32_16x16x32_bf16 v[34:37], v[186:189], v[154:157], v[34:37]
	v_mfma_f32_16x16x32_bf16 v[194:197], v[86:89], v[150:153], v[54:57]
	v_mfma_f32_16x16x32_bf16 v[214:217], v[86:89], v[158:161], v[50:53]
	v_mfma_f32_16x16x32_bf16 v[218:221], v[182:185], v[158:161], v[42:45]
	v_mfma_f32_16x16x32_bf16 v[146:149], v[190:193], v[158:161], v[34:37]
	v_mfma_f32_16x16x32_bf16 v[30:33], v[66:69], v[98:101], v[30:33]
	v_mfma_f32_16x16x32_bf16 v[26:29], v[66:69], v[114:117], v[26:29]
	v_mfma_f32_16x16x32_bf16 v[14:17], v[178:181], v[98:101], v[14:17]
	v_mfma_f32_16x16x32_bf16 v[6:9], v[186:189], v[98:101], v[6:9]
	v_mfma_f32_16x16x32_bf16 v[30:33], v[70:73], v[102:105], v[30:33]
	v_mfma_f32_16x16x32_bf16 v[26:29], v[70:73], v[118:121], v[26:29]
	v_mfma_f32_16x16x32_bf16 v[22:25], v[82:85], v[98:101], v[22:25]
	v_mfma_f32_16x16x32_bf16 v[18:21], v[82:85], v[114:117], v[18:21]
	v_mfma_f32_16x16x32_bf16 v[14:17], v[182:185], v[102:105], v[14:17]
	v_mfma_f32_16x16x32_bf16 v[10:13], v[178:181], v[114:117], v[10:13]
	v_mfma_f32_16x16x32_bf16 v[6:9], v[190:193], v[102:105], v[6:9]
	v_mfma_f32_16x16x32_bf16 v[2:5], v[186:189], v[114:117], v[2:5]
	v_mfma_f32_16x16x32_bf16 v[150:153], v[86:89], v[102:105], v[22:25]
	v_mfma_f32_16x16x32_bf16 v[154:157], v[86:89], v[118:121], v[18:21]
	v_mfma_f32_16x16x32_bf16 v[158:161], v[182:185], v[118:121], v[10:13]
	v_mfma_f32_16x16x32_bf16 v[178:181], v[190:193], v[118:121], v[2:5]
	s_barrier
; #define WAIT_V(n) asm volatile("s_waitcnt vmcnt(" #n ")" ::: "memory")
; #define WAIT_L(n) asm volatile("s_waitcnt lgkmcnt(" #n ")" ::: "memory")
; #define BAR __builtin_amdgcn_s_barrier()
; #define LDA(dst, b, h) for (int m = 0; m < 4; ++m) for (int k = 0; k < 2; ++k) \
;     dst[m][k] = *reinterpret_cast<const bf16x8*>((char*)SA(b, h) + lds_byte(wr * 64 + m * 16 + fr, k * 32 + fq * 8))
; #define LDB(dst, b, h) for (int n = 0; n < 2; ++n) for (int k = 0; k < 2; ++k) \
;     dst[n][k] = *reinterpret_cast<const bf16x8*>((char*)SB(b, h) + lds_byte(wc * 32 + n * 16 + fr, k * 32 + fq * 8))
; #define MMA(ai, bj, At_, Bt_) do { __builtin_amdgcn_s_setprio(1); \
;     for (int m = 0; m < 4; ++m) for (int n = 0; n < 2; ++n) for (int k = 0; k < 2; ++k) \
;       acc[ai][bj][m][n] = __builtin_amdgcn_mfma_f32_16x16x32_bf16(At_[m][k], Bt_[n][k], acc[ai][bj][m][n], 0, 0, 0); \
;     __builtin_amdgcn_s_setprio(0); } while (0)
; template <int K, int LD = K>
; __device__ __forceinline__ void gemm_main(const GAS bf16* A, const GAS bf16* Bt, int brow, int bcol, f32x4 (&acc)[2][2][4][2]) {
;     ...
;   { LDB(B0, 1, 0); LDA(At, 1, 0); WAIT_V(2); BAR; WAIT_L(0); MMA(0, 0, At, B0); BAR;
;     LDB(B1, 1, 1); WAIT_V(0); BAR; WAIT_L(0); MMA(0, 1, At, B1); BAR;
;     LDA(At, 1, 1); BAR; WAIT_L(0); MMA(1, 0, At, B0); MMA(1, 1, At, B1); BAR; }
;   if (wr == 0) BAR;
	s_nop 1
	ds_read_b128 v[2:5], v141
	ds_read_b128 v[10:13], v141 offset:1024
	ds_read_b128 v[182:185], v141 offset:2048
	ds_read_b128 v[186:189], v141 offset:3072
	ds_read_b128 v[18:21], v139 offset:32768
	ds_read_b128 v[22:25], v139 offset:33792
	ds_read_b128 v[34:37], v138 offset:32768
	ds_read_b128 v[42:45], v138 offset:33792
	ds_read_b128 v[50:53], v137 offset:32768
	ds_read_b128 v[54:57], v137 offset:33792
	ds_read_b128 v[190:193], v136 offset:32768
	ds_read_b128 v[222:225], v136 offset:33792
	s_waitcnt vmcnt(2)
	s_barrier
	s_waitcnt lgkmcnt(0)
	s_waitcnt lgkmcnt(0)
	v_mfma_f32_16x16x32_bf16 v[66:69], v[18:21], v[2:5], v[126:129]
	v_mfma_f32_16x16x32_bf16 v[118:121], v[22:25], v[10:13], v[66:69]
	v_mfma_f32_16x16x32_bf16 v[66:69], v[18:21], v[182:185], v[122:125]
	v_mfma_f32_16x16x32_bf16 v[114:117], v[22:25], v[186:189], v[66:69]
	v_mfma_f32_16x16x32_bf16 v[66:69], v[34:37], v[2:5], v[198:201]
	v_mfma_f32_16x16x32_bf16 v[102:105], v[42:45], v[10:13], v[66:69]
	v_mfma_f32_16x16x32_bf16 v[66:69], v[34:37], v[182:185], v[202:205]
	v_mfma_f32_16x16x32_bf16 v[98:101], v[42:45], v[186:189], v[66:69]
	v_mfma_f32_16x16x32_bf16 v[66:69], v[50:53], v[2:5], v[110:113]
	v_mfma_f32_16x16x32_bf16 v[86:89], v[54:57], v[10:13], v[66:69]
	v_mfma_f32_16x16x32_bf16 v[66:69], v[50:53], v[182:185], v[106:109]
	v_mfma_f32_16x16x32_bf16 v[82:85], v[54:57], v[186:189], v[66:69]
	v_mfma_f32_16x16x32_bf16 v[66:69], v[190:193], v[2:5], v[206:209]
	v_mfma_f32_16x16x32_bf16 v[70:73], v[222:225], v[10:13], v[66:69]
	v_mfma_f32_16x16x32_bf16 v[66:69], v[190:193], v[182:185], v[210:213]
	v_mfma_f32_16x16x32_bf16 v[66:69], v[222:225], v[186:189], v[66:69]
	s_barrier
	ds_read_b128 v[198:201], v140
	ds_read_b128 v[202:205], v140 offset:1024
	ds_read_b128 v[206:209], v140 offset:2048
	ds_read_b128 v[210:213], v140 offset:3072
	s_waitcnt vmcnt(0)
	s_barrier
	s_waitcnt lgkmcnt(0)
	s_waitcnt lgkmcnt(0)
	v_mfma_f32_16x16x32_bf16 v[94:97], v[18:21], v[198:201], v[94:97]
	v_mfma_f32_16x16x32_bf16 v[18:21], v[18:21], v[206:209], v[90:93]
	v_mfma_f32_16x16x32_bf16 v[122:125], v[22:25], v[210:213], v[18:21]
	v_mfma_f32_16x16x32_bf16 v[18:21], v[34:37], v[198:201], v[142:145]
	v_mfma_f32_16x16x32_bf16 v[110:113], v[42:45], v[202:205], v[18:21]
	v_mfma_f32_16x16x32_bf16 v[18:21], v[34:37], v[206:209], v[162:165]
	v_mfma_f32_16x16x32_bf16 v[106:109], v[42:45], v[210:213], v[18:21]
	v_mfma_f32_16x16x32_bf16 v[18:21], v[50:53], v[198:201], v[78:81]
	v_mfma_f32_16x16x32_bf16 v[126:129], v[22:25], v[202:205], v[94:97]
	v_mfma_f32_16x16x32_bf16 v[94:97], v[54:57], v[202:205], v[18:21]
	v_mfma_f32_16x16x32_bf16 v[18:21], v[50:53], v[206:209], v[74:77]
	v_mfma_f32_16x16x32_bf16 v[90:93], v[54:57], v[210:213], v[18:21]
	v_mfma_f32_16x16x32_bf16 v[18:21], v[190:193], v[198:201], v[166:169]
	v_mfma_f32_16x16x32_bf16 v[78:81], v[222:225], v[202:205], v[18:21]
	v_mfma_f32_16x16x32_bf16 v[18:21], v[190:193], v[206:209], v[174:177]
	v_mfma_f32_16x16x32_bf16 v[74:77], v[222:225], v[210:213], v[18:21]
	s_barrier
	ds_read_b128 v[140:143], v139 offset:49152
	ds_read_b128 v[162:165], v139 offset:50176
	ds_read_b128 v[166:169], v138 offset:49152
	ds_read_b128 v[174:177], v138 offset:50176
	ds_read_b128 v[190:193], v137 offset:49152
	ds_read_b128 v[222:225], v137 offset:50176
	ds_read_b128 v[226:229], v136 offset:49152
	ds_read_b128 v[136:139], v136 offset:50176
	s_barrier
	s_waitcnt lgkmcnt(0)
	s_waitcnt lgkmcnt(0)
	v_mfma_f32_16x16x32_bf16 v[18:21], v[140:143], v[2:5], v[62:65]
	v_mfma_f32_16x16x32_bf16 v[54:57], v[162:165], v[10:13], v[18:21]
	v_mfma_f32_16x16x32_bf16 v[18:21], v[140:143], v[182:185], v[58:61]
	v_mfma_f32_16x16x32_bf16 v[50:53], v[162:165], v[186:189], v[18:21]
	v_mfma_f32_16x16x32_bf16 v[18:21], v[166:169], v[2:5], v[194:197]
	v_mfma_f32_16x16x32_bf16 v[42:45], v[174:177], v[10:13], v[18:21]
	v_mfma_f32_16x16x32_bf16 v[18:21], v[166:169], v[182:185], v[214:217]
	v_mfma_f32_16x16x32_bf16 v[34:37], v[174:177], v[186:189], v[18:21]
	v_mfma_f32_16x16x32_bf16 v[18:21], v[190:193], v[2:5], v[46:49]
	v_mfma_f32_16x16x32_bf16 v[2:5], v[226:229], v[2:5], v[38:41]
	v_mfma_f32_16x16x32_bf16 v[22:25], v[222:225], v[10:13], v[18:21]
	v_mfma_f32_16x16x32_bf16 v[18:21], v[190:193], v[182:185], v[218:221]
	v_mfma_f32_16x16x32_bf16 v[10:13], v[136:139], v[10:13], v[2:5]
	v_mfma_f32_16x16x32_bf16 v[2:5], v[226:229], v[182:185], v[146:149]
	v_mfma_f32_16x16x32_bf16 v[18:21], v[222:225], v[186:189], v[18:21]
	v_mfma_f32_16x16x32_bf16 v[2:5], v[136:139], v[186:189], v[2:5]
	v_mfma_f32_16x16x32_bf16 v[26:29], v[140:143], v[206:209], v[26:29]
	v_mfma_f32_16x16x32_bf16 v[30:33], v[140:143], v[198:201], v[30:33]
	v_mfma_f32_16x16x32_bf16 v[58:61], v[162:165], v[210:213], v[26:29]
	v_mfma_f32_16x16x32_bf16 v[26:29], v[166:169], v[198:201], v[150:153]
	v_mfma_f32_16x16x32_bf16 v[14:17], v[190:193], v[198:201], v[14:17]
	v_mfma_f32_16x16x32_bf16 v[62:65], v[162:165], v[202:205], v[30:33]
	v_mfma_f32_16x16x32_bf16 v[46:49], v[174:177], v[202:205], v[26:29]
	v_mfma_f32_16x16x32_bf16 v[26:29], v[166:169], v[206:209], v[154:157]
	v_mfma_f32_16x16x32_bf16 v[30:33], v[222:225], v[202:205], v[14:17]
	v_mfma_f32_16x16x32_bf16 v[14:17], v[190:193], v[206:209], v[158:161]
	v_mfma_f32_16x16x32_bf16 v[6:9], v[226:229], v[198:201], v[6:9]
	v_mfma_f32_16x16x32_bf16 v[38:41], v[174:177], v[210:213], v[26:29]
	v_mfma_f32_16x16x32_bf16 v[26:29], v[222:225], v[210:213], v[14:17]
	v_mfma_f32_16x16x32_bf16 v[14:17], v[136:139], v[202:205], v[6:9]
	v_mfma_f32_16x16x32_bf16 v[6:9], v[226:229], v[206:209], v[178:181]
	v_mfma_f32_16x16x32_bf16 v[6:9], v[136:139], v[210:213], v[6:9]
	v_cmp_gt_u32_e32 vcc, s34, v135
	s_barrier
	s_and_saveexec_b64 s[12:13], vcc
	s_cbranch_execz .LBB0_887
	s_barrier

; #define GAS __attribute__((address_space(1)))
; #define STAGE(P, GP, ktrel) do { const GAS char* _g = (GP) + (ktrel) * (BK * 2); \
;     __builtin_amdgcn_global_load_lds((const GAS unsigned*)(_g + so0), (unsigned*)((char*)(P) + tid_ * 16), 16, 0, 0); \
;     __builtin_amdgcn_global_load_lds((const GAS unsigned*)(_g + so1), (unsigned*)((char*)(P) + tid_ * 16 + 8192), 16, 0, 0); } while (0)
; #define WAIT_V(n) asm volatile("s_waitcnt vmcnt(" #n ")" ::: "memory")
; #define WAIT_L(n) asm volatile("s_waitcnt lgkmcnt(" #n ")" ::: "memory")
; #define BAR __builtin_amdgcn_s_barrier()
; #define SCHED __builtin_amdgcn_sched_barrier(0)
; #define LDA(dst, b, h) for (int m = 0; m < 4; ++m) for (int k = 0; k < 2; ++k) \
;     dst[m][k] = *reinterpret_cast<const bf16x8*>((char*)SA(b, h) + lds_byte(wr * 64 + m * 16 + fr, k * 32 + fq * 8))
; #define LDB(dst, b, h) for (int n = 0; n < 2; ++n) for (int k = 0; k < 2; ++k) \
;     dst[n][k] = *reinterpret_cast<const bf16x8*>((char*)SB(b, h) + lds_byte(wc * 32 + n * 16 + fr, k * 32 + fq * 8))
; template <int K, int LD = K>
; __device__ __forceinline__ void gemm_main(const GAS bf16* A, const GAS bf16* Bt, int brow, int bcol, f32x4 (&acc)[2][2][4][2]) {
;     ...
;         for (int n = 0; n < 2; ++n) acc[a][b][m][n] = f32x4{0.f, 0.f, 0.f, 0.f};
;   bf16x8 At[4][2], B0[2][2], B1[2][2];
;   unsigned so0, so1;
;   { int r_, c_; stage_rc(tid_ * 16, r_, c_); so0 = (unsigned)(r_ * LD + c_) * 2u; stage_rc(tid_ * 16 + 8192, r_, c_); so1 = (unsigned)(r_ * LD + c_) * 2u; }
;   const GAS char* pA0 = (const GAS char*)A + (long)brow * LD * 2; const GAS char* pA1 = pA0 + (long)HALF * LD * 2;
;   const GAS char* pB0 = (const GAS char*)Bt + (long)bcol * LD * 2; const GAS char* pB1 = pB0 + (long)HALF * LD * 2;
;   asm volatile("" : "+s"(pA0), "+s"(pA1), "+s"(pB0), "+s"(pB1));
;   constexpr int nt = K / BK;
;   static_assert(K % 128 == 0 && K >= 256, "K");
;   if (wr == 1) BAR;
;   WAIT_V(0); BAR;
;   BAR;
;   for (int t = 0; t < nt - 2; t += 2) {
;     LDB(B0, 0, 0); SCHED; LDA(At, 0, 0); STAGE(SA(1, 1), pA1, 1);
;     WAIT_L(8); BAR; WAIT_L(0); MMA(0, 0, At, B0); BAR; SCHED;
;     LDB(B1, 0, 1); STAGE(SB(0, 0), pB0, 2);
;     BAR; WAIT_L(0); MMA(0, 1, At, B1); BAR;
.LBB0_1104:
	s_or_b64 exec, exec, s[22:23]
	v_bfe_i32 v7, v134, 27, 1
	v_lshlrev_b32_e32 v5, 4, v134
	v_lshrrev_b32_e32 v7, 22, v7
	v_add_u32_e32 v7, v5, v7
	v_and_b32_e32 v7, 0xfffffc00, v7
	v_ashrrev_i32_e32 v6, 31, v134
	v_sub_u32_e32 v7, v5, v7
	v_lshrrev_b32_e32 v6, 26, v6
	v_lshrrev_b32_e32 v8, 4, v7
	v_add_u32_e32 v6, v134, v6
	v_bitop3_b32 v8, v8, v7, 32 bitop3:0x6c
	v_ashrrev_i32_e32 v7, 31, v7
	v_ashrrev_i32_e32 v6, 6, v6
	v_lshrrev_b32_e32 v7, 26, v7
	v_lshlrev_b32_e32 v9, 3, v6
	v_add_u32_e32 v7, v8, v7
	v_and_b32_e32 v9, 0x3fffff0, v9
	v_ashrrev_i32_e32 v7, 6, v7
	v_add_u32_e32 v9, v7, v9
	v_mul_i32_i24_e32 v7, 64, v7
	v_sub_u32_e32 v7, v8, v7
	v_lshlrev_b32_e32 v6, 5, v6
	v_ashrrev_i16_sdwa v7, v1, sext(v7) dst_sel:DWORD dst_unused:UNUSED_PAD src0_sel:DWORD src1_sel:BYTE_0
	v_mul_lo_u32 v8, v9, s31
	v_bfe_i32 v7, v7, 0, 16
	v_and_or_b32 v6, v6, 32, v8
	v_add_lshl_u32 v130, v6, v7, 1
	v_add_u32_e32 v6, 0x2000, v5
	v_ashrrev_i32_e32 v7, 31, v6
	v_lshrrev_b32_e32 v7, 22, v7
	v_add_u32_e32 v7, v6, v7
	v_ashrrev_i32_e32 v7, 10, v7
	v_mul_i32_i24_e32 v8, 0x400, v7
	v_sub_u32_e32 v6, v6, v8
	v_lshrrev_b32_e32 v8, 4, v6
	v_bitop3_b32 v6, v8, v6, 32 bitop3:0x6c
	v_ashrrev_i32_e32 v9, 31, v6
	v_lshrrev_b32_e32 v9, 26, v9
	v_lshlrev_b32_e32 v8, 3, v7
	v_add_u32_e32 v9, v6, v9
	v_and_b32_e32 v8, 0x3fffff0, v8
	v_lshrrev_b32_e32 v10, 6, v9
	v_and_b32_e32 v9, 0xc0, v9
	v_add_u32_e32 v8, v10, v8
	v_sub_u32_e32 v6, v6, v9
	v_lshlrev_b32_e32 v7, 5, v7
	v_ashrrev_i16_sdwa v6, v1, sext(v6) dst_sel:DWORD dst_unused:UNUSED_PAD src0_sel:DWORD src1_sel:BYTE_0
	v_mul_lo_u32 v8, v8, s31
	v_bfe_i32 v6, v6, 0, 16
	v_and_or_b32 v7, v7, 32, v8
	v_and_b32_e32 v3, 15, v134
	v_add_lshl_u32 v132, v7, v6, 1
	v_lshlrev_b32_e32 v6, 2, v134
	v_and_b32_e32 v4, 48, v134
	v_lshlrev_b32_e32 v3, 6, v3
	v_and_b32_e32 v6, 32, v6
	v_lshlrev_b32_e32 v11, 6, v134
	v_bitop3_b32 v3, v3, v6, v4 bitop3:0x36
	v_lshlrev_b32_e32 v13, 13, v2
	v_and_or_b32 v2, v11, s38, v4
	v_add_u32_e32 v7, s34, v3
	v_add_u32_e32 v8, s35, v3
	v_add_u32_e32 v9, s36, v3
	v_add_u32_e32 v10, s37, v3
	v_and_b32_e32 v12, 0x3000, v11
	v_add_u32_e32 v3, 0x100, v3
	v_xad_u32 v4, v2, v6, s33
	v_or_b32_e32 v6, 0x800, v13
	v_or_b32_e32 v11, 0x1000, v13
	v_or_b32_e32 v14, 0x1800, v13
	v_mov_b32_e32 v2, 0
	v_add_u32_e32 v145, 0x100, v5
	v_add_u32_e32 v151, s34, v5
	v_add_u32_e32 v153, s35, v5
	v_add_u32_e32 v155, s36, v5
	v_add_u32_e32 v157, s37, v5
	v_mov_b32_e32 v133, v131
	s_mov_b32 s22, -2
	v_add_u32_e32 v144, v7, v12
	v_add_u32_e32 v138, v3, v13
	v_add_u32_e32 v137, v4, v6
	v_add_u32_e32 v136, v4, v11
	v_add_u32_e32 v135, v4, v14
	v_add_u32_e32 v143, 0xc000, v145
	v_add_u32_e32 v142, 0xe000, v145
	v_add_u32_e32 v141, v8, v12
	v_add_u32_e32 v146, 0x2000, v145
	v_add_u32_e32 v140, v9, v12
	v_add_u32_e32 v147, 0x4000, v145
	v_add_u32_e32 v148, 0x6000, v145
	v_add_u32_e32 v139, v10, v12
	v_add_u32_e32 v149, 0x8000, v145
	v_add_u32_e32 v150, 0xa000, v145
	v_add_u32_e32 v152, 0x2000, v151
	v_add_u32_e32 v154, 0x2000, v153
	v_add_u32_e32 v156, 0x2000, v155
	v_add_u32_e32 v158, 0x2000, v157
	s_waitcnt vmcnt(0)
	s_barrier
	s_barrier
	ds_read_b128 v[160:163], v144
	ds_read_b128 v[164:167], v144 offset:1024
	ds_read_b128 v[174:177], v144 offset:2048
	ds_read_b128 v[178:181], v144 offset:3072
	v_lshl_add_u64 v[168:169], s[12:13], 0, v[130:131]
	v_readfirstlane_b32 s23, v143
	v_lshl_add_u64 v[214:215], v[168:169], 0, s[6:7]
	s_mov_b32 m0, s23
	v_lshl_add_u64 v[230:231], s[12:13], 0, v[132:133]
	v_readfirstlane_b32 s23, v142
	ds_read_b128 v[182:185], v138
	ds_read_b128 v[186:189], v138 offset:1024
	ds_read_b128 v[190:193], v137
	ds_read_b128 v[194:197], v137 offset:1024
	ds_read_b128 v[198:201], v136
	ds_read_b128 v[202:205], v136 offset:1024
	ds_read_b128 v[206:209], v135
	ds_read_b128 v[210:213], v135 offset:1024
	global_load_lds_dwordx4 v[214:215], off
	v_lshl_add_u64 v[214:215], v[230:231], 0, s[6:7]
	s_mov_b32 m0, s23
	s_nop 0
	global_load_lds_dwordx4 v[214:215], off
	s_waitcnt lgkmcnt(8)
	s_waitcnt vmcnt(10)
	s_barrier
	s_waitcnt lgkmcnt(0)
	s_waitcnt lgkmcnt(0)
	v_mfma_f32_16x16x32_bf16 v[126:129], v[182:185], v[160:163], 0
	v_mfma_f32_16x16x32_bf16 v[122:125], v[182:185], v[174:177], 0
	v_mfma_f32_16x16x32_bf16 v[118:121], v[190:193], v[160:163], 0
	v_mfma_f32_16x16x32_bf16 v[114:117], v[190:193], v[174:177], 0
	v_mfma_f32_16x16x32_bf16 v[110:113], v[198:201], v[160:163], 0
	v_mfma_f32_16x16x32_bf16 v[106:109], v[198:201], v[174:177], 0
	v_mfma_f32_16x16x32_bf16 v[102:105], v[206:209], v[160:163], 0
	v_mfma_f32_16x16x32_bf16 v[98:101], v[206:209], v[174:177], 0
	v_mfma_f32_16x16x32_bf16 v[126:129], v[186:189], v[164:167], v[126:129]
	v_mfma_f32_16x16x32_bf16 v[122:125], v[186:189], v[178:181], v[122:125]
	v_mfma_f32_16x16x32_bf16 v[118:121], v[194:197], v[164:167], v[118:121]
	v_mfma_f32_16x16x32_bf16 v[114:117], v[194:197], v[178:181], v[114:117]
	v_mfma_f32_16x16x32_bf16 v[110:113], v[202:205], v[164:167], v[110:113]
	v_mfma_f32_16x16x32_bf16 v[106:109], v[202:205], v[178:181], v[106:109]
	v_mfma_f32_16x16x32_bf16 v[102:105], v[210:213], v[164:167], v[102:105]
	v_mfma_f32_16x16x32_bf16 v[98:101], v[210:213], v[178:181], v[98:101]
	s_barrier
	v_lshl_add_u64 v[232:233], s[20:21], 0, v[130:131]
	v_readfirstlane_b32 s23, v151
	v_lshl_add_u64 v[234:235], v[232:233], 0, s[8:9]
	s_mov_b32 m0, s23
	ds_read_b128 v[214:217], v141
	ds_read_b128 v[218:221], v141 offset:1024
	ds_read_b128 v[222:225], v141 offset:2048
	ds_read_b128 v[226:229], v141 offset:3072
	global_load_lds_dwordx4 v[234:235], off
	v_lshl_add_u64 v[234:235], s[20:21], 0, v[132:133]
	v_readfirstlane_b32 s23, v152
	v_lshl_add_u64 v[236:237], v[234:235], 0, s[8:9]
	s_mov_b32 m0, s23
	s_add_u32 s20, s20, 0x100
	global_load_lds_dwordx4 v[236:237], off
	s_waitcnt vmcnt(10)
	s_barrier
; #define STAGE(P, GP, ktrel) do { const GAS char* _g = (GP) + (ktrel) * (BK * 2); \
;     __builtin_amdgcn_global_load_lds((const GAS unsigned*)(_g + so0), (unsigned*)((char*)(P) + tid_ * 16), 16, 0, 0); \
;     __builtin_amdgcn_global_load_lds((const GAS unsigned*)(_g + so1), (unsigned*)((char*)(P) + tid_ * 16 + 8192), 16, 0, 0); } while (0)
; #define WAIT_V(n) asm volatile("s_waitcnt vmcnt(" #n ")" ::: "memory")
; #define WAIT_L(n) asm volatile("s_waitcnt lgkmcnt(" #n ")" ::: "memory")
; #define BAR __builtin_amdgcn_s_barrier()
; #define SCHED __builtin_amdgcn_sched_barrier(0)
; #define LDA(dst, b, h) for (int m = 0; m < 4; ++m) for (int k = 0; k < 2; ++k) \
;     dst[m][k] = *reinterpret_cast<const bf16x8*>((char*)SA(b, h) + lds_byte(wr * 64 + m * 16 + fr, k * 32 + fq * 8))
; #define LDB(dst, b, h) for (int n = 0; n < 2; ++n) for (int k = 0; k < 2; ++k) \
;     dst[n][k] = *reinterpret_cast<const bf16x8*>((char*)SB(b, h) + lds_byte(wc * 32 + n * 16 + fr, k * 32 + fq * 8))
; #define MMA(ai, bj, At_, Bt_) do { __builtin_amdgcn_s_setprio(1); \
;     for (int m = 0; m < 4; ++m) for (int n = 0; n < 2; ++n) for (int k = 0; k < 2; ++k) \
;       acc[ai][bj][m][n] = __builtin_amdgcn_mfma_f32_16x16x32_bf16(At_[m][k], Bt_[n][k], acc[ai][bj][m][n], 0, 0, 0); \
;     __builtin_amdgcn_s_setprio(0); } while (0)
; template <int K, int LD = K>
; __device__ __forceinline__ void gemm_main(const GAS bf16* A, const GAS bf16* Bt, int brow, int bcol, f32x4 (&acc)[2][2][4][2]) {
;     ...
;     BAR; WAIT_L(0); MMA(0, 1, At, B1); BAR;
;     LDA(At, 0, 1); STAGE(SA(0, 0), pA0, 2);
;     BAR; WAIT_L(0); MMA(1, 0, At, B0); BAR; SCHED;
;     STAGE(SB(0, 1), pB1, 2);
;     WAIT_V(6); BAR; MMA(1, 1, At, B1); BAR;
;     LDB(B0, 1, 0); SCHED; LDA(At, 1, 0); STAGE(SA(0, 1), pA1, 2);
;     WAIT_L(8); BAR; WAIT_L(0); MMA(0, 0, At, B0); BAR; SCHED;
	s_waitcnt lgkmcnt(0)
	s_addc_u32 s21, s21, 0
	s_waitcnt lgkmcnt(0)
	v_mfma_f32_16x16x32_bf16 v[94:97], v[182:185], v[214:217], 0
	v_mfma_f32_16x16x32_bf16 v[90:93], v[182:185], v[222:225], 0
	v_mfma_f32_16x16x32_bf16 v[86:89], v[190:193], v[214:217], 0
	v_mfma_f32_16x16x32_bf16 v[82:85], v[190:193], v[222:225], 0
	v_mfma_f32_16x16x32_bf16 v[78:81], v[198:201], v[214:217], 0
	v_mfma_f32_16x16x32_bf16 v[74:77], v[198:201], v[222:225], 0
	v_mfma_f32_16x16x32_bf16 v[70:73], v[206:209], v[214:217], 0
	v_mfma_f32_16x16x32_bf16 v[66:69], v[206:209], v[222:225], 0
	v_mfma_f32_16x16x32_bf16 v[94:97], v[186:189], v[218:221], v[94:97]
	v_mfma_f32_16x16x32_bf16 v[90:93], v[186:189], v[226:229], v[90:93]
	v_mfma_f32_16x16x32_bf16 v[86:89], v[194:197], v[218:221], v[86:89]
	v_mfma_f32_16x16x32_bf16 v[82:85], v[194:197], v[226:229], v[82:85]
	v_mfma_f32_16x16x32_bf16 v[78:81], v[202:205], v[218:221], v[78:81]
	v_mfma_f32_16x16x32_bf16 v[74:77], v[202:205], v[226:229], v[74:77]
	v_mfma_f32_16x16x32_bf16 v[70:73], v[210:213], v[218:221], v[70:73]
	v_mfma_f32_16x16x32_bf16 v[66:69], v[210:213], v[226:229], v[66:69]
	v_lshl_add_u64 v[236:237], s[18:19], 0, v[130:131]
	v_readfirstlane_b32 s23, v145
	v_lshl_add_u64 v[238:239], v[236:237], 0, s[8:9]
	s_mov_b32 m0, s23
	s_barrier
	ds_read_b128 v[182:185], v138 offset:16384
	ds_read_b128 v[186:189], v138 offset:17408
	ds_read_b128 v[190:193], v137 offset:16384
	ds_read_b128 v[194:197], v137 offset:17408
	ds_read_b128 v[198:201], v136 offset:16384
	ds_read_b128 v[202:205], v136 offset:17408
	ds_read_b128 v[206:209], v135 offset:16384
	ds_read_b128 v[210:213], v135 offset:17408
	global_load_lds_dwordx4 v[238:239], off
	v_lshl_add_u64 v[238:239], s[18:19], 0, v[132:133]
	v_readfirstlane_b32 s23, v146
	v_lshl_add_u64 v[240:241], v[238:239], 0, s[8:9]
	s_mov_b32 m0, s23
	s_add_u32 s18, s18, 0x100
	global_load_lds_dwordx4 v[240:241], off
	s_barrier
	s_waitcnt lgkmcnt(0)
	s_addc_u32 s19, s19, 0
	s_waitcnt lgkmcnt(0)
	v_mfma_f32_16x16x32_bf16 v[62:65], v[182:185], v[160:163], 0
	v_mfma_f32_16x16x32_bf16 v[58:61], v[182:185], v[174:177], 0
	v_mfma_f32_16x16x32_bf16 v[54:57], v[190:193], v[160:163], 0
	v_mfma_f32_16x16x32_bf16 v[50:53], v[190:193], v[174:177], 0
	v_mfma_f32_16x16x32_bf16 v[46:49], v[198:201], v[160:163], 0
	v_mfma_f32_16x16x32_bf16 v[42:45], v[198:201], v[174:177], 0
	v_mfma_f32_16x16x32_bf16 v[38:41], v[206:209], v[160:163], 0
	v_mfma_f32_16x16x32_bf16 v[34:37], v[206:209], v[174:177], 0
	v_mfma_f32_16x16x32_bf16 v[62:65], v[186:189], v[164:167], v[62:65]
	v_mfma_f32_16x16x32_bf16 v[58:61], v[186:189], v[178:181], v[58:61]
	v_mfma_f32_16x16x32_bf16 v[54:57], v[194:197], v[164:167], v[54:57]
	v_mfma_f32_16x16x32_bf16 v[50:53], v[194:197], v[178:181], v[50:53]
	v_mfma_f32_16x16x32_bf16 v[46:49], v[202:205], v[164:167], v[46:49]
	v_mfma_f32_16x16x32_bf16 v[42:45], v[202:205], v[178:181], v[42:45]
	v_mfma_f32_16x16x32_bf16 v[38:41], v[210:213], v[164:167], v[38:41]
	v_mfma_f32_16x16x32_bf16 v[34:37], v[210:213], v[178:181], v[34:37]
	s_barrier
	v_lshl_add_u64 v[240:241], s[16:17], 0, v[130:131]
	v_readfirstlane_b32 s23, v153
	v_lshl_add_u64 v[160:161], v[240:241], 0, s[8:9]
	s_mov_b32 m0, s23
	v_lshl_add_u64 v[242:243], s[16:17], 0, v[132:133]
	v_readfirstlane_b32 s23, v154
	global_load_lds_dwordx4 v[160:161], off
	v_lshl_add_u64 v[160:161], v[242:243], 0, s[8:9]
	s_mov_b32 m0, s23
	s_add_u32 s16, s16, 0x100
	global_load_lds_dwordx4 v[160:161], off
	s_waitcnt vmcnt(10)
	s_addc_u32 s17, s17, 0
	s_barrier
	v_mfma_f32_16x16x32_bf16 v[30:33], v[182:185], v[214:217], 0
	v_mfma_f32_16x16x32_bf16 v[26:29], v[182:185], v[222:225], 0
	v_mfma_f32_16x16x32_bf16 v[22:25], v[190:193], v[214:217], 0
	v_mfma_f32_16x16x32_bf16 v[18:21], v[190:193], v[222:225], 0
	v_mfma_f32_16x16x32_bf16 v[14:17], v[198:201], v[214:217], 0
	v_mfma_f32_16x16x32_bf16 v[10:13], v[198:201], v[222:225], 0
	v_mfma_f32_16x16x32_bf16 v[6:9], v[206:209], v[214:217], 0
	v_mfma_f32_16x16x32_bf16 v[2:5], v[206:209], v[222:225], 0
	v_mfma_f32_16x16x32_bf16 v[30:33], v[186:189], v[218:221], v[30:33]
	v_mfma_f32_16x16x32_bf16 v[26:29], v[186:189], v[226:229], v[26:29]
	v_mfma_f32_16x16x32_bf16 v[22:25], v[194:197], v[218:221], v[22:25]
	v_mfma_f32_16x16x32_bf16 v[18:21], v[194:197], v[226:229], v[18:21]
	v_mfma_f32_16x16x32_bf16 v[14:17], v[202:205], v[218:221], v[14:17]
	v_mfma_f32_16x16x32_bf16 v[10:13], v[202:205], v[226:229], v[10:13]
	v_mfma_f32_16x16x32_bf16 v[6:9], v[210:213], v[218:221], v[6:9]
	v_mfma_f32_16x16x32_bf16 v[2:5], v[210:213], v[226:229], v[2:5]
	s_barrier
	ds_read_b128 v[160:163], v140
	ds_read_b128 v[164:167], v140 offset:1024
	ds_read_b128 v[174:177], v140 offset:2048
	ds_read_b128 v[178:181], v140 offset:3072
	v_readfirstlane_b32 s23, v147
	v_lshl_add_u64 v[168:169], v[168:169], 0, s[8:9]
	s_mov_b32 m0, s23
	v_readfirstlane_b32 s23, v148
	ds_read_b128 v[182:185], v138 offset:32768
	ds_read_b128 v[186:189], v138 offset:33792
	ds_read_b128 v[190:193], v137 offset:32768
	ds_read_b128 v[194:197], v137 offset:33792
	ds_read_b128 v[198:201], v136 offset:32768
	ds_read_b128 v[202:205], v136 offset:33792
	ds_read_b128 v[206:209], v135 offset:32768
	ds_read_b128 v[210:213], v135 offset:33792
	global_load_lds_dwordx4 v[168:169], off
	v_lshl_add_u64 v[168:169], v[230:231], 0, s[8:9]
	s_mov_b32 m0, s23
	s_add_u32 s12, s12, 0x100
	global_load_lds_dwordx4 v[168:169], off
	s_waitcnt lgkmcnt(8)
	s_waitcnt vmcnt(10)
	s_barrier
; #define STAGE(P, GP, ktrel) do { const GAS char* _g = (GP) + (ktrel) * (BK * 2); \
;     __builtin_amdgcn_global_load_lds((const GAS unsigned*)(_g + so0), (unsigned*)((char*)(P) + tid_ * 16), 16, 0, 0); \
;     __builtin_amdgcn_global_load_lds((const GAS unsigned*)(_g + so1), (unsigned*)((char*)(P) + tid_ * 16 + 8192), 16, 0, 0); } while (0)
; #define WAIT_V(n) asm volatile("s_waitcnt vmcnt(" #n ")" ::: "memory")
; #define WAIT_L(n) asm volatile("s_waitcnt lgkmcnt(" #n ")" ::: "memory")
; #define BAR __builtin_amdgcn_s_barrier()
; #define SCHED __builtin_amdgcn_sched_barrier(0)
; #define LDA(dst, b, h) for (int m = 0; m < 4; ++m) for (int k = 0; k < 2; ++k) \
;     dst[m][k] = *reinterpret_cast<const bf16x8*>((char*)SA(b, h) + lds_byte(wr * 64 + m * 16 + fr, k * 32 + fq * 8))
; #define LDB(dst, b, h) for (int n = 0; n < 2; ++n) for (int k = 0; k < 2; ++k) \
;     dst[n][k] = *reinterpret_cast<const bf16x8*>((char*)SB(b, h) + lds_byte(wc * 32 + n * 16 + fr, k * 32 + fq * 8))
; #define MMA(ai, bj, At_, Bt_) do { __builtin_amdgcn_s_setprio(1); \
;     for (int m = 0; m < 4; ++m) for (int n = 0; n < 2; ++n) for (int k = 0; k < 2; ++k) \
;       acc[ai][bj][m][n] = __builtin_amdgcn_mfma_f32_16x16x32_bf16(At_[m][k], Bt_[n][k], acc[ai][bj][m][n], 0, 0, 0); \
;     __builtin_amdgcn_s_setprio(0); } while (0)
; template <int K, int LD = K>
; __device__ __forceinline__ void gemm_main(const GAS bf16* A, const GAS bf16* Bt, int brow, int bcol, f32x4 (&acc)[2][2][4][2]) {
;     ...
;     WAIT_L(8); BAR; WAIT_L(0); MMA(0, 0, At, B0); BAR; SCHED;
;     LDB(B1, 1, 1); STAGE(SB(1, 0), pB0, 3);
;     BAR; WAIT_L(0); MMA(0, 1, At, B1); BAR;
;     LDA(At, 1, 1); STAGE(SA(1, 0), pA0, 3);
;     BAR; WAIT_L(0); MMA(1, 0, At, B0); BAR; SCHED;
;     STAGE(SB(1, 1), pB1, 3);
;     WAIT_V(6); BAR; MMA(1, 1, At, B1); BAR;
;     pA0 += 4 * BK; pA1 += 4 * BK; pB0 += 4 * BK; pB1 += 4 * BK;
;     asm volatile("" : "+s"(pA0), "+s"(pA1), "+s"(pB0), "+s"(pB1));
;   }
	s_waitcnt lgkmcnt(0)
	s_addc_u32 s13, s13, 0
	s_waitcnt lgkmcnt(0)
	v_mfma_f32_16x16x32_bf16 v[126:129], v[182:185], v[160:163], v[126:129]
	v_mfma_f32_16x16x32_bf16 v[122:125], v[182:185], v[174:177], v[122:125]
	v_mfma_f32_16x16x32_bf16 v[118:121], v[190:193], v[160:163], v[118:121]
	v_mfma_f32_16x16x32_bf16 v[114:117], v[190:193], v[174:177], v[114:117]
	v_mfma_f32_16x16x32_bf16 v[110:113], v[198:201], v[160:163], v[110:113]
	v_mfma_f32_16x16x32_bf16 v[106:109], v[198:201], v[174:177], v[106:109]
	v_mfma_f32_16x16x32_bf16 v[102:105], v[206:209], v[160:163], v[102:105]
	v_mfma_f32_16x16x32_bf16 v[98:101], v[206:209], v[174:177], v[98:101]
	v_mfma_f32_16x16x32_bf16 v[126:129], v[186:189], v[164:167], v[126:129]
	v_mfma_f32_16x16x32_bf16 v[122:125], v[186:189], v[178:181], v[122:125]
	v_mfma_f32_16x16x32_bf16 v[118:121], v[194:197], v[164:167], v[118:121]
	v_mfma_f32_16x16x32_bf16 v[114:117], v[194:197], v[178:181], v[114:117]
	v_mfma_f32_16x16x32_bf16 v[110:113], v[202:205], v[164:167], v[110:113]
	v_mfma_f32_16x16x32_bf16 v[106:109], v[202:205], v[178:181], v[106:109]
	v_mfma_f32_16x16x32_bf16 v[102:105], v[210:213], v[164:167], v[102:105]
	v_mfma_f32_16x16x32_bf16 v[98:101], v[210:213], v[178:181], v[98:101]
	s_barrier
	v_readfirstlane_b32 s23, v155
	v_lshl_add_u64 v[168:169], v[232:233], 0, s[10:11]
	s_mov_b32 m0, s23
	v_readfirstlane_b32 s23, v156
	ds_read_b128 v[214:217], v139
	ds_read_b128 v[218:221], v139 offset:1024
	ds_read_b128 v[222:225], v139 offset:2048
	ds_read_b128 v[226:229], v139 offset:3072
	global_load_lds_dwordx4 v[168:169], off
	v_lshl_add_u64 v[168:169], v[234:235], 0, s[10:11]
	s_mov_b32 m0, s23
	s_nop 0
	global_load_lds_dwordx4 v[168:169], off
	s_waitcnt vmcnt(10)
	s_barrier
	s_waitcnt lgkmcnt(0)
	s_waitcnt lgkmcnt(0)
	v_mfma_f32_16x16x32_bf16 v[94:97], v[182:185], v[214:217], v[94:97]
	v_mfma_f32_16x16x32_bf16 v[90:93], v[182:185], v[222:225], v[90:93]
	v_mfma_f32_16x16x32_bf16 v[86:89], v[190:193], v[214:217], v[86:89]
	v_mfma_f32_16x16x32_bf16 v[82:85], v[190:193], v[222:225], v[82:85]
	v_mfma_f32_16x16x32_bf16 v[78:81], v[198:201], v[214:217], v[78:81]
	v_mfma_f32_16x16x32_bf16 v[74:77], v[198:201], v[222:225], v[74:77]
	v_mfma_f32_16x16x32_bf16 v[70:73], v[206:209], v[214:217], v[70:73]
	v_mfma_f32_16x16x32_bf16 v[66:69], v[206:209], v[222:225], v[66:69]
	v_mfma_f32_16x16x32_bf16 v[94:97], v[186:189], v[218:221], v[94:97]
	v_mfma_f32_16x16x32_bf16 v[90:93], v[186:189], v[226:229], v[90:93]
	v_mfma_f32_16x16x32_bf16 v[86:89], v[194:197], v[218:221], v[86:89]
	v_mfma_f32_16x16x32_bf16 v[82:85], v[194:197], v[226:229], v[82:85]
	v_mfma_f32_16x16x32_bf16 v[78:81], v[202:205], v[218:221], v[78:81]
	v_mfma_f32_16x16x32_bf16 v[74:77], v[202:205], v[226:229], v[74:77]
	v_mfma_f32_16x16x32_bf16 v[70:73], v[210:213], v[218:221], v[70:73]
	v_mfma_f32_16x16x32_bf16 v[66:69], v[210:213], v[226:229], v[66:69]
	v_readfirstlane_b32 s23, v149
	v_lshl_add_u64 v[168:169], v[236:237], 0, s[10:11]
	s_mov_b32 m0, s23
	v_readfirstlane_b32 s23, v150
	s_barrier
	ds_read_b128 v[182:185], v138 offset:49152
	ds_read_b128 v[186:189], v138 offset:50176
	ds_read_b128 v[190:193], v137 offset:49152
	ds_read_b128 v[194:197], v137 offset:50176
	ds_read_b128 v[198:201], v136 offset:49152
	ds_read_b128 v[202:205], v136 offset:50176
	ds_read_b128 v[206:209], v135 offset:49152
	ds_read_b128 v[210:213], v135 offset:50176
	global_load_lds_dwordx4 v[168:169], off
	v_lshl_add_u64 v[168:169], v[238:239], 0, s[10:11]
	s_mov_b32 m0, s23
	s_nop 0
	global_load_lds_dwordx4 v[168:169], off
	s_barrier
	s_waitcnt lgkmcnt(0)
	s_waitcnt lgkmcnt(0)
	v_mfma_f32_16x16x32_bf16 v[62:65], v[182:185], v[160:163], v[62:65]
	v_mfma_f32_16x16x32_bf16 v[58:61], v[182:185], v[174:177], v[58:61]
	v_mfma_f32_16x16x32_bf16 v[54:57], v[190:193], v[160:163], v[54:57]
	v_mfma_f32_16x16x32_bf16 v[50:53], v[190:193], v[174:177], v[50:53]
	v_mfma_f32_16x16x32_bf16 v[46:49], v[198:201], v[160:163], v[46:49]
	v_mfma_f32_16x16x32_bf16 v[42:45], v[198:201], v[174:177], v[42:45]
	v_mfma_f32_16x16x32_bf16 v[38:41], v[206:209], v[160:163], v[38:41]
	v_mfma_f32_16x16x32_bf16 v[34:37], v[206:209], v[174:177], v[34:37]
	v_mfma_f32_16x16x32_bf16 v[62:65], v[186:189], v[164:167], v[62:65]
	v_mfma_f32_16x16x32_bf16 v[58:61], v[186:189], v[178:181], v[58:61]
	v_mfma_f32_16x16x32_bf16 v[54:57], v[194:197], v[164:167], v[54:57]
	v_mfma_f32_16x16x32_bf16 v[50:53], v[194:197], v[178:181], v[50:53]
	v_mfma_f32_16x16x32_bf16 v[46:49], v[202:205], v[164:167], v[46:49]
	v_mfma_f32_16x16x32_bf16 v[42:45], v[202:205], v[178:181], v[42:45]
	v_mfma_f32_16x16x32_bf16 v[38:41], v[210:213], v[164:167], v[38:41]
	v_mfma_f32_16x16x32_bf16 v[34:37], v[210:213], v[178:181], v[34:37]
	s_barrier
	v_readfirstlane_b32 s23, v157
	v_lshl_add_u64 v[160:161], v[240:241], 0, s[10:11]
	s_mov_b32 m0, s23
	v_readfirstlane_b32 s23, v158
	global_load_lds_dwordx4 v[160:161], off
	v_lshl_add_u64 v[160:161], v[242:243], 0, s[10:11]
	s_mov_b32 m0, s23
	s_nop 0
	global_load_lds_dwordx4 v[160:161], off
	s_waitcnt vmcnt(10)
	s_barrier
	v_mfma_f32_16x16x32_bf16 v[30:33], v[182:185], v[214:217], v[30:33]
	v_mfma_f32_16x16x32_bf16 v[26:29], v[182:185], v[222:225], v[26:29]
	v_mfma_f32_16x16x32_bf16 v[22:25], v[190:193], v[214:217], v[22:25]
	v_mfma_f32_16x16x32_bf16 v[18:21], v[190:193], v[222:225], v[18:21]
	v_mfma_f32_16x16x32_bf16 v[14:17], v[198:201], v[214:217], v[14:17]
	v_mfma_f32_16x16x32_bf16 v[10:13], v[198:201], v[222:225], v[10:13]
	v_mfma_f32_16x16x32_bf16 v[6:9], v[206:209], v[214:217], v[6:9]
	v_mfma_f32_16x16x32_bf16 v[2:5], v[206:209], v[222:225], v[2:5]
	v_mfma_f32_16x16x32_bf16 v[30:33], v[186:189], v[218:221], v[30:33]
	v_mfma_f32_16x16x32_bf16 v[26:29], v[186:189], v[226:229], v[26:29]
	v_mfma_f32_16x16x32_bf16 v[22:25], v[194:197], v[218:221], v[22:25]
	v_mfma_f32_16x16x32_bf16 v[18:21], v[194:197], v[226:229], v[18:21]
	v_mfma_f32_16x16x32_bf16 v[14:17], v[202:205], v[218:221], v[14:17]
	v_mfma_f32_16x16x32_bf16 v[10:13], v[202:205], v[226:229], v[10:13]
	v_mfma_f32_16x16x32_bf16 v[6:9], v[210:213], v[218:221], v[6:9]
	v_mfma_f32_16x16x32_bf16 v[2:5], v[210:213], v[226:229], v[2:5]
	s_add_i32 s22, s22, 2
	s_cmp_lt_u32 s22, 40
	s_barrier
	s_cbranch_scc1 .LBB0_1105
	s_branch .Lpeel1_exit

; #define STAGE(P, GP, ktrel) do { const GAS char* _g = (GP) + (ktrel) * (BK * 2); \
;     __builtin_amdgcn_global_load_lds((const GAS unsigned*)(_g + so0), (unsigned*)((char*)(P) + tid_ * 16), 16, 0, 0); \
;     __builtin_amdgcn_global_load_lds((const GAS unsigned*)(_g + so1), (unsigned*)((char*)(P) + tid_ * 16 + 8192), 16, 0, 0); } while (0)
; #define WAIT_V(n) asm volatile("s_waitcnt vmcnt(" #n ")" ::: "memory")
; #define WAIT_L(n) asm volatile("s_waitcnt lgkmcnt(" #n ")" ::: "memory")
; #define BAR __builtin_amdgcn_s_barrier()
; #define LDA(dst, b, h) for (int m = 0; m < 4; ++m) for (int k = 0; k < 2; ++k) \
;     dst[m][k] = *reinterpret_cast<const bf16x8*>((char*)SA(b, h) + lds_byte(wr * 64 + m * 16 + fr, k * 32 + fq * 8))
; #define LDB(dst, b, h) for (int n = 0; n < 2; ++n) for (int k = 0; k < 2; ++k) \
;     dst[n][k] = *reinterpret_cast<const bf16x8*>((char*)SB(b, h) + lds_byte(wc * 32 + n * 16 + fr, k * 32 + fq * 8))
; #define MMA(ai, bj, At_, Bt_) do { __builtin_amdgcn_s_setprio(1); \
;     for (int m = 0; m < 4; ++m) for (int n = 0; n < 2; ++n) for (int k = 0; k < 2; ++k) \
;       acc[ai][bj][m][n] = __builtin_amdgcn_mfma_f32_16x16x32_bf16(At_[m][k], Bt_[n][k], acc[ai][bj][m][n], 0, 0, 0); \
;     __builtin_amdgcn_s_setprio(0); } while (0)
; template <int K, int LD = K>
; __device__ __forceinline__ void gemm_main(const GAS bf16* A, const GAS bf16* Bt, int brow, int bcol, f32x4 (&acc)[2][2][4][2]) {
;     ...
;   { LDB(B0, 0, 0); LDA(At, 0, 0); STAGE(SA(1, 1), pA1, 1);
;     BAR; WAIT_L(0); MMA(0, 0, At, B0); BAR;
;     LDB(B1, 0, 1); BAR; WAIT_L(0); MMA(0, 1, At, B1); BAR;
;     LDA(At, 0, 1); WAIT_V(4); BAR; WAIT_L(0); MMA(1, 0, At, B0); MMA(1, 1, At, B1); BAR; }
.Lpeel1_exit:
	ds_read_b128 v[146:149], v144
	ds_read_b128 v[150:153], v144 offset:1024
	ds_read_b128 v[154:157], v144 offset:2048
	ds_read_b128 v[158:161], v144 offset:3072
	ds_read_b128 v[162:165], v138
	ds_read_b128 v[166:169], v138 offset:1024
	ds_read_b128 v[174:177], v137
	ds_read_b128 v[178:181], v137 offset:1024
	ds_read_b128 v[182:185], v136
	ds_read_b128 v[186:189], v136 offset:1024
	ds_read_b128 v[190:193], v135
	ds_read_b128 v[194:197], v135 offset:1024
	v_lshl_add_u64 v[144:145], s[12:13], 0, v[130:131]
	v_readfirstlane_b32 s16, v143
	v_lshl_add_u64 v[144:145], v[144:145], 0, s[6:7]
	s_mov_b32 m0, s16
	v_lshl_add_u64 v[132:133], s[12:13], 0, v[132:133]
	v_readfirstlane_b32 s12, v142
	global_load_lds_dwordx4 v[144:145], off
	v_lshl_add_u64 v[132:133], v[132:133], 0, s[6:7]
	s_mov_b32 m0, s12
	s_nop 0
	global_load_lds_dwordx4 v[132:133], off
	s_waitcnt vmcnt(10)
	s_barrier
	s_waitcnt lgkmcnt(0)
	s_waitcnt lgkmcnt(0)
	v_mfma_f32_16x16x32_bf16 v[126:129], v[162:165], v[146:149], v[126:129]
	v_mfma_f32_16x16x32_bf16 v[122:125], v[162:165], v[154:157], v[122:125]
	v_mfma_f32_16x16x32_bf16 v[110:113], v[182:185], v[146:149], v[110:113]
	v_mfma_f32_16x16x32_bf16 v[106:109], v[182:185], v[154:157], v[106:109]
	v_mfma_f32_16x16x32_bf16 v[126:129], v[166:169], v[150:153], v[126:129]
	v_mfma_f32_16x16x32_bf16 v[122:125], v[166:169], v[158:161], v[122:125]
	v_mfma_f32_16x16x32_bf16 v[118:121], v[174:177], v[146:149], v[118:121]
	v_mfma_f32_16x16x32_bf16 v[114:117], v[174:177], v[154:157], v[114:117]
	v_mfma_f32_16x16x32_bf16 v[110:113], v[186:189], v[150:153], v[110:113]
	v_mfma_f32_16x16x32_bf16 v[106:109], v[186:189], v[158:161], v[106:109]
	v_mfma_f32_16x16x32_bf16 v[102:105], v[190:193], v[146:149], v[102:105]
	v_mfma_f32_16x16x32_bf16 v[98:101], v[190:193], v[154:157], v[98:101]
	v_mfma_f32_16x16x32_bf16 v[142:145], v[178:181], v[150:153], v[118:121]
	v_mfma_f32_16x16x32_bf16 v[198:201], v[178:181], v[158:161], v[114:117]
	v_mfma_f32_16x16x32_bf16 v[202:205], v[194:197], v[150:153], v[102:105]
	v_mfma_f32_16x16x32_bf16 v[206:209], v[194:197], v[158:161], v[98:101]
	s_barrier
	s_nop 1
	ds_read_b128 v[98:101], v141
	ds_read_b128 v[102:105], v141 offset:1024
	ds_read_b128 v[114:117], v141 offset:2048
	ds_read_b128 v[118:121], v141 offset:3072
	s_waitcnt vmcnt(8)
	s_barrier
	s_waitcnt lgkmcnt(0)
	s_waitcnt lgkmcnt(0)
	v_mfma_f32_16x16x32_bf16 v[94:97], v[162:165], v[98:101], v[94:97]
	v_mfma_f32_16x16x32_bf16 v[90:93], v[162:165], v[114:117], v[90:93]
	v_mfma_f32_16x16x32_bf16 v[78:81], v[182:185], v[98:101], v[78:81]
	v_mfma_f32_16x16x32_bf16 v[74:77], v[182:185], v[114:117], v[74:77]
	v_mfma_f32_16x16x32_bf16 v[94:97], v[166:169], v[102:105], v[94:97]
	v_mfma_f32_16x16x32_bf16 v[90:93], v[166:169], v[118:121], v[90:93]
	v_mfma_f32_16x16x32_bf16 v[86:89], v[174:177], v[98:101], v[86:89]
	v_mfma_f32_16x16x32_bf16 v[82:85], v[174:177], v[114:117], v[82:85]
	v_mfma_f32_16x16x32_bf16 v[78:81], v[186:189], v[102:105], v[78:81]
	v_mfma_f32_16x16x32_bf16 v[74:77], v[186:189], v[118:121], v[74:77]
	v_mfma_f32_16x16x32_bf16 v[70:73], v[190:193], v[98:101], v[70:73]
	v_mfma_f32_16x16x32_bf16 v[66:69], v[190:193], v[114:117], v[66:69]
	v_mfma_f32_16x16x32_bf16 v[162:165], v[178:181], v[102:105], v[86:89]
	v_mfma_f32_16x16x32_bf16 v[166:169], v[178:181], v[118:121], v[82:85]
	v_mfma_f32_16x16x32_bf16 v[174:177], v[194:197], v[102:105], v[70:73]
	v_mfma_f32_16x16x32_bf16 v[178:181], v[194:197], v[118:121], v[66:69]
	s_barrier
	s_nop 1
	ds_read_b128 v[66:69], v138 offset:16384
	ds_read_b128 v[70:73], v138 offset:17408
	ds_read_b128 v[82:85], v137 offset:16384
	ds_read_b128 v[86:89], v137 offset:17408
	ds_read_b128 v[182:185], v136 offset:16384
	ds_read_b128 v[186:189], v136 offset:17408
	ds_read_b128 v[190:193], v135 offset:16384
	ds_read_b128 v[194:197], v135 offset:17408
	s_waitcnt vmcnt(4)
	s_barrier
	s_waitcnt lgkmcnt(0)
	s_waitcnt lgkmcnt(0)
	v_mfma_f32_16x16x32_bf16 v[62:65], v[66:69], v[146:149], v[62:65]
	v_mfma_f32_16x16x32_bf16 v[58:61], v[66:69], v[154:157], v[58:61]
	v_mfma_f32_16x16x32_bf16 v[46:49], v[182:185], v[146:149], v[46:49]
	v_mfma_f32_16x16x32_bf16 v[42:45], v[182:185], v[154:157], v[42:45]
	v_mfma_f32_16x16x32_bf16 v[62:65], v[70:73], v[150:153], v[62:65]
	v_mfma_f32_16x16x32_bf16 v[58:61], v[70:73], v[158:161], v[58:61]
	v_mfma_f32_16x16x32_bf16 v[54:57], v[82:85], v[146:149], v[54:57]
	v_mfma_f32_16x16x32_bf16 v[50:53], v[82:85], v[154:157], v[50:53]
	v_mfma_f32_16x16x32_bf16 v[46:49], v[186:189], v[150:153], v[46:49]
	v_mfma_f32_16x16x32_bf16 v[42:45], v[186:189], v[158:161], v[42:45]
	v_mfma_f32_16x16x32_bf16 v[38:41], v[190:193], v[146:149], v[38:41]
	v_mfma_f32_16x16x32_bf16 v[34:37], v[190:193], v[154:157], v[34:37]
	v_mfma_f32_16x16x32_bf16 v[210:213], v[86:89], v[150:153], v[54:57]
	v_mfma_f32_16x16x32_bf16 v[214:217], v[86:89], v[158:161], v[50:53]
	v_mfma_f32_16x16x32_bf16 v[146:149], v[194:197], v[150:153], v[38:41]
	v_mfma_f32_16x16x32_bf16 v[150:153], v[194:197], v[158:161], v[34:37]
	v_mfma_f32_16x16x32_bf16 v[30:33], v[66:69], v[98:101], v[30:33]
	v_mfma_f32_16x16x32_bf16 v[26:29], v[66:69], v[114:117], v[26:29]
	v_mfma_f32_16x16x32_bf16 v[14:17], v[182:185], v[98:101], v[14:17]
	v_mfma_f32_16x16x32_bf16 v[10:13], v[182:185], v[114:117], v[10:13]
	v_mfma_f32_16x16x32_bf16 v[30:33], v[70:73], v[102:105], v[30:33]
	v_mfma_f32_16x16x32_bf16 v[26:29], v[70:73], v[118:121], v[26:29]
	v_mfma_f32_16x16x32_bf16 v[22:25], v[82:85], v[98:101], v[22:25]
	v_mfma_f32_16x16x32_bf16 v[18:21], v[82:85], v[114:117], v[18:21]
	v_mfma_f32_16x16x32_bf16 v[14:17], v[186:189], v[102:105], v[14:17]
	v_mfma_f32_16x16x32_bf16 v[10:13], v[186:189], v[118:121], v[10:13]
	v_mfma_f32_16x16x32_bf16 v[6:9], v[190:193], v[98:101], v[6:9]
	v_mfma_f32_16x16x32_bf16 v[2:5], v[190:193], v[114:117], v[2:5]
	v_mfma_f32_16x16x32_bf16 v[154:157], v[86:89], v[102:105], v[22:25]
	v_mfma_f32_16x16x32_bf16 v[158:161], v[86:89], v[118:121], v[18:21]
	v_mfma_f32_16x16x32_bf16 v[182:185], v[194:197], v[102:105], v[6:9]
	v_mfma_f32_16x16x32_bf16 v[186:189], v[194:197], v[118:121], v[2:5]
	s_barrier
; #define WAIT_V(n) asm volatile("s_waitcnt vmcnt(" #n ")" ::: "memory")
; #define WAIT_L(n) asm volatile("s_waitcnt lgkmcnt(" #n ")" ::: "memory")
; #define BAR __builtin_amdgcn_s_barrier()
; #define LDA(dst, b, h) for (int m = 0; m < 4; ++m) for (int k = 0; k < 2; ++k) \
;     dst[m][k] = *reinterpret_cast<const bf16x8*>((char*)SA(b, h) + lds_byte(wr * 64 + m * 16 + fr, k * 32 + fq * 8))
; #define LDB(dst, b, h) for (int n = 0; n < 2; ++n) for (int k = 0; k < 2; ++k) \
;     dst[n][k] = *reinterpret_cast<const bf16x8*>((char*)SB(b, h) + lds_byte(wc * 32 + n * 16 + fr, k * 32 + fq * 8))
; #define MMA(ai, bj, At_, Bt_) do { __builtin_amdgcn_s_setprio(1); \
;     for (int m = 0; m < 4; ++m) for (int n = 0; n < 2; ++n) for (int k = 0; k < 2; ++k) \
;       acc[ai][bj][m][n] = __builtin_amdgcn_mfma_f32_16x16x32_bf16(At_[m][k], Bt_[n][k], acc[ai][bj][m][n], 0, 0, 0); \
;     __builtin_amdgcn_s_setprio(0); } while (0)
; template <int K, int LD = K>
; __device__ __forceinline__ void gemm_main(const GAS bf16* A, const GAS bf16* Bt, int brow, int bcol, f32x4 (&acc)[2][2][4][2]) {
;     ...
;   { LDB(B0, 1, 0); LDA(At, 1, 0); WAIT_V(2); BAR; WAIT_L(0); MMA(0, 0, At, B0); BAR;
;     LDB(B1, 1, 1); WAIT_V(0); BAR; WAIT_L(0); MMA(0, 1, At, B1); BAR;
;     LDA(At, 1, 1); BAR; WAIT_L(0); MMA(1, 0, At, B0); MMA(1, 1, At, B1); BAR; }
;   if (wr == 0) BAR;
	s_nop 1
	ds_read_b128 v[2:5], v140
	ds_read_b128 v[6:9], v140 offset:1024
	ds_read_b128 v[190:193], v140 offset:2048
	ds_read_b128 v[194:197], v140 offset:3072
	ds_read_b128 v[18:21], v138 offset:32768
	ds_read_b128 v[22:25], v138 offset:33792
	ds_read_b128 v[34:37], v137 offset:32768
	ds_read_b128 v[38:41], v137 offset:33792
	ds_read_b128 v[50:53], v136 offset:32768
	ds_read_b128 v[54:57], v136 offset:33792
	ds_read_b128 v[218:221], v135 offset:32768
	ds_read_b128 v[222:225], v135 offset:33792
	s_waitcnt vmcnt(2)
	s_barrier
	s_waitcnt lgkmcnt(0)
	s_waitcnt lgkmcnt(0)
	v_mfma_f32_16x16x32_bf16 v[66:69], v[18:21], v[2:5], v[126:129]
	v_mfma_f32_16x16x32_bf16 v[118:121], v[22:25], v[6:9], v[66:69]
	v_mfma_f32_16x16x32_bf16 v[66:69], v[18:21], v[190:193], v[122:125]
	v_mfma_f32_16x16x32_bf16 v[114:117], v[22:25], v[194:197], v[66:69]
	v_mfma_f32_16x16x32_bf16 v[66:69], v[34:37], v[2:5], v[142:145]
	v_mfma_f32_16x16x32_bf16 v[102:105], v[38:41], v[6:9], v[66:69]
	v_mfma_f32_16x16x32_bf16 v[66:69], v[34:37], v[190:193], v[198:201]
	v_mfma_f32_16x16x32_bf16 v[98:101], v[38:41], v[194:197], v[66:69]
	v_mfma_f32_16x16x32_bf16 v[66:69], v[50:53], v[2:5], v[110:113]
	v_mfma_f32_16x16x32_bf16 v[86:89], v[54:57], v[6:9], v[66:69]
	v_mfma_f32_16x16x32_bf16 v[66:69], v[50:53], v[190:193], v[106:109]
	v_mfma_f32_16x16x32_bf16 v[82:85], v[54:57], v[194:197], v[66:69]
	v_mfma_f32_16x16x32_bf16 v[66:69], v[218:221], v[2:5], v[202:205]
	v_mfma_f32_16x16x32_bf16 v[70:73], v[222:225], v[6:9], v[66:69]
	v_mfma_f32_16x16x32_bf16 v[66:69], v[218:221], v[190:193], v[206:209]
	v_mfma_f32_16x16x32_bf16 v[66:69], v[222:225], v[194:197], v[66:69]
	s_barrier
	ds_read_b128 v[140:143], v139
	ds_read_b128 v[198:201], v139 offset:1024
	ds_read_b128 v[202:205], v139 offset:2048
	ds_read_b128 v[206:209], v139 offset:3072
	s_waitcnt vmcnt(0)
	s_barrier
	s_waitcnt lgkmcnt(0)
	s_waitcnt lgkmcnt(0)
	v_mfma_f32_16x16x32_bf16 v[94:97], v[18:21], v[140:143], v[94:97]
	v_mfma_f32_16x16x32_bf16 v[18:21], v[18:21], v[202:205], v[90:93]
	v_mfma_f32_16x16x32_bf16 v[122:125], v[22:25], v[206:209], v[18:21]
	v_mfma_f32_16x16x32_bf16 v[18:21], v[34:37], v[140:143], v[162:165]
	v_mfma_f32_16x16x32_bf16 v[110:113], v[38:41], v[198:201], v[18:21]
	v_mfma_f32_16x16x32_bf16 v[18:21], v[34:37], v[202:205], v[166:169]
	v_mfma_f32_16x16x32_bf16 v[106:109], v[38:41], v[206:209], v[18:21]
	v_mfma_f32_16x16x32_bf16 v[18:21], v[50:53], v[140:143], v[78:81]
	v_mfma_f32_16x16x32_bf16 v[126:129], v[22:25], v[198:201], v[94:97]
	v_mfma_f32_16x16x32_bf16 v[94:97], v[54:57], v[198:201], v[18:21]
	v_mfma_f32_16x16x32_bf16 v[18:21], v[50:53], v[202:205], v[74:77]
	v_mfma_f32_16x16x32_bf16 v[90:93], v[54:57], v[206:209], v[18:21]
	v_mfma_f32_16x16x32_bf16 v[18:21], v[218:221], v[140:143], v[174:177]
	v_mfma_f32_16x16x32_bf16 v[78:81], v[222:225], v[198:201], v[18:21]
	v_mfma_f32_16x16x32_bf16 v[18:21], v[218:221], v[202:205], v[178:181]
	v_mfma_f32_16x16x32_bf16 v[74:77], v[222:225], v[206:209], v[18:21]
	s_barrier
	ds_read_b128 v[162:165], v138 offset:49152
	ds_read_b128 v[166:169], v138 offset:50176
	ds_read_b128 v[174:177], v137 offset:49152
	ds_read_b128 v[178:181], v137 offset:50176
	ds_read_b128 v[218:221], v136 offset:49152
	ds_read_b128 v[136:139], v136 offset:50176
	ds_read_b128 v[222:225], v135 offset:49152
	ds_read_b128 v[226:229], v135 offset:50176
	s_barrier
	s_waitcnt lgkmcnt(0)
	s_waitcnt lgkmcnt(0)
	v_mfma_f32_16x16x32_bf16 v[18:21], v[162:165], v[2:5], v[62:65]
	v_mfma_f32_16x16x32_bf16 v[54:57], v[166:169], v[6:9], v[18:21]
	v_mfma_f32_16x16x32_bf16 v[18:21], v[162:165], v[190:193], v[58:61]
	v_mfma_f32_16x16x32_bf16 v[50:53], v[166:169], v[194:197], v[18:21]
	v_mfma_f32_16x16x32_bf16 v[18:21], v[174:177], v[2:5], v[210:213]
	v_mfma_f32_16x16x32_bf16 v[38:41], v[178:181], v[6:9], v[18:21]
	v_mfma_f32_16x16x32_bf16 v[18:21], v[174:177], v[190:193], v[214:217]
	v_mfma_f32_16x16x32_bf16 v[34:37], v[178:181], v[194:197], v[18:21]
	v_mfma_f32_16x16x32_bf16 v[18:21], v[218:221], v[2:5], v[46:49]
	v_mfma_f32_16x16x32_bf16 v[2:5], v[222:225], v[2:5], v[146:149]
	v_mfma_f32_16x16x32_bf16 v[22:25], v[136:139], v[6:9], v[18:21]
	v_mfma_f32_16x16x32_bf16 v[18:21], v[218:221], v[190:193], v[42:45]
	v_mfma_f32_16x16x32_bf16 v[6:9], v[226:229], v[6:9], v[2:5]
	v_mfma_f32_16x16x32_bf16 v[2:5], v[222:225], v[190:193], v[150:153]
	v_mfma_f32_16x16x32_bf16 v[18:21], v[136:139], v[194:197], v[18:21]
	v_mfma_f32_16x16x32_bf16 v[2:5], v[226:229], v[194:197], v[2:5]
	v_mfma_f32_16x16x32_bf16 v[26:29], v[162:165], v[202:205], v[26:29]
	v_mfma_f32_16x16x32_bf16 v[58:61], v[166:169], v[206:209], v[26:29]
	v_mfma_f32_16x16x32_bf16 v[26:29], v[174:177], v[140:143], v[154:157]
	v_mfma_f32_16x16x32_bf16 v[46:49], v[178:181], v[198:201], v[26:29]
	v_mfma_f32_16x16x32_bf16 v[26:29], v[174:177], v[202:205], v[158:161]
	v_mfma_f32_16x16x32_bf16 v[10:13], v[218:221], v[202:205], v[10:13]
	v_mfma_f32_16x16x32_bf16 v[30:33], v[162:165], v[140:143], v[30:33]
	v_mfma_f32_16x16x32_bf16 v[42:45], v[178:181], v[206:209], v[26:29]
	v_mfma_f32_16x16x32_bf16 v[14:17], v[218:221], v[140:143], v[14:17]
	v_mfma_f32_16x16x32_bf16 v[26:29], v[136:139], v[206:209], v[10:13]
	v_mfma_f32_16x16x32_bf16 v[10:13], v[222:225], v[140:143], v[182:185]
	v_mfma_f32_16x16x32_bf16 v[62:65], v[166:169], v[198:201], v[30:33]
	v_mfma_f32_16x16x32_bf16 v[30:33], v[136:139], v[198:201], v[14:17]
	v_mfma_f32_16x16x32_bf16 v[14:17], v[226:229], v[198:201], v[10:13]
	v_mfma_f32_16x16x32_bf16 v[10:13], v[222:225], v[202:205], v[186:189]
	v_mfma_f32_16x16x32_bf16 v[10:13], v[226:229], v[206:209], v[10:13]
	v_cmp_gt_u32_e32 vcc, s33, v134
	s_barrier
	s_and_saveexec_b64 s[12:13], vcc
	s_cbranch_execz .LBB0_1108
	s_barrier

; #define GAS __attribute__((address_space(1)))
; #define STAGE(P, GP, ktrel) do { const GAS char* _g = (GP) + (ktrel) * (BK * 2); \
;     __builtin_amdgcn_global_load_lds((const GAS unsigned*)(_g + so0), (unsigned*)((char*)(P) + tid_ * 16), 16, 0, 0); \
;     __builtin_amdgcn_global_load_lds((const GAS unsigned*)(_g + so1), (unsigned*)((char*)(P) + tid_ * 16 + 8192), 16, 0, 0); } while (0)
; #define WAIT_V(n) asm volatile("s_waitcnt vmcnt(" #n ")" ::: "memory")
; #define WAIT_L(n) asm volatile("s_waitcnt lgkmcnt(" #n ")" ::: "memory")
; #define BAR __builtin_amdgcn_s_barrier()
; #define SCHED __builtin_amdgcn_sched_barrier(0)
; #define LDA(dst, b, h) for (int m = 0; m < 4; ++m) for (int k = 0; k < 2; ++k) \
;     dst[m][k] = *reinterpret_cast<const bf16x8*>((char*)SA(b, h) + lds_byte(wr * 64 + m * 16 + fr, k * 32 + fq * 8))
; #define LDB(dst, b, h) for (int n = 0; n < 2; ++n) for (int k = 0; k < 2; ++k) \
;     dst[n][k] = *reinterpret_cast<const bf16x8*>((char*)SB(b, h) + lds_byte(wc * 32 + n * 16 + fr, k * 32 + fq * 8))
; template <int K, int LD = K>
; __device__ __forceinline__ void gemm_main(const GAS bf16* A, const GAS bf16* Bt, int brow, int bcol, f32x4 (&acc)[2][2][4][2]) {
;     ...
;         for (int n = 0; n < 2; ++n) acc[a][b][m][n] = f32x4{0.f, 0.f, 0.f, 0.f};
;   bf16x8 At[4][2], B0[2][2], B1[2][2];
;   unsigned so0, so1;
;   { int r_, c_; stage_rc(tid_ * 16, r_, c_); so0 = (unsigned)(r_ * LD + c_) * 2u; stage_rc(tid_ * 16 + 8192, r_, c_); so1 = (unsigned)(r_ * LD + c_) * 2u; }
;   const GAS char* pA0 = (const GAS char*)A + (long)brow * LD * 2; const GAS char* pA1 = pA0 + (long)HALF * LD * 2;
;   const GAS char* pB0 = (const GAS char*)Bt + (long)bcol * LD * 2; const GAS char* pB1 = pB0 + (long)HALF * LD * 2;
;   asm volatile("" : "+s"(pA0), "+s"(pA1), "+s"(pB0), "+s"(pB1));
;   constexpr int nt = K / BK;
;   static_assert(K % 128 == 0 && K >= 256, "K");
;   if (wr == 1) BAR;
;   WAIT_V(0); BAR;
;   BAR;
;   for (int t = 0; t < nt - 2; t += 2) {
;     LDB(B0, 0, 0); SCHED; LDA(At, 0, 0); STAGE(SA(1, 1), pA1, 1);
;     WAIT_L(8); BAR; WAIT_L(0); MMA(0, 0, At, B0); BAR; SCHED;
;     LDB(B1, 0, 1); STAGE(SB(0, 0), pB0, 2);
;     BAR; WAIT_L(0); MMA(0, 1, At, B1); BAR;
.LBB0_1225:
	s_or_b64 exec, exec, s[30:31]
	v_bfe_i32 v6, v132, 27, 1
	v_lshlrev_b32_e32 v141, 4, v132
	v_lshrrev_b32_e32 v6, 22, v6
	v_add_u32_e32 v6, v141, v6
	v_and_b32_e32 v6, 0xfffffc00, v6
	v_sub_u32_e32 v6, v141, v6
	v_lshrrev_b32_e32 v7, 4, v6
	v_bitop3_b32 v7, v7, v6, 32 bitop3:0x6c
	v_ashrrev_i32_e32 v6, 31, v6
	v_ashrrev_i32_e32 v5, 31, v132
	v_lshrrev_b32_e32 v6, 26, v6
	v_lshrrev_b32_e32 v5, 26, v5
	v_add_u32_e32 v6, v7, v6
	v_add_u32_e32 v5, v132, v5
	v_ashrrev_i32_e32 v6, 6, v6
	v_ashrrev_i32_e32 v5, 6, v5
	v_mul_i32_i24_e32 v9, 64, v6
	v_lshlrev_b32_e32 v8, 3, v5
	v_lshlrev_b32_e32 v5, 5, v5
	v_sub_u32_e32 v7, v7, v9
	v_and_b32_e32 v8, 0x1ffff0, v8
	v_and_b32_e32 v5, 32, v5
	v_ashrrev_i16_sdwa v7, v1, sext(v7) dst_sel:DWORD dst_unused:UNUSED_PAD src0_sel:DWORD src1_sel:BYTE_0
	v_add_u32_sdwa v5, v5, sext(v7) dst_sel:DWORD dst_unused:UNUSED_PAD src0_sel:DWORD src1_sel:WORD_0
	v_add_lshl_u32 v6, v6, v8, 11
	v_lshl_add_u32 v138, v5, 1, v6
	v_add_u32_e32 v5, 0x2000, v141
	v_ashrrev_i32_e32 v6, 31, v5
	v_lshrrev_b32_e32 v6, 22, v6
	v_add_u32_e32 v6, v5, v6
	v_ashrrev_i32_e32 v6, 10, v6
	v_mul_i32_i24_e32 v7, 0x400, v6
	v_sub_u32_e32 v5, v5, v7
	v_lshrrev_b32_e32 v7, 4, v5
	v_bitop3_b32 v5, v7, v5, 32 bitop3:0x6c
	v_ashrrev_i32_e32 v8, 31, v5
	v_lshrrev_b32_e32 v8, 26, v8
	v_add_u32_e32 v8, v5, v8
	v_lshrrev_b32_e32 v9, 6, v8
	v_and_b32_e32 v8, 0xc0, v8
	v_lshlrev_b32_e32 v7, 3, v6
	v_lshlrev_b32_e32 v6, 5, v6
	v_sub_u32_e32 v5, v5, v8
	v_and_b32_e32 v7, 0x1ffff0, v7
	v_and_b32_e32 v6, 32, v6
	v_ashrrev_i16_sdwa v5, v1, sext(v5) dst_sel:DWORD dst_unused:UNUSED_PAD src0_sel:DWORD src1_sel:BYTE_0
	v_add_u32_sdwa v5, v6, sext(v5) dst_sel:DWORD dst_unused:UNUSED_PAD src0_sel:DWORD src1_sel:WORD_0
	v_add_lshl_u32 v6, v9, v7, 11
	v_and_b32_e32 v3, 15, v132
	v_lshl_add_u32 v130, v5, 1, v6
	v_lshlrev_b32_e32 v5, 2, v132
	v_and_b32_e32 v4, 48, v132
	v_lshlrev_b32_e32 v3, 6, v3
	v_and_b32_e32 v5, 32, v5
	v_lshlrev_b32_e32 v10, 6, v132
	v_bitop3_b32 v3, v3, v5, v4 bitop3:0x36
	v_lshlrev_b32_e32 v12, 13, v2
	v_and_or_b32 v2, v10, s46, v4
	v_add_u32_e32 v6, s38, v3
	v_add_u32_e32 v7, s39, v3
	v_add_u32_e32 v8, s40, v3
	v_add_u32_e32 v9, s41, v3
	v_and_b32_e32 v11, 0x3000, v10
	v_add_u32_e32 v3, 0x100, v3
	v_xad_u32 v4, v2, v5, s42
	v_or_b32_e32 v5, 0x800, v12
	v_or_b32_e32 v10, 0x1000, v12
	v_or_b32_e32 v13, 0x1800, v12
	v_mov_b32_e32 v2, 0
	v_mov_b32_e32 v131, v139
	s_mov_b32 s21, -2
	v_add_u32_e32 v143, v6, v11
	v_add_u32_e32 v136, v3, v12
	v_add_u32_e32 v135, v4, v5
	v_add_u32_e32 v134, v4, v10
	v_add_u32_e32 v133, v4, v13
	v_add_u32_e32 v142, v7, v11
	v_add_u32_e32 v140, v8, v11
	v_add_u32_e32 v137, v9, v11
	s_waitcnt vmcnt(0)
	s_barrier
	s_barrier
	ds_read_b128 v[146:149], v143
	ds_read_b128 v[150:153], v143 offset:1024
	ds_read_b128 v[156:159], v143 offset:2048
	ds_read_b128 v[160:163], v143 offset:3072
	v_add_u32_e32 v155, 0x100, v141
	v_add_u32_e32 v144, 0xc000, v155
	v_lshl_add_u64 v[168:169], s[18:19], 0, v[138:139]
	v_readfirstlane_b32 s30, v144
	v_add_u32_e32 v145, 0xe000, v155
	v_lshl_add_u64 v[202:203], v[168:169], 0, s[8:9]
	s_mov_b32 m0, s30
	v_lshl_add_u64 v[218:219], s[18:19], 0, v[130:131]
	v_readfirstlane_b32 s30, v145
	ds_read_b128 v[164:167], v136
	ds_read_b128 v[174:177], v136 offset:1024
	ds_read_b128 v[178:181], v135
	ds_read_b128 v[182:185], v135 offset:1024
	ds_read_b128 v[186:189], v134
	ds_read_b128 v[190:193], v134 offset:1024
	ds_read_b128 v[194:197], v133
	ds_read_b128 v[198:201], v133 offset:1024
	global_load_lds_dwordx4 v[202:203], off
	v_lshl_add_u64 v[202:203], v[218:219], 0, s[8:9]
	s_mov_b32 m0, s30
	s_nop 0
	global_load_lds_dwordx4 v[202:203], off
	s_waitcnt lgkmcnt(8)
	s_waitcnt vmcnt(10)
	s_barrier
	s_waitcnt lgkmcnt(0)
	s_waitcnt lgkmcnt(0)
	v_mfma_f32_16x16x32_bf16 v[126:129], v[164:167], v[146:149], 0
	v_mfma_f32_16x16x32_bf16 v[122:125], v[164:167], v[156:159], 0
	v_mfma_f32_16x16x32_bf16 v[118:121], v[178:181], v[146:149], 0
	v_mfma_f32_16x16x32_bf16 v[114:117], v[178:181], v[156:159], 0
	v_mfma_f32_16x16x32_bf16 v[110:113], v[186:189], v[146:149], 0
	v_mfma_f32_16x16x32_bf16 v[106:109], v[186:189], v[156:159], 0
	v_mfma_f32_16x16x32_bf16 v[102:105], v[194:197], v[146:149], 0
	v_mfma_f32_16x16x32_bf16 v[98:101], v[194:197], v[156:159], 0
	v_mfma_f32_16x16x32_bf16 v[126:129], v[174:177], v[150:153], v[126:129]
	v_mfma_f32_16x16x32_bf16 v[122:125], v[174:177], v[160:163], v[122:125]
	v_mfma_f32_16x16x32_bf16 v[118:121], v[182:185], v[150:153], v[118:121]
	v_mfma_f32_16x16x32_bf16 v[114:117], v[182:185], v[160:163], v[114:117]
	v_mfma_f32_16x16x32_bf16 v[110:113], v[190:193], v[150:153], v[110:113]
	v_mfma_f32_16x16x32_bf16 v[106:109], v[190:193], v[160:163], v[106:109]
	v_mfma_f32_16x16x32_bf16 v[102:105], v[198:201], v[150:153], v[102:105]
	v_mfma_f32_16x16x32_bf16 v[98:101], v[198:201], v[160:163], v[98:101]
	s_barrier
	v_add_u32_e32 v226, s38, v141
	v_lshl_add_u64 v[220:221], s[28:29], 0, v[138:139]
	v_readfirstlane_b32 s30, v226
	v_lshl_add_u64 v[222:223], v[220:221], 0, s[14:15]
	s_mov_b32 m0, s30
	v_add_u32_e32 v226, 0x2000, v226
	ds_read_b128 v[202:205], v142
	ds_read_b128 v[206:209], v142 offset:1024
	ds_read_b128 v[210:213], v142 offset:2048
	ds_read_b128 v[214:217], v142 offset:3072
	global_load_lds_dwordx4 v[222:223], off
	v_lshl_add_u64 v[222:223], s[28:29], 0, v[130:131]
	v_readfirstlane_b32 s30, v226
	v_lshl_add_u64 v[224:225], v[222:223], 0, s[14:15]
	s_mov_b32 m0, s30
	s_add_u32 s28, s28, 0x100
	global_load_lds_dwordx4 v[224:225], off
	s_waitcnt vmcnt(10)
	s_barrier
; #define STAGE(P, GP, ktrel) do { const GAS char* _g = (GP) + (ktrel) * (BK * 2); \
;     __builtin_amdgcn_global_load_lds((const GAS unsigned*)(_g + so0), (unsigned*)((char*)(P) + tid_ * 16), 16, 0, 0); \
;     __builtin_amdgcn_global_load_lds((const GAS unsigned*)(_g + so1), (unsigned*)((char*)(P) + tid_ * 16 + 8192), 16, 0, 0); } while (0)
; #define WAIT_V(n) asm volatile("s_waitcnt vmcnt(" #n ")" ::: "memory")
; #define WAIT_L(n) asm volatile("s_waitcnt lgkmcnt(" #n ")" ::: "memory")
; #define BAR __builtin_amdgcn_s_barrier()
; #define SCHED __builtin_amdgcn_sched_barrier(0)
; #define LDA(dst, b, h) for (int m = 0; m < 4; ++m) for (int k = 0; k < 2; ++k) \
;     dst[m][k] = *reinterpret_cast<const bf16x8*>((char*)SA(b, h) + lds_byte(wr * 64 + m * 16 + fr, k * 32 + fq * 8))
; #define LDB(dst, b, h) for (int n = 0; n < 2; ++n) for (int k = 0; k < 2; ++k) \
;     dst[n][k] = *reinterpret_cast<const bf16x8*>((char*)SB(b, h) + lds_byte(wc * 32 + n * 16 + fr, k * 32 + fq * 8))
; #define MMA(ai, bj, At_, Bt_) do { __builtin_amdgcn_s_setprio(1); \
;     for (int m = 0; m < 4; ++m) for (int n = 0; n < 2; ++n) for (int k = 0; k < 2; ++k) \
;       acc[ai][bj][m][n] = __builtin_amdgcn_mfma_f32_16x16x32_bf16(At_[m][k], Bt_[n][k], acc[ai][bj][m][n], 0, 0, 0); \
;     __builtin_amdgcn_s_setprio(0); } while (0)
; template <int K, int LD = K>
; __device__ __forceinline__ void gemm_main(const GAS bf16* A, const GAS bf16* Bt, int brow, int bcol, f32x4 (&acc)[2][2][4][2]) {
;     ...
;     BAR; WAIT_L(0); MMA(0, 1, At, B1); BAR;
;     LDA(At, 0, 1); STAGE(SA(0, 0), pA0, 2);
;     BAR; WAIT_L(0); MMA(1, 0, At, B0); BAR; SCHED;
;     STAGE(SB(0, 1), pB1, 2);
;     WAIT_V(6); BAR; MMA(1, 1, At, B1); BAR;
;     LDB(B0, 1, 0); SCHED; LDA(At, 1, 0); STAGE(SA(0, 1), pA1, 2);
;     WAIT_L(8); BAR; WAIT_L(0); MMA(0, 0, At, B0); BAR; SCHED;
	s_waitcnt lgkmcnt(0)
	s_addc_u32 s29, s29, 0
	s_waitcnt lgkmcnt(0)
	v_mfma_f32_16x16x32_bf16 v[94:97], v[164:167], v[202:205], 0
	v_mfma_f32_16x16x32_bf16 v[90:93], v[164:167], v[210:213], 0
	v_mfma_f32_16x16x32_bf16 v[86:89], v[178:181], v[202:205], 0
	v_mfma_f32_16x16x32_bf16 v[82:85], v[178:181], v[210:213], 0
	v_mfma_f32_16x16x32_bf16 v[78:81], v[186:189], v[202:205], 0
	v_mfma_f32_16x16x32_bf16 v[74:77], v[186:189], v[210:213], 0
	v_mfma_f32_16x16x32_bf16 v[70:73], v[194:197], v[202:205], 0
	v_mfma_f32_16x16x32_bf16 v[66:69], v[194:197], v[210:213], 0
	v_mfma_f32_16x16x32_bf16 v[94:97], v[174:177], v[206:209], v[94:97]
	v_mfma_f32_16x16x32_bf16 v[90:93], v[174:177], v[214:217], v[90:93]
	v_mfma_f32_16x16x32_bf16 v[86:89], v[182:185], v[206:209], v[86:89]
	v_mfma_f32_16x16x32_bf16 v[82:85], v[182:185], v[214:217], v[82:85]
	v_mfma_f32_16x16x32_bf16 v[78:81], v[190:193], v[206:209], v[78:81]
	v_mfma_f32_16x16x32_bf16 v[74:77], v[190:193], v[214:217], v[74:77]
	v_mfma_f32_16x16x32_bf16 v[70:73], v[198:201], v[206:209], v[70:73]
	v_mfma_f32_16x16x32_bf16 v[66:69], v[198:201], v[214:217], v[66:69]
	v_lshl_add_u64 v[224:225], s[26:27], 0, v[138:139]
	v_readfirstlane_b32 s30, v155
	v_lshl_add_u64 v[226:227], v[224:225], 0, s[14:15]
	s_mov_b32 m0, s30
	v_add_u32_e32 v230, 0x2000, v155
	s_barrier
	ds_read_b128 v[164:167], v136 offset:16384
	ds_read_b128 v[174:177], v136 offset:17408
	ds_read_b128 v[178:181], v135 offset:16384
	ds_read_b128 v[182:185], v135 offset:17408
	ds_read_b128 v[186:189], v134 offset:16384
	ds_read_b128 v[190:193], v134 offset:17408
	ds_read_b128 v[194:197], v133 offset:16384
	ds_read_b128 v[198:201], v133 offset:17408
	global_load_lds_dwordx4 v[226:227], off
	v_lshl_add_u64 v[226:227], s[26:27], 0, v[130:131]
	v_readfirstlane_b32 s30, v230
	v_lshl_add_u64 v[228:229], v[226:227], 0, s[14:15]
	s_mov_b32 m0, s30
	s_add_u32 s26, s26, 0x100
	global_load_lds_dwordx4 v[228:229], off
	s_barrier
	s_waitcnt lgkmcnt(0)
	s_addc_u32 s27, s27, 0
	s_waitcnt lgkmcnt(0)
	v_mfma_f32_16x16x32_bf16 v[62:65], v[164:167], v[146:149], 0
	v_mfma_f32_16x16x32_bf16 v[58:61], v[164:167], v[156:159], 0
	v_mfma_f32_16x16x32_bf16 v[54:57], v[178:181], v[146:149], 0
	v_mfma_f32_16x16x32_bf16 v[50:53], v[178:181], v[156:159], 0
	v_mfma_f32_16x16x32_bf16 v[46:49], v[186:189], v[146:149], 0
	v_mfma_f32_16x16x32_bf16 v[42:45], v[186:189], v[156:159], 0
	v_mfma_f32_16x16x32_bf16 v[38:41], v[194:197], v[146:149], 0
	v_mfma_f32_16x16x32_bf16 v[34:37], v[194:197], v[156:159], 0
	v_mfma_f32_16x16x32_bf16 v[62:65], v[174:177], v[150:153], v[62:65]
	v_mfma_f32_16x16x32_bf16 v[58:61], v[174:177], v[160:163], v[58:61]
	v_mfma_f32_16x16x32_bf16 v[54:57], v[182:185], v[150:153], v[54:57]
	v_mfma_f32_16x16x32_bf16 v[50:53], v[182:185], v[160:163], v[50:53]
	v_mfma_f32_16x16x32_bf16 v[46:49], v[190:193], v[150:153], v[46:49]
	v_mfma_f32_16x16x32_bf16 v[42:45], v[190:193], v[160:163], v[42:45]
	v_mfma_f32_16x16x32_bf16 v[38:41], v[198:201], v[150:153], v[38:41]
	v_mfma_f32_16x16x32_bf16 v[34:37], v[198:201], v[160:163], v[34:37]
	s_barrier
	v_add_u32_e32 v148, s39, v141
	v_lshl_add_u64 v[228:229], s[24:25], 0, v[138:139]
	v_readfirstlane_b32 s30, v148
	v_add_u32_e32 v148, 0x2000, v148
	v_lshl_add_u64 v[146:147], v[228:229], 0, s[14:15]
	s_mov_b32 m0, s30
	v_lshl_add_u64 v[230:231], s[24:25], 0, v[130:131]
	v_readfirstlane_b32 s30, v148
	global_load_lds_dwordx4 v[146:147], off
	v_lshl_add_u64 v[146:147], v[230:231], 0, s[14:15]
	s_mov_b32 m0, s30
	s_add_u32 s24, s24, 0x100
	global_load_lds_dwordx4 v[146:147], off
	s_waitcnt vmcnt(10)
	s_addc_u32 s25, s25, 0
	s_barrier
	v_mfma_f32_16x16x32_bf16 v[30:33], v[164:167], v[202:205], 0
	v_mfma_f32_16x16x32_bf16 v[26:29], v[164:167], v[210:213], 0
	v_mfma_f32_16x16x32_bf16 v[22:25], v[178:181], v[202:205], 0
	v_mfma_f32_16x16x32_bf16 v[18:21], v[178:181], v[210:213], 0
	v_mfma_f32_16x16x32_bf16 v[14:17], v[186:189], v[202:205], 0
	v_mfma_f32_16x16x32_bf16 v[10:13], v[186:189], v[210:213], 0
	v_mfma_f32_16x16x32_bf16 v[6:9], v[194:197], v[202:205], 0
	v_mfma_f32_16x16x32_bf16 v[2:5], v[194:197], v[210:213], 0
	v_mfma_f32_16x16x32_bf16 v[30:33], v[174:177], v[206:209], v[30:33]
	v_mfma_f32_16x16x32_bf16 v[26:29], v[174:177], v[214:217], v[26:29]
	v_mfma_f32_16x16x32_bf16 v[22:25], v[182:185], v[206:209], v[22:25]
	v_mfma_f32_16x16x32_bf16 v[18:21], v[182:185], v[214:217], v[18:21]
	v_mfma_f32_16x16x32_bf16 v[14:17], v[190:193], v[206:209], v[14:17]
	v_mfma_f32_16x16x32_bf16 v[10:13], v[190:193], v[214:217], v[10:13]
	v_mfma_f32_16x16x32_bf16 v[6:9], v[198:201], v[206:209], v[6:9]
	v_mfma_f32_16x16x32_bf16 v[2:5], v[198:201], v[214:217], v[2:5]
	s_barrier
	ds_read_b128 v[146:149], v140
	ds_read_b128 v[150:153], v140 offset:1024
	ds_read_b128 v[156:159], v140 offset:2048
	ds_read_b128 v[160:163], v140 offset:3072
	v_add_u32_e32 v202, 0x4000, v155
	v_lshl_add_u64 v[168:169], v[168:169], 0, s[14:15]
	v_readfirstlane_b32 s30, v202
	v_add_u32_e32 v202, 0x6000, v155
	s_mov_b32 m0, s30
	v_readfirstlane_b32 s30, v202
	ds_read_b128 v[164:167], v136 offset:32768
	ds_read_b128 v[174:177], v136 offset:33792
	ds_read_b128 v[178:181], v135 offset:32768
	ds_read_b128 v[182:185], v135 offset:33792
	ds_read_b128 v[186:189], v134 offset:32768
	ds_read_b128 v[190:193], v134 offset:33792
	ds_read_b128 v[194:197], v133 offset:32768
	ds_read_b128 v[198:201], v133 offset:33792
	global_load_lds_dwordx4 v[168:169], off
	v_lshl_add_u64 v[168:169], v[218:219], 0, s[14:15]
	s_mov_b32 m0, s30
	s_add_u32 s18, s18, 0x100
	global_load_lds_dwordx4 v[168:169], off
	s_waitcnt lgkmcnt(8)
	s_waitcnt vmcnt(10)
	s_barrier
; #define STAGE(P, GP, ktrel) do { const GAS char* _g = (GP) + (ktrel) * (BK * 2); \
;     __builtin_amdgcn_global_load_lds((const GAS unsigned*)(_g + so0), (unsigned*)((char*)(P) + tid_ * 16), 16, 0, 0); \
;     __builtin_amdgcn_global_load_lds((const GAS unsigned*)(_g + so1), (unsigned*)((char*)(P) + tid_ * 16 + 8192), 16, 0, 0); } while (0)
; #define WAIT_V(n) asm volatile("s_waitcnt vmcnt(" #n ")" ::: "memory")
; #define WAIT_L(n) asm volatile("s_waitcnt lgkmcnt(" #n ")" ::: "memory")
; #define BAR __builtin_amdgcn_s_barrier()
; #define SCHED __builtin_amdgcn_sched_barrier(0)
; #define LDA(dst, b, h) for (int m = 0; m < 4; ++m) for (int k = 0; k < 2; ++k) \
;     dst[m][k] = *reinterpret_cast<const bf16x8*>((char*)SA(b, h) + lds_byte(wr * 64 + m * 16 + fr, k * 32 + fq * 8))
; #define LDB(dst, b, h) for (int n = 0; n < 2; ++n) for (int k = 0; k < 2; ++k) \
;     dst[n][k] = *reinterpret_cast<const bf16x8*>((char*)SB(b, h) + lds_byte(wc * 32 + n * 16 + fr, k * 32 + fq * 8))
; #define MMA(ai, bj, At_, Bt_) do { __builtin_amdgcn_s_setprio(1); \
;     for (int m = 0; m < 4; ++m) for (int n = 0; n < 2; ++n) for (int k = 0; k < 2; ++k) \
;       acc[ai][bj][m][n] = __builtin_amdgcn_mfma_f32_16x16x32_bf16(At_[m][k], Bt_[n][k], acc[ai][bj][m][n], 0, 0, 0); \
;     __builtin_amdgcn_s_setprio(0); } while (0)
; template <int K, int LD = K>
; __device__ __forceinline__ void gemm_main(const GAS bf16* A, const GAS bf16* Bt, int brow, int bcol, f32x4 (&acc)[2][2][4][2]) {
;     ...
;     WAIT_L(8); BAR; WAIT_L(0); MMA(0, 0, At, B0); BAR; SCHED;
;     LDB(B1, 1, 1); STAGE(SB(1, 0), pB0, 3);
;     BAR; WAIT_L(0); MMA(0, 1, At, B1); BAR;
;     LDA(At, 1, 1); STAGE(SA(1, 0), pA0, 3);
;     BAR; WAIT_L(0); MMA(1, 0, At, B0); BAR; SCHED;
;     STAGE(SB(1, 1), pB1, 3);
;     WAIT_V(6); BAR; MMA(1, 1, At, B1); BAR;
;     pA0 += 4 * BK; pA1 += 4 * BK; pB0 += 4 * BK; pB1 += 4 * BK;
;     asm volatile("" : "+s"(pA0), "+s"(pA1), "+s"(pB0), "+s"(pB1));
;   }
	s_waitcnt lgkmcnt(0)
	s_addc_u32 s19, s19, 0
	s_waitcnt lgkmcnt(0)
	v_mfma_f32_16x16x32_bf16 v[126:129], v[164:167], v[146:149], v[126:129]
	v_mfma_f32_16x16x32_bf16 v[122:125], v[164:167], v[156:159], v[122:125]
	v_mfma_f32_16x16x32_bf16 v[118:121], v[178:181], v[146:149], v[118:121]
	v_mfma_f32_16x16x32_bf16 v[114:117], v[178:181], v[156:159], v[114:117]
	v_mfma_f32_16x16x32_bf16 v[110:113], v[186:189], v[146:149], v[110:113]
	v_mfma_f32_16x16x32_bf16 v[106:109], v[186:189], v[156:159], v[106:109]
	v_mfma_f32_16x16x32_bf16 v[102:105], v[194:197], v[146:149], v[102:105]
	v_mfma_f32_16x16x32_bf16 v[98:101], v[194:197], v[156:159], v[98:101]
	v_mfma_f32_16x16x32_bf16 v[126:129], v[174:177], v[150:153], v[126:129]
	v_mfma_f32_16x16x32_bf16 v[122:125], v[174:177], v[160:163], v[122:125]
	v_mfma_f32_16x16x32_bf16 v[118:121], v[182:185], v[150:153], v[118:121]
	v_mfma_f32_16x16x32_bf16 v[114:117], v[182:185], v[160:163], v[114:117]
	v_mfma_f32_16x16x32_bf16 v[110:113], v[190:193], v[150:153], v[110:113]
	v_mfma_f32_16x16x32_bf16 v[106:109], v[190:193], v[160:163], v[106:109]
	v_mfma_f32_16x16x32_bf16 v[102:105], v[198:201], v[150:153], v[102:105]
	v_mfma_f32_16x16x32_bf16 v[98:101], v[198:201], v[160:163], v[98:101]
	s_barrier
	v_add_u32_e32 v218, s40, v141
	v_lshl_add_u64 v[168:169], v[220:221], 0, s[16:17]
	v_readfirstlane_b32 s30, v218
	v_add_u32_e32 v218, 0x2000, v218
	s_mov_b32 m0, s30
	v_readfirstlane_b32 s30, v218
	ds_read_b128 v[202:205], v137
	ds_read_b128 v[206:209], v137 offset:1024
	ds_read_b128 v[210:213], v137 offset:2048
	ds_read_b128 v[214:217], v137 offset:3072
	global_load_lds_dwordx4 v[168:169], off
	v_lshl_add_u64 v[168:169], v[222:223], 0, s[16:17]
	s_mov_b32 m0, s30
	s_nop 0
	global_load_lds_dwordx4 v[168:169], off
	s_waitcnt vmcnt(10)
	s_barrier
	s_waitcnt lgkmcnt(0)
	s_waitcnt lgkmcnt(0)
	v_mfma_f32_16x16x32_bf16 v[94:97], v[164:167], v[202:205], v[94:97]
	v_mfma_f32_16x16x32_bf16 v[90:93], v[164:167], v[210:213], v[90:93]
	v_mfma_f32_16x16x32_bf16 v[86:89], v[178:181], v[202:205], v[86:89]
	v_mfma_f32_16x16x32_bf16 v[82:85], v[178:181], v[210:213], v[82:85]
	v_mfma_f32_16x16x32_bf16 v[78:81], v[186:189], v[202:205], v[78:81]
	v_mfma_f32_16x16x32_bf16 v[74:77], v[186:189], v[210:213], v[74:77]
	v_mfma_f32_16x16x32_bf16 v[70:73], v[194:197], v[202:205], v[70:73]
	v_mfma_f32_16x16x32_bf16 v[66:69], v[194:197], v[210:213], v[66:69]
	v_mfma_f32_16x16x32_bf16 v[94:97], v[174:177], v[206:209], v[94:97]
	v_mfma_f32_16x16x32_bf16 v[90:93], v[174:177], v[214:217], v[90:93]
	v_mfma_f32_16x16x32_bf16 v[86:89], v[182:185], v[206:209], v[86:89]
	v_mfma_f32_16x16x32_bf16 v[82:85], v[182:185], v[214:217], v[82:85]
	v_mfma_f32_16x16x32_bf16 v[78:81], v[190:193], v[206:209], v[78:81]
	v_mfma_f32_16x16x32_bf16 v[74:77], v[190:193], v[214:217], v[74:77]
	v_mfma_f32_16x16x32_bf16 v[70:73], v[198:201], v[206:209], v[70:73]
	v_mfma_f32_16x16x32_bf16 v[66:69], v[198:201], v[214:217], v[66:69]
	v_add_u32_e32 v218, 0x8000, v155
	v_add_u32_e32 v155, 0xa000, v155
	v_readfirstlane_b32 s30, v218
	v_lshl_add_u64 v[168:169], v[224:225], 0, s[16:17]
	s_mov_b32 m0, s30
	v_readfirstlane_b32 s30, v155
	s_barrier
	ds_read_b128 v[164:167], v136 offset:49152
	ds_read_b128 v[174:177], v136 offset:50176
	ds_read_b128 v[178:181], v135 offset:49152
	ds_read_b128 v[182:185], v135 offset:50176
	ds_read_b128 v[186:189], v134 offset:49152
	ds_read_b128 v[190:193], v134 offset:50176
	ds_read_b128 v[194:197], v133 offset:49152
	ds_read_b128 v[198:201], v133 offset:50176
	global_load_lds_dwordx4 v[168:169], off
	v_lshl_add_u64 v[168:169], v[226:227], 0, s[16:17]
	s_mov_b32 m0, s30
	s_nop 0
	global_load_lds_dwordx4 v[168:169], off
	s_barrier
	s_waitcnt lgkmcnt(0)
	s_waitcnt lgkmcnt(0)
	v_mfma_f32_16x16x32_bf16 v[62:65], v[164:167], v[146:149], v[62:65]
	v_mfma_f32_16x16x32_bf16 v[58:61], v[164:167], v[156:159], v[58:61]
	v_mfma_f32_16x16x32_bf16 v[54:57], v[178:181], v[146:149], v[54:57]
	v_mfma_f32_16x16x32_bf16 v[50:53], v[178:181], v[156:159], v[50:53]
	v_mfma_f32_16x16x32_bf16 v[46:49], v[186:189], v[146:149], v[46:49]
	v_mfma_f32_16x16x32_bf16 v[42:45], v[186:189], v[156:159], v[42:45]
	v_mfma_f32_16x16x32_bf16 v[38:41], v[194:197], v[146:149], v[38:41]
	v_mfma_f32_16x16x32_bf16 v[34:37], v[194:197], v[156:159], v[34:37]
	v_mfma_f32_16x16x32_bf16 v[62:65], v[174:177], v[150:153], v[62:65]
	v_mfma_f32_16x16x32_bf16 v[58:61], v[174:177], v[160:163], v[58:61]
	v_mfma_f32_16x16x32_bf16 v[54:57], v[182:185], v[150:153], v[54:57]
	v_mfma_f32_16x16x32_bf16 v[50:53], v[182:185], v[160:163], v[50:53]
	v_mfma_f32_16x16x32_bf16 v[46:49], v[190:193], v[150:153], v[46:49]
	v_mfma_f32_16x16x32_bf16 v[42:45], v[190:193], v[160:163], v[42:45]
	v_mfma_f32_16x16x32_bf16 v[38:41], v[198:201], v[150:153], v[38:41]
	v_mfma_f32_16x16x32_bf16 v[34:37], v[198:201], v[160:163], v[34:37]
	s_barrier
	v_add_u32_e32 v148, s41, v141
	v_lshl_add_u64 v[146:147], v[228:229], 0, s[16:17]
	v_readfirstlane_b32 s30, v148
	v_add_u32_e32 v148, 0x2000, v148
	s_mov_b32 m0, s30
	v_readfirstlane_b32 s30, v148
	global_load_lds_dwordx4 v[146:147], off
	v_lshl_add_u64 v[146:147], v[230:231], 0, s[16:17]
	s_mov_b32 m0, s30
	s_nop 0
	global_load_lds_dwordx4 v[146:147], off
	s_waitcnt vmcnt(10)
	s_barrier
	v_mfma_f32_16x16x32_bf16 v[30:33], v[164:167], v[202:205], v[30:33]
	v_mfma_f32_16x16x32_bf16 v[26:29], v[164:167], v[210:213], v[26:29]
	v_mfma_f32_16x16x32_bf16 v[22:25], v[178:181], v[202:205], v[22:25]
	v_mfma_f32_16x16x32_bf16 v[18:21], v[178:181], v[210:213], v[18:21]
	v_mfma_f32_16x16x32_bf16 v[14:17], v[186:189], v[202:205], v[14:17]
	v_mfma_f32_16x16x32_bf16 v[10:13], v[186:189], v[210:213], v[10:13]
	v_mfma_f32_16x16x32_bf16 v[6:9], v[194:197], v[202:205], v[6:9]
	v_mfma_f32_16x16x32_bf16 v[2:5], v[194:197], v[210:213], v[2:5]
	v_mfma_f32_16x16x32_bf16 v[30:33], v[174:177], v[206:209], v[30:33]
	v_mfma_f32_16x16x32_bf16 v[26:29], v[174:177], v[214:217], v[26:29]
	v_mfma_f32_16x16x32_bf16 v[22:25], v[182:185], v[206:209], v[22:25]
	v_mfma_f32_16x16x32_bf16 v[18:21], v[182:185], v[214:217], v[18:21]
	v_mfma_f32_16x16x32_bf16 v[14:17], v[190:193], v[206:209], v[14:17]
	v_mfma_f32_16x16x32_bf16 v[10:13], v[190:193], v[214:217], v[10:13]
	v_mfma_f32_16x16x32_bf16 v[6:9], v[198:201], v[206:209], v[6:9]
	v_mfma_f32_16x16x32_bf16 v[2:5], v[198:201], v[214:217], v[2:5]
	s_add_i32 s21, s21, 2
	s_cmp_lt_u32 s21, 12
	s_barrier
	s_cbranch_scc1 .LBB0_1226
	s_branch .Lpeel0_exit

; #define STAGE(P, GP, ktrel) do { const GAS char* _g = (GP) + (ktrel) * (BK * 2); \
;     __builtin_amdgcn_global_load_lds((const GAS unsigned*)(_g + so0), (unsigned*)((char*)(P) + tid_ * 16), 16, 0, 0); \
;     __builtin_amdgcn_global_load_lds((const GAS unsigned*)(_g + so1), (unsigned*)((char*)(P) + tid_ * 16 + 8192), 16, 0, 0); } while (0)
; #define WAIT_V(n) asm volatile("s_waitcnt vmcnt(" #n ")" ::: "memory")
; #define WAIT_L(n) asm volatile("s_waitcnt lgkmcnt(" #n ")" ::: "memory")
; #define BAR __builtin_amdgcn_s_barrier()
; #define LDA(dst, b, h) for (int m = 0; m < 4; ++m) for (int k = 0; k < 2; ++k) \
;     dst[m][k] = *reinterpret_cast<const bf16x8*>((char*)SA(b, h) + lds_byte(wr * 64 + m * 16 + fr, k * 32 + fq * 8))
; #define LDB(dst, b, h) for (int n = 0; n < 2; ++n) for (int k = 0; k < 2; ++k) \
;     dst[n][k] = *reinterpret_cast<const bf16x8*>((char*)SB(b, h) + lds_byte(wc * 32 + n * 16 + fr, k * 32 + fq * 8))
; #define MMA(ai, bj, At_, Bt_) do { __builtin_amdgcn_s_setprio(1); \
;     for (int m = 0; m < 4; ++m) for (int n = 0; n < 2; ++n) for (int k = 0; k < 2; ++k) \
;       acc[ai][bj][m][n] = __builtin_amdgcn_mfma_f32_16x16x32_bf16(At_[m][k], Bt_[n][k], acc[ai][bj][m][n], 0, 0, 0); \
;     __builtin_amdgcn_s_setprio(0); } while (0)
; template <int K, int LD = K>
; __device__ __forceinline__ void gemm_main(const GAS bf16* A, const GAS bf16* Bt, int brow, int bcol, f32x4 (&acc)[2][2][4][2]) {
;     ...
;   { LDB(B0, 0, 0); LDA(At, 0, 0); STAGE(SA(1, 1), pA1, 1);
;     BAR; WAIT_L(0); MMA(0, 0, At, B0); BAR;
;     LDB(B1, 0, 1); BAR; WAIT_L(0); MMA(0, 1, At, B1); BAR;
;     LDA(At, 0, 1); WAIT_V(4); BAR; WAIT_L(0); MMA(1, 0, At, B0); MMA(1, 1, At, B1); BAR; }
.Lpeel0_exit:
	v_lshl_add_u64 v[168:169], s[18:19], 0, v[138:139]
	v_readfirstlane_b32 s21, v144
	v_lshl_add_u64 v[168:169], v[168:169], 0, s[8:9]
	s_mov_b32 m0, s21
	v_lshl_add_u64 v[130:131], s[18:19], 0, v[130:131]
	v_readfirstlane_b32 s18, v145
	ds_read_b128 v[146:149], v143
	ds_read_b128 v[150:153], v143 offset:1024
	ds_read_b128 v[156:159], v143 offset:2048
	ds_read_b128 v[160:163], v143 offset:3072
	ds_read_b128 v[164:167], v136
	ds_read_b128 v[174:177], v136 offset:1024
	ds_read_b128 v[178:181], v135
	ds_read_b128 v[182:185], v135 offset:1024
	ds_read_b128 v[186:189], v134
	ds_read_b128 v[190:193], v134 offset:1024
	ds_read_b128 v[194:197], v133
	ds_read_b128 v[198:201], v133 offset:1024
	global_load_lds_dwordx4 v[168:169], off
	v_lshl_add_u64 v[130:131], v[130:131], 0, s[8:9]
	s_mov_b32 m0, s18
	s_nop 0
	global_load_lds_dwordx4 v[130:131], off
	s_waitcnt vmcnt(10)
	s_barrier
	s_waitcnt lgkmcnt(0)
	s_waitcnt lgkmcnt(0)
	v_mfma_f32_16x16x32_bf16 v[126:129], v[164:167], v[146:149], v[126:129]
	v_mfma_f32_16x16x32_bf16 v[122:125], v[164:167], v[156:159], v[122:125]
	v_mfma_f32_16x16x32_bf16 v[110:113], v[186:189], v[146:149], v[110:113]
	v_mfma_f32_16x16x32_bf16 v[106:109], v[186:189], v[156:159], v[106:109]
	v_mfma_f32_16x16x32_bf16 v[126:129], v[174:177], v[150:153], v[126:129]
	v_mfma_f32_16x16x32_bf16 v[122:125], v[174:177], v[160:163], v[122:125]
	v_mfma_f32_16x16x32_bf16 v[118:121], v[178:181], v[146:149], v[118:121]
	v_mfma_f32_16x16x32_bf16 v[114:117], v[178:181], v[156:159], v[114:117]
	v_mfma_f32_16x16x32_bf16 v[110:113], v[190:193], v[150:153], v[110:113]
	v_mfma_f32_16x16x32_bf16 v[106:109], v[190:193], v[160:163], v[106:109]
	v_mfma_f32_16x16x32_bf16 v[102:105], v[194:197], v[146:149], v[102:105]
	v_mfma_f32_16x16x32_bf16 v[98:101], v[194:197], v[156:159], v[98:101]
	v_mfma_f32_16x16x32_bf16 v[202:205], v[182:185], v[150:153], v[118:121]
	v_mfma_f32_16x16x32_bf16 v[206:209], v[182:185], v[160:163], v[114:117]
	v_mfma_f32_16x16x32_bf16 v[210:213], v[198:201], v[150:153], v[102:105]
	v_mfma_f32_16x16x32_bf16 v[214:217], v[198:201], v[160:163], v[98:101]
	s_barrier
	s_nop 1
	ds_read_b128 v[98:101], v142
	ds_read_b128 v[102:105], v142 offset:1024
	ds_read_b128 v[114:117], v142 offset:2048
	ds_read_b128 v[118:121], v142 offset:3072
	s_waitcnt vmcnt(8)
	s_barrier
	s_waitcnt lgkmcnt(0)
	s_waitcnt lgkmcnt(0)
	v_mfma_f32_16x16x32_bf16 v[94:97], v[164:167], v[98:101], v[94:97]
	v_mfma_f32_16x16x32_bf16 v[90:93], v[164:167], v[114:117], v[90:93]
	v_mfma_f32_16x16x32_bf16 v[78:81], v[186:189], v[98:101], v[78:81]
	v_mfma_f32_16x16x32_bf16 v[74:77], v[186:189], v[114:117], v[74:77]
	v_mfma_f32_16x16x32_bf16 v[94:97], v[174:177], v[102:105], v[94:97]
	v_mfma_f32_16x16x32_bf16 v[90:93], v[174:177], v[118:121], v[90:93]
	v_mfma_f32_16x16x32_bf16 v[86:89], v[178:181], v[98:101], v[86:89]
	v_mfma_f32_16x16x32_bf16 v[82:85], v[178:181], v[114:117], v[82:85]
	v_mfma_f32_16x16x32_bf16 v[78:81], v[190:193], v[102:105], v[78:81]
	v_mfma_f32_16x16x32_bf16 v[74:77], v[190:193], v[118:121], v[74:77]
	v_mfma_f32_16x16x32_bf16 v[70:73], v[194:197], v[98:101], v[70:73]
	v_mfma_f32_16x16x32_bf16 v[66:69], v[194:197], v[114:117], v[66:69]
	v_mfma_f32_16x16x32_bf16 v[142:145], v[182:185], v[102:105], v[86:89]
	v_mfma_f32_16x16x32_bf16 v[164:167], v[182:185], v[118:121], v[82:85]
	v_mfma_f32_16x16x32_bf16 v[174:177], v[198:201], v[102:105], v[70:73]
	v_mfma_f32_16x16x32_bf16 v[178:181], v[198:201], v[118:121], v[66:69]
	s_barrier
	s_nop 1
	ds_read_b128 v[66:69], v136 offset:16384
	ds_read_b128 v[70:73], v136 offset:17408
	ds_read_b128 v[82:85], v135 offset:16384
	ds_read_b128 v[86:89], v135 offset:17408
	ds_read_b128 v[182:185], v134 offset:16384
	ds_read_b128 v[186:189], v134 offset:17408
	ds_read_b128 v[190:193], v133 offset:16384
	ds_read_b128 v[194:197], v133 offset:17408
	s_waitcnt vmcnt(4)
	s_barrier
	s_waitcnt lgkmcnt(0)
	s_waitcnt lgkmcnt(0)
	v_mfma_f32_16x16x32_bf16 v[62:65], v[66:69], v[146:149], v[62:65]
	v_mfma_f32_16x16x32_bf16 v[58:61], v[66:69], v[156:159], v[58:61]
	v_mfma_f32_16x16x32_bf16 v[46:49], v[182:185], v[146:149], v[46:49]
	v_mfma_f32_16x16x32_bf16 v[42:45], v[182:185], v[156:159], v[42:45]
	v_mfma_f32_16x16x32_bf16 v[62:65], v[70:73], v[150:153], v[62:65]
	v_mfma_f32_16x16x32_bf16 v[58:61], v[70:73], v[160:163], v[58:61]
	v_mfma_f32_16x16x32_bf16 v[54:57], v[82:85], v[146:149], v[54:57]
	v_mfma_f32_16x16x32_bf16 v[50:53], v[82:85], v[156:159], v[50:53]
	v_mfma_f32_16x16x32_bf16 v[46:49], v[186:189], v[150:153], v[46:49]
	v_mfma_f32_16x16x32_bf16 v[42:45], v[186:189], v[160:163], v[42:45]
	v_mfma_f32_16x16x32_bf16 v[38:41], v[190:193], v[146:149], v[38:41]
	v_mfma_f32_16x16x32_bf16 v[34:37], v[190:193], v[156:159], v[34:37]
	v_mfma_f32_16x16x32_bf16 v[198:201], v[86:89], v[150:153], v[54:57]
	v_mfma_f32_16x16x32_bf16 v[218:221], v[86:89], v[160:163], v[50:53]
	v_mfma_f32_16x16x32_bf16 v[146:149], v[194:197], v[150:153], v[38:41]
	v_mfma_f32_16x16x32_bf16 v[150:153], v[194:197], v[160:163], v[34:37]
	v_mfma_f32_16x16x32_bf16 v[30:33], v[66:69], v[98:101], v[30:33]
	v_mfma_f32_16x16x32_bf16 v[26:29], v[66:69], v[114:117], v[26:29]
	v_mfma_f32_16x16x32_bf16 v[10:13], v[182:185], v[114:117], v[10:13]
	v_mfma_f32_16x16x32_bf16 v[2:5], v[190:193], v[114:117], v[2:5]
	v_mfma_f32_16x16x32_bf16 v[30:33], v[70:73], v[102:105], v[30:33]
	v_mfma_f32_16x16x32_bf16 v[26:29], v[70:73], v[118:121], v[26:29]
	v_mfma_f32_16x16x32_bf16 v[22:25], v[82:85], v[98:101], v[22:25]
	v_mfma_f32_16x16x32_bf16 v[18:21], v[82:85], v[114:117], v[18:21]
	v_mfma_f32_16x16x32_bf16 v[14:17], v[182:185], v[98:101], v[14:17]
	v_mfma_f32_16x16x32_bf16 v[10:13], v[186:189], v[118:121], v[10:13]
	v_mfma_f32_16x16x32_bf16 v[6:9], v[190:193], v[98:101], v[6:9]
	v_mfma_f32_16x16x32_bf16 v[2:5], v[194:197], v[118:121], v[2:5]
	v_mfma_f32_16x16x32_bf16 v[156:159], v[86:89], v[102:105], v[22:25]
	v_mfma_f32_16x16x32_bf16 v[160:163], v[86:89], v[118:121], v[18:21]
	v_mfma_f32_16x16x32_bf16 v[222:225], v[186:189], v[102:105], v[14:17]
	v_mfma_f32_16x16x32_bf16 v[182:185], v[194:197], v[102:105], v[6:9]
	s_barrier
; #define WAIT_V(n) asm volatile("s_waitcnt vmcnt(" #n ")" ::: "memory")
; #define WAIT_L(n) asm volatile("s_waitcnt lgkmcnt(" #n ")" ::: "memory")
; #define BAR __builtin_amdgcn_s_barrier()
; #define LDA(dst, b, h) for (int m = 0; m < 4; ++m) for (int k = 0; k < 2; ++k) \
;     dst[m][k] = *reinterpret_cast<const bf16x8*>((char*)SA(b, h) + lds_byte(wr * 64 + m * 16 + fr, k * 32 + fq * 8))
; #define LDB(dst, b, h) for (int n = 0; n < 2; ++n) for (int k = 0; k < 2; ++k) \
;     dst[n][k] = *reinterpret_cast<const bf16x8*>((char*)SB(b, h) + lds_byte(wc * 32 + n * 16 + fr, k * 32 + fq * 8))
; #define MMA(ai, bj, At_, Bt_) do { __builtin_amdgcn_s_setprio(1); \
;     for (int m = 0; m < 4; ++m) for (int n = 0; n < 2; ++n) for (int k = 0; k < 2; ++k) \
;       acc[ai][bj][m][n] = __builtin_amdgcn_mfma_f32_16x16x32_bf16(At_[m][k], Bt_[n][k], acc[ai][bj][m][n], 0, 0, 0); \
;     __builtin_amdgcn_s_setprio(0); } while (0)
; template <int K, int LD = K>
; __device__ __forceinline__ void gemm_main(const GAS bf16* A, const GAS bf16* Bt, int brow, int bcol, f32x4 (&acc)[2][2][4][2]) {
;     ...
;   { LDB(B0, 1, 0); LDA(At, 1, 0); WAIT_V(2); BAR; WAIT_L(0); MMA(0, 0, At, B0); BAR;
;     LDB(B1, 1, 1); WAIT_V(0); BAR; WAIT_L(0); MMA(0, 1, At, B1); BAR;
;     LDA(At, 1, 1); BAR; WAIT_L(0); MMA(1, 0, At, B0); MMA(1, 1, At, B1); BAR; }
;   if (wr == 0) BAR;
	s_nop 0
	ds_read_b128 v[6:9], v140
	ds_read_b128 v[14:17], v140 offset:1024
	ds_read_b128 v[186:189], v140 offset:2048
	ds_read_b128 v[190:193], v140 offset:3072
	ds_read_b128 v[18:21], v136 offset:32768
	ds_read_b128 v[22:25], v136 offset:33792
	ds_read_b128 v[34:37], v135 offset:32768
	ds_read_b128 v[38:41], v135 offset:33792
	ds_read_b128 v[50:53], v134 offset:32768
	ds_read_b128 v[54:57], v134 offset:33792
	ds_read_b128 v[194:197], v133 offset:32768
	ds_read_b128 v[226:229], v133 offset:33792
	s_waitcnt vmcnt(2)
	s_barrier
	s_waitcnt lgkmcnt(0)
	s_waitcnt lgkmcnt(0)
	v_mfma_f32_16x16x32_bf16 v[66:69], v[18:21], v[6:9], v[126:129]
	v_mfma_f32_16x16x32_bf16 v[118:121], v[22:25], v[14:17], v[66:69]
	v_mfma_f32_16x16x32_bf16 v[66:69], v[18:21], v[186:189], v[122:125]
	v_mfma_f32_16x16x32_bf16 v[114:117], v[22:25], v[190:193], v[66:69]
	v_mfma_f32_16x16x32_bf16 v[66:69], v[34:37], v[6:9], v[202:205]
	v_mfma_f32_16x16x32_bf16 v[102:105], v[38:41], v[14:17], v[66:69]
	v_mfma_f32_16x16x32_bf16 v[66:69], v[34:37], v[186:189], v[206:209]
	v_mfma_f32_16x16x32_bf16 v[98:101], v[38:41], v[190:193], v[66:69]
	v_mfma_f32_16x16x32_bf16 v[66:69], v[50:53], v[6:9], v[110:113]
	v_mfma_f32_16x16x32_bf16 v[86:89], v[54:57], v[14:17], v[66:69]
	v_mfma_f32_16x16x32_bf16 v[66:69], v[50:53], v[186:189], v[106:109]
	v_mfma_f32_16x16x32_bf16 v[82:85], v[54:57], v[190:193], v[66:69]
	v_mfma_f32_16x16x32_bf16 v[66:69], v[194:197], v[6:9], v[210:213]
	v_mfma_f32_16x16x32_bf16 v[70:73], v[226:229], v[14:17], v[66:69]
	v_mfma_f32_16x16x32_bf16 v[66:69], v[194:197], v[186:189], v[214:217]
	v_mfma_f32_16x16x32_bf16 v[66:69], v[226:229], v[190:193], v[66:69]
	s_barrier
	ds_read_b128 v[202:205], v137
	ds_read_b128 v[206:209], v137 offset:1024
	ds_read_b128 v[210:213], v137 offset:2048
	ds_read_b128 v[214:217], v137 offset:3072
	s_waitcnt vmcnt(0)
	s_barrier
	s_waitcnt lgkmcnt(0)
	s_waitcnt lgkmcnt(0)
	v_mfma_f32_16x16x32_bf16 v[94:97], v[18:21], v[202:205], v[94:97]
	v_mfma_f32_16x16x32_bf16 v[18:21], v[18:21], v[210:213], v[90:93]
	v_mfma_f32_16x16x32_bf16 v[122:125], v[22:25], v[214:217], v[18:21]
	v_mfma_f32_16x16x32_bf16 v[18:21], v[34:37], v[202:205], v[142:145]
	v_mfma_f32_16x16x32_bf16 v[110:113], v[38:41], v[206:209], v[18:21]
	v_mfma_f32_16x16x32_bf16 v[18:21], v[34:37], v[210:213], v[164:167]
	v_mfma_f32_16x16x32_bf16 v[106:109], v[38:41], v[214:217], v[18:21]
	v_mfma_f32_16x16x32_bf16 v[18:21], v[50:53], v[202:205], v[78:81]
	v_mfma_f32_16x16x32_bf16 v[126:129], v[22:25], v[206:209], v[94:97]
	v_mfma_f32_16x16x32_bf16 v[94:97], v[54:57], v[206:209], v[18:21]
	v_mfma_f32_16x16x32_bf16 v[18:21], v[50:53], v[210:213], v[74:77]
	v_mfma_f32_16x16x32_bf16 v[90:93], v[54:57], v[214:217], v[18:21]
	v_mfma_f32_16x16x32_bf16 v[18:21], v[194:197], v[202:205], v[174:177]
	v_mfma_f32_16x16x32_bf16 v[78:81], v[226:229], v[206:209], v[18:21]
	v_mfma_f32_16x16x32_bf16 v[18:21], v[194:197], v[210:213], v[178:181]
	v_mfma_f32_16x16x32_bf16 v[74:77], v[226:229], v[214:217], v[18:21]
	s_barrier
	ds_read_b128 v[140:143], v136 offset:49152
	ds_read_b128 v[164:167], v136 offset:50176
	ds_read_b128 v[174:177], v135 offset:49152
	ds_read_b128 v[178:181], v135 offset:50176
	ds_read_b128 v[194:197], v134 offset:49152
	ds_read_b128 v[134:137], v134 offset:50176
	ds_read_b128 v[226:229], v133 offset:49152
	ds_read_b128 v[230:233], v133 offset:50176
	s_barrier
	s_waitcnt lgkmcnt(0)
	s_waitcnt lgkmcnt(0)
	v_mfma_f32_16x16x32_bf16 v[18:21], v[140:143], v[6:9], v[62:65]
	v_mfma_f32_16x16x32_bf16 v[54:57], v[164:167], v[14:17], v[18:21]
	v_mfma_f32_16x16x32_bf16 v[18:21], v[140:143], v[186:189], v[58:61]
	v_mfma_f32_16x16x32_bf16 v[50:53], v[164:167], v[190:193], v[18:21]
	v_mfma_f32_16x16x32_bf16 v[18:21], v[174:177], v[6:9], v[198:201]
	v_mfma_f32_16x16x32_bf16 v[38:41], v[178:181], v[14:17], v[18:21]
	v_mfma_f32_16x16x32_bf16 v[18:21], v[174:177], v[186:189], v[218:221]
	v_mfma_f32_16x16x32_bf16 v[34:37], v[178:181], v[190:193], v[18:21]
	v_mfma_f32_16x16x32_bf16 v[18:21], v[194:197], v[6:9], v[46:49]
	v_mfma_f32_16x16x32_bf16 v[6:9], v[226:229], v[6:9], v[146:149]
	v_mfma_f32_16x16x32_bf16 v[22:25], v[134:137], v[14:17], v[18:21]
	v_mfma_f32_16x16x32_bf16 v[18:21], v[194:197], v[186:189], v[42:45]
	v_mfma_f32_16x16x32_bf16 v[14:17], v[230:233], v[14:17], v[6:9]
	v_mfma_f32_16x16x32_bf16 v[6:9], v[226:229], v[186:189], v[150:153]
	v_mfma_f32_16x16x32_bf16 v[18:21], v[134:137], v[190:193], v[18:21]
	v_mfma_f32_16x16x32_bf16 v[6:9], v[230:233], v[190:193], v[6:9]
	v_mfma_f32_16x16x32_bf16 v[26:29], v[140:143], v[210:213], v[26:29]
	v_mfma_f32_16x16x32_bf16 v[58:61], v[164:167], v[214:217], v[26:29]
	v_mfma_f32_16x16x32_bf16 v[26:29], v[174:177], v[202:205], v[156:159]
	v_mfma_f32_16x16x32_bf16 v[46:49], v[178:181], v[206:209], v[26:29]
	v_mfma_f32_16x16x32_bf16 v[26:29], v[174:177], v[210:213], v[160:163]
	v_mfma_f32_16x16x32_bf16 v[30:33], v[140:143], v[202:205], v[30:33]
	v_mfma_f32_16x16x32_bf16 v[42:45], v[178:181], v[214:217], v[26:29]
	v_mfma_f32_16x16x32_bf16 v[26:29], v[194:197], v[202:205], v[222:225]
	v_mfma_f32_16x16x32_bf16 v[10:13], v[194:197], v[210:213], v[10:13]
	v_mfma_f32_16x16x32_bf16 v[62:65], v[164:167], v[206:209], v[30:33]
	v_mfma_f32_16x16x32_bf16 v[30:33], v[134:137], v[206:209], v[26:29]
	v_mfma_f32_16x16x32_bf16 v[26:29], v[134:137], v[214:217], v[10:13]
	v_mfma_f32_16x16x32_bf16 v[10:13], v[226:229], v[202:205], v[182:185]
	v_mfma_f32_16x16x32_bf16 v[2:5], v[226:229], v[210:213], v[2:5]
	v_mfma_f32_16x16x32_bf16 v[10:13], v[230:233], v[206:209], v[10:13]
	v_mfma_f32_16x16x32_bf16 v[2:5], v[230:233], v[214:217], v[2:5]
	v_cmp_gt_u32_e32 vcc, s42, v132
	s_barrier
	s_and_saveexec_b64 s[18:19], vcc
	s_cbranch_execz .LBB0_1229
	s_barrier
